# all FLAT loads/stores/atomics re-encoded as GLOBAL (addresses are global memory); no lgkmcnt coupling
# speedup vs baseline: 1.0028x; 1.0028x over previous
.Ltr_go:
	ds_write2_b32 v61, v14, v15 offset1:1
	ds_write2_b32 v61, v16, v17 offset0:2 offset1:3
	v_add_u32_e32 v14, 0x1040, v61
	ds_write2_b32 v14, v10, v11 offset1:1
	v_add_u32_e32 v10, 0x1048, v61
	ds_write2_b32 v10, v12, v13 offset1:1
	v_add_u32_e32 v10, 0x2080, v61
	ds_write2_b32 v10, v6, v7 offset1:1
	v_add_u32_e32 v6, 0x2088, v61
	ds_write2_b32 v6, v8, v9 offset1:1
	v_add_u32_e32 v6, 0x30c0, v61
	ds_write2_b32 v6, v2, v3 offset1:1
	v_add_u32_e32 v2, 0x30c8, v61
	ds_write2_b32 v2, v4, v5 offset1:1
	v_add_u32_e32 v2, 0xc00, v55
	v_add_u32_e32 v4, 0xc00, v56
	s_waitcnt lgkmcnt(0)
	s_barrier
	ds_read2_b32 v[2:3], v2 offset0:12 offset1:142
	ds_read2_b32 v[4:5], v4 offset0:77 offset1:207
	v_add_u32_e32 v8, 0x400, v55
	ds_read2_b32 v[8:9], v8 offset0:4 offset1:134
	v_add_u32_e32 v6, 0x800, v56
	v_add_u32_e32 v10, 0x400, v56
	s_waitcnt lgkmcnt(1)
	v_cvt_pk_bf16_f32 v4, v2, v4
	v_add_u32_e32 v2, 0x800, v55
	v_cvt_pk_bf16_f32 v5, v3, v5
	ds_read2_b32 v[2:3], v2 offset0:8 offset1:138
	ds_read2_b32 v[6:7], v6 offset0:73 offset1:203
	ds_read2_b32 v[10:11], v10 offset0:69 offset1:199
	ds_read2_b32 v[12:13], v55 offset1:130
	ds_read2_b32 v[14:15], v56 offset0:65 offset1:195
	v_add_u32_e32 v16, v42, v43
	v_cmp_eq_u32_e32 vcc, 1, v35
	s_waitcnt lgkmcnt(2)
	v_cvt_pk_bf16_f32 v8, v8, v10
	v_lshlrev_b32_e32 v10, 1, v16
	v_and_b32_e32 v10, 0xffffffe0, v10
	v_lshl_add_u32 v10, v39, 4, v10
	v_and_or_b32 v10, v16, 15, v10
	v_cndmask_b32_e32 v10, v16, v10, vcc
	v_cvt_pk_bf16_f32 v3, v3, v7
	v_cvt_pk_bf16_f32 v9, v9, v11
	s_waitcnt lgkmcnt(0)
	v_cvt_pk_bf16_f32 v7, v13, v15
	v_ashrrev_i32_e32 v13, 31, v10
	v_mad_u64_u32 v[10:11], s[4:5], v10, v1, 0
	v_cvt_pk_bf16_f32 v2, v2, v6
	v_cvt_pk_bf16_f32 v6, v12, v14
	v_mov_b32_e32 v12, v11
	v_mad_u64_u32 v[12:13], s[4:5], v13, v1, v[12:13]
	v_mov_b32_e32 v11, v12
	v_lshl_add_u64 v[10:11], v[10:11], 1, v[40:41]
	v_ashrrev_i32_e32 v39, 31, v38
	v_lshl_add_u64 v[10:11], v[38:39], 1, v[10:11]
	v_mov_b32_e32 v47, v45
	v_lshl_add_u64 v[10:11], v[10:11], 0, v[46:47]
	global_store_dwordx4 v[10:11], v[6:9], off
	global_store_dwordx4 v[10:11], v[2:5], off offset:16
	v_add_u32_e32 v57, s2, v57
	v_add_u32_e32 v58, s3, v58
	v_add_u32_e32 v59, s11, v59
	v_add_u32_e32 v60, s33, v60
	s_andn2_b64 vcc, exec, s[22:23]
	v_mov_b32_e32 v39, v68
	v_mov_b32_e32 v35, v66
	v_mov_b32_e32 v42, v50
	v_mov_b32_e32 v38, v67
	v_mov_b64_e32 v[40:41], v[48:49]
	v_mov_b32_e32 v1, v65
	s_waitcnt vmcnt(2)
	v_mov_b64_e32 v[14:15], v[18:19]
	v_mov_b64_e32 v[16:17], v[20:21]
	v_mov_b64_e32 v[10:11], v[22:23]
	v_mov_b64_e32 v[12:13], v[24:25]
	v_mov_b64_e32 v[6:7], v[26:27]
	v_mov_b64_e32 v[8:9], v[28:29]
	v_mov_b64_e32 v[2:3], v[30:31]
	v_mov_b64_e32 v[4:5], v[32:33]
	s_waitcnt lgkmcnt(0)
	s_barrier
	s_cbranch_vccz .LBB0_50

.LBB0_52:
	v_lshl_add_u64 v[10:11], s[68:69], 0, v[4:5]
	v_lshl_add_u64 v[12:13], s[6:7], 0, v[4:5]
	v_cmp_gt_u64_e32 vcc, s[20:21], v[8:9]
	v_lshl_add_u64 v[8:9], v[8:9], 0, s[12:13]
	v_lshl_add_u64 v[4:5], v[4:5], 0, s[14:15]
	v_cndmask_b32_e32 v11, v13, v11, vcc
	v_cndmask_b32_e32 v10, v12, v10, vcc
	global_load_dwordx4 v[10:13], v[10:11], off
	v_add_co_u32_e32 v14, vcc, -4, v6
	s_waitcnt vmcnt(0)
	v_cvt_pk_bf16_f32 v10, v10, v11
	v_addc_co_u32_e32 v15, vcc, -1, v7, vcc
	v_cmp_lt_u64_e32 vcc, s[22:23], v[8:9]
	v_lshl_add_u64 v[6:7], v[6:7], 0, s[16:17]
	s_or_b64 s[18:19], vcc, s[18:19]
	v_cvt_pk_bf16_f32 v11, v12, v13
	global_store_dwordx2 v[14:15], v[10:11], off
	s_andn2_b64 exec, exec, s[18:19]
	s_cbranch_execnz .LBB0_52

.LBB0_55:
	global_load_dwordx4 v[12:15], v[8:9], off offset:-8
	v_lshl_add_u64 v[10:11], v[10:11], 0, s[12:13]
	v_cmp_lt_u64_e32 vcc, s[16:17], v[10:11]
	v_lshl_add_u64 v[8:9], v[8:9], 0, s[4:5]
	s_or_b64 s[14:15], vcc, s[14:15]
	s_waitcnt vmcnt(0)
	v_cvt_pk_bf16_f32 v12, v12, v13
	v_cvt_pk_bf16_f32 v13, v14, v15
	global_store_dwordx2 v[6:7], v[12:13], off
	v_lshl_add_u64 v[6:7], v[6:7], 0, s[6:7]
	s_andn2_b64 exec, exec, s[14:15]
	s_cbranch_execnz .LBB0_55
	s_or_b64 exec, exec, s[14:15]
	s_add_u32 s14, s8, 0x39c4000
	s_addc_u32 s15, s9, 0
	v_lshl_add_u64 v[4:5], s[80:81], 0, v[4:5]
	s_mov_b64 s[6:7], 0
	s_mov_b32 s3, 0x300000
	v_mov_b64_e32 v[6:7], s[14:15]
	v_mov_b32_e32 v9, 0
	s_mov_b64 s[14:15], 0x7ffff
	v_mov_b64_e32 v[10:11], v[2:3]
.LBB0_57:
	global_load_dwordx4 v[12:15], v[4:5], off offset:-8
	v_alignbit_b32 v8, v11, v10, 18
	v_and_b32_e32 v1, 0x3ffff, v10
	v_lshrrev_b32_e32 v18, 18, v11
	v_lshl_add_u64 v[10:11], v[10:11], 0, s[12:13]
	v_mad_u64_u32 v[16:17], s[16:17], v8, s3, v[6:7]
	v_lshlrev_b32_e32 v8, 3, v1
	v_cmp_lt_u64_e32 vcc, s[14:15], v[10:11]
	v_mad_u32_u24 v17, v18, s3, v17
	v_lshl_add_u64 v[4:5], v[4:5], 0, s[4:5]
	s_or_b64 s[6:7], vcc, s[6:7]
	v_lshl_add_u64 v[16:17], v[16:17], 0, v[8:9]
	s_waitcnt vmcnt(0)
	v_cvt_pk_bf16_f32 v12, v12, v13
	v_cvt_pk_bf16_f32 v13, v14, v15
	global_store_dwordx2 v[16:17], v[12:13], off
	s_andn2_b64 exec, exec, s[6:7]
	s_cbranch_execnz .LBB0_57

.LBB0_60:
	v_bfe_u32 v10, v8, 16, 4
	v_alignbit_b32 v11, v9, v8, 20
	v_lshlrev_b32_e32 v4, 12, v11
	v_lshlrev_b32_e32 v12, 8, v10
	v_or3_b32 v4, v12, v4, v36
	v_bfe_u32 v14, v8, 14, 2
	v_lshlrev_b64 v[12:13], 10, v[4:5]
	v_bfe_u32 v1, v8, 8, 6
	v_lshlrev_b32_e32 v4, 8, v14
	s_waitcnt lgkmcnt(0)
	v_lshl_add_u64 v[12:13], s[82:83], 0, v[12:13]
	v_lshl_add_u64 v[12:13], v[12:13], 0, v[4:5]
	v_lshlrev_b32_e32 v4, 2, v1
	v_lshl_add_u64 v[12:13], v[12:13], 0, v[4:5]
	global_load_dword v12, v[12:13], off
	v_mad_u64_u32 v[10:11], s[16:17], v11, 24, v[10:11]
	v_lshl_or_b32 v4, v10, 2, v14
	v_add_u32_e32 v4, 32, v4
	v_lshlrev_b64 v[10:11], 15, v[4:5]
	v_lshl_add_u64 v[8:9], v[8:9], 0, s[12:13]
	v_lshlrev_b32_e32 v4, 9, v1
	v_lshl_add_u64 v[10:11], s[4:5], 0, v[10:11]
	v_cmp_lt_u64_e32 vcc, s[14:15], v[8:9]
	v_lshl_add_u64 v[10:11], v[10:11], 0, v[4:5]
	s_or_b64 s[6:7], vcc, s[6:7]
	v_lshl_add_u64 v[10:11], v[10:11], 0, v[6:7]
	s_waitcnt vmcnt(0)
	v_cvt_pk_bf16_f32 v1, v12, s0
	global_store_short v[10:11], v1, off
	s_andn2_b64 exec, exec, s[6:7]
	s_cbranch_execnz .LBB0_60

.LBB0_63:
	s_or_b64 exec, exec, s[0:1]
	v_mul_f32_e32 v17, v6, v6
	v_fmamk_f32 v18, v17, 0xb94c1982, v10
	v_fmaak_f32 v18, v17, v18, 0xbe2aaa9d
	v_mul_f32_e32 v18, v17, v18
	v_fmac_f32_e32 v6, v6, v18
	v_fmamk_f32 v18, v17, 0x37d75334, v11
	v_fmaak_f32 v18, v17, v18, 0x3d2aabf7
	v_fmaak_f32 v18, v17, v18, 0xbf000004
	v_fma_f32 v17, v17, v18, 1.0
	v_lshlrev_b32_e32 v18, 30, v16
	v_and_b32_e32 v16, 1, v16
	v_cmp_eq_u32_e32 vcc, 0, v16
	v_lshl_add_u64 v[8:9], v[8:9], 0, s[12:13]
	s_nop 0
	v_cndmask_b32_e32 v16, v17, v6, vcc
	v_xor_b32_e32 v6, 0x80000000, v6
	v_cndmask_b32_e32 v6, v6, v17, vcc
	v_bitop3_b32 v19, v16, v18, s40 bitop3:0x78
	v_bitop3_b32 v6, v6, v18, s40 bitop3:0x78
	v_cmp_lg_f32_e32 vcc, s3, v15
	s_nop 1
	v_cndmask_b32_e32 v16, v14, v6, vcc
	v_cndmask_b32_e32 v17, v14, v19, vcc
	v_add_co_u32_e32 v18, vcc, -4, v4
	s_nop 1
	v_addc_co_u32_e32 v19, vcc, -1, v5, vcc
	v_cmp_lt_u64_e32 vcc, s[20:21], v[8:9]
	s_or_b64 s[18:19], vcc, s[18:19]
	v_lshl_add_u64 v[4:5], v[4:5], 0, s[16:17]
	global_store_dwordx2 v[18:19], v[16:17], off
	s_andn2_b64 exec, exec, s[18:19]
	s_cbranch_execz .LBB0_68

.LBB0_70:
	s_or_b64 exec, exec, s[0:1]
	v_mul_f32_e32 v15, v6, v6
	v_fmamk_f32 v16, v15, 0xb94c1982, v8
	v_fmaak_f32 v16, v15, v16, 0xbe2aaa9d
	v_mul_f32_e32 v16, v15, v16
	v_fmac_f32_e32 v6, v6, v16
	v_fmamk_f32 v16, v15, 0x37d75334, v9
	v_fmaak_f32 v16, v15, v16, 0x3d2aabf7
	v_fmaak_f32 v16, v15, v16, 0xbf000004
	v_fma_f32 v15, v15, v16, 1.0
	v_lshlrev_b32_e32 v16, 30, v14
	v_and_b32_e32 v14, 1, v14
	v_cmp_eq_u32_e32 vcc, 0, v14
	v_lshl_add_u64 v[2:3], v[2:3], 0, s[12:13]
	s_nop 0
	v_cndmask_b32_e32 v14, v15, v6, vcc
	v_xor_b32_e32 v6, 0x80000000, v6
	v_cndmask_b32_e32 v6, v6, v15, vcc
	v_bitop3_b32 v17, v14, v16, s39 bitop3:0x78
	v_bitop3_b32 v6, v6, v16, s39 bitop3:0x78
	v_cmp_lg_f32_e32 vcc, s3, v13
	s_nop 1
	v_cndmask_b32_e32 v14, v12, v6, vcc
	v_cndmask_b32_e32 v15, v12, v17, vcc
	v_add_co_u32_e32 v16, vcc, -4, v4
	s_nop 1
	v_addc_co_u32_e32 v17, vcc, -1, v5, vcc
	v_cmp_lt_u64_e32 vcc, s[20:21], v[2:3]
	s_or_b64 s[18:19], vcc, s[18:19]
	v_lshl_add_u64 v[4:5], v[4:5], 0, s[16:17]
	global_store_dwordx2 v[16:17], v[14:15], off
	s_andn2_b64 exec, exec, s[18:19]
	s_cbranch_execz .LBB0_75

.LBB0_75:
	s_or_b64 exec, exec, s[14:15]
	s_cmp_eq_u32 s10, 0
	s_cselect_b64 s[0:1], -1, 0
	v_cmp_gt_i32_e32 vcc, 64, v34
	s_and_b64 s[4:5], s[0:1], vcc
	s_and_saveexec_b64 s[0:1], s[4:5]
	s_cbranch_execz .LBB0_77
	v_lshl_add_u64 v[2:3], v[34:35], 2, s[8:9]
	v_mov_b32_e32 v1, 0
	global_store_dword v[2:3], v1, off

.LBB0_147:
	v_or_b32_e32 v130, s48, v158
	v_add_u32_e32 v134, v130, v159
	v_lshlrev_b32_e32 v130, 5, v156
	v_lshlrev_b32_e32 v131, 2, v157
	v_or3_b32 v130, v130, v131, s46
	v_cvt_pk_bf16_f32 v124, v124, v125
	v_cvt_pk_bf16_f32 v125, v126, v127
	v_mov_b64_e32 v[126:127], s[12:13]
	v_ashrrev_i32_e32 v131, 31, v130
	v_mad_i64_i32 v[132:133], s[4:5], v134, s61, v[126:127]
	v_lshlrev_b64 v[130:131], 1, v[130:131]
	v_lshl_add_u64 v[132:133], v[132:133], 0, v[130:131]
	v_cvt_pk_bf16_f32 v120, v120, v121
	v_cvt_pk_bf16_f32 v121, v122, v123
	global_store_dwordx2 v[132:133], v[120:121], off offset:32
	v_or_b32_e32 v120, 16, v134
	v_cvt_pk_bf16_f32 v116, v116, v117
	v_cvt_pk_bf16_f32 v117, v118, v119
	v_mad_i64_i32 v[118:119], s[4:5], v120, s61, v[126:127]
	v_lshl_add_u64 v[118:119], v[118:119], 0, v[130:131]
	v_cvt_pk_bf16_f32 v112, v112, v113
	v_cvt_pk_bf16_f32 v113, v114, v115
	global_store_dwordx2 v[118:119], v[112:113], off offset:32
	v_or_b32_e32 v112, 32, v134
	v_cvt_pk_bf16_f32 v108, v108, v109
	v_cvt_pk_bf16_f32 v109, v110, v111
	v_mad_i64_i32 v[110:111], s[4:5], v112, s61, v[126:127]
	v_lshl_add_u64 v[110:111], v[110:111], 0, v[130:131]
	v_cvt_pk_bf16_f32 v104, v104, v105
	v_cvt_pk_bf16_f32 v105, v106, v107
	global_store_dwordx2 v[110:111], v[104:105], off offset:32
	v_or_b32_e32 v104, 48, v134
	v_cvt_pk_bf16_f32 v96, v96, v97
	v_cvt_pk_bf16_f32 v97, v98, v99
	v_mad_i64_i32 v[98:99], s[4:5], v104, s61, v[126:127]
	v_cvt_pk_bf16_f32 v52, v52, v53
	v_cvt_pk_bf16_f32 v53, v54, v55
	v_add_u32_e32 v54, 0x80, v134
	v_lshl_add_u64 v[98:99], v[98:99], 0, v[130:131]
	v_mad_i64_i32 v[54:55], s[4:5], v54, s61, v[126:127]
	v_cvt_pk_bf16_f32 v60, v60, v61
	v_cvt_pk_bf16_f32 v61, v62, v63
	global_store_dwordx2 v[98:99], v[52:53], off offset:288
	v_cvt_pk_bf16_f32 v52, v76, v77
	v_cvt_pk_bf16_f32 v53, v78, v79
	v_lshl_add_u64 v[54:55], v[54:55], 0, v[130:131]
	global_store_dwordx2 v[98:99], v[60:61], off offset:256
	global_store_dwordx2 v[54:55], v[52:53], off
	v_cvt_pk_bf16_f32 v52, v64, v65
	v_cvt_pk_bf16_f32 v53, v66, v67
	v_add_u32_e32 v60, 0x90, v134
	global_store_dwordx2 v[54:55], v[52:53], off offset:32
	v_cvt_pk_bf16_f32 v52, v56, v57
	v_mad_i64_i32 v[56:57], s[4:5], v60, s61, v[126:127]
	v_lshl_add_u64 v[56:57], v[56:57], 0, v[130:131]
	v_cvt_pk_bf16_f32 v48, v48, v49
	v_cvt_pk_bf16_f32 v49, v50, v51
	global_store_dwordx2 v[56:57], v[48:49], off offset:32
	v_add_u32_e32 v48, 0xa0, v134
	v_cvt_pk_bf16_f32 v44, v44, v45
	v_cvt_pk_bf16_f32 v45, v46, v47
	v_mad_i64_i32 v[46:47], s[4:5], v48, s61, v[126:127]
	v_cvt_pk_bf16_f32 v84, v84, v85
	v_cvt_pk_bf16_f32 v85, v86, v87
	v_lshl_add_u64 v[46:47], v[46:47], 0, v[130:131]
	v_cvt_pk_bf16_f32 v40, v40, v41
	v_cvt_pk_bf16_f32 v41, v42, v43
	global_store_dwordx2 v[98:99], v[84:85], off offset:32
	v_cvt_pk_bf16_f32 v84, v100, v101
	v_cvt_pk_bf16_f32 v85, v102, v103
	global_store_dwordx2 v[46:47], v[40:41], off offset:32
	v_add_u32_e32 v40, 0xb0, v134
	global_store_dwordx2 v[132:133], v[84:85], off offset:256
	v_cvt_pk_bf16_f32 v84, v92, v93
	v_cvt_pk_bf16_f32 v85, v94, v95
	v_cvt_pk_bf16_f32 v36, v36, v37
	v_cvt_pk_bf16_f32 v37, v38, v39
	v_mad_i64_i32 v[38:39], s[4:5], v40, s61, v[126:127]
	global_store_dwordx2 v[132:133], v[84:85], off offset:288
	v_cvt_pk_bf16_f32 v84, v88, v89
	v_cvt_pk_bf16_f32 v85, v90, v91
	v_cvt_pk_bf16_f32 v80, v80, v81
	v_cvt_pk_bf16_f32 v81, v82, v83
	v_cvt_pk_bf16_f32 v72, v72, v73
	v_cvt_pk_bf16_f32 v73, v74, v75
	v_cvt_pk_bf16_f32 v68, v68, v69
	v_cvt_pk_bf16_f32 v69, v70, v71
	v_cvt_pk_bf16_f32 v53, v58, v59
	v_lshl_add_u64 v[38:39], v[38:39], 0, v[130:131]
	v_cvt_pk_bf16_f32 v32, v32, v33
	v_cvt_pk_bf16_f32 v33, v34, v35
	v_cvt_pk_bf16_f32 v28, v28, v29
	v_cvt_pk_bf16_f32 v29, v30, v31
	v_cvt_pk_bf16_f32 v24, v24, v25
	v_cvt_pk_bf16_f32 v25, v26, v27
	v_cvt_pk_bf16_f32 v20, v20, v21
	v_cvt_pk_bf16_f32 v21, v22, v23
	v_cvt_pk_bf16_f32 v16, v16, v17
	v_cvt_pk_bf16_f32 v17, v18, v19
	v_cvt_pk_bf16_f32 v12, v12, v13
	v_cvt_pk_bf16_f32 v13, v14, v15
	v_cvt_pk_bf16_f32 v8, v8, v9
	v_cvt_pk_bf16_f32 v9, v10, v11
	v_cvt_pk_bf16_f32 v4, v4, v5
	v_cvt_pk_bf16_f32 v5, v6, v7
	v_cvt_pk_bf16_f32 v0, v0, v1
	v_cvt_pk_bf16_f32 v1, v2, v3
	s_mov_b64 s[4:5], -1
	s_andn2_b64 vcc, exec, s[0:1]
	s_mov_b32 s14, s63
	s_mov_b32 s65, s64
	global_store_dwordx2 v[132:133], v[124:125], off
	global_store_dwordx2 v[118:119], v[116:117], off
	global_store_dwordx2 v[110:111], v[108:109], off
	global_store_dwordx2 v[98:99], v[96:97], off
	global_store_dwordx2 v[118:119], v[84:85], off offset:256
	global_store_dwordx2 v[118:119], v[80:81], off offset:288
	global_store_dwordx2 v[110:111], v[72:73], off offset:256
	global_store_dwordx2 v[110:111], v[68:69], off offset:288
	global_store_dwordx2 v[56:57], v[52:53], off
	global_store_dwordx2 v[46:47], v[44:45], off
	global_store_dwordx2 v[38:39], v[36:37], off
	global_store_dwordx2 v[38:39], v[32:33], off offset:32
	global_store_dwordx2 v[54:55], v[28:29], off offset:256
	global_store_dwordx2 v[54:55], v[24:25], off offset:288
	global_store_dwordx2 v[56:57], v[20:21], off offset:256
	global_store_dwordx2 v[56:57], v[16:17], off offset:288
	global_store_dwordx2 v[46:47], v[12:13], off offset:256
	global_store_dwordx2 v[46:47], v[8:9], off offset:288
	global_store_dwordx2 v[38:39], v[4:5], off offset:256
	global_store_dwordx2 v[38:39], v[0:1], off offset:288
	s_cbranch_vccz .LBB0_164

.LBB0_175:
	v_lshl_add_u64 v[4:5], v[128:129], 2, v[46:47]
	global_store_dwordx4 v[4:5], v[0:3], off offset:576
	s_nop 1
	v_cvt_pk_bf16_f32 v0, v0, v1
	v_cvt_pk_bf16_f32 v1, v2, v3
	v_lshl_add_u64 v[2:3], v[128:129], 1, v[42:43]
	global_store_dwordx2 v[2:3], v[0:1], off offset:288

.LBB0_189:
	s_or_b64 exec, exec, s[56:57]
	v_or_b32_e32 v128, s52, v145
	v_add_u32_e32 v132, v128, v146
	v_lshlrev_b32_e32 v128, 2, v143
	v_lshl_or_b32 v131, v142, 5, v128
	v_or_b32_e32 v128, s0, v131
	s_cmp_lg_u32 s87, 0
	v_ashrrev_i32_e32 v133, 31, v132
	s_cselect_b64 s[52:53], -1, 0
	v_and_b32_e32 v138, 0xcf, v132
	v_lshlrev_b64 v[134:135], 10, v[132:133]
	v_and_b32_e32 v146, 0xffffff00, v132
	v_add_u32_e32 v130, 0xffffff00, v128
	s_and_b64 vcc, exec, s[52:53]
	v_lshl_add_u64 v[136:137], s[44:45], 0, v[134:135]
	v_and_b32_e32 v145, 44, v131
	v_ashrrev_i32_e32 v131, 31, v130
	v_add_u32_e32 v147, v130, v146
	v_lshlrev_b32_e32 v134, 1, v138
	s_cbranch_vccz .LBB0_191
	v_lshl_add_u64 v[138:139], v[130:131], 2, v[136:137]
	global_store_dwordx4 v[138:139], v[124:127], off
	v_and_or_b32 v138, v147, s80, v145
	v_mov_b32_e32 v135, v129
	v_ashrrev_i32_e32 v139, 31, v138
	v_lshl_add_u64 v[140:141], s[48:49], 0, v[134:135]
	v_lshlrev_b64 v[142:143], 9, v[138:139]
	v_cvt_pk_bf16_f32 v135, v124, s0
	v_lshl_add_u64 v[142:143], v[140:141], 0, v[142:143]
	global_store_short v[142:143], v135, off
	v_or_b32_e32 v142, 1, v138
	v_ashrrev_i32_e32 v143, 31, v142
	v_lshlrev_b64 v[142:143], 9, v[142:143]
	v_cvt_pk_bf16_f32 v135, v125, s0
	v_lshl_add_u64 v[142:143], v[140:141], 0, v[142:143]
	global_store_short v[142:143], v135, off
	v_or_b32_e32 v142, 2, v138
	v_ashrrev_i32_e32 v143, 31, v142
	v_or_b32_e32 v138, 3, v138
	v_lshlrev_b64 v[142:143], 9, v[142:143]
	v_ashrrev_i32_e32 v139, 31, v138
	v_cvt_pk_bf16_f32 v135, v126, s0
	v_lshl_add_u64 v[142:143], v[140:141], 0, v[142:143]
	v_lshlrev_b64 v[138:139], 9, v[138:139]
	global_store_short v[142:143], v135, off
	v_cvt_pk_bf16_f32 v135, v127, s0
	v_lshl_add_u64 v[138:139], v[140:141], 0, v[138:139]
	global_store_short v[138:139], v135, off
	s_mov_b64 s[0:1], 0
	s_branch .LBB0_192

.LBB0_192:
	v_lshlrev_b64 v[138:139], 8, v[132:133]
	s_andn2_b64 vcc, exec, s[0:1]
	v_lshl_add_u64 v[140:141], v[138:139], 2, s[42:43]
	v_lshl_add_u64 v[138:139], v[138:139], 1, s[46:47]
	s_cbranch_vccnz .LBB0_194
	v_lshl_add_u64 v[142:143], v[128:129], 2, v[140:141]
	global_store_dwordx4 v[142:143], v[124:127], off
	s_nop 1
	v_cvt_pk_bf16_f32 v124, v124, v125
	v_cvt_pk_bf16_f32 v125, v126, v127
	v_lshl_add_u64 v[126:127], v[128:129], 1, v[138:139]
	global_store_dwordx2 v[126:127], v[124:125], off
.LBB0_194:
	v_cndmask_b32_e64 v124, 0, 1, s[52:53]
	v_or_b32_e32 v125, 16, v128
	v_cmp_ne_u32_e64 s[0:1], 1, v124
	v_add_u32_e32 v124, 0xffffff10, v128
	s_andn2_b64 vcc, exec, s[52:53]
	v_and_b32_e32 v133, 60, v125
	v_ashrrev_i32_e32 v125, 31, v124
	v_add_u32_e32 v148, v124, v146
	s_cbranch_vccnz .LBB0_199
	v_lshl_add_u64 v[126:127], v[124:125], 2, v[136:137]
	global_store_dwordx4 v[126:127], v[120:123], off
	v_and_or_b32 v126, v148, s80, v133
	v_mov_b32_e32 v135, v129
	v_ashrrev_i32_e32 v127, 31, v126
	v_lshl_add_u64 v[142:143], s[48:49], 0, v[134:135]
	v_lshlrev_b64 v[150:151], 9, v[126:127]
	v_cvt_pk_bf16_f32 v135, v120, s0
	v_lshl_add_u64 v[150:151], v[142:143], 0, v[150:151]
	global_store_short v[150:151], v135, off
	v_or_b32_e32 v150, 1, v126
	v_ashrrev_i32_e32 v151, 31, v150
	v_lshlrev_b64 v[150:151], 9, v[150:151]
	v_cvt_pk_bf16_f32 v127, v121, s0
	v_lshl_add_u64 v[150:151], v[142:143], 0, v[150:151]
	global_store_short v[150:151], v127, off
	v_or_b32_e32 v150, 2, v126
	v_ashrrev_i32_e32 v151, 31, v150
	v_lshlrev_b64 v[150:151], 9, v[150:151]
	v_cvt_pk_bf16_f32 v127, v122, s0
	v_lshl_add_u64 v[150:151], v[142:143], 0, v[150:151]
	v_or_b32_e32 v126, 3, v126
	global_store_short v[150:151], v127, off
	v_ashrrev_i32_e32 v127, 31, v126
	v_lshlrev_b64 v[126:127], 9, v[126:127]
	v_cvt_pk_bf16_f32 v135, v123, s0
	v_lshl_add_u64 v[126:127], v[142:143], 0, v[126:127]
	global_store_short v[126:127], v135, off
	s_cbranch_execnz .LBB0_197
.LBB0_196:
	v_lshl_add_u64 v[126:127], v[128:129], 2, v[140:141]
	global_store_dwordx4 v[126:127], v[120:123], off offset:64
	s_nop 1
	v_cvt_pk_bf16_f32 v120, v120, v121
	v_cvt_pk_bf16_f32 v121, v122, v123
	v_lshl_add_u64 v[122:123], v[128:129], 1, v[138:139]
	global_store_dwordx2 v[122:123], v[120:121], off offset:32
.LBB0_197:
	v_or_b32_e32 v122, 16, v132
	s_movk_i32 s52, 0xdf
	v_ashrrev_i32_e32 v123, 31, v122
	v_bitop3_b32 v135, v132, s52, 16 bitop3:0xc8
	v_lshlrev_b64 v[120:121], 10, v[122:123]
	s_and_b64 vcc, exec, s[0:1]
	v_lshl_add_u64 v[126:127], s[44:45], 0, v[120:121]
	v_lshlrev_b32_e32 v120, 1, v135
	s_cbranch_vccnz .LBB0_200
	v_lshl_add_u64 v[142:143], v[130:131], 2, v[126:127]
	global_store_dwordx4 v[142:143], v[116:119], off
	v_and_or_b32 v142, v147, s80, v145
	v_mov_b32_e32 v121, v129
	v_ashrrev_i32_e32 v143, 31, v142
	v_lshl_add_u64 v[150:151], s[48:49], 0, v[120:121]
	v_lshlrev_b64 v[152:153], 9, v[142:143]
	v_cvt_pk_bf16_f32 v121, v116, s0
	v_lshl_add_u64 v[152:153], v[150:151], 0, v[152:153]
	global_store_short v[152:153], v121, off
	v_or_b32_e32 v152, 1, v142
	v_ashrrev_i32_e32 v153, 31, v152
	v_lshlrev_b64 v[152:153], 9, v[152:153]
	v_cvt_pk_bf16_f32 v121, v117, s0
	v_lshl_add_u64 v[152:153], v[150:151], 0, v[152:153]
	global_store_short v[152:153], v121, off
	v_or_b32_e32 v152, 2, v142
	v_ashrrev_i32_e32 v153, 31, v152
	v_or_b32_e32 v142, 3, v142
	v_lshlrev_b64 v[152:153], 9, v[152:153]
	v_ashrrev_i32_e32 v143, 31, v142
	v_cvt_pk_bf16_f32 v121, v118, s0
	v_lshl_add_u64 v[152:153], v[150:151], 0, v[152:153]
	v_lshlrev_b64 v[142:143], 9, v[142:143]
	global_store_short v[152:153], v121, off
	v_cvt_pk_bf16_f32 v121, v119, s0
	v_lshl_add_u64 v[142:143], v[150:151], 0, v[142:143]
	s_mov_b64 s[52:53], 0
	global_store_short v[142:143], v121, off
	s_branch .LBB0_201

.LBB0_201:
	v_lshlrev_b64 v[122:123], 8, v[122:123]
	s_andn2_b64 vcc, exec, s[52:53]
	v_lshl_add_u64 v[142:143], v[122:123], 2, s[42:43]
	v_lshl_add_u64 v[122:123], v[122:123], 1, s[46:47]
	s_cbranch_vccnz .LBB0_203
	v_lshl_add_u64 v[150:151], v[128:129], 2, v[142:143]
	global_store_dwordx4 v[150:151], v[116:119], off
	s_nop 1
	v_cvt_pk_bf16_f32 v116, v116, v117
	v_cvt_pk_bf16_f32 v117, v118, v119
	v_lshl_add_u64 v[118:119], v[128:129], 1, v[122:123]
	global_store_dwordx2 v[118:119], v[116:117], off
.LBB0_203:
	s_and_b64 vcc, exec, s[0:1]
	s_cbranch_vccnz .LBB0_208
	v_lshl_add_u64 v[116:117], v[124:125], 2, v[126:127]
	global_store_dwordx4 v[116:117], v[112:115], off
	v_and_or_b32 v116, v148, s80, v133
	v_mov_b32_e32 v121, v129
	v_ashrrev_i32_e32 v117, 31, v116
	v_lshl_add_u64 v[118:119], s[48:49], 0, v[120:121]
	v_lshlrev_b64 v[150:151], 9, v[116:117]
	v_cvt_pk_bf16_f32 v121, v112, s0
	v_lshl_add_u64 v[150:151], v[118:119], 0, v[150:151]
	global_store_short v[150:151], v121, off
	v_or_b32_e32 v150, 1, v116
	v_ashrrev_i32_e32 v151, 31, v150
	v_lshlrev_b64 v[150:151], 9, v[150:151]
	v_cvt_pk_bf16_f32 v117, v113, s0
	v_lshl_add_u64 v[150:151], v[118:119], 0, v[150:151]
	global_store_short v[150:151], v117, off
	v_or_b32_e32 v150, 2, v116
	v_ashrrev_i32_e32 v151, 31, v150
	v_lshlrev_b64 v[150:151], 9, v[150:151]
	v_cvt_pk_bf16_f32 v117, v114, s0
	v_lshl_add_u64 v[150:151], v[118:119], 0, v[150:151]
	v_or_b32_e32 v116, 3, v116
	global_store_short v[150:151], v117, off
	v_ashrrev_i32_e32 v117, 31, v116
	v_lshlrev_b64 v[116:117], 9, v[116:117]
	v_cvt_pk_bf16_f32 v121, v115, s0
	v_lshl_add_u64 v[116:117], v[118:119], 0, v[116:117]
	global_store_short v[116:117], v121, off
	s_cbranch_execnz .LBB0_206
.LBB0_205:
	v_lshl_add_u64 v[116:117], v[128:129], 2, v[142:143]
	global_store_dwordx4 v[116:117], v[112:115], off offset:64
	s_nop 1
	v_cvt_pk_bf16_f32 v112, v112, v113
	v_cvt_pk_bf16_f32 v113, v114, v115
	v_lshl_add_u64 v[114:115], v[128:129], 1, v[122:123]
	global_store_dwordx2 v[114:115], v[112:113], off offset:32
.LBB0_206:
	v_or_b32_e32 v114, 32, v132
	s_movk_i32 s52, 0xef
	v_ashrrev_i32_e32 v115, 31, v114
	v_bitop3_b32 v118, v132, s52, 32 bitop3:0xc8
	v_lshlrev_b64 v[112:113], 10, v[114:115]
	s_and_b64 vcc, exec, s[0:1]
	v_lshl_add_u64 v[116:117], s[44:45], 0, v[112:113]
	v_lshlrev_b32_e32 v112, 1, v118
	s_cbranch_vccnz .LBB0_209
	v_lshl_add_u64 v[118:119], v[130:131], 2, v[116:117]
	global_store_dwordx4 v[118:119], v[108:111], off
	v_and_or_b32 v118, v147, s80, v145
	v_mov_b32_e32 v113, v129
	v_ashrrev_i32_e32 v119, 31, v118
	v_lshl_add_u64 v[150:151], s[48:49], 0, v[112:113]
	v_lshlrev_b64 v[152:153], 9, v[118:119]
	v_cvt_pk_bf16_f32 v113, v108, s0
	v_lshl_add_u64 v[152:153], v[150:151], 0, v[152:153]
	global_store_short v[152:153], v113, off
	v_or_b32_e32 v152, 1, v118
	v_ashrrev_i32_e32 v153, 31, v152
	v_lshlrev_b64 v[152:153], 9, v[152:153]
	v_cvt_pk_bf16_f32 v113, v109, s0
	v_lshl_add_u64 v[152:153], v[150:151], 0, v[152:153]
	global_store_short v[152:153], v113, off
	v_or_b32_e32 v152, 2, v118
	v_ashrrev_i32_e32 v153, 31, v152
	v_or_b32_e32 v118, 3, v118
	v_lshlrev_b64 v[152:153], 9, v[152:153]
	v_ashrrev_i32_e32 v119, 31, v118
	v_cvt_pk_bf16_f32 v113, v110, s0
	v_lshl_add_u64 v[152:153], v[150:151], 0, v[152:153]
	v_lshlrev_b64 v[118:119], 9, v[118:119]
	global_store_short v[152:153], v113, off
	v_cvt_pk_bf16_f32 v113, v111, s0
	v_lshl_add_u64 v[118:119], v[150:151], 0, v[118:119]
	s_mov_b64 s[52:53], 0
	global_store_short v[118:119], v113, off
	s_branch .LBB0_210

.LBB0_210:
	v_lshlrev_b64 v[114:115], 8, v[114:115]
	s_andn2_b64 vcc, exec, s[52:53]
	v_lshl_add_u64 v[118:119], v[114:115], 2, s[42:43]
	v_lshl_add_u64 v[114:115], v[114:115], 1, s[46:47]
	s_cbranch_vccnz .LBB0_212
	v_lshl_add_u64 v[150:151], v[128:129], 2, v[118:119]
	global_store_dwordx4 v[150:151], v[108:111], off
	s_nop 1
	v_cvt_pk_bf16_f32 v108, v108, v109
	v_cvt_pk_bf16_f32 v109, v110, v111
	v_lshl_add_u64 v[110:111], v[128:129], 1, v[114:115]
	global_store_dwordx2 v[110:111], v[108:109], off
.LBB0_212:
	s_and_b64 vcc, exec, s[0:1]
	s_cbranch_vccnz .LBB0_217
	v_lshl_add_u64 v[108:109], v[124:125], 2, v[116:117]
	global_store_dwordx4 v[108:109], v[104:107], off
	v_and_or_b32 v108, v148, s80, v133
	v_mov_b32_e32 v113, v129
	v_ashrrev_i32_e32 v109, 31, v108
	v_lshl_add_u64 v[110:111], s[48:49], 0, v[112:113]
	v_lshlrev_b64 v[150:151], 9, v[108:109]
	v_cvt_pk_bf16_f32 v113, v104, s0
	v_lshl_add_u64 v[150:151], v[110:111], 0, v[150:151]
	global_store_short v[150:151], v113, off
	v_or_b32_e32 v150, 1, v108
	v_ashrrev_i32_e32 v151, 31, v150
	v_lshlrev_b64 v[150:151], 9, v[150:151]
	v_cvt_pk_bf16_f32 v109, v105, s0
	v_lshl_add_u64 v[150:151], v[110:111], 0, v[150:151]
	global_store_short v[150:151], v109, off
	v_or_b32_e32 v150, 2, v108
	v_ashrrev_i32_e32 v151, 31, v150
	v_lshlrev_b64 v[150:151], 9, v[150:151]
	v_cvt_pk_bf16_f32 v109, v106, s0
	v_lshl_add_u64 v[150:151], v[110:111], 0, v[150:151]
	v_or_b32_e32 v108, 3, v108
	global_store_short v[150:151], v109, off
	v_ashrrev_i32_e32 v109, 31, v108
	v_lshlrev_b64 v[108:109], 9, v[108:109]
	v_cvt_pk_bf16_f32 v113, v107, s0
	v_lshl_add_u64 v[108:109], v[110:111], 0, v[108:109]
	global_store_short v[108:109], v113, off
	s_cbranch_execnz .LBB0_215
.LBB0_214:
	v_lshl_add_u64 v[108:109], v[128:129], 2, v[118:119]
	global_store_dwordx4 v[108:109], v[104:107], off offset:64
	s_nop 1
	v_cvt_pk_bf16_f32 v104, v104, v105
	v_cvt_pk_bf16_f32 v105, v106, v107
	v_lshl_add_u64 v[106:107], v[128:129], 1, v[114:115]
	global_store_dwordx2 v[106:107], v[104:105], off offset:32
.LBB0_215:
	v_or_b32_e32 v106, 48, v132
	s_movk_i32 s52, 0xff
	v_ashrrev_i32_e32 v107, 31, v106
	v_bitop3_b32 v110, v132, s52, 48 bitop3:0xc8
	v_lshlrev_b64 v[104:105], 10, v[106:107]
	s_and_b64 vcc, exec, s[0:1]
	v_lshl_add_u64 v[108:109], s[44:45], 0, v[104:105]
	v_lshlrev_b32_e32 v104, 1, v110
	s_cbranch_vccnz .LBB0_218
	v_lshl_add_u64 v[110:111], v[130:131], 2, v[108:109]
	global_store_dwordx4 v[110:111], v[100:103], off
	v_and_or_b32 v110, v147, s80, v145
	v_mov_b32_e32 v105, v129
	v_ashrrev_i32_e32 v111, 31, v110
	v_lshl_add_u64 v[150:151], s[48:49], 0, v[104:105]
	v_lshlrev_b64 v[152:153], 9, v[110:111]
	v_cvt_pk_bf16_f32 v105, v100, s0
	v_lshl_add_u64 v[152:153], v[150:151], 0, v[152:153]
	global_store_short v[152:153], v105, off
	v_or_b32_e32 v152, 1, v110
	v_ashrrev_i32_e32 v153, 31, v152
	v_lshlrev_b64 v[152:153], 9, v[152:153]
	v_cvt_pk_bf16_f32 v105, v101, s0
	v_lshl_add_u64 v[152:153], v[150:151], 0, v[152:153]
	global_store_short v[152:153], v105, off
	v_or_b32_e32 v152, 2, v110
	v_ashrrev_i32_e32 v153, 31, v152
	v_or_b32_e32 v110, 3, v110
	v_lshlrev_b64 v[152:153], 9, v[152:153]
	v_ashrrev_i32_e32 v111, 31, v110
	v_cvt_pk_bf16_f32 v105, v102, s0
	v_lshl_add_u64 v[152:153], v[150:151], 0, v[152:153]
	v_lshlrev_b64 v[110:111], 9, v[110:111]
	global_store_short v[152:153], v105, off
	v_cvt_pk_bf16_f32 v105, v103, s0
	v_lshl_add_u64 v[110:111], v[150:151], 0, v[110:111]
	s_mov_b64 s[52:53], 0
	global_store_short v[110:111], v105, off
	s_branch .LBB0_219

.LBB0_219:
	v_lshlrev_b64 v[106:107], 8, v[106:107]
	s_andn2_b64 vcc, exec, s[52:53]
	v_lshl_add_u64 v[110:111], v[106:107], 2, s[42:43]
	v_lshl_add_u64 v[106:107], v[106:107], 1, s[46:47]
	s_cbranch_vccnz .LBB0_221
	v_lshl_add_u64 v[150:151], v[128:129], 2, v[110:111]
	global_store_dwordx4 v[150:151], v[100:103], off
	s_nop 1
	v_cvt_pk_bf16_f32 v100, v100, v101
	v_cvt_pk_bf16_f32 v101, v102, v103
	v_lshl_add_u64 v[102:103], v[128:129], 1, v[106:107]
	global_store_dwordx2 v[102:103], v[100:101], off
.LBB0_221:
	s_and_b64 vcc, exec, s[0:1]
	s_cbranch_vccnz .LBB0_250
	v_lshl_add_u64 v[100:101], v[124:125], 2, v[108:109]
	global_store_dwordx4 v[100:101], v[96:99], off
	v_and_or_b32 v100, v148, s80, v133
	v_mov_b32_e32 v105, v129
	v_ashrrev_i32_e32 v101, 31, v100
	v_lshl_add_u64 v[102:103], s[48:49], 0, v[104:105]
	v_lshlrev_b64 v[148:149], 9, v[100:101]
	v_cvt_pk_bf16_f32 v105, v96, s0
	v_lshl_add_u64 v[148:149], v[102:103], 0, v[148:149]
	global_store_short v[148:149], v105, off
	v_or_b32_e32 v148, 1, v100
	v_ashrrev_i32_e32 v149, 31, v148
	v_lshlrev_b64 v[148:149], 9, v[148:149]
	v_cvt_pk_bf16_f32 v101, v97, s0
	v_lshl_add_u64 v[148:149], v[102:103], 0, v[148:149]
	global_store_short v[148:149], v101, off
	v_or_b32_e32 v148, 2, v100
	v_ashrrev_i32_e32 v149, 31, v148
	v_lshlrev_b64 v[148:149], 9, v[148:149]
	v_cvt_pk_bf16_f32 v101, v98, s0
	v_lshl_add_u64 v[148:149], v[102:103], 0, v[148:149]
	v_or_b32_e32 v100, 3, v100
	global_store_short v[148:149], v101, off
	v_ashrrev_i32_e32 v101, 31, v100
	v_lshlrev_b64 v[100:101], 9, v[100:101]
	v_cvt_pk_bf16_f32 v105, v99, s0
	v_lshl_add_u64 v[100:101], v[102:103], 0, v[100:101]
	global_store_short v[100:101], v105, off
	s_cbranch_execnz .LBB0_224
.LBB0_223:
	v_lshl_add_u64 v[100:101], v[128:129], 2, v[110:111]
	global_store_dwordx4 v[100:101], v[96:99], off offset:64
	s_nop 1
	v_cvt_pk_bf16_f32 v96, v96, v97
	v_cvt_pk_bf16_f32 v97, v98, v99
	v_lshl_add_u64 v[98:99], v[128:129], 1, v[106:107]
	global_store_dwordx2 v[98:99], v[96:97], off offset:32
.LBB0_224:
	v_add_u32_e32 v96, 0xffffff80, v128
	s_and_b64 vcc, exec, s[0:1]
	v_ashrrev_i32_e32 v97, 31, v96
	v_add_u32_e32 v98, v96, v146
	s_cbranch_vccnz .LBB0_251
	v_lshl_add_u64 v[100:101], v[96:97], 2, v[136:137]
	global_store_dwordx4 v[100:101], v[92:95], off
	v_and_or_b32 v100, v98, s80, v145
	v_mov_b32_e32 v135, v129
	v_ashrrev_i32_e32 v101, 31, v100
	v_lshl_add_u64 v[102:103], s[48:49], 0, v[134:135]
	v_lshlrev_b64 v[148:149], 9, v[100:101]
	v_cvt_pk_bf16_f32 v99, v92, s0
	v_lshl_add_u64 v[148:149], v[102:103], 0, v[148:149]
	global_store_short v[148:149], v99, off
	v_or_b32_e32 v148, 1, v100
	v_ashrrev_i32_e32 v149, 31, v148
	v_lshlrev_b64 v[148:149], 9, v[148:149]
	v_cvt_pk_bf16_f32 v99, v93, s0
	v_lshl_add_u64 v[148:149], v[102:103], 0, v[148:149]
	global_store_short v[148:149], v99, off
	v_or_b32_e32 v148, 2, v100
	v_ashrrev_i32_e32 v149, 31, v148
	v_or_b32_e32 v100, 3, v100
	v_lshlrev_b64 v[148:149], 9, v[148:149]
	v_ashrrev_i32_e32 v101, 31, v100
	v_cvt_pk_bf16_f32 v99, v94, s0
	v_lshl_add_u64 v[148:149], v[102:103], 0, v[148:149]
	v_lshlrev_b64 v[100:101], 9, v[100:101]
	global_store_short v[148:149], v99, off
	v_cvt_pk_bf16_f32 v99, v95, s0
	v_lshl_add_u64 v[100:101], v[102:103], 0, v[100:101]
	global_store_short v[100:101], v99, off
	s_cbranch_execnz .LBB0_227
.LBB0_226:
	v_lshl_add_u64 v[100:101], v[128:129], 2, v[140:141]
	global_store_dwordx4 v[100:101], v[92:95], off offset:512
	s_nop 1
	v_cvt_pk_bf16_f32 v92, v92, v93
	v_cvt_pk_bf16_f32 v93, v94, v95
	v_lshl_add_u64 v[94:95], v[128:129], 1, v[138:139]
	global_store_dwordx2 v[94:95], v[92:93], off offset:256
.LBB0_227:
	v_or_b32_e32 v93, 0x90, v128
	v_add_u32_e32 v92, 0xffffff90, v128
	s_and_b64 vcc, exec, s[0:1]
	v_and_b32_e32 v94, 60, v93
	v_ashrrev_i32_e32 v93, 31, v92
	v_add_u32_e32 v95, v92, v146
	s_cbranch_vccnz .LBB0_252
	v_lshl_add_u64 v[100:101], v[92:93], 2, v[136:137]
	global_store_dwordx4 v[100:101], v[88:91], off
	v_and_or_b32 v100, v95, s80, v94
	v_mov_b32_e32 v135, v129
	v_ashrrev_i32_e32 v101, 31, v100
	v_lshl_add_u64 v[102:103], s[48:49], 0, v[134:135]
	v_lshlrev_b64 v[134:135], 9, v[100:101]
	v_cvt_pk_bf16_f32 v99, v88, s0
	v_lshl_add_u64 v[134:135], v[102:103], 0, v[134:135]
	global_store_short v[134:135], v99, off
	v_or_b32_e32 v134, 1, v100
	v_ashrrev_i32_e32 v135, 31, v134
	v_lshlrev_b64 v[134:135], 9, v[134:135]
	v_cvt_pk_bf16_f32 v99, v89, s0
	v_lshl_add_u64 v[134:135], v[102:103], 0, v[134:135]
	global_store_short v[134:135], v99, off
	v_or_b32_e32 v134, 2, v100
	v_ashrrev_i32_e32 v135, 31, v134
	v_or_b32_e32 v100, 3, v100
	v_lshlrev_b64 v[134:135], 9, v[134:135]
	v_ashrrev_i32_e32 v101, 31, v100
	v_cvt_pk_bf16_f32 v99, v90, s0
	v_lshl_add_u64 v[134:135], v[102:103], 0, v[134:135]
	v_lshlrev_b64 v[100:101], 9, v[100:101]
	global_store_short v[134:135], v99, off
	v_cvt_pk_bf16_f32 v99, v91, s0
	v_lshl_add_u64 v[100:101], v[102:103], 0, v[100:101]
	global_store_short v[100:101], v99, off
	s_cbranch_execnz .LBB0_230
.LBB0_229:
	v_lshl_add_u64 v[100:101], v[128:129], 2, v[140:141]
	global_store_dwordx4 v[100:101], v[88:91], off offset:576
	s_nop 1
	v_cvt_pk_bf16_f32 v88, v88, v89
	v_cvt_pk_bf16_f32 v89, v90, v91
	v_lshl_add_u64 v[90:91], v[128:129], 1, v[138:139]
	global_store_dwordx2 v[90:91], v[88:89], off offset:288
.LBB0_230:
	s_and_b64 vcc, exec, s[0:1]
	s_cbranch_vccnz .LBB0_253
	v_lshl_add_u64 v[88:89], v[96:97], 2, v[126:127]
	global_store_dwordx4 v[88:89], v[84:87], off
	v_and_or_b32 v88, v98, s80, v145
	v_mov_b32_e32 v121, v129
	v_ashrrev_i32_e32 v89, 31, v88
	v_lshl_add_u64 v[90:91], s[48:49], 0, v[120:121]
	v_lshlrev_b64 v[100:101], 9, v[88:89]
	v_cvt_pk_bf16_f32 v99, v84, s0
	v_lshl_add_u64 v[100:101], v[90:91], 0, v[100:101]
	global_store_short v[100:101], v99, off
	v_or_b32_e32 v100, 1, v88
	v_ashrrev_i32_e32 v101, 31, v100
	v_lshlrev_b64 v[100:101], 9, v[100:101]
	v_cvt_pk_bf16_f32 v89, v85, s0
	v_lshl_add_u64 v[100:101], v[90:91], 0, v[100:101]
	global_store_short v[100:101], v89, off
	v_or_b32_e32 v100, 2, v88
	v_ashrrev_i32_e32 v101, 31, v100
	v_lshlrev_b64 v[100:101], 9, v[100:101]
	v_cvt_pk_bf16_f32 v89, v86, s0
	v_lshl_add_u64 v[100:101], v[90:91], 0, v[100:101]
	v_or_b32_e32 v88, 3, v88
	global_store_short v[100:101], v89, off
	v_ashrrev_i32_e32 v89, 31, v88
	v_lshlrev_b64 v[88:89], 9, v[88:89]
	v_cvt_pk_bf16_f32 v99, v87, s0
	v_lshl_add_u64 v[88:89], v[90:91], 0, v[88:89]
	global_store_short v[88:89], v99, off
	s_cbranch_execnz .LBB0_233
.LBB0_232:
	v_lshl_add_u64 v[88:89], v[128:129], 2, v[142:143]
	global_store_dwordx4 v[88:89], v[84:87], off offset:512
	s_nop 1
	v_cvt_pk_bf16_f32 v84, v84, v85
	v_cvt_pk_bf16_f32 v85, v86, v87
	v_lshl_add_u64 v[86:87], v[128:129], 1, v[122:123]
	global_store_dwordx2 v[86:87], v[84:85], off offset:256
.LBB0_233:
	s_and_b64 vcc, exec, s[0:1]
	s_cbranch_vccnz .LBB0_254
	v_lshl_add_u64 v[84:85], v[92:93], 2, v[126:127]
	global_store_dwordx4 v[84:85], v[80:83], off
	v_and_or_b32 v84, v95, s80, v94
	v_mov_b32_e32 v121, v129
	v_ashrrev_i32_e32 v85, 31, v84
	v_lshl_add_u64 v[86:87], s[48:49], 0, v[120:121]
	v_lshlrev_b64 v[88:89], 9, v[84:85]
	v_cvt_pk_bf16_f32 v90, v80, s0
	v_lshl_add_u64 v[88:89], v[86:87], 0, v[88:89]
	global_store_short v[88:89], v90, off
	v_or_b32_e32 v88, 1, v84
	v_ashrrev_i32_e32 v89, 31, v88
	v_lshlrev_b64 v[88:89], 9, v[88:89]
	v_cvt_pk_bf16_f32 v85, v81, s0
	v_lshl_add_u64 v[88:89], v[86:87], 0, v[88:89]
	global_store_short v[88:89], v85, off
	v_or_b32_e32 v88, 2, v84
	v_ashrrev_i32_e32 v89, 31, v88
	v_lshlrev_b64 v[88:89], 9, v[88:89]
	v_cvt_pk_bf16_f32 v85, v82, s0
	v_lshl_add_u64 v[88:89], v[86:87], 0, v[88:89]
	v_or_b32_e32 v84, 3, v84
	global_store_short v[88:89], v85, off
	v_ashrrev_i32_e32 v85, 31, v84
	v_lshlrev_b64 v[84:85], 9, v[84:85]
	v_cvt_pk_bf16_f32 v88, v83, s0
	v_lshl_add_u64 v[84:85], v[86:87], 0, v[84:85]
	global_store_short v[84:85], v88, off
	s_cbranch_execnz .LBB0_236
.LBB0_235:
	v_lshl_add_u64 v[84:85], v[128:129], 2, v[142:143]
	global_store_dwordx4 v[84:85], v[80:83], off offset:576
	s_nop 1
	v_cvt_pk_bf16_f32 v80, v80, v81
	v_cvt_pk_bf16_f32 v81, v82, v83
	v_lshl_add_u64 v[82:83], v[128:129], 1, v[122:123]
	global_store_dwordx2 v[82:83], v[80:81], off offset:288
.LBB0_236:
	s_and_b64 vcc, exec, s[0:1]
	s_cbranch_vccnz .LBB0_255
	v_lshl_add_u64 v[80:81], v[96:97], 2, v[116:117]
	global_store_dwordx4 v[80:81], v[76:79], off
	v_and_or_b32 v80, v98, s80, v145
	v_mov_b32_e32 v113, v129
	v_ashrrev_i32_e32 v81, 31, v80
	v_lshl_add_u64 v[82:83], s[48:49], 0, v[112:113]
	v_lshlrev_b64 v[84:85], 9, v[80:81]
	v_cvt_pk_bf16_f32 v86, v76, s0
	v_lshl_add_u64 v[84:85], v[82:83], 0, v[84:85]
	global_store_short v[84:85], v86, off
	v_or_b32_e32 v84, 1, v80
	v_ashrrev_i32_e32 v85, 31, v84
	v_lshlrev_b64 v[84:85], 9, v[84:85]
	v_cvt_pk_bf16_f32 v81, v77, s0
	v_lshl_add_u64 v[84:85], v[82:83], 0, v[84:85]
	global_store_short v[84:85], v81, off
	v_or_b32_e32 v84, 2, v80
	v_ashrrev_i32_e32 v85, 31, v84
	v_lshlrev_b64 v[84:85], 9, v[84:85]
	v_cvt_pk_bf16_f32 v81, v78, s0
	v_lshl_add_u64 v[84:85], v[82:83], 0, v[84:85]
	v_or_b32_e32 v80, 3, v80
	global_store_short v[84:85], v81, off
	v_ashrrev_i32_e32 v81, 31, v80
	v_lshlrev_b64 v[80:81], 9, v[80:81]
	v_cvt_pk_bf16_f32 v84, v79, s0
	v_lshl_add_u64 v[80:81], v[82:83], 0, v[80:81]
	global_store_short v[80:81], v84, off
	s_cbranch_execnz .LBB0_239
.LBB0_238:
	v_lshl_add_u64 v[80:81], v[128:129], 2, v[118:119]
	global_store_dwordx4 v[80:81], v[76:79], off offset:512
	s_nop 1
	v_cvt_pk_bf16_f32 v76, v76, v77
	v_cvt_pk_bf16_f32 v77, v78, v79
	v_lshl_add_u64 v[78:79], v[128:129], 1, v[114:115]
	global_store_dwordx2 v[78:79], v[76:77], off offset:256
.LBB0_239:
	s_and_b64 vcc, exec, s[0:1]
	s_cbranch_vccnz .LBB0_256
	v_lshl_add_u64 v[76:77], v[92:93], 2, v[116:117]
	global_store_dwordx4 v[76:77], v[72:75], off
	v_and_or_b32 v76, v95, s80, v94
	v_mov_b32_e32 v113, v129
	v_ashrrev_i32_e32 v77, 31, v76
	v_lshl_add_u64 v[78:79], s[48:49], 0, v[112:113]
	v_lshlrev_b64 v[80:81], 9, v[76:77]
	v_cvt_pk_bf16_f32 v82, v72, s0
	v_lshl_add_u64 v[80:81], v[78:79], 0, v[80:81]
	global_store_short v[80:81], v82, off
	v_or_b32_e32 v80, 1, v76
	v_ashrrev_i32_e32 v81, 31, v80
	v_lshlrev_b64 v[80:81], 9, v[80:81]
	v_cvt_pk_bf16_f32 v77, v73, s0
	v_lshl_add_u64 v[80:81], v[78:79], 0, v[80:81]
	global_store_short v[80:81], v77, off
	v_or_b32_e32 v80, 2, v76
	v_ashrrev_i32_e32 v81, 31, v80
	v_lshlrev_b64 v[80:81], 9, v[80:81]
	v_cvt_pk_bf16_f32 v77, v74, s0
	v_lshl_add_u64 v[80:81], v[78:79], 0, v[80:81]
	v_or_b32_e32 v76, 3, v76
	global_store_short v[80:81], v77, off
	v_ashrrev_i32_e32 v77, 31, v76
	v_lshlrev_b64 v[76:77], 9, v[76:77]
	v_cvt_pk_bf16_f32 v80, v75, s0
	v_lshl_add_u64 v[76:77], v[78:79], 0, v[76:77]
	global_store_short v[76:77], v80, off
	s_cbranch_execnz .LBB0_242
.LBB0_241:
	v_lshl_add_u64 v[76:77], v[128:129], 2, v[118:119]
	global_store_dwordx4 v[76:77], v[72:75], off offset:576
	s_nop 1
	v_cvt_pk_bf16_f32 v72, v72, v73
	v_cvt_pk_bf16_f32 v73, v74, v75
	v_lshl_add_u64 v[74:75], v[128:129], 1, v[114:115]
	global_store_dwordx2 v[74:75], v[72:73], off offset:288
.LBB0_242:
	s_and_b64 vcc, exec, s[0:1]
	s_cbranch_vccnz .LBB0_257
	v_lshl_add_u64 v[72:73], v[96:97], 2, v[108:109]
	global_store_dwordx4 v[72:73], v[68:71], off
	v_and_or_b32 v72, v98, s80, v145
	v_mov_b32_e32 v105, v129
	v_ashrrev_i32_e32 v73, 31, v72
	v_lshl_add_u64 v[74:75], s[48:49], 0, v[104:105]
	v_lshlrev_b64 v[76:77], 9, v[72:73]
	v_cvt_pk_bf16_f32 v78, v68, s0
	v_lshl_add_u64 v[76:77], v[74:75], 0, v[76:77]
	global_store_short v[76:77], v78, off
	v_or_b32_e32 v76, 1, v72
	v_ashrrev_i32_e32 v77, 31, v76
	v_lshlrev_b64 v[76:77], 9, v[76:77]
	v_cvt_pk_bf16_f32 v73, v69, s0
	v_lshl_add_u64 v[76:77], v[74:75], 0, v[76:77]
	global_store_short v[76:77], v73, off
	v_or_b32_e32 v76, 2, v72
	v_ashrrev_i32_e32 v77, 31, v76
	v_lshlrev_b64 v[76:77], 9, v[76:77]
	v_cvt_pk_bf16_f32 v73, v70, s0
	v_lshl_add_u64 v[76:77], v[74:75], 0, v[76:77]
	v_or_b32_e32 v72, 3, v72
	global_store_short v[76:77], v73, off
	v_ashrrev_i32_e32 v73, 31, v72
	v_lshlrev_b64 v[72:73], 9, v[72:73]
	v_cvt_pk_bf16_f32 v76, v71, s0
	v_lshl_add_u64 v[72:73], v[74:75], 0, v[72:73]
	global_store_short v[72:73], v76, off
	s_cbranch_execnz .LBB0_245
.LBB0_244:
	v_lshl_add_u64 v[72:73], v[128:129], 2, v[110:111]
	global_store_dwordx4 v[72:73], v[68:71], off offset:512
	s_nop 1
	v_cvt_pk_bf16_f32 v68, v68, v69
	v_cvt_pk_bf16_f32 v69, v70, v71
	v_lshl_add_u64 v[70:71], v[128:129], 1, v[106:107]
	global_store_dwordx2 v[70:71], v[68:69], off offset:256
.LBB0_245:
	s_and_b64 vcc, exec, s[0:1]
	s_cbranch_vccnz .LBB0_258
	v_lshl_add_u64 v[68:69], v[92:93], 2, v[108:109]
	global_store_dwordx4 v[68:69], v[64:67], off
	v_and_or_b32 v68, v95, s80, v94
	v_mov_b32_e32 v105, v129
	v_ashrrev_i32_e32 v69, 31, v68
	v_lshl_add_u64 v[70:71], s[48:49], 0, v[104:105]
	v_lshlrev_b64 v[72:73], 9, v[68:69]
	v_cvt_pk_bf16_f32 v74, v64, s0
	v_lshl_add_u64 v[72:73], v[70:71], 0, v[72:73]
	global_store_short v[72:73], v74, off
	v_or_b32_e32 v72, 1, v68
	v_ashrrev_i32_e32 v73, 31, v72
	v_lshlrev_b64 v[72:73], 9, v[72:73]
	v_cvt_pk_bf16_f32 v69, v65, s0
	v_lshl_add_u64 v[72:73], v[70:71], 0, v[72:73]
	global_store_short v[72:73], v69, off
	v_or_b32_e32 v72, 2, v68
	v_ashrrev_i32_e32 v73, 31, v72
	v_lshlrev_b64 v[72:73], 9, v[72:73]
	v_cvt_pk_bf16_f32 v69, v66, s0
	v_lshl_add_u64 v[72:73], v[70:71], 0, v[72:73]
	v_or_b32_e32 v68, 3, v68
	global_store_short v[72:73], v69, off
	v_ashrrev_i32_e32 v69, 31, v68
	v_lshlrev_b64 v[68:69], 9, v[68:69]
	v_cvt_pk_bf16_f32 v72, v67, s0
	v_lshl_add_u64 v[68:69], v[70:71], 0, v[68:69]
	global_store_short v[68:69], v72, off
	s_cbranch_execnz .LBB0_248
.LBB0_247:
	v_lshl_add_u64 v[68:69], v[128:129], 2, v[110:111]
	global_store_dwordx4 v[68:69], v[64:67], off offset:576
	s_nop 1
	v_cvt_pk_bf16_f32 v64, v64, v65
	v_cvt_pk_bf16_f32 v65, v66, v67
	v_lshl_add_u64 v[66:67], v[128:129], 1, v[106:107]
	global_store_dwordx2 v[66:67], v[64:65], off offset:288
.LBB0_248:
	v_add_u32_e32 v66, 0x80, v132
	v_ashrrev_i32_e32 v67, 31, v66
	v_and_b32_e32 v70, 0xcf, v66
	v_lshlrev_b64 v[64:65], 10, v[66:67]
	v_and_b32_e32 v72, 0xffffff00, v66
	s_and_b64 vcc, exec, s[0:1]
	v_lshl_add_u64 v[68:69], s[44:45], 0, v[64:65]
	v_lshlrev_b32_e32 v64, 1, v70
	s_cbranch_vccnz .LBB0_259
	v_lshl_add_u64 v[70:71], v[130:131], 2, v[68:69]
	v_add_u32_e32 v65, v130, v72
	global_store_dwordx4 v[70:71], v[60:63], off
	v_and_or_b32 v70, v65, s80, v145
	v_mov_b32_e32 v65, v129
	v_ashrrev_i32_e32 v71, 31, v70
	v_lshl_add_u64 v[74:75], s[48:49], 0, v[64:65]
	v_lshlrev_b64 v[76:77], 9, v[70:71]
	v_cvt_pk_bf16_f32 v65, v60, s0
	v_lshl_add_u64 v[76:77], v[74:75], 0, v[76:77]
	global_store_short v[76:77], v65, off
	v_or_b32_e32 v76, 1, v70
	v_ashrrev_i32_e32 v77, 31, v76
	v_lshlrev_b64 v[76:77], 9, v[76:77]
	v_cvt_pk_bf16_f32 v65, v61, s0
	v_lshl_add_u64 v[76:77], v[74:75], 0, v[76:77]
	global_store_short v[76:77], v65, off
	v_or_b32_e32 v76, 2, v70
	v_ashrrev_i32_e32 v77, 31, v76
	v_or_b32_e32 v70, 3, v70
	v_lshlrev_b64 v[76:77], 9, v[76:77]
	v_ashrrev_i32_e32 v71, 31, v70
	v_cvt_pk_bf16_f32 v65, v62, s0
	v_lshl_add_u64 v[76:77], v[74:75], 0, v[76:77]
	v_lshlrev_b64 v[70:71], 9, v[70:71]
	global_store_short v[76:77], v65, off
	v_cvt_pk_bf16_f32 v65, v63, s0
	v_lshl_add_u64 v[70:71], v[74:75], 0, v[70:71]
	s_mov_b64 s[52:53], 0
	global_store_short v[70:71], v65, off
	s_branch .LBB0_260

.LBB0_260:
	v_lshlrev_b64 v[66:67], 8, v[66:67]
	s_andn2_b64 vcc, exec, s[52:53]
	v_lshl_add_u64 v[70:71], v[66:67], 2, s[42:43]
	v_lshl_add_u64 v[66:67], v[66:67], 1, s[46:47]
	s_cbranch_vccnz .LBB0_262
	v_lshl_add_u64 v[74:75], v[128:129], 2, v[70:71]
	global_store_dwordx4 v[74:75], v[60:63], off
	s_nop 1
	v_cvt_pk_bf16_f32 v60, v60, v61
	v_cvt_pk_bf16_f32 v61, v62, v63
	v_lshl_add_u64 v[62:63], v[128:129], 1, v[66:67]
	global_store_dwordx2 v[62:63], v[60:61], off
.LBB0_262:
	s_and_b64 vcc, exec, s[0:1]
	s_cbranch_vccnz .LBB0_267
	v_lshl_add_u64 v[60:61], v[124:125], 2, v[68:69]
	global_store_dwordx4 v[60:61], v[56:59], off
	v_add_u32_e32 v60, v124, v72
	v_and_or_b32 v60, v60, s80, v133
	v_mov_b32_e32 v65, v129
	v_ashrrev_i32_e32 v61, 31, v60
	v_lshl_add_u64 v[62:63], s[48:49], 0, v[64:65]
	v_lshlrev_b64 v[74:75], 9, v[60:61]
	v_cvt_pk_bf16_f32 v65, v56, s0
	v_lshl_add_u64 v[74:75], v[62:63], 0, v[74:75]
	global_store_short v[74:75], v65, off
	v_or_b32_e32 v74, 1, v60
	v_ashrrev_i32_e32 v75, 31, v74
	v_lshlrev_b64 v[74:75], 9, v[74:75]
	v_cvt_pk_bf16_f32 v61, v57, s0
	v_lshl_add_u64 v[74:75], v[62:63], 0, v[74:75]
	global_store_short v[74:75], v61, off
	v_or_b32_e32 v74, 2, v60
	v_ashrrev_i32_e32 v75, 31, v74
	v_lshlrev_b64 v[74:75], 9, v[74:75]
	v_cvt_pk_bf16_f32 v61, v58, s0
	v_lshl_add_u64 v[74:75], v[62:63], 0, v[74:75]
	v_or_b32_e32 v60, 3, v60
	global_store_short v[74:75], v61, off
	v_ashrrev_i32_e32 v61, 31, v60
	v_lshlrev_b64 v[60:61], 9, v[60:61]
	v_cvt_pk_bf16_f32 v65, v59, s0
	v_lshl_add_u64 v[60:61], v[62:63], 0, v[60:61]
	global_store_short v[60:61], v65, off
	s_cbranch_execnz .LBB0_265
.LBB0_264:
	v_lshl_add_u64 v[60:61], v[128:129], 2, v[70:71]
	global_store_dwordx4 v[60:61], v[56:59], off offset:64
	s_nop 1
	v_cvt_pk_bf16_f32 v56, v56, v57
	v_cvt_pk_bf16_f32 v57, v58, v59
	v_lshl_add_u64 v[58:59], v[128:129], 1, v[66:67]
	global_store_dwordx2 v[58:59], v[56:57], off offset:32
.LBB0_265:
	v_add_u32_e32 v58, 0x90, v132
	v_ashrrev_i32_e32 v59, 31, v58
	v_and_b32_e32 v62, 0xdf, v58
	v_lshlrev_b64 v[56:57], 10, v[58:59]
	v_and_b32_e32 v73, 0xffffff00, v58
	s_and_b64 vcc, exec, s[0:1]
	v_lshl_add_u64 v[60:61], s[44:45], 0, v[56:57]
	v_lshlrev_b32_e32 v56, 1, v62
	s_cbranch_vccnz .LBB0_268
	v_lshl_add_u64 v[62:63], v[130:131], 2, v[60:61]
	v_add_u32_e32 v57, v130, v73
	global_store_dwordx4 v[62:63], v[52:55], off
	v_and_or_b32 v62, v57, s80, v145
	v_mov_b32_e32 v57, v129
	v_ashrrev_i32_e32 v63, 31, v62
	v_lshl_add_u64 v[74:75], s[48:49], 0, v[56:57]
	v_lshlrev_b64 v[76:77], 9, v[62:63]
	v_cvt_pk_bf16_f32 v57, v52, s0
	v_lshl_add_u64 v[76:77], v[74:75], 0, v[76:77]
	global_store_short v[76:77], v57, off
	v_or_b32_e32 v76, 1, v62
	v_ashrrev_i32_e32 v77, 31, v76
	v_lshlrev_b64 v[76:77], 9, v[76:77]
	v_cvt_pk_bf16_f32 v57, v53, s0
	v_lshl_add_u64 v[76:77], v[74:75], 0, v[76:77]
	global_store_short v[76:77], v57, off
	v_or_b32_e32 v76, 2, v62
	v_ashrrev_i32_e32 v77, 31, v76
	v_or_b32_e32 v62, 3, v62
	v_lshlrev_b64 v[76:77], 9, v[76:77]
	v_ashrrev_i32_e32 v63, 31, v62
	v_cvt_pk_bf16_f32 v57, v54, s0
	v_lshl_add_u64 v[76:77], v[74:75], 0, v[76:77]
	v_lshlrev_b64 v[62:63], 9, v[62:63]
	global_store_short v[76:77], v57, off
	v_cvt_pk_bf16_f32 v57, v55, s0
	v_lshl_add_u64 v[62:63], v[74:75], 0, v[62:63]
	s_mov_b64 s[52:53], 0
	global_store_short v[62:63], v57, off
	s_branch .LBB0_269

.LBB0_269:
	v_lshlrev_b64 v[58:59], 8, v[58:59]
	s_andn2_b64 vcc, exec, s[52:53]
	v_lshl_add_u64 v[62:63], v[58:59], 2, s[42:43]
	v_lshl_add_u64 v[58:59], v[58:59], 1, s[46:47]
	s_cbranch_vccnz .LBB0_271
	v_lshl_add_u64 v[74:75], v[128:129], 2, v[62:63]
	global_store_dwordx4 v[74:75], v[52:55], off
	s_nop 1
	v_cvt_pk_bf16_f32 v52, v52, v53
	v_cvt_pk_bf16_f32 v53, v54, v55
	v_lshl_add_u64 v[54:55], v[128:129], 1, v[58:59]
	global_store_dwordx2 v[54:55], v[52:53], off
.LBB0_271:
	s_and_b64 vcc, exec, s[0:1]
	s_cbranch_vccnz .LBB0_276
	v_lshl_add_u64 v[52:53], v[124:125], 2, v[60:61]
	global_store_dwordx4 v[52:53], v[48:51], off
	v_add_u32_e32 v52, v124, v73
	v_and_or_b32 v52, v52, s80, v133
	v_mov_b32_e32 v57, v129
	v_ashrrev_i32_e32 v53, 31, v52
	v_lshl_add_u64 v[54:55], s[48:49], 0, v[56:57]
	v_lshlrev_b64 v[74:75], 9, v[52:53]
	v_cvt_pk_bf16_f32 v57, v48, s0
	v_lshl_add_u64 v[74:75], v[54:55], 0, v[74:75]
	global_store_short v[74:75], v57, off
	v_or_b32_e32 v74, 1, v52
	v_ashrrev_i32_e32 v75, 31, v74
	v_lshlrev_b64 v[74:75], 9, v[74:75]
	v_cvt_pk_bf16_f32 v53, v49, s0
	v_lshl_add_u64 v[74:75], v[54:55], 0, v[74:75]
	global_store_short v[74:75], v53, off
	v_or_b32_e32 v74, 2, v52
	v_ashrrev_i32_e32 v75, 31, v74
	v_lshlrev_b64 v[74:75], 9, v[74:75]
	v_cvt_pk_bf16_f32 v53, v50, s0
	v_lshl_add_u64 v[74:75], v[54:55], 0, v[74:75]
	v_or_b32_e32 v52, 3, v52
	global_store_short v[74:75], v53, off
	v_ashrrev_i32_e32 v53, 31, v52
	v_lshlrev_b64 v[52:53], 9, v[52:53]
	v_cvt_pk_bf16_f32 v57, v51, s0
	v_lshl_add_u64 v[52:53], v[54:55], 0, v[52:53]
	global_store_short v[52:53], v57, off
	s_cbranch_execnz .LBB0_274
.LBB0_273:
	v_lshl_add_u64 v[52:53], v[128:129], 2, v[62:63]
	global_store_dwordx4 v[52:53], v[48:51], off offset:64
	s_nop 1
	v_cvt_pk_bf16_f32 v48, v48, v49
	v_cvt_pk_bf16_f32 v49, v50, v51
	v_lshl_add_u64 v[50:51], v[128:129], 1, v[58:59]
	global_store_dwordx2 v[50:51], v[48:49], off offset:32
.LBB0_274:
	v_add_u32_e32 v50, 0xa0, v132
	v_ashrrev_i32_e32 v51, 31, v50
	v_and_b32_e32 v54, 0xef, v50
	v_lshlrev_b64 v[48:49], 10, v[50:51]
	v_and_b32_e32 v74, 0xffffff00, v50
	s_and_b64 vcc, exec, s[0:1]
	v_lshl_add_u64 v[52:53], s[44:45], 0, v[48:49]
	v_lshlrev_b32_e32 v48, 1, v54
	s_cbranch_vccnz .LBB0_277
	v_lshl_add_u64 v[54:55], v[130:131], 2, v[52:53]
	v_add_u32_e32 v49, v130, v74
	global_store_dwordx4 v[54:55], v[44:47], off
	v_and_or_b32 v54, v49, s80, v145
	v_mov_b32_e32 v49, v129
	v_ashrrev_i32_e32 v55, 31, v54
	v_lshl_add_u64 v[76:77], s[48:49], 0, v[48:49]
	v_lshlrev_b64 v[78:79], 9, v[54:55]
	v_cvt_pk_bf16_f32 v49, v44, s0
	v_lshl_add_u64 v[78:79], v[76:77], 0, v[78:79]
	global_store_short v[78:79], v49, off
	v_or_b32_e32 v78, 1, v54
	v_ashrrev_i32_e32 v79, 31, v78
	v_lshlrev_b64 v[78:79], 9, v[78:79]
	v_cvt_pk_bf16_f32 v49, v45, s0
	v_lshl_add_u64 v[78:79], v[76:77], 0, v[78:79]
	global_store_short v[78:79], v49, off
	v_or_b32_e32 v78, 2, v54
	v_ashrrev_i32_e32 v79, 31, v78
	v_or_b32_e32 v54, 3, v54
	v_lshlrev_b64 v[78:79], 9, v[78:79]
	v_ashrrev_i32_e32 v55, 31, v54
	v_cvt_pk_bf16_f32 v49, v46, s0
	v_lshl_add_u64 v[78:79], v[76:77], 0, v[78:79]
	v_lshlrev_b64 v[54:55], 9, v[54:55]
	global_store_short v[78:79], v49, off
	v_cvt_pk_bf16_f32 v49, v47, s0
	v_lshl_add_u64 v[54:55], v[76:77], 0, v[54:55]
	s_mov_b64 s[52:53], 0
	global_store_short v[54:55], v49, off
	s_branch .LBB0_278

.LBB0_278:
	v_lshlrev_b64 v[50:51], 8, v[50:51]
	s_andn2_b64 vcc, exec, s[52:53]
	v_lshl_add_u64 v[54:55], v[50:51], 2, s[42:43]
	v_lshl_add_u64 v[50:51], v[50:51], 1, s[46:47]
	s_cbranch_vccnz .LBB0_280
	v_lshl_add_u64 v[76:77], v[128:129], 2, v[54:55]
	global_store_dwordx4 v[76:77], v[44:47], off
	s_nop 1
	v_cvt_pk_bf16_f32 v44, v44, v45
	v_cvt_pk_bf16_f32 v45, v46, v47
	v_lshl_add_u64 v[46:47], v[128:129], 1, v[50:51]
	global_store_dwordx2 v[46:47], v[44:45], off
.LBB0_280:
	s_and_b64 vcc, exec, s[0:1]
	s_cbranch_vccnz .LBB0_285
	v_lshl_add_u64 v[44:45], v[124:125], 2, v[52:53]
	global_store_dwordx4 v[44:45], v[40:43], off
	v_add_u32_e32 v44, v124, v74
	v_and_or_b32 v44, v44, s80, v133
	v_mov_b32_e32 v49, v129
	v_ashrrev_i32_e32 v45, 31, v44
	v_lshl_add_u64 v[46:47], s[48:49], 0, v[48:49]
	v_lshlrev_b64 v[76:77], 9, v[44:45]
	v_cvt_pk_bf16_f32 v49, v40, s0
	v_lshl_add_u64 v[76:77], v[46:47], 0, v[76:77]
	global_store_short v[76:77], v49, off
	v_or_b32_e32 v76, 1, v44
	v_ashrrev_i32_e32 v77, 31, v76
	v_lshlrev_b64 v[76:77], 9, v[76:77]
	v_cvt_pk_bf16_f32 v45, v41, s0
	v_lshl_add_u64 v[76:77], v[46:47], 0, v[76:77]
	global_store_short v[76:77], v45, off
	v_or_b32_e32 v76, 2, v44
	v_ashrrev_i32_e32 v77, 31, v76
	v_lshlrev_b64 v[76:77], 9, v[76:77]
	v_cvt_pk_bf16_f32 v45, v42, s0
	v_lshl_add_u64 v[76:77], v[46:47], 0, v[76:77]
	v_or_b32_e32 v44, 3, v44
	global_store_short v[76:77], v45, off
	v_ashrrev_i32_e32 v45, 31, v44
	v_lshlrev_b64 v[44:45], 9, v[44:45]
	v_cvt_pk_bf16_f32 v49, v43, s0
	v_lshl_add_u64 v[44:45], v[46:47], 0, v[44:45]
	global_store_short v[44:45], v49, off
	s_cbranch_execnz .LBB0_283
.LBB0_282:
	v_lshl_add_u64 v[44:45], v[128:129], 2, v[54:55]
	global_store_dwordx4 v[44:45], v[40:43], off offset:64
	s_nop 1
	v_cvt_pk_bf16_f32 v40, v40, v41
	v_cvt_pk_bf16_f32 v41, v42, v43
	v_lshl_add_u64 v[42:43], v[128:129], 1, v[50:51]
	global_store_dwordx2 v[42:43], v[40:41], off offset:32
.LBB0_283:
	v_add_u32_e32 v42, 0xb0, v132
	v_ashrrev_i32_e32 v43, 31, v42
	v_lshlrev_b64 v[40:41], 10, v[42:43]
	v_and_b32_e32 v75, 0xffffff00, v42
	s_and_b64 vcc, exec, s[0:1]
	v_lshl_add_u64 v[44:45], s[44:45], 0, v[40:41]
	v_lshlrev_b32_sdwa v40, v144, v42 dst_sel:DWORD dst_unused:UNUSED_PAD src0_sel:DWORD src1_sel:BYTE_0
	s_cbranch_vccnz .LBB0_286
	v_lshl_add_u64 v[46:47], v[130:131], 2, v[44:45]
	v_add_u32_e32 v41, v130, v75
	global_store_dwordx4 v[46:47], v[36:39], off
	v_and_or_b32 v46, v41, s80, v145
	v_mov_b32_e32 v41, v129
	v_ashrrev_i32_e32 v47, 31, v46
	v_lshl_add_u64 v[76:77], s[48:49], 0, v[40:41]
	v_lshlrev_b64 v[78:79], 9, v[46:47]
	v_cvt_pk_bf16_f32 v41, v36, s0
	v_lshl_add_u64 v[78:79], v[76:77], 0, v[78:79]
	global_store_short v[78:79], v41, off
	v_or_b32_e32 v78, 1, v46
	v_ashrrev_i32_e32 v79, 31, v78
	v_lshlrev_b64 v[78:79], 9, v[78:79]
	v_cvt_pk_bf16_f32 v41, v37, s0
	v_lshl_add_u64 v[78:79], v[76:77], 0, v[78:79]
	global_store_short v[78:79], v41, off
	v_or_b32_e32 v78, 2, v46
	v_ashrrev_i32_e32 v79, 31, v78
	v_or_b32_e32 v46, 3, v46
	v_lshlrev_b64 v[78:79], 9, v[78:79]
	v_ashrrev_i32_e32 v47, 31, v46
	v_cvt_pk_bf16_f32 v41, v38, s0
	v_lshl_add_u64 v[78:79], v[76:77], 0, v[78:79]
	v_lshlrev_b64 v[46:47], 9, v[46:47]
	global_store_short v[78:79], v41, off
	v_cvt_pk_bf16_f32 v41, v39, s0
	v_lshl_add_u64 v[46:47], v[76:77], 0, v[46:47]
	s_mov_b64 s[52:53], 0
	global_store_short v[46:47], v41, off
	s_branch .LBB0_287

.LBB0_287:
	v_lshlrev_b64 v[42:43], 8, v[42:43]
	s_andn2_b64 vcc, exec, s[52:53]
	v_lshl_add_u64 v[46:47], v[42:43], 2, s[42:43]
	v_lshl_add_u64 v[42:43], v[42:43], 1, s[46:47]
	s_cbranch_vccnz .LBB0_289
	v_lshl_add_u64 v[76:77], v[128:129], 2, v[46:47]
	global_store_dwordx4 v[76:77], v[36:39], off
	s_nop 1
	v_cvt_pk_bf16_f32 v36, v36, v37
	v_cvt_pk_bf16_f32 v37, v38, v39
	v_lshl_add_u64 v[38:39], v[128:129], 1, v[42:43]
	global_store_dwordx2 v[38:39], v[36:37], off
.LBB0_289:
	s_and_b64 vcc, exec, s[0:1]
	s_cbranch_vccnz .LBB0_315
	v_lshl_add_u64 v[36:37], v[124:125], 2, v[44:45]
	global_store_dwordx4 v[36:37], v[32:35], off
	v_add_u32_e32 v36, v124, v75
	v_and_or_b32 v36, v36, s80, v133
	v_mov_b32_e32 v41, v129
	v_ashrrev_i32_e32 v37, 31, v36
	v_lshl_add_u64 v[38:39], s[48:49], 0, v[40:41]
	v_lshlrev_b64 v[76:77], 9, v[36:37]
	v_cvt_pk_bf16_f32 v41, v32, s0
	v_lshl_add_u64 v[76:77], v[38:39], 0, v[76:77]
	global_store_short v[76:77], v41, off
	v_or_b32_e32 v76, 1, v36
	v_ashrrev_i32_e32 v77, 31, v76
	v_lshlrev_b64 v[76:77], 9, v[76:77]
	v_cvt_pk_bf16_f32 v37, v33, s0
	v_lshl_add_u64 v[76:77], v[38:39], 0, v[76:77]
	global_store_short v[76:77], v37, off
	v_or_b32_e32 v76, 2, v36
	v_ashrrev_i32_e32 v77, 31, v76
	v_lshlrev_b64 v[76:77], 9, v[76:77]
	v_cvt_pk_bf16_f32 v37, v34, s0
	v_lshl_add_u64 v[76:77], v[38:39], 0, v[76:77]
	v_or_b32_e32 v36, 3, v36
	global_store_short v[76:77], v37, off
	v_ashrrev_i32_e32 v37, 31, v36
	v_lshlrev_b64 v[36:37], 9, v[36:37]
	v_cvt_pk_bf16_f32 v41, v35, s0
	v_lshl_add_u64 v[36:37], v[38:39], 0, v[36:37]
	global_store_short v[36:37], v41, off
	s_cbranch_execnz .LBB0_292
.LBB0_291:
	v_lshl_add_u64 v[36:37], v[128:129], 2, v[46:47]
	global_store_dwordx4 v[36:37], v[32:35], off offset:64
	s_nop 1
	v_cvt_pk_bf16_f32 v32, v32, v33
	v_cvt_pk_bf16_f32 v33, v34, v35
	v_lshl_add_u64 v[34:35], v[128:129], 1, v[42:43]
	global_store_dwordx2 v[34:35], v[32:33], off offset:32
.LBB0_292:
	s_and_b64 vcc, exec, s[0:1]
	s_cbranch_vccnz .LBB0_316
	v_lshl_add_u64 v[32:33], v[96:97], 2, v[68:69]
	global_store_dwordx4 v[32:33], v[28:31], off
	v_add_u32_e32 v32, v96, v72
	v_and_or_b32 v32, v32, s80, v145
	v_mov_b32_e32 v65, v129
	v_ashrrev_i32_e32 v33, 31, v32
	v_lshl_add_u64 v[34:35], s[48:49], 0, v[64:65]
	v_lshlrev_b64 v[36:37], 9, v[32:33]
	v_cvt_pk_bf16_f32 v38, v28, s0
	v_lshl_add_u64 v[36:37], v[34:35], 0, v[36:37]
	global_store_short v[36:37], v38, off
	v_or_b32_e32 v36, 1, v32
	v_ashrrev_i32_e32 v37, 31, v36
	v_lshlrev_b64 v[36:37], 9, v[36:37]
	v_cvt_pk_bf16_f32 v33, v29, s0
	v_lshl_add_u64 v[36:37], v[34:35], 0, v[36:37]
	global_store_short v[36:37], v33, off
	v_or_b32_e32 v36, 2, v32
	v_ashrrev_i32_e32 v37, 31, v36
	v_lshlrev_b64 v[36:37], 9, v[36:37]
	v_cvt_pk_bf16_f32 v33, v30, s0
	v_lshl_add_u64 v[36:37], v[34:35], 0, v[36:37]
	v_or_b32_e32 v32, 3, v32
	global_store_short v[36:37], v33, off
	v_ashrrev_i32_e32 v33, 31, v32
	v_lshlrev_b64 v[32:33], 9, v[32:33]
	v_cvt_pk_bf16_f32 v36, v31, s0
	v_lshl_add_u64 v[32:33], v[34:35], 0, v[32:33]
	global_store_short v[32:33], v36, off
	s_cbranch_execnz .LBB0_295
.LBB0_294:
	v_lshl_add_u64 v[32:33], v[128:129], 2, v[70:71]
	global_store_dwordx4 v[32:33], v[28:31], off offset:512
	s_nop 1
	v_cvt_pk_bf16_f32 v28, v28, v29
	v_cvt_pk_bf16_f32 v29, v30, v31
	v_lshl_add_u64 v[30:31], v[128:129], 1, v[66:67]
	global_store_dwordx2 v[30:31], v[28:29], off offset:256
.LBB0_295:
	s_and_b64 vcc, exec, s[0:1]
	s_cbranch_vccnz .LBB0_317
	v_lshl_add_u64 v[28:29], v[92:93], 2, v[68:69]
	global_store_dwordx4 v[28:29], v[24:27], off
	v_add_u32_e32 v28, v92, v72
	v_and_or_b32 v28, v28, s80, v94
	v_mov_b32_e32 v65, v129
	v_ashrrev_i32_e32 v29, 31, v28
	v_lshl_add_u64 v[30:31], s[48:49], 0, v[64:65]
	v_lshlrev_b64 v[32:33], 9, v[28:29]
	v_cvt_pk_bf16_f32 v34, v24, s0
	v_lshl_add_u64 v[32:33], v[30:31], 0, v[32:33]
	global_store_short v[32:33], v34, off
	v_or_b32_e32 v32, 1, v28
	v_ashrrev_i32_e32 v33, 31, v32
	v_lshlrev_b64 v[32:33], 9, v[32:33]
	v_cvt_pk_bf16_f32 v29, v25, s0
	v_lshl_add_u64 v[32:33], v[30:31], 0, v[32:33]
	global_store_short v[32:33], v29, off
	v_or_b32_e32 v32, 2, v28
	v_ashrrev_i32_e32 v33, 31, v32
	v_lshlrev_b64 v[32:33], 9, v[32:33]
	v_cvt_pk_bf16_f32 v29, v26, s0
	v_lshl_add_u64 v[32:33], v[30:31], 0, v[32:33]
	v_or_b32_e32 v28, 3, v28
	global_store_short v[32:33], v29, off
	v_ashrrev_i32_e32 v29, 31, v28
	v_lshlrev_b64 v[28:29], 9, v[28:29]
	v_cvt_pk_bf16_f32 v32, v27, s0
	v_lshl_add_u64 v[28:29], v[30:31], 0, v[28:29]
	global_store_short v[28:29], v32, off
	s_cbranch_execnz .LBB0_298
.LBB0_297:
	v_lshl_add_u64 v[28:29], v[128:129], 2, v[70:71]
	global_store_dwordx4 v[28:29], v[24:27], off offset:576
	s_nop 1
	v_cvt_pk_bf16_f32 v24, v24, v25
	v_cvt_pk_bf16_f32 v25, v26, v27
	v_lshl_add_u64 v[26:27], v[128:129], 1, v[66:67]
	global_store_dwordx2 v[26:27], v[24:25], off offset:288
.LBB0_298:
	s_and_b64 vcc, exec, s[0:1]
	s_cbranch_vccnz .LBB0_318
	v_lshl_add_u64 v[24:25], v[96:97], 2, v[60:61]
	global_store_dwordx4 v[24:25], v[20:23], off
	v_add_u32_e32 v24, v96, v73
	v_and_or_b32 v24, v24, s80, v145
	v_mov_b32_e32 v57, v129
	v_ashrrev_i32_e32 v25, 31, v24
	v_lshl_add_u64 v[26:27], s[48:49], 0, v[56:57]
	v_lshlrev_b64 v[28:29], 9, v[24:25]
	v_cvt_pk_bf16_f32 v30, v20, s0
	v_lshl_add_u64 v[28:29], v[26:27], 0, v[28:29]
	global_store_short v[28:29], v30, off
	v_or_b32_e32 v28, 1, v24
	v_ashrrev_i32_e32 v29, 31, v28
	v_lshlrev_b64 v[28:29], 9, v[28:29]
	v_cvt_pk_bf16_f32 v25, v21, s0
	v_lshl_add_u64 v[28:29], v[26:27], 0, v[28:29]
	global_store_short v[28:29], v25, off
	v_or_b32_e32 v28, 2, v24
	v_ashrrev_i32_e32 v29, 31, v28
	v_lshlrev_b64 v[28:29], 9, v[28:29]
	v_cvt_pk_bf16_f32 v25, v22, s0
	v_lshl_add_u64 v[28:29], v[26:27], 0, v[28:29]
	v_or_b32_e32 v24, 3, v24
	global_store_short v[28:29], v25, off
	v_ashrrev_i32_e32 v25, 31, v24
	v_lshlrev_b64 v[24:25], 9, v[24:25]
	v_cvt_pk_bf16_f32 v28, v23, s0
	v_lshl_add_u64 v[24:25], v[26:27], 0, v[24:25]
	global_store_short v[24:25], v28, off
	s_cbranch_execnz .LBB0_301
.LBB0_300:
	v_lshl_add_u64 v[24:25], v[128:129], 2, v[62:63]
	global_store_dwordx4 v[24:25], v[20:23], off offset:512
	s_nop 1
	v_cvt_pk_bf16_f32 v20, v20, v21
	v_cvt_pk_bf16_f32 v21, v22, v23
	v_lshl_add_u64 v[22:23], v[128:129], 1, v[58:59]
	global_store_dwordx2 v[22:23], v[20:21], off offset:256
.LBB0_301:
	s_and_b64 vcc, exec, s[0:1]
	s_cbranch_vccnz .LBB0_319
	v_lshl_add_u64 v[20:21], v[92:93], 2, v[60:61]
	global_store_dwordx4 v[20:21], v[16:19], off
	v_add_u32_e32 v20, v92, v73
	v_and_or_b32 v20, v20, s80, v94
	v_mov_b32_e32 v57, v129
	v_ashrrev_i32_e32 v21, 31, v20
	v_lshl_add_u64 v[22:23], s[48:49], 0, v[56:57]
	v_lshlrev_b64 v[24:25], 9, v[20:21]
	v_cvt_pk_bf16_f32 v26, v16, s0
	v_lshl_add_u64 v[24:25], v[22:23], 0, v[24:25]
	global_store_short v[24:25], v26, off
	v_or_b32_e32 v24, 1, v20
	v_ashrrev_i32_e32 v25, 31, v24
	v_lshlrev_b64 v[24:25], 9, v[24:25]
	v_cvt_pk_bf16_f32 v21, v17, s0
	v_lshl_add_u64 v[24:25], v[22:23], 0, v[24:25]
	global_store_short v[24:25], v21, off
	v_or_b32_e32 v24, 2, v20
	v_ashrrev_i32_e32 v25, 31, v24
	v_lshlrev_b64 v[24:25], 9, v[24:25]
	v_cvt_pk_bf16_f32 v21, v18, s0
	v_lshl_add_u64 v[24:25], v[22:23], 0, v[24:25]
	v_or_b32_e32 v20, 3, v20
	global_store_short v[24:25], v21, off
	v_ashrrev_i32_e32 v21, 31, v20
	v_lshlrev_b64 v[20:21], 9, v[20:21]
	v_cvt_pk_bf16_f32 v24, v19, s0
	v_lshl_add_u64 v[20:21], v[22:23], 0, v[20:21]
	global_store_short v[20:21], v24, off
	s_cbranch_execnz .LBB0_304
.LBB0_303:
	v_lshl_add_u64 v[20:21], v[128:129], 2, v[62:63]
	global_store_dwordx4 v[20:21], v[16:19], off offset:576
	s_nop 1
	v_cvt_pk_bf16_f32 v16, v16, v17
	v_cvt_pk_bf16_f32 v17, v18, v19
	v_lshl_add_u64 v[18:19], v[128:129], 1, v[58:59]
	global_store_dwordx2 v[18:19], v[16:17], off offset:288
.LBB0_304:
	s_and_b64 vcc, exec, s[0:1]
	s_cbranch_vccnz .LBB0_320
	v_lshl_add_u64 v[16:17], v[96:97], 2, v[52:53]
	global_store_dwordx4 v[16:17], v[12:15], off
	v_add_u32_e32 v16, v96, v74
	v_and_or_b32 v16, v16, s80, v145
	v_mov_b32_e32 v49, v129
	v_ashrrev_i32_e32 v17, 31, v16
	v_lshl_add_u64 v[18:19], s[48:49], 0, v[48:49]
	v_lshlrev_b64 v[20:21], 9, v[16:17]
	v_cvt_pk_bf16_f32 v22, v12, s0
	v_lshl_add_u64 v[20:21], v[18:19], 0, v[20:21]
	global_store_short v[20:21], v22, off
	v_or_b32_e32 v20, 1, v16
	v_ashrrev_i32_e32 v21, 31, v20
	v_lshlrev_b64 v[20:21], 9, v[20:21]
	v_cvt_pk_bf16_f32 v17, v13, s0
	v_lshl_add_u64 v[20:21], v[18:19], 0, v[20:21]
	global_store_short v[20:21], v17, off
	v_or_b32_e32 v20, 2, v16
	v_ashrrev_i32_e32 v21, 31, v20
	v_lshlrev_b64 v[20:21], 9, v[20:21]
	v_cvt_pk_bf16_f32 v17, v14, s0
	v_lshl_add_u64 v[20:21], v[18:19], 0, v[20:21]
	v_or_b32_e32 v16, 3, v16
	global_store_short v[20:21], v17, off
	v_ashrrev_i32_e32 v17, 31, v16
	v_lshlrev_b64 v[16:17], 9, v[16:17]
	v_cvt_pk_bf16_f32 v20, v15, s0
	v_lshl_add_u64 v[16:17], v[18:19], 0, v[16:17]
	global_store_short v[16:17], v20, off
	s_cbranch_execnz .LBB0_307
.LBB0_306:
	v_lshl_add_u64 v[16:17], v[128:129], 2, v[54:55]
	global_store_dwordx4 v[16:17], v[12:15], off offset:512
	s_nop 1
	v_cvt_pk_bf16_f32 v12, v12, v13
	v_cvt_pk_bf16_f32 v13, v14, v15
	v_lshl_add_u64 v[14:15], v[128:129], 1, v[50:51]
	global_store_dwordx2 v[14:15], v[12:13], off offset:256
.LBB0_307:
	s_and_b64 vcc, exec, s[0:1]
	s_cbranch_vccnz .LBB0_321
	v_lshl_add_u64 v[12:13], v[92:93], 2, v[52:53]
	global_store_dwordx4 v[12:13], v[8:11], off
	v_add_u32_e32 v12, v92, v74
	v_and_or_b32 v12, v12, s80, v94
	v_mov_b32_e32 v49, v129
	v_ashrrev_i32_e32 v13, 31, v12
	v_lshl_add_u64 v[14:15], s[48:49], 0, v[48:49]
	v_lshlrev_b64 v[16:17], 9, v[12:13]
	v_cvt_pk_bf16_f32 v18, v8, s0
	v_lshl_add_u64 v[16:17], v[14:15], 0, v[16:17]
	global_store_short v[16:17], v18, off
	v_or_b32_e32 v16, 1, v12
	v_ashrrev_i32_e32 v17, 31, v16
	v_lshlrev_b64 v[16:17], 9, v[16:17]
	v_cvt_pk_bf16_f32 v13, v9, s0
	v_lshl_add_u64 v[16:17], v[14:15], 0, v[16:17]
	global_store_short v[16:17], v13, off
	v_or_b32_e32 v16, 2, v12
	v_ashrrev_i32_e32 v17, 31, v16
	v_lshlrev_b64 v[16:17], 9, v[16:17]
	v_cvt_pk_bf16_f32 v13, v10, s0
	v_lshl_add_u64 v[16:17], v[14:15], 0, v[16:17]
	v_or_b32_e32 v12, 3, v12
	global_store_short v[16:17], v13, off
	v_ashrrev_i32_e32 v13, 31, v12
	v_lshlrev_b64 v[12:13], 9, v[12:13]
	v_cvt_pk_bf16_f32 v16, v11, s0
	v_lshl_add_u64 v[12:13], v[14:15], 0, v[12:13]
	global_store_short v[12:13], v16, off
	s_cbranch_execnz .LBB0_310
.LBB0_309:
	v_lshl_add_u64 v[12:13], v[128:129], 2, v[54:55]
	global_store_dwordx4 v[12:13], v[8:11], off offset:576
	s_nop 1
	v_cvt_pk_bf16_f32 v8, v8, v9
	v_cvt_pk_bf16_f32 v9, v10, v11
	v_lshl_add_u64 v[10:11], v[128:129], 1, v[50:51]
	global_store_dwordx2 v[10:11], v[8:9], off offset:288
.LBB0_310:
	s_and_b64 vcc, exec, s[0:1]
	s_cbranch_vccnz .LBB0_322
	v_lshl_add_u64 v[8:9], v[96:97], 2, v[44:45]
	global_store_dwordx4 v[8:9], v[4:7], off
	v_add_u32_e32 v8, v96, v75
	v_and_or_b32 v8, v8, s80, v145
	v_mov_b32_e32 v41, v129
	v_ashrrev_i32_e32 v9, 31, v8
	v_lshl_add_u64 v[10:11], s[48:49], 0, v[40:41]
	v_lshlrev_b64 v[12:13], 9, v[8:9]
	v_cvt_pk_bf16_f32 v14, v4, s0
	v_lshl_add_u64 v[12:13], v[10:11], 0, v[12:13]
	global_store_short v[12:13], v14, off
	v_or_b32_e32 v12, 1, v8
	v_ashrrev_i32_e32 v13, 31, v12
	v_lshlrev_b64 v[12:13], 9, v[12:13]
	v_cvt_pk_bf16_f32 v9, v5, s0
	v_lshl_add_u64 v[12:13], v[10:11], 0, v[12:13]
	global_store_short v[12:13], v9, off
	v_or_b32_e32 v12, 2, v8
	v_ashrrev_i32_e32 v13, 31, v12
	v_lshlrev_b64 v[12:13], 9, v[12:13]
	v_cvt_pk_bf16_f32 v9, v6, s0
	v_lshl_add_u64 v[12:13], v[10:11], 0, v[12:13]
	v_or_b32_e32 v8, 3, v8
	global_store_short v[12:13], v9, off
	v_ashrrev_i32_e32 v9, 31, v8
	v_lshlrev_b64 v[8:9], 9, v[8:9]
	v_cvt_pk_bf16_f32 v12, v7, s0
	v_lshl_add_u64 v[8:9], v[10:11], 0, v[8:9]
	global_store_short v[8:9], v12, off
	s_cbranch_execnz .LBB0_313
.LBB0_312:
	v_lshl_add_u64 v[8:9], v[128:129], 2, v[46:47]
	global_store_dwordx4 v[8:9], v[4:7], off offset:512
	s_nop 1
	v_cvt_pk_bf16_f32 v4, v4, v5
	v_cvt_pk_bf16_f32 v5, v6, v7
	v_lshl_add_u64 v[6:7], v[128:129], 1, v[42:43]
	global_store_dwordx2 v[6:7], v[4:5], off offset:256
.LBB0_313:
	s_and_b64 vcc, exec, s[0:1]
	s_cbranch_vccnz .LBB0_323
	v_lshl_add_u64 v[4:5], v[92:93], 2, v[44:45]
	global_store_dwordx4 v[4:5], v[0:3], off
	v_add_u32_e32 v4, v92, v75
	v_and_or_b32 v4, v4, s80, v94
	v_mov_b32_e32 v41, v129
	v_ashrrev_i32_e32 v5, 31, v4
	v_lshl_add_u64 v[6:7], s[48:49], 0, v[40:41]
	v_lshlrev_b64 v[8:9], 9, v[4:5]
	v_cvt_pk_bf16_f32 v10, v0, s0
	v_lshl_add_u64 v[8:9], v[6:7], 0, v[8:9]
	global_store_short v[8:9], v10, off
	v_or_b32_e32 v8, 1, v4
	v_ashrrev_i32_e32 v9, 31, v8
	v_lshlrev_b64 v[8:9], 9, v[8:9]
	v_cvt_pk_bf16_f32 v5, v1, s0
	v_lshl_add_u64 v[8:9], v[6:7], 0, v[8:9]
	global_store_short v[8:9], v5, off
	v_or_b32_e32 v8, 2, v4
	v_ashrrev_i32_e32 v9, 31, v8
	v_lshlrev_b64 v[8:9], 9, v[8:9]
	v_cvt_pk_bf16_f32 v5, v2, s0
	v_lshl_add_u64 v[8:9], v[6:7], 0, v[8:9]
	v_or_b32_e32 v4, 3, v4
	global_store_short v[8:9], v5, off
	v_ashrrev_i32_e32 v5, 31, v4
	v_lshlrev_b64 v[4:5], 9, v[4:5]
	v_cvt_pk_bf16_f32 v8, v3, s0
	v_lshl_add_u64 v[4:5], v[6:7], 0, v[4:5]
	global_store_short v[4:5], v8, off
	s_cbranch_execnz .LBB0_176
	s_branch .LBB0_175

.LBB0_377:
	s_and_b64 s[0:1], s[28:29], exec
	s_cselect_b32 s0, s61, 0x8700000
	s_add_u32 s0, s4, s0
	s_addc_u32 s1, s5, 0
	s_add_u32 s0, s0, s30
	s_addc_u32 s1, s1, s31
	s_waitcnt vmcnt(0)
	v_ashrrev_i32_e32 v1, 31, v122
	v_mov_b32_e32 v0, v122
	v_lshl_add_u64 v[0:1], v[0:1], 2, s[0:1]
	global_store_dword v[0:1], v64, off
	v_lshl_add_u64 v[0:1], v[122:123], 2, s[0:1]
	v_or_b32_e32 v122, 16, v122
	global_store_dword v[0:1], v65, off offset:512
	global_store_dword v[0:1], v66, off offset:1024
	global_store_dword v[0:1], v67, off offset:1536
	global_store_dword v[0:1], v52, off offset:64
	v_lshl_add_u64 v[0:1], v[122:123], 2, s[0:1]
	global_store_dword v[0:1], v53, off offset:512
	global_store_dword v[0:1], v54, off offset:1024
	global_store_dword v[0:1], v55, off offset:1536
	s_waitcnt lgkmcnt(0)
	s_barrier

.LBB0_380:
	v_mov_b32_e32 v0, v154
	s_nop 0
	v_cmp_eq_u32_e32 vcc, 0, v0
	s_and_saveexec_b64 s[0:1], vcc
	s_cbranch_execz .LBB0_382
	v_mov_b64_e32 v[0:1], s[6:7]
	global_atomic_add v0, v[0:1], v150, off sc0
	v_mov_b32_e32 v1, s46
	s_waitcnt vmcnt(0) lgkmcnt(0)
	ds_write_b32 v1, v0
.LBB0_382:
	s_or_b64 exec, exec, s[0:1]
	s_waitcnt lgkmcnt(0)
	s_barrier
	ds_read_b32 v0, v151
	s_movk_i32 s0, 0x2df
	s_waitcnt lgkmcnt(0)
	s_barrier
	v_cmp_lt_i32_e32 vcc, s0, v0
	v_readfirstlane_b32 s30, v0
	s_mov_b64 s[0:1], -1
	s_cbranch_vccnz .LBB0_379
	s_cmpk_gt_i32 s30, 0x23f
	s_cbranch_scc0 .LBB0_389
	s_add_i32 s1, s30, 0xfffffdc0
	s_lshr_b32 s0, s1, 5
	s_lshl_b32 s1, s1, 9
	s_lshl_b32 s16, s0, 12
	s_and_b32 s1, s1, 0xe00
	s_or_b32 s28, s16, s1
	s_mov_b32 s1, s17
	s_bfe_u32 s29, s30, 0x20003
	s_lshl_b64 s[38:39], s[0:1], 17
	s_add_u32 s1, s2, s38
	v_mov_b32_e32 v16, v154
	s_addc_u32 s31, s25, s39
	s_lshl_b32 s16, s29, 7
	s_add_u32 s38, s1, s16
	v_lshrrev_b32_e32 v17, 4, v16
	s_addc_u32 s39, s31, 0
	s_lshl_b32 s0, s0, 2
	v_xor_b32_e32 v1, v17, v16
	s_or_b32 s0, s0, s29
	s_mov_b32 s1, s17
	v_lshlrev_b32_e32 v1, 4, v1
	s_lshl_b64 s[0:1], s[0:1], 15
	v_and_b32_e32 v120, 0x70, v1
	v_ashrrev_i32_e32 v4, 5, v16
	v_and_b32_e32 v1, 31, v16
	s_add_u32 s0, s44, s0
	v_readfirstlane_b32 s29, v16
	v_ashrrev_i32_e32 v0, 3, v16
	v_bitop3_b32 v1, v4, v1, 15 bitop3:0x6c
	s_addc_u32 s1, s45, s1
	s_lshl_b32 s29, s29, 4
	v_lshl_add_u64 v[2:3], s[38:39], 0, v[120:121]
	v_lshlrev_b32_e32 v120, 4, v1
	v_ashrrev_i32_e32 v1, 31, v0
	s_and_b32 s29, s29, 0xfffffc00
	v_lshlrev_b64 v[0:1], 9, v[0:1]
	v_ashrrev_i32_e32 v5, 31, v4
	s_waitcnt vmcnt(0) lgkmcnt(0)
	s_barrier
	s_add_i32 s29, s29, 0
	v_lshl_add_u64 v[6:7], s[0:1], 0, v[120:121]
	v_lshl_add_u64 v[0:1], v[2:3], 0, v[0:1]
	s_mov_b32 s1, m0
	s_mov_b32 m0, s29
	s_nop 0
	global_load_lds_dwordx4 v[0:1], off
	s_mov_b32 m0, s1
	v_lshlrev_b64 v[2:3], 9, v[4:5]
	s_add_i32 s0, s29, 0x8000
	v_lshl_add_u64 v[2:3], v[6:7], 0, v[2:3]
	s_mov_b32 s1, m0
	s_mov_b32 m0, s0
	s_nop 0
	global_load_lds_dwordx4 v[2:3], off
	s_mov_b32 m0, s1
	v_lshl_add_u64 v[4:5], v[0:1], 0, s[18:19]
	s_add_i32 s0, s29, 0x2000
	s_mov_b32 s1, m0
	s_mov_b32 m0, s0
	s_nop 0
	global_load_lds_dwordx4 v[4:5], off
	s_mov_b32 m0, s1
	s_mov_b64 s[0:1], 0x2000
	v_lshl_add_u64 v[4:5], v[2:3], 0, s[0:1]
	s_add_i32 s0, s29, 0xa000
	s_mov_b32 s1, m0
	s_mov_b32 m0, s0
	s_nop 0
	global_load_lds_dwordx4 v[4:5], off
	s_mov_b32 m0, s1
	v_lshl_add_u64 v[4:5], v[0:1], 0, s[20:21]
	s_add_i32 s0, s29, 0x4000
	s_mov_b32 s1, m0
	s_mov_b32 m0, s0
	s_nop 0
	global_load_lds_dwordx4 v[4:5], off
	s_mov_b32 m0, s1
	s_mov_b64 s[0:1], 0x4000
	v_lshl_add_u64 v[4:5], v[2:3], 0, s[0:1]
	s_add_i32 s0, s29, 0xc000
	s_mov_b32 s1, m0
	s_mov_b32 m0, s0
	s_nop 0
	global_load_lds_dwordx4 v[4:5], off
	s_mov_b32 m0, s1
	v_lshl_add_u64 v[0:1], v[0:1], 0, s[22:23]
	s_add_i32 s0, s29, 0x6000
	s_mov_b32 s1, m0
	s_mov_b32 m0, s0
	s_nop 0
	global_load_lds_dwordx4 v[0:1], off
	s_mov_b32 m0, s1
	s_mov_b64 s[0:1], 0x6000
	v_lshl_add_u64 v[0:1], v[2:3], 0, s[0:1]
	s_add_i32 s29, s29, 0xe000
	s_mov_b32 s0, m0
	s_mov_b32 m0, s29
	s_nop 0
	global_load_lds_dwordx4 v[0:1], off
	s_mov_b32 m0, s0
	v_ashrrev_i32_e32 v0, 2, v16
	v_and_b32_e32 v19, 15, v16
	v_and_b32_e32 v0, -16, v0
	s_mov_b32 s29, s17
	v_ashrrev_i32_e32 v1, 31, v0
	v_or_b32_e32 v0, v0, v19
	v_lshl_add_u64 v[0:1], v[0:1], 0, s[28:29]
	v_mov_b64_e32 v[2:3], s[10:11]
	v_mad_u64_u32 v[2:3], s[0:1], v0, s47, v[2:3]
	v_bfe_u32 v18, v16, 4, 2
	v_mad_i32_i24 v3, v1, s47, v3
	v_lshl_add_u64 v[2:3], v[2:3], 0, s[16:17]
	v_lshlrev_b32_e32 v120, 4, v18
	v_lshl_add_u64 v[2:3], v[2:3], 0, v[120:121]
	global_load_dwordx4 v[12:15], v[2:3], off
	global_load_dwordx4 v[8:11], v[2:3], off offset:64
	v_lshrrev_b32_e32 v2, 1, v16
	v_bfe_u32 v4, v16, 1, 3
	v_lshl_add_u32 v5, v19, 7, 0
	v_mul_u32_u24_e32 v3, 0x180, v19
	v_and_b32_e32 v2, 8, v2
	v_bfe_u32 v6, v17, 1, 1
	v_bitop3_b32 v7, v17, v4, 3 bitop3:0x6c
	v_add3_u32 v17, v5, v3, v2
	v_mad_u64_u32 v[2:3], s[0:1], v0, s47, 0
	v_mad_i32_i24 v3, v1, s47, v3
	v_bitop3_b32 v4, v18, v4, 4 bitop3:0x36
	v_bitop3_b32 v16, v6, v16, 15 bitop3:0x78
	v_bitop3_b32 v20, v6, v19, 2 bitop3:0x36
	v_bitop3_b32 v21, v6, v19, 4 bitop3:0x36
	v_bitop3_b32 v22, v6, v19, 6 bitop3:0x36
	v_bitop3_b32 v23, v6, v19, 8 bitop3:0x36
	v_bitop3_b32 v24, v6, v19, 10 bitop3:0x36
	v_bitop3_b32 v25, v6, v19, 12 bitop3:0x36
	v_bitop3_b32 v26, v6, v19, 14 bitop3:0x36
	v_bitop3_b32 v27, v6, v19, 16 bitop3:0x36
	v_bitop3_b32 v28, v6, v19, 18 bitop3:0x36
	v_bitop3_b32 v29, v6, v19, 20 bitop3:0x36
	v_bitop3_b32 v30, v6, v19, 22 bitop3:0x36
	v_bitop3_b32 v31, v6, v19, 24 bitop3:0x36
	v_bitop3_b32 v32, v6, v19, 26 bitop3:0x36
	v_bitop3_b32 v33, v6, v19, 28 bitop3:0x36
	v_bitop3_b32 v6, v6, v19, 30 bitop3:0x36
	v_cmp_lt_i32_e32 vcc, v157, v156
	v_lshlrev_b64 v[0:1], 11, v[0:1]
	v_lshlrev_b32_e32 v7, 4, v7
	s_waitcnt vmcnt(0) lgkmcnt(0)
	s_waitcnt vmcnt(0)
	v_lshlrev_b32_e32 v4, 4, v4
	v_lshlrev_b32_e32 v6, 4, v6
	v_cndmask_b32_e32 v19, v155, v157, vcc
	v_cmp_lt_i32_e32 vcc, v158, v156
	v_or_b32_e32 v2, v2, v120
	v_lshl_or_b32 v0, v18, 3, v0
	v_lshlrev_b32_e32 v16, 4, v16
	v_lshlrev_b32_e32 v20, 4, v20
	v_lshlrev_b32_e32 v21, 4, v21
	v_lshlrev_b32_e32 v22, 4, v22
	v_lshlrev_b32_e32 v23, 4, v23
	v_lshlrev_b32_e32 v24, 4, v24
	v_lshlrev_b32_e32 v25, 4, v25
	v_lshlrev_b32_e32 v26, 4, v26
	v_lshlrev_b32_e32 v27, 4, v27
	v_lshlrev_b32_e32 v28, 4, v28
	v_lshlrev_b32_e32 v29, 4, v29
	v_lshlrev_b32_e32 v30, 4, v30
	v_lshlrev_b32_e32 v31, 4, v31
	v_lshlrev_b32_e32 v32, 4, v32
	v_lshlrev_b32_e32 v33, 4, v33
	v_lshlrev_b32_e32 v108, 2, v19
	v_cndmask_b32_e32 v19, v155, v158, vcc
	v_lshl_add_u64 v[76:77], s[6:7], 0, v[2:3]
	v_lshl_add_u64 v[78:79], s[6:7], 0, v[0:1]
	v_add_u32_e32 v110, v5, v7
	v_add_u32_e32 v111, v5, v4
	v_add_u32_e32 v128, v17, v6
	v_mov_b64_e32 v[0:1], v[12:13]
	v_mov_b64_e32 v[4:5], v[8:9]
	s_mov_b32 s0, 0
	v_lshlrev_b32_e32 v109, 2, v19
	v_add_u32_e32 v112, v17, v16
	v_add_u32_e32 v113, v17, v20
	v_add_u32_e32 v114, v17, v21
	v_add_u32_e32 v115, v17, v22
	v_add_u32_e32 v116, v17, v23
	v_add_u32_e32 v117, v17, v24
	v_add_u32_e32 v118, v17, v25
	v_add_u32_e32 v119, v17, v26
	v_add_u32_e32 v120, v17, v27
	v_add_u32_e32 v122, v17, v28
	v_add_u32_e32 v123, v17, v29
	v_add_u32_e32 v124, v17, v30
	v_add_u32_e32 v125, v17, v31
	v_add_u32_e32 v126, v17, v32
	v_add_u32_e32 v127, v17, v33
	v_mov_b64_e32 v[2:3], v[14:15]
	v_mov_b64_e32 v[6:7], v[10:11]
	s_barrier
	s_branch .LBB0_386
.LBB0_385:
	ds_read_b128 v[16:19], v110
	ds_read_b128 v[20:23], v110 offset:2048
	ds_read_b128 v[24:27], v111
	ds_read_b128 v[28:31], v111 offset:2048
	s_mov_b32 s1, 0xff61b1e6
	s_waitcnt lgkmcnt(0)
	v_mfma_f32_16x16x32_bf16 v[16:19], v[16:19], v[12:15], 0
	s_add_i32 s0, s0, 1
	s_cmp_lg_u32 s0, 4
	v_mfma_f32_16x16x32_bf16 v[20:23], v[20:23], v[12:15], 0
	v_mfma_f32_16x16x32_bf16 v[16:19], v[24:27], v[8:11], v[16:19]
	ds_read_b128 v[24:27], v111 offset:4096
	ds_read_b128 v[32:35], v110 offset:4096
	ds_read_b128 v[36:39], v110 offset:6144
	v_mfma_f32_16x16x32_bf16 v[20:23], v[28:31], v[8:11], v[20:23]
	s_nop 3
	v_max_f32_e32 v28, v19, v19
	v_max_f32_e32 v29, v18, v18
	v_max_f32_e32 v40, v29, v28
	s_nop 0
	v_max_f32_e32 v30, v23, v23
	v_max_f32_e32 v31, v22, v22
	v_max_f32_e32 v41, v31, v30
	s_waitcnt lgkmcnt(0)
	v_mfma_f32_16x16x32_bf16 v[28:31], v[32:35], v[12:15], 0
	v_max3_f32 v32, v16, v17, v40
	v_max3_f32 v33, v20, v21, v41
	v_max3_f32 v48, v32, s1, v33
	ds_read_b128 v[32:35], v111 offset:6144
	v_mfma_f32_16x16x32_bf16 v[24:27], v[24:27], v[8:11], v[28:31]
	s_mov_b32 s1, 0x86c4000
	s_nop 6
	v_max_f32_e32 v28, v27, v27
	v_max_f32_e32 v29, v26, v26
	v_max_f32_e32 v40, v29, v28
	v_mfma_f32_16x16x32_bf16 v[28:31], v[36:39], v[12:15], 0
	v_max3_f32 v49, v24, v25, v40
	ds_read_b128 v[36:39], v110 offset:8192
	ds_read_b128 v[40:43], v111 offset:8192
	ds_read_b128 v[44:47], v110 offset:10240
	s_waitcnt lgkmcnt(0)
	v_mfma_f32_16x16x32_bf16 v[28:31], v[32:35], v[8:11], v[28:31]
	v_mfma_f32_16x16x32_bf16 v[32:35], v[36:39], v[12:15], 0
	v_mfma_f32_16x16x32_bf16 v[32:35], v[40:43], v[8:11], v[32:35]
	s_nop 5
	v_max_f32_e32 v50, v31, v31
	v_max_f32_e32 v51, v30, v30
	v_max_f32_e32 v36, v51, v50
	v_max3_f32 v50, v28, v29, v36
	ds_read_b128 v[36:39], v111 offset:10240
	v_max3_f32 v52, v48, v49, v50
	v_max_f32_e32 v48, v35, v35
	v_max_f32_e32 v49, v34, v34
	v_mfma_f32_16x16x32_bf16 v[40:43], v[44:47], v[12:15], 0
	v_max_f32_e32 v44, v49, v48
	v_max3_f32 v53, v32, v33, v44
	ds_read_b128 v[44:47], v110 offset:12288
	s_waitcnt lgkmcnt(0)
	v_mfma_f32_16x16x32_bf16 v[36:39], v[36:39], v[8:11], v[40:43]
	s_nop 2
	ds_read_b128 v[40:43], v111 offset:12288
	s_nop 3
	v_max_f32_e32 v48, v39, v39
	v_max_f32_e32 v49, v38, v38
	v_max_f32_e32 v54, v49, v48
	ds_read_b128 v[48:51], v110 offset:14336
	v_mfma_f32_16x16x32_bf16 v[44:47], v[44:47], v[12:15], 0
	v_max3_f32 v54, v36, v37, v54
	v_max3_f32 v64, v52, v53, v54
	ds_read_b128 v[52:55], v111 offset:14336
	s_waitcnt lgkmcnt(0)
	v_mfma_f32_16x16x32_bf16 v[40:43], v[40:43], v[8:11], v[44:47]
	s_nop 7
	v_max_f32_e32 v44, v43, v43
	v_max_f32_e32 v45, v42, v42
	v_max_f32_e32 v56, v45, v44
	v_mfma_f32_16x16x32_bf16 v[44:47], v[48:51], v[12:15], 0
	v_max3_f32 v65, v40, v41, v56
	ds_read_b128 v[48:51], v110 offset:16384
	ds_read_b128 v[56:59], v111 offset:16384
	v_mfma_f32_16x16x32_bf16 v[44:47], v[52:55], v[8:11], v[44:47]
	ds_read_b128 v[52:55], v110 offset:18432
	s_waitcnt lgkmcnt(0)
	v_mfma_f32_16x16x32_bf16 v[48:51], v[48:51], v[12:15], 0
	v_mfma_f32_16x16x32_bf16 v[48:51], v[56:59], v[8:11], v[48:51]
	s_nop 3
	v_max_f32_e32 v60, v47, v47
	v_max_f32_e32 v61, v46, v46
	v_max_f32_e32 v60, v61, v60
	v_max3_f32 v66, v44, v45, v60
	ds_read_b128 v[60:63], v111 offset:18432
	v_max_f32_e32 v56, v51, v51
	v_max_f32_e32 v57, v50, v50
	v_max_f32_e32 v56, v57, v56
	v_max3_f32 v69, v48, v49, v56
	ds_read_b128 v[56:59], v110 offset:20480
	v_mfma_f32_16x16x32_bf16 v[52:55], v[52:55], v[12:15], 0
	v_max3_f32 v68, v64, v65, v66
	s_waitcnt lgkmcnt(0)
	v_mfma_f32_16x16x32_bf16 v[52:55], v[60:63], v[8:11], v[52:55]
	ds_read_b128 v[60:63], v111 offset:20480
	v_mfma_f32_16x16x32_bf16 v[56:59], v[56:59], v[12:15], 0
	s_nop 5
	v_max_f32_e32 v64, v55, v55
	v_max_f32_e32 v65, v54, v54
	v_max_f32_e32 v70, v65, v64
	ds_read_b128 v[64:67], v110 offset:22528
	v_max3_f32 v70, v52, v53, v70
	v_max3_f32 v84, v68, v69, v70
	ds_read_b128 v[68:71], v111 offset:22528
	s_waitcnt lgkmcnt(0)
	v_mfma_f32_16x16x32_bf16 v[56:59], v[60:63], v[8:11], v[56:59]
	s_nop 7
	v_max_f32_e32 v60, v59, v59
	v_max_f32_e32 v61, v58, v58
	v_max_f32_e32 v72, v61, v60
	v_mfma_f32_16x16x32_bf16 v[60:63], v[64:67], v[12:15], 0
	v_max3_f32 v85, v56, v57, v72
	ds_read_b128 v[64:67], v110 offset:24576
	ds_read_b128 v[72:75], v111 offset:24576
	v_mfma_f32_16x16x32_bf16 v[60:63], v[68:71], v[8:11], v[60:63]
	ds_read_b128 v[68:71], v110 offset:26624
	s_waitcnt lgkmcnt(0)
	v_mfma_f32_16x16x32_bf16 v[64:67], v[64:67], v[12:15], 0
	v_mfma_f32_16x16x32_bf16 v[64:67], v[72:75], v[8:11], v[64:67]
	s_nop 3
	v_max_f32_e32 v80, v63, v63
	v_max_f32_e32 v81, v62, v62
	v_max_f32_e32 v80, v81, v80
	v_max3_f32 v86, v60, v61, v80
	ds_read_b128 v[80:83], v111 offset:26624
	ds_read_b128 v[72:75], v110 offset:28672
	v_mfma_f32_16x16x32_bf16 v[68:71], v[68:71], v[12:15], 0
	v_max3_f32 v92, v84, v85, v86
	v_max_f32_e32 v84, v67, v67
	v_max_f32_e32 v85, v66, v66
	s_waitcnt lgkmcnt(0)
	v_mfma_f32_16x16x32_bf16 v[68:71], v[80:83], v[8:11], v[68:71]
	v_max_f32_e32 v88, v85, v84
	ds_read_b128 v[84:87], v111 offset:28672
	ds_read_b128 v[80:83], v110 offset:30720
	v_max3_f32 v93, v64, v65, v88
	s_nop 3
	v_max_f32_e32 v88, v71, v71
	v_max_f32_e32 v89, v70, v70
	v_max_f32_e32 v94, v89, v88
	ds_read_b128 v[88:91], v111 offset:30720
	v_mfma_f32_16x16x32_bf16 v[72:75], v[72:75], v[12:15], 0
	s_waitcnt lgkmcnt(0)
	v_mfma_f32_16x16x32_bf16 v[12:15], v[80:83], v[12:15], 0
	v_mfma_f32_16x16x32_bf16 v[72:75], v[84:87], v[8:11], v[72:75]
	v_max3_f32 v84, v68, v69, v94
	v_max3_f32 v84, v92, v93, v84
	v_mfma_f32_16x16x32_bf16 v[8:11], v[88:91], v[8:11], v[12:15]
	s_nop 4
	v_max_f32_e32 v85, v75, v75
	v_max_f32_e32 v80, v74, v74
	s_nop 0
	v_max_f32_e32 v12, v11, v11
	v_max_f32_e32 v13, v10, v10
	v_max_f32_e32 v80, v80, v85
	v_max_f32_e32 v12, v13, v12
	v_max3_f32 v80, v72, v73, v80
	v_max3_f32 v12, v8, v9, v12
	v_max3_f32 v12, v84, v80, v12
	ds_bpermute_b32 v13, v108, v12
	s_waitcnt lgkmcnt(0)
	v_max_f32_e32 v13, v13, v13
	v_max_f32_e32 v12, v12, v13
	ds_bpermute_b32 v13, v109, v12
	s_waitcnt lgkmcnt(0)
	v_max_f32_e32 v13, v13, v13
	v_max_f32_e32 v13, v12, v13
	v_mov_b32_e32 v12, v11
	v_pk_mul_f32 v[106:107], v[12:13], s[24:25] op_sel_hi:[1,0]
	s_nop 0
	v_fma_f32 v11, v16, s24, -v107
	v_exp_f32_e32 v96, v11
	v_fma_f32 v11, v17, s24, -v107
	v_exp_f32_e32 v97, v11
	v_fma_f32 v11, v18, s24, -v107
	v_exp_f32_e32 v104, v11
	v_fma_f32 v11, v19, s24, -v107
	v_exp_f32_e32 v105, v11
	v_fma_f32 v12, v20, s24, -v107
	v_add_f32_e32 v11, 0, v96
	v_exp_f32_e32 v100, v12
	v_fma_f32 v12, v21, s24, -v107
	v_add_f32_e32 v11, v97, v11
	v_exp_f32_e32 v101, v12
	v_fma_f32 v12, v22, s24, -v107
	v_add_f32_e32 v11, v104, v11
	v_exp_f32_e32 v102, v12
	v_fma_f32 v12, v23, s24, -v107
	v_add_f32_e32 v11, v105, v11
	v_exp_f32_e32 v103, v12
	v_fma_f32 v12, v24, s24, -v107
	v_add_f32_e32 v11, v100, v11
	v_exp_f32_e32 v88, v12
	v_fma_f32 v12, v25, s24, -v107
	v_add_f32_e32 v11, v101, v11
	v_exp_f32_e32 v89, v12
	v_fma_f32 v12, v26, s24, -v107
	v_add_f32_e32 v11, v102, v11
	v_exp_f32_e32 v98, v12
	v_fma_f32 v12, v27, s24, -v107
	v_add_f32_e32 v11, v103, v11
	v_exp_f32_e32 v99, v12
	v_fma_f32 v12, v28, s24, -v107
	v_add_f32_e32 v11, v88, v11
	v_exp_f32_e32 v92, v12
	v_fma_f32 v12, v29, s24, -v107
	v_add_f32_e32 v11, v89, v11
	v_exp_f32_e32 v93, v12
	v_fma_f32 v12, v30, s24, -v107
	v_add_f32_e32 v11, v98, v11
	v_exp_f32_e32 v94, v12
	v_fma_f32 v12, v31, s24, -v107
	v_add_f32_e32 v11, v99, v11
	v_exp_f32_e32 v95, v12
	v_fma_f32 v12, v32, s24, -v107
	v_add_f32_e32 v11, v92, v11
	v_exp_f32_e32 v80, v12
	v_fma_f32 v12, v33, s24, -v107
	v_add_f32_e32 v11, v93, v11
	v_exp_f32_e32 v81, v12
	v_fma_f32 v12, v34, s24, -v107
	v_add_f32_e32 v11, v94, v11
	v_exp_f32_e32 v90, v12
	v_fma_f32 v12, v35, s24, -v107
	v_add_f32_e32 v11, v95, v11
	v_exp_f32_e32 v91, v12
	v_fma_f32 v12, v36, s24, -v107
	v_add_f32_e32 v11, v80, v11
	v_exp_f32_e32 v84, v12
	v_fma_f32 v12, v37, s24, -v107
	v_add_f32_e32 v11, v81, v11
	v_exp_f32_e32 v85, v12
	v_fma_f32 v12, v38, s24, -v107
	v_add_f32_e32 v11, v90, v11
	v_exp_f32_e32 v86, v12
	v_fma_f32 v12, v39, s24, -v107
	v_add_f32_e32 v11, v91, v11
	v_exp_f32_e32 v87, v12
	v_fma_f32 v12, v40, s24, -v107
	v_add_f32_e32 v11, v84, v11
	v_exp_f32_e32 v40, v12
	v_fma_f32 v12, v41, s24, -v107
	v_add_f32_e32 v11, v85, v11
	v_exp_f32_e32 v41, v12
	v_fma_f32 v12, v42, s24, -v107
	v_add_f32_e32 v11, v86, v11
	v_exp_f32_e32 v82, v12
	v_fma_f32 v12, v43, s24, -v107
	v_add_f32_e32 v11, v87, v11
	v_exp_f32_e32 v83, v12
	v_fma_f32 v12, v44, s24, -v107
	v_add_f32_e32 v11, v40, v11
	v_exp_f32_e32 v44, v12
	v_fma_f32 v12, v45, s24, -v107
	v_add_f32_e32 v11, v41, v11
	v_exp_f32_e32 v45, v12
	v_fma_f32 v12, v46, s24, -v107
	v_add_f32_e32 v11, v82, v11
	v_exp_f32_e32 v46, v12
	v_fma_f32 v12, v47, s24, -v107
	v_add_f32_e32 v11, v83, v11
	v_exp_f32_e32 v47, v12
	v_fma_f32 v12, v48, s24, -v107
	v_add_f32_e32 v11, v44, v11
	v_exp_f32_e32 v32, v12
	v_fma_f32 v12, v49, s24, -v107
	v_add_f32_e32 v11, v45, v11
	v_exp_f32_e32 v33, v12
	v_fma_f32 v12, v50, s24, -v107
	v_add_f32_e32 v11, v46, v11
	v_exp_f32_e32 v42, v12
	v_fma_f32 v12, v51, s24, -v107
	v_add_f32_e32 v11, v47, v11
	v_exp_f32_e32 v43, v12
	v_fma_f32 v12, v52, s24, -v107
	v_add_f32_e32 v11, v32, v11
	v_exp_f32_e32 v36, v12
	v_fma_f32 v12, v53, s24, -v107
	v_add_f32_e32 v11, v33, v11
	v_exp_f32_e32 v37, v12
	v_fma_f32 v12, v54, s24, -v107
	v_add_f32_e32 v11, v42, v11
	v_exp_f32_e32 v38, v12
	v_fma_f32 v12, v55, s24, -v107
	v_add_f32_e32 v11, v43, v11
	v_exp_f32_e32 v39, v12
	v_fma_f32 v12, v56, s24, -v107
	v_add_f32_e32 v11, v36, v11
	v_exp_f32_e32 v24, v12
	v_fma_f32 v12, v57, s24, -v107
	v_add_f32_e32 v11, v37, v11
	v_exp_f32_e32 v25, v12
	v_fma_f32 v12, v58, s24, -v107
	v_add_f32_e32 v11, v38, v11
	v_exp_f32_e32 v34, v12
	v_fma_f32 v12, v59, s24, -v107
	v_add_f32_e32 v11, v39, v11
	v_exp_f32_e32 v35, v12
	v_fma_f32 v12, v60, s24, -v107
	v_add_f32_e32 v11, v24, v11
	v_exp_f32_e32 v28, v12
	v_fma_f32 v12, v61, s24, -v107
	v_add_f32_e32 v11, v25, v11
	v_exp_f32_e32 v29, v12
	v_fma_f32 v12, v62, s24, -v107
	v_add_f32_e32 v11, v34, v11
	v_exp_f32_e32 v30, v12
	v_fma_f32 v12, v63, s24, -v107
	v_add_f32_e32 v11, v35, v11
	v_exp_f32_e32 v31, v12
	v_fma_f32 v12, v64, s24, -v107
	v_add_f32_e32 v11, v28, v11
	v_exp_f32_e32 v14, v12
	v_fma_f32 v12, v65, s24, -v107
	v_add_f32_e32 v11, v29, v11
	v_exp_f32_e32 v15, v12
	v_fma_f32 v12, v66, s24, -v107
	v_add_f32_e32 v11, v30, v11
	v_exp_f32_e32 v26, v12
	v_fma_f32 v12, v67, s24, -v107
	v_add_f32_e32 v11, v31, v11
	v_exp_f32_e32 v27, v12
	v_fma_f32 v12, v68, s24, -v107
	v_add_f32_e32 v11, v14, v11
	v_exp_f32_e32 v18, v12
	v_fma_f32 v12, v69, s24, -v107
	v_add_f32_e32 v11, v15, v11
	v_exp_f32_e32 v19, v12
	v_fma_f32 v12, v70, s24, -v107
	v_add_f32_e32 v11, v26, v11
	v_exp_f32_e32 v22, v12
	v_fma_f32 v12, v71, s24, -v107
	v_add_f32_e32 v11, v27, v11
	v_exp_f32_e32 v23, v12
	v_fma_f32 v12, v72, s24, -v107
	v_add_f32_e32 v11, v18, v11
	v_exp_f32_e32 v12, v12
	v_fma_f32 v13, v73, s24, -v107
	v_add_f32_e32 v11, v19, v11
	v_exp_f32_e32 v13, v13
	v_fma_f32 v16, v74, s24, -v107
	v_add_f32_e32 v11, v22, v11
	v_exp_f32_e32 v16, v16
	v_fma_f32 v17, v75, s24, -v107
	v_add_f32_e32 v11, v23, v11
	v_exp_f32_e32 v17, v17
	v_add_f32_e32 v11, v12, v11
	v_fma_f32 v8, v8, s24, -v107
	v_add_f32_e32 v11, v13, v11
	v_exp_f32_e32 v8, v8
	v_fma_f32 v9, v9, s24, -v107
	v_add_f32_e32 v11, v16, v11
	v_exp_f32_e32 v9, v9
	v_fma_f32 v10, v10, s24, -v107
	v_add_f32_e32 v20, v17, v11
	v_exp_f32_e32 v10, v10
	v_sub_f32_e32 v11, v106, v107
	v_exp_f32_e32 v11, v11
	v_add_f32_e32 v20, v8, v20
	v_add_f32_e32 v20, v9, v20
	v_add_f32_e32 v20, v10, v20
	v_add_f32_e32 v20, v11, v20
	ds_bpermute_b32 v21, v108, v20
	ds_read2st64_b64 v[52:55], v113 offset0:64 offset1:80
	s_waitcnt lgkmcnt(0)
	v_add_f32_e32 v20, v20, v21
	ds_bpermute_b32 v21, v109, v20
	v_mov_b32_e32 v58, v52
	v_mov_b32_e32 v59, v53
	s_waitcnt lgkmcnt(0)
	v_add_f32_e32 v20, v20, v21
	v_div_scale_f32 v21, s[28:29], v20, v20, 1.0
	v_rcp_f32_e32 v48, v21
	s_mov_b64 s[28:29], 0xd0000
	v_lshl_add_u64 v[76:77], v[76:77], 0, s[28:29]
	s_mov_b64 s[28:29], 0x40000
	v_fma_f32 v49, -v21, v48, 1.0
	v_fmac_f32_e32 v48, v49, v48
	v_div_scale_f32 v49, vcc, 1.0, v20, 1.0
	v_mul_f32_e32 v50, v49, v48
	v_fma_f32 v51, -v21, v50, v49
	v_fmac_f32_e32 v50, v51, v48
	v_fma_f32 v21, -v21, v50, v49
	v_div_fmas_f32 v21, v21, v48, v50
	ds_read2st64_b64 v[48:51], v112 offset0:64 offset1:80
	v_div_fixup_f32 v20, v21, v20, 1.0
	v_pk_mul_f32 v[62:63], v[104:105], v[20:21] op_sel_hi:[1,0]
	v_pk_mul_f32 v[60:61], v[96:97], v[20:21] op_sel_hi:[1,0]
	v_pk_mul_f32 v[64:65], v[102:103], v[20:21] op_sel_hi:[1,0]
	v_pk_mul_f32 v[66:67], v[100:101], v[20:21] op_sel_hi:[1,0]
	s_waitcnt lgkmcnt(0)
	v_mov_b32_e32 v56, v48
	v_mov_b32_e32 v57, v49
	v_cvt_pk_bf16_f32 v60, v60, v61
	v_cvt_pk_bf16_f32 v61, v62, v63
	v_cvt_pk_bf16_f32 v62, v66, v67
	v_cvt_pk_bf16_f32 v63, v64, v65
	v_mov_b32_e32 v52, v50
	v_mov_b32_e32 v53, v51
	ds_read2st64_b64 v[48:51], v112 offset0:96 offset1:112
	ds_read2st64_b64 v[64:67], v113 offset0:96 offset1:112
	v_mfma_f32_16x16x32_bf16 v[56:59], v[56:59], v[60:63], 0
	v_mul_f32_e64 v96, v98, v20
	v_mul_f32_e64 v97, v99, v20
	v_pk_mul_f32 v[88:89], v[88:89], v[20:21] op_sel_hi:[1,0]
	s_waitcnt lgkmcnt(0)
	v_mov_b32_e32 v68, v48
	v_mov_b32_e32 v69, v49
	v_mov_b32_e32 v70, v64
	v_mov_b32_e32 v71, v65
	v_mov_b32_e32 v64, v50
	v_mov_b32_e32 v65, v51
	v_mfma_f32_16x16x32_bf16 v[52:55], v[52:55], v[60:63], 0
	v_mul_f32_e64 v98, v94, v20
	v_mul_f32_e64 v99, v95, v20
	v_pk_mul_f32 v[94:95], v[92:93], v[20:21] op_sel_hi:[1,0]
	v_cvt_pk_bf16_f32 v92, v88, v89
	v_mfma_f32_16x16x32_bf16 v[68:71], v[68:71], v[60:63], 0
	v_cvt_pk_bf16_f32 v93, v96, v97
	v_cvt_pk_bf16_f32 v94, v94, v95
	v_cvt_pk_bf16_f32 v95, v98, v99
	v_mfma_f32_16x16x32_bf16 v[48:51], v[64:67], v[60:63], 0
	ds_read2st64_b64 v[60:63], v114 offset0:64 offset1:80
	ds_read2st64_b64 v[64:67], v115 offset0:64 offset1:80
	v_pk_mul_f32 v[88:89], v[90:91], v[20:21] op_sel_hi:[1,0]
	v_pk_mul_f32 v[80:81], v[80:81], v[20:21] op_sel_hi:[1,0]
	v_pk_mul_f32 v[90:91], v[86:87], v[20:21] op_sel_hi:[1,0]
	s_waitcnt lgkmcnt(0)
	v_mov_b32_e32 v72, v60
	v_mov_b32_e32 v73, v61
	v_mov_b32_e32 v74, v64
	v_mov_b32_e32 v75, v65
	v_mov_b32_e32 v64, v62
	v_mov_b32_e32 v65, v63
	v_mfma_f32_16x16x32_bf16 v[56:59], v[72:75], v[92:95], v[56:59]
	ds_read2st64_b64 v[60:63], v114 offset0:96 offset1:112
	ds_read2st64_b64 v[72:75], v115 offset0:96 offset1:112
	v_pk_mul_f32 v[86:87], v[84:85], v[20:21] op_sel_hi:[1,0]
	v_cvt_pk_bf16_f32 v84, v80, v81
	v_mfma_f32_16x16x32_bf16 v[52:55], v[64:67], v[92:95], v[52:55]
	s_waitcnt lgkmcnt(0)
	v_mov_b32_e32 v64, v60
	v_mov_b32_e32 v65, v61
	v_mov_b32_e32 v66, v72
	v_mov_b32_e32 v67, v73
	v_mov_b32_e32 v72, v62
	v_mov_b32_e32 v73, v63
	v_mfma_f32_16x16x32_bf16 v[64:67], v[64:67], v[92:95], v[68:71]
	ds_read2st64_b64 v[60:63], v116 offset0:64 offset1:80
	s_nop 1
	ds_read2st64_b64 v[68:71], v117 offset0:64 offset1:80
	v_cvt_pk_bf16_f32 v85, v88, v89
	v_mfma_f32_16x16x32_bf16 v[48:51], v[72:75], v[92:95], v[48:51]
	v_cvt_pk_bf16_f32 v86, v86, v87
	s_waitcnt lgkmcnt(0)
	v_mov_b32_e32 v72, v60
	v_mov_b32_e32 v73, v61
	v_mov_b32_e32 v74, v68
	v_mov_b32_e32 v75, v69
	v_cvt_pk_bf16_f32 v87, v90, v91
	v_mov_b32_e32 v68, v62
	v_mov_b32_e32 v69, v63
	v_mfma_f32_16x16x32_bf16 v[56:59], v[72:75], v[84:87], v[56:59]
	ds_read2st64_b64 v[60:63], v116 offset0:96 offset1:112
	ds_read2st64_b64 v[72:75], v117 offset0:96 offset1:112
	v_pk_mul_f32 v[80:81], v[46:47], v[20:21] op_sel_hi:[1,0]
	v_pk_mul_f32 v[40:41], v[40:41], v[20:21] op_sel_hi:[1,0]
	v_mfma_f32_16x16x32_bf16 v[52:55], v[68:71], v[84:87], v[52:55]
	s_waitcnt lgkmcnt(0)
	v_mov_b32_e32 v68, v60
	v_mov_b32_e32 v69, v61
	v_mov_b32_e32 v70, v72
	v_mov_b32_e32 v71, v73
	v_mov_b32_e32 v72, v62
	v_mov_b32_e32 v73, v63
	v_mfma_f32_16x16x32_bf16 v[64:67], v[68:71], v[84:87], v[64:67]
	ds_read2st64_b64 v[60:63], v118 offset0:64 offset1:80
	ds_read2st64_b64 v[68:71], v119 offset0:64 offset1:80
	v_pk_mul_f32 v[32:33], v[32:33], v[20:21] op_sel_hi:[1,0]
	v_mfma_f32_16x16x32_bf16 v[48:51], v[72:75], v[84:87], v[48:51]
	v_mul_f32_e64 v74, v82, v20
	v_mul_f32_e64 v75, v83, v20
	v_pk_mul_f32 v[82:83], v[44:45], v[20:21] op_sel_hi:[1,0]
	s_waitcnt lgkmcnt(0)
	v_mov_b32_e32 v44, v60
	v_mov_b32_e32 v45, v61
	v_mov_b32_e32 v46, v68
	v_mov_b32_e32 v47, v69
	v_cvt_pk_bf16_f32 v72, v40, v41
	v_cvt_pk_bf16_f32 v73, v74, v75
	v_cvt_pk_bf16_f32 v74, v82, v83
	v_cvt_pk_bf16_f32 v75, v80, v81
	v_mov_b32_e32 v68, v62
	v_mov_b32_e32 v69, v63
	v_mfma_f32_16x16x32_bf16 v[44:47], v[44:47], v[72:75], v[56:59]
	s_nop 2
	ds_read2st64_b64 v[56:59], v118 offset0:96 offset1:112
	ds_read2st64_b64 v[60:63], v119 offset0:96 offset1:112
	v_pk_mul_f32 v[24:25], v[24:25], v[20:21] op_sel_hi:[1,0]
	v_pk_mul_f32 v[14:15], v[14:15], v[20:21] op_sel_hi:[1,0]
	v_mfma_f32_16x16x32_bf16 v[52:55], v[68:71], v[72:75], v[52:55]
	s_waitcnt lgkmcnt(0)
	v_mov_b32_e32 v68, v56
	v_mov_b32_e32 v70, v60
	v_mov_b32_e32 v71, v61
	v_mov_b32_e32 v60, v58
	v_mov_b32_e32 v61, v59
	v_mov_b32_e32 v69, v57
	ds_read2st64_b64 v[56:59], v122 offset0:64 offset1:80
	v_mfma_f32_16x16x32_bf16 v[48:51], v[60:63], v[72:75], v[48:51]
	v_mul_f32_e64 v62, v42, v20
	v_mul_f32_e64 v63, v43, v20
	ds_read2st64_b64 v[40:43], v120 offset0:64 offset1:80
	v_cvt_pk_bf16_f32 v60, v32, v33
	v_mfma_f32_16x16x32_bf16 v[64:67], v[68:71], v[72:75], v[64:67]
	v_mul_f32_e64 v68, v38, v20
	v_mul_f32_e64 v69, v39, v20
	v_pk_mul_f32 v[70:71], v[36:37], v[20:21] op_sel_hi:[1,0]
	s_waitcnt lgkmcnt(0)
	v_mov_b32_e32 v36, v40
	v_mov_b32_e32 v37, v41
	v_mov_b32_e32 v38, v56
	v_mov_b32_e32 v39, v57
	v_cvt_pk_bf16_f32 v61, v62, v63
	v_cvt_pk_bf16_f32 v62, v70, v71
	v_cvt_pk_bf16_f32 v63, v68, v69
	v_mov_b32_e32 v56, v42
	v_mov_b32_e32 v57, v43
	v_mfma_f32_16x16x32_bf16 v[36:39], v[36:39], v[60:63], v[44:47]
	ds_read2st64_b64 v[40:43], v120 offset0:96 offset1:112
	s_nop 1
	ds_read2st64_b64 v[44:47], v122 offset0:96 offset1:112
	v_pk_mul_f32 v[18:19], v[18:19], v[20:21] op_sel_hi:[1,0]
	v_pk_mul_f32 v[12:13], v[12:13], v[20:21] op_sel_hi:[1,0]
	v_mfma_f32_16x16x32_bf16 v[52:55], v[56:59], v[60:63], v[52:55]
	s_waitcnt lgkmcnt(0)
	v_mov_b32_e32 v56, v40
	v_mov_b32_e32 v58, v44
	v_mov_b32_e32 v59, v45
	v_mov_b32_e32 v44, v42
	v_mov_b32_e32 v45, v43
	v_mov_b32_e32 v57, v41
	v_cvt_pk_bf16_f32 v12, v12, v13
	v_mfma_f32_16x16x32_bf16 v[40:43], v[44:47], v[60:63], v[48:51]
	ds_read2st64_b64 v[44:47], v124 offset0:64 offset1:80
	s_nop 1
	v_pk_mul_f32 v[50:51], v[34:35], v[20:21] op_sel_hi:[1,0]
	ds_read2st64_b64 v[32:35], v123 offset0:64 offset1:80
	v_mfma_f32_16x16x32_bf16 v[56:59], v[56:59], v[60:63], v[64:67]
	v_mul_f32_e64 v60, v30, v20
	v_mul_f32_e64 v61, v31, v20
	v_pk_mul_f32 v[62:63], v[28:29], v[20:21] op_sel_hi:[1,0]
	s_waitcnt lgkmcnt(0)
	v_mov_b32_e32 v30, v44
	v_mov_b32_e32 v28, v32
	v_mov_b32_e32 v29, v33
	v_mov_b32_e32 v31, v45
	v_cvt_pk_bf16_f32 v48, v24, v25
	v_cvt_pk_bf16_f32 v49, v50, v51
	v_cvt_pk_bf16_f32 v50, v62, v63
	v_cvt_pk_bf16_f32 v51, v60, v61
	v_mov_b32_e32 v44, v34
	v_mov_b32_e32 v45, v35
	v_mfma_f32_16x16x32_bf16 v[28:31], v[28:31], v[48:51], v[36:39]
	ds_read2st64_b64 v[32:35], v123 offset0:96 offset1:112
	s_nop 1
	ds_read2st64_b64 v[36:39], v124 offset0:96 offset1:112
	v_mfma_f32_16x16x32_bf16 v[44:47], v[44:47], v[48:51], v[52:55]
	s_waitcnt lgkmcnt(0)
	s_nop 1
	v_mov_b32_e32 v54, v36
	v_mov_b32_e32 v55, v37
	v_mov_b32_e32 v36, v34
	v_mov_b32_e32 v37, v35
	v_mov_b32_e32 v52, v32
	v_mov_b32_e32 v53, v33
	v_mfma_f32_16x16x32_bf16 v[32:35], v[36:39], v[48:51], v[40:43]
	ds_read2st64_b64 v[36:39], v126 offset0:64 offset1:80
	s_nop 1
	v_pk_mul_f32 v[42:43], v[26:27], v[20:21] op_sel_hi:[1,0]
	ds_read2st64_b64 v[24:27], v125 offset0:64 offset1:80
	v_mfma_f32_16x16x32_bf16 v[52:55], v[52:55], v[48:51], v[56:59]
	v_mul_f32_e64 v48, v22, v20
	v_mul_f32_e64 v49, v23, v20
	v_cvt_pk_bf16_f32 v40, v14, v15
	v_cvt_pk_bf16_f32 v41, v42, v43
	s_waitcnt lgkmcnt(0)
	v_mov_b32_e32 v22, v24
	v_mov_b32_e32 v23, v25
	v_mov_b32_e32 v24, v36
	v_mov_b32_e32 v25, v37
	v_cvt_pk_bf16_f32 v42, v18, v19
	v_cvt_pk_bf16_f32 v43, v48, v49
	v_mov_b32_e32 v36, v26
	v_mov_b32_e32 v37, v27
	v_mfma_f32_16x16x32_bf16 v[22:25], v[22:25], v[40:43], v[28:31]
	s_nop 2
	ds_read2st64_b64 v[26:29], v125 offset0:96 offset1:112
	ds_read2st64_b64 v[48:51], v126 offset0:96 offset1:112
	v_pk_mul_f32 v[18:19], v[16:17], v[20:21] op_sel_hi:[1,0]
	ds_read2st64_b64 v[14:17], v127 offset0:64 offset1:80
	v_mfma_f32_16x16x32_bf16 v[36:39], v[36:39], v[40:43], v[44:47]
	v_cvt_pk_bf16_f32 v13, v18, v19
	s_waitcnt lgkmcnt(0)
	s_nop 0
	v_mov_b32_e32 v46, v48
	v_mov_b32_e32 v47, v49
	v_mov_b32_e32 v48, v28
	v_mov_b32_e32 v49, v29
	v_mov_b32_e32 v44, v26
	v_mov_b32_e32 v45, v27
	v_mfma_f32_16x16x32_bf16 v[26:29], v[48:51], v[40:43], v[32:35]
	s_nop 2
	ds_read2st64_b64 v[30:33], v128 offset0:64 offset1:80
	v_pk_mul_f32 v[34:35], v[10:11], v[20:21] op_sel_hi:[1,0]
	v_pk_mul_f32 v[20:21], v[8:9], v[20:21] op_sel_hi:[1,0]
	v_mov_b32_e32 v8, v14
	v_mov_b32_e32 v9, v15
	s_waitcnt lgkmcnt(0)
	v_mov_b32_e32 v10, v30
	v_mov_b32_e32 v11, v31
	v_cvt_pk_bf16_f32 v14, v20, v21
	v_cvt_pk_bf16_f32 v15, v34, v35
	v_mov_b32_e32 v30, v16
	v_mov_b32_e32 v31, v17
	v_mfma_f32_16x16x32_bf16 v[8:11], v[8:11], v[12:15], v[22:25]
	ds_read2st64_b64 v[16:19], v127 offset0:96 offset1:112
	s_nop 1
	ds_read2st64_b64 v[20:23], v128 offset0:96 offset1:112
	s_waitcnt lgkmcnt(0)
	v_mov_b32_e32 v34, v16
	v_mfma_f32_16x16x32_bf16 v[30:33], v[30:33], v[12:15], v[36:39]
	v_mov_b32_e32 v35, v17
	v_lshl_add_u64 v[16:17], v[78:79], 0, s[16:17]
	v_cvt_pk_bf16_f32 v8, v8, v9
	v_mov_b32_e32 v36, v20
	v_mov_b32_e32 v37, v21
	v_mfma_f32_16x16x32_bf16 v[44:47], v[44:47], v[40:43], v[52:55]
	v_mov_b32_e32 v20, v18
	v_mov_b32_e32 v21, v19
	v_cvt_pk_bf16_f32 v9, v10, v11
	v_mfma_f32_16x16x32_bf16 v[34:37], v[34:37], v[12:15], v[44:47]
	v_add_co_u32_e32 v10, vcc, s1, v16
	v_lshl_add_u64 v[78:79], v[78:79], 0, s[28:29]
	v_mfma_f32_16x16x32_bf16 v[12:15], v[20:23], v[12:15], v[26:29]
	v_addc_co_u32_e32 v11, vcc, 0, v17, vcc
	global_store_dwordx2 v[10:11], v[8:9], off offset:1536
	v_cvt_pk_bf16_f32 v8, v30, v31
	v_cvt_pk_bf16_f32 v9, v32, v33
	global_store_dwordx2 v[10:11], v[8:9], off offset:1568
	v_cvt_pk_bf16_f32 v8, v34, v35
	v_cvt_pk_bf16_f32 v9, v36, v37
	global_store_dwordx2 v[10:11], v[8:9], off offset:1600
	v_cvt_pk_bf16_f32 v8, v12, v13
	v_cvt_pk_bf16_f32 v9, v14, v15
	global_store_dwordx2 v[10:11], v[8:9], off offset:1632
	s_waitcnt vmcnt(0)
	v_mov_b64_e32 v[10:11], v[6:7]
	v_mov_b64_e32 v[14:15], v[2:3]
	v_mov_b64_e32 v[8:9], v[4:5]
	v_mov_b64_e32 v[12:13], v[0:1]
	s_cbranch_scc0 .LBB0_388
.LBB0_386:
	s_cmp_gt_u32 s0, 2
	s_cbranch_scc1 .LBB0_385
	v_lshl_add_u64 v[0:1], v[76:77], 0, s[16:17]
	v_add_co_u32_e32 v4, vcc, 0xc995000, v0
	s_nop 1
	v_addc_co_u32_e32 v5, vcc, 0, v1, vcc
	global_load_dwordx4 v[0:3], v[4:5], off offset:2048
	s_nop 0
	global_load_dwordx4 v[4:7], v[4:5], off offset:2112
	s_branch .LBB0_385

.LBB0_406:
	s_mul_hi_i32 s0, s38, 0x2aaaaaab
	s_lshr_b32 s1, s0, 31
	s_add_i32 s0, s0, s1
	s_mul_i32 s1, s0, 6
	s_lshl_b32 s63, s0, 12
	s_lshl_b32 s0, s0, 6
	s_sub_i32 s41, s38, s1
	s_add_i32 s42, s0, 0x8000
	s_and_b64 s[0:1], s[28:29], exec
	s_cselect_b32 s62, s63, s42
	v_ashrrev_i32_e32 v124, 3, v134
	v_lshlrev_b32_e32 v0, 3, v134
	v_and_b32_e32 v136, 56, v0
	v_add_u32_e32 v0, s62, v124
	v_mov_b64_e32 v[20:21], s[8:9]
	s_cselect_b32 s40, 0, 0x400
	v_mad_i64_i32 v[0:1], s[0:1], v0, s47, v[20:21]
	s_lshl_b32 s0, s41, 7
	v_add_u32_e32 v8, s40, v124
	s_ashr_i32 s1, s0, 31
	v_ashrrev_i32_e32 v9, 31, v8
	s_lshl_b64 s[42:43], s[0:1], 1
	v_lshlrev_b64 v[8:9], 9, v[8:9]
	v_lshl_add_u64 v[0:1], v[0:1], 0, s[42:43]
	v_lshlrev_b32_e32 v120, 1, v136
	v_lshl_add_u64 v[8:9], s[14:15], 0, v[8:9]
	v_lshlrev_b32_e32 v100, 3, v136
	v_mov_b32_e32 v101, v121
	v_bfe_u32 v160, v134, 2, 6
	v_lshl_add_u64 v[4:5], v[0:1], 0, v[120:121]
	v_lshl_add_u64 v[22:23], v[8:9], 0, v[100:101]
	global_load_dwordx4 v[0:3], v[4:5], off offset:1536
	s_nop 0
	global_load_dwordx4 v[4:7], v[4:5], off offset:1664
	s_nop 0
	global_load_dwordx4 v[8:11], v[22:23], off
	global_load_dwordx4 v[12:15], v[22:23], off offset:16
	global_load_dwordx4 v[16:19], v[22:23], off offset:32
	global_load_dwordx4 v[24:27], v[22:23], off offset:48
	v_or_b32_e32 v22, s62, v160
	v_mad_i64_i32 v[20:21], s[0:1], v22, s47, v[20:21]
	v_and_b32_e32 v135, 3, v134
	v_lshl_add_u64 v[20:21], v[20:21], 0, s[42:43]
	s_lshl_b32 s16, s16, 1
	v_lshl_add_u64 v[20:21], v[20:21], 0, s[16:17]
	v_lshlrev_b32_e32 v22, 4, v135
	v_mov_b32_e32 v23, v121
	v_lshl_add_u64 v[20:21], v[20:21], 0, v[22:23]
	global_load_dwordx4 v[32:35], v[20:21], off offset:3072
	v_lshlrev_b32_e32 v20, 3, v135
	v_cndmask_b32_e64 v21, 0, 1, s[28:29]
	v_cmp_ne_u32_e64 s[0:1], 1, v21
	s_andn2_b64 vcc, exec, s[28:29]
	v_ashrrev_i32_e32 v125, 31, v124
	v_lshlrev_b32_e32 v132, 1, v20
	s_cbranch_vccnz .LBB0_408
	s_or_b32 s65, s63, 64
	v_add_u32_e32 v20, s65, v124
	v_mov_b64_e32 v[56:57], s[8:9]
	v_lshlrev_b64 v[36:37], 9, v[124:125]
	v_mad_i64_i32 v[20:21], s[66:67], v20, s47, v[56:57]
	v_lshl_add_u64 v[36:37], s[14:15], 0, v[36:37]
	v_lshl_add_u64 v[36:37], v[36:37], 0, v[100:101]
	s_mov_b32 s66, 0x8000
	v_or_b32_e32 v58, s65, v160
	v_lshl_add_u64 v[20:21], v[20:21], 0, s[42:43]
	v_lshl_add_u64 v[48:49], v[36:37], 0, s[18:19]
	v_add_co_u32_e32 v36, vcc, s66, v36
	v_mad_i64_i32 v[56:57], s[66:67], v58, s47, v[56:57]
	v_lshl_add_u64 v[28:29], v[20:21], 0, v[120:121]
	v_addc_co_u32_e32 v37, vcc, 0, v37, vcc
	v_lshl_add_u64 v[56:57], v[56:57], 0, s[42:43]
	global_load_dwordx4 v[20:23], v[28:29], off offset:1536
	s_nop 0
	global_load_dwordx4 v[28:31], v[28:29], off offset:1664
	s_nop 0
	global_load_dwordx4 v[40:43], v[48:49], off offset:16
	global_load_dwordx4 v[44:47], v[48:49], off offset:32
	s_nop 0
	global_load_dwordx4 v[36:39], v[36:37], off
	s_nop 0
	global_load_dwordx4 v[48:51], v[48:49], off offset:48
	v_lshl_add_u64 v[56:57], v[56:57], 0, s[16:17]
	v_mov_b32_e32 v133, v121
	v_lshl_add_u64 v[56:57], v[56:57], 0, v[132:133]
	global_load_dwordx4 v[56:59], v[56:57], off offset:3072
.LBB0_408:
	s_and_b64 vcc, exec, s[0:1]
	s_cbranch_vccnz .LBB0_410
	s_or_b32 s65, s63, 0x80
	v_add_u32_e32 v60, s65, v124
	v_mov_b64_e32 v[88:89], s[8:9]
	v_lshlrev_b64 v[72:73], 9, v[124:125]
	v_mad_i64_i32 v[60:61], s[66:67], v60, s47, v[88:89]
	v_lshl_add_u64 v[72:73], s[14:15], 0, v[72:73]
	v_mov_b32_e32 v101, v121
	v_lshl_add_u64 v[72:73], v[72:73], 0, v[100:101]
	s_mov_b32 s66, 0x10000
	v_or_b32_e32 v90, s65, v160
	v_lshl_add_u64 v[60:61], v[60:61], 0, s[42:43]
	v_lshl_add_u64 v[84:85], v[72:73], 0, s[20:21]
	v_add_co_u32_e32 v72, vcc, s66, v72
	v_mad_i64_i32 v[88:89], s[66:67], v90, s47, v[88:89]
	v_lshl_add_u64 v[68:69], v[60:61], 0, v[120:121]
	v_addc_co_u32_e32 v73, vcc, 0, v73, vcc
	v_lshl_add_u64 v[88:89], v[88:89], 0, s[42:43]
	global_load_dwordx4 v[60:63], v[68:69], off offset:1536
	s_nop 0
	global_load_dwordx4 v[68:71], v[68:69], off offset:1664
	s_nop 0
	global_load_dwordx4 v[76:79], v[84:85], off offset:16
	global_load_dwordx4 v[80:83], v[84:85], off offset:32
	s_nop 0
	global_load_dwordx4 v[72:75], v[72:73], off
	s_nop 0
	global_load_dwordx4 v[84:87], v[84:85], off offset:48
	v_lshl_add_u64 v[88:89], v[88:89], 0, s[16:17]
	v_mov_b32_e32 v133, v121
	v_lshl_add_u64 v[88:89], v[88:89], 0, v[132:133]
	global_load_dwordx4 v[88:91], v[88:89], off offset:3072
.LBB0_410:
	s_and_b64 vcc, exec, s[0:1]
	s_cbranch_vccnz .LBB0_412
	s_or_b32 s63, s63, 0xc0
	v_add_u32_e32 v92, s63, v124
	v_mov_b64_e32 v[116:117], s[8:9]
	v_lshlrev_b64 v[102:103], 9, v[124:125]
	v_mad_i64_i32 v[92:93], s[0:1], v92, s47, v[116:117]
	v_lshl_add_u64 v[102:103], s[14:15], 0, v[102:103]
	v_mov_b32_e32 v101, v121
	v_lshl_add_u64 v[100:101], v[102:103], 0, v[100:101]
	s_mov_b32 s0, 0x18000
	v_or_b32_e32 v118, s63, v160
	v_lshl_add_u64 v[92:93], v[92:93], 0, s[42:43]
	v_add_co_u32_e32 v104, vcc, s0, v100
	v_mad_i64_i32 v[116:117], s[0:1], v118, s47, v[116:117]
	v_lshl_add_u64 v[96:97], v[92:93], 0, v[120:121]
	v_lshl_add_u64 v[112:113], v[100:101], 0, s[22:23]
	v_addc_co_u32_e32 v105, vcc, 0, v101, vcc
	v_lshl_add_u64 v[116:117], v[116:117], 0, s[42:43]
	global_load_dwordx4 v[92:95], v[96:97], off offset:1536
	s_nop 0
	global_load_dwordx4 v[96:99], v[96:97], off offset:1664
	s_nop 0
	global_load_dwordx4 v[100:103], v[112:113], off offset:16
	global_load_dwordx4 v[108:111], v[112:113], off offset:32
	s_nop 0
	global_load_dwordx4 v[104:107], v[104:105], off
	s_nop 0
	global_load_dwordx4 v[112:115], v[112:113], off offset:48
	v_lshl_add_u64 v[116:117], v[116:117], 0, s[16:17]
	v_mov_b32_e32 v133, v121
	v_lshl_add_u64 v[116:117], v[116:117], 0, v[132:133]
	global_load_dwordx4 v[116:119], v[116:117], off offset:3072

.LBB0_413:
	v_add_co_u32_e32 v146, vcc, s57, v146
	v_cvt_pk_bf16_f32 v170, v64, v65
	s_nop 0
	v_addc_co_u32_e32 v147, vcc, 0, v147, vcc
	v_cvt_pk_bf16_f32 v171, v66, v67
	v_add_co_u32_e32 v148, vcc, s57, v148
	s_waitcnt lgkmcnt(0)
	s_barrier
	global_store_dwordx2 v[146:147], v[170:171], off
	v_cvt_pk_bf16_f32 v146, v52, v53
	v_cvt_pk_bf16_f32 v147, v54, v55
	v_addc_co_u32_e32 v149, vcc, 0, v149, vcc
	global_store_dwordx2 v[148:149], v[146:147], off
	ds_read_b128 v[146:149], v120 offset:18432
	ds_read_b128 v[170:173], v125 offset:41472
	v_mov_b32_e32 v127, v126
	v_pk_mul_f32 v[66:67], v[126:127], v[66:67]
	v_pk_mul_f32 v[64:65], v[128:129], v[64:65]
	v_pk_mul_f32 v[54:55], v[126:127], v[54:55]
	v_pk_mul_f32 v[52:53], v[128:129], v[52:53]
	s_waitcnt lgkmcnt(0)
	v_mfma_f32_16x16x32_bf16 v[64:67], v[146:149], v[170:173], v[64:67]
	ds_read_b128 v[170:173], v166 offset:43776
	s_waitcnt lgkmcnt(0)
	v_mfma_f32_16x16x32_bf16 v[52:55], v[146:149], v[170:173], v[52:55]
	ds_read_b128 v[146:149], v167 offset:18432
	ds_read_b128 v[170:173], v168 offset:41472
	s_waitcnt lgkmcnt(0)
	v_mfma_f32_16x16x32_bf16 v[64:67], v[146:149], v[170:173], v[64:67]
	ds_read_b128 v[170:173], v169 offset:43776
	s_waitcnt lgkmcnt(0)
	v_mfma_f32_16x16x32_bf16 v[52:55], v[146:149], v[170:173], v[52:55]

.LBB0_417:
	s_or_b64 exec, exec, s[40:41]
	s_add_i32 s42, s16, -3
	s_cmp_ge_u32 s42, s63
	s_cbranch_scc1 .LBB0_419
	v_add_u32_e32 v0, s62, v124
	v_lshl_add_u64 v[8:9], v[144:145], 0, s[38:39]
	v_add_u32_e32 v0, 0x100, v0
	v_add_co_u32_e32 v24, vcc, 0x24000, v8
	v_mad_i64_i32 v[4:5], s[40:41], v0, s47, v[130:131]
	s_nop 0
	v_addc_co_u32_e32 v25, vcc, 0, v9, vcc
	v_add_u32_e32 v32, s62, v160
	global_load_dwordx4 v[0:3], v[4:5], off offset:1536
	s_nop 0
	global_load_dwordx4 v[4:7], v[4:5], off offset:1664
	s_nop 0
	global_load_dwordx4 v[8:11], v[24:25], off
	global_load_dwordx4 v[12:15], v[24:25], off offset:16
	global_load_dwordx4 v[16:19], v[24:25], off offset:32
	s_nop 0
	global_load_dwordx4 v[24:27], v[24:25], off offset:48
	v_add_u32_e32 v32, 0x100, v32
	v_mad_i64_i32 v[32:33], s[40:41], v32, s47, v[132:133]
	global_load_dwordx4 v[32:35], v[32:33], off offset:3072
.LBB0_419:
	v_lshl_add_u64 v[146:147], v[142:143], 0, s[38:39]
	v_add_co_u32_e32 v170, vcc, s54, v146
	v_cvt_pk_bf16_f32 v148, v64, v65
	v_cvt_pk_bf16_f32 v149, v66, v67
	v_addc_co_u32_e32 v171, vcc, 0, v147, vcc
	s_waitcnt lgkmcnt(0)
	s_barrier
	global_store_dwordx2 v[170:171], v[148:149], off
	v_lshl_add_u64 v[148:149], v[140:141], 0, s[38:39]
	v_add_co_u32_e32 v172, vcc, s54, v148
	v_cvt_pk_bf16_f32 v170, v52, v53
	v_cvt_pk_bf16_f32 v171, v54, v55
	v_addc_co_u32_e32 v173, vcc, 0, v149, vcc
	global_store_dwordx2 v[172:173], v[170:171], off
	ds_read_b128 v[170:173], v120
	ds_read_b128 v[174:177], v125 offset:36864
	v_mov_b32_e32 v127, v126
	v_pk_mul_f32 v[66:67], v[126:127], v[66:67]
	v_pk_mul_f32 v[64:65], v[128:129], v[64:65]
	v_pk_mul_f32 v[54:55], v[126:127], v[54:55]
	v_pk_mul_f32 v[52:53], v[128:129], v[52:53]
	s_waitcnt lgkmcnt(0)
	v_mfma_f32_16x16x32_bf16 v[64:67], v[170:173], v[174:177], v[64:67]
	ds_read_b128 v[174:177], v166 offset:39168
	s_add_i32 s40, s16, -6
	s_cmp_ge_u32 s40, s63
	s_waitcnt lgkmcnt(0)
	v_mfma_f32_16x16x32_bf16 v[52:55], v[170:173], v[174:177], v[52:55]
	ds_read_b128 v[170:173], v167
	ds_read_b128 v[174:177], v168 offset:36864
	s_waitcnt lgkmcnt(0)
	v_mfma_f32_16x16x32_bf16 v[64:67], v[170:173], v[174:177], v[64:67]
	ds_read_b128 v[174:177], v169 offset:39168
	s_waitcnt lgkmcnt(0)
	v_mfma_f32_16x16x32_bf16 v[52:55], v[170:173], v[174:177], v[52:55]
	s_cbranch_scc1 .LBB0_426
	v_lshlrev_b32_e32 v177, 16, v28
	v_lshlrev_b32_e32 v127, 16, v20
	v_mul_f32_e32 v185, v37, v177
	v_mul_f32_e32 v177, v36, v177
	v_fmac_f32_e32 v177, v37, v127
	v_fma_f32 v185, v36, v127, -v185
	v_mul_f32_e32 v127, v161, v177
	v_and_b32_e32 v178, 0xffff0000, v28
	v_cvt_pk_bf16_f32 v127, v127, s0
	v_and_b32_e32 v170, 0xffff0000, v20
	ds_write_b16 v163, v127 offset:27648
	v_mul_f32_e32 v127, v39, v178
	v_fma_f32 v127, v38, v170, -v127
	v_mul_f32_e32 v127, v161, v127
	v_cvt_pk_bf16_f32 v127, v127, s0
	ds_write_b16 v163, v127 offset:18576
	v_mul_f32_e32 v127, v38, v178
	v_fmac_f32_e32 v127, v39, v170
	v_mul_f32_e32 v127, v161, v127
	v_lshlrev_b32_e32 v179, 16, v29
	v_cvt_pk_bf16_f32 v127, v127, s0
	v_lshlrev_b32_e32 v171, 16, v21
	ds_write_b16 v163, v127 offset:27792
	v_mul_f32_e32 v127, v41, v179
	v_fma_f32 v127, v40, v171, -v127
	v_mul_f32_e32 v127, v161, v127
	v_cvt_pk_bf16_f32 v127, v127, s0
	ds_write_b16 v162, v127 offset:18720
	v_mul_f32_e32 v127, v40, v179
	v_fmac_f32_e32 v127, v41, v171
	v_mul_f32_e32 v127, v161, v127
	v_and_b32_e32 v180, 0xffff0000, v29
	v_cvt_pk_bf16_f32 v127, v127, s0
	v_and_b32_e32 v172, 0xffff0000, v21
	ds_write_b16 v163, v127 offset:27936
	v_mul_f32_e32 v127, v43, v180
	v_fma_f32 v127, v42, v172, -v127
	v_mul_f32_e32 v127, v161, v127
	v_cvt_pk_bf16_f32 v127, v127, s0
	ds_write_b16 v163, v127 offset:18864
	v_mul_f32_e32 v127, v42, v180
	v_fmac_f32_e32 v127, v43, v172
	v_mul_f32_e32 v127, v161, v127
	v_lshlrev_b32_e32 v181, 16, v30
	v_cvt_pk_bf16_f32 v127, v127, s0
	v_lshlrev_b32_e32 v173, 16, v22
	ds_write_b16 v163, v127 offset:28080
	v_mul_f32_e32 v127, v45, v181
	v_fma_f32 v127, v44, v173, -v127
	v_mul_f32_e32 v127, v161, v127
	v_cvt_pk_bf16_f32 v127, v127, s0
	ds_write_b16 v162, v127 offset:19008
	v_mul_f32_e32 v127, v44, v181
	v_fmac_f32_e32 v127, v45, v173
	v_mul_f32_e32 v127, v161, v127
	v_and_b32_e32 v182, 0xffff0000, v30
	v_cvt_pk_bf16_f32 v127, v127, s0
	v_and_b32_e32 v174, 0xffff0000, v22
	ds_write_b16 v163, v127 offset:28224
	v_mul_f32_e32 v127, v47, v182
	v_fma_f32 v127, v46, v174, -v127
	v_mul_f32_e32 v127, v161, v127
	v_cvt_pk_bf16_f32 v127, v127, s0
	ds_write_b16 v163, v127 offset:19152
	v_mul_f32_e32 v127, v46, v182
	v_fmac_f32_e32 v127, v47, v174
	v_mul_f32_e32 v127, v161, v127
	v_lshlrev_b32_e32 v183, 16, v31
	v_cvt_pk_bf16_f32 v127, v127, s0
	v_lshlrev_b32_e32 v175, 16, v23
	ds_write_b16 v163, v127 offset:28368
	v_mul_f32_e32 v127, v49, v183
	v_fma_f32 v127, v48, v175, -v127
	v_mul_f32_e32 v127, v161, v127
	v_cvt_pk_bf16_f32 v127, v127, s0
	ds_write_b16 v162, v127 offset:19296
	v_mul_f32_e32 v127, v48, v183
	v_fmac_f32_e32 v127, v49, v175
	v_mul_f32_e32 v127, v161, v127
	v_and_b32_e32 v184, 0xffff0000, v31
	v_cvt_pk_bf16_f32 v127, v127, s0
	v_and_b32_e32 v176, 0xffff0000, v23
	ds_write_b16 v163, v127 offset:28512
	v_mul_f32_e32 v127, v51, v184
	v_fma_f32 v127, v50, v176, -v127
	v_mul_f32_e32 v127, v161, v127
	v_cvt_pk_bf16_f32 v127, v127, s0
	ds_write_b16 v163, v127 offset:19440
	v_mul_f32_e32 v127, v50, v184
	v_fmac_f32_e32 v127, v51, v176
	v_mul_f32_e32 v185, v161, v185
	v_mul_f32_e32 v127, v161, v127
	v_cvt_pk_bf16_f32 v185, v185, s0
	v_cvt_pk_bf16_f32 v127, v127, s0
	ds_write_b16 v162, v185 offset:18432
	ds_write_b16 v163, v127 offset:28656
	s_and_saveexec_b64 s[40:41], s[0:1]
	s_cbranch_execz .LBB0_422
	ds_write_b16 v164, v56 offset:41472
	ds_write_b16_d16_hi v165, v56 offset:41616
	ds_write_b16 v164, v57 offset:41760
	ds_write_b16_d16_hi v165, v57 offset:41904
	ds_write_b16 v164, v58 offset:42048
	ds_write_b16_d16_hi v165, v58 offset:42192
	ds_write_b16 v164, v59 offset:42336
	ds_write_b16_d16_hi v165, v59 offset:42480
.LBB0_422:
	s_or_b64 exec, exec, s[40:41]
	s_add_i32 s40, s16, -2
	s_cmp_ge_u32 s40, s63
	s_cbranch_scc1 .LBB0_424
	v_add_u32_e32 v20, s62, v124
	v_lshl_add_u64 v[36:37], v[134:135], 0, s[38:39]
	v_add_u32_e32 v20, 0x140, v20
	v_add_co_u32_e32 v48, vcc, 0x4000, v36
	v_mad_i64_i32 v[28:29], s[40:41], v20, s47, v[130:131]
	s_nop 0
	v_addc_co_u32_e32 v49, vcc, 0, v37, vcc
	v_add_u32_e32 v56, s62, v160
	global_load_dwordx4 v[20:23], v[28:29], off offset:1536
	s_nop 0
	global_load_dwordx4 v[28:31], v[28:29], off offset:1664
	s_nop 0
	global_load_dwordx4 v[36:39], v[48:49], off
	global_load_dwordx4 v[40:43], v[48:49], off offset:16
	global_load_dwordx4 v[44:47], v[48:49], off offset:32
	s_nop 0
	global_load_dwordx4 v[48:51], v[48:49], off offset:48
	v_add_u32_e32 v56, 0x140, v56
	v_mad_i64_i32 v[56:57], s[40:41], v56, s47, v[132:133]
	global_load_dwordx4 v[56:59], v[56:57], off offset:3072
.LBB0_424:
	v_add_co_u32_e32 v172, vcc, s55, v146
	v_cvt_pk_bf16_f32 v170, v64, v65
	v_cvt_pk_bf16_f32 v171, v66, v67
	v_addc_co_u32_e32 v173, vcc, 0, v147, vcc
	s_waitcnt lgkmcnt(0)
	s_barrier
	global_store_dwordx2 v[172:173], v[170:171], off
	v_add_co_u32_e32 v172, vcc, s55, v148
	v_cvt_pk_bf16_f32 v170, v52, v53
	v_cvt_pk_bf16_f32 v171, v54, v55
	v_addc_co_u32_e32 v173, vcc, 0, v149, vcc
	global_store_dwordx2 v[172:173], v[170:171], off
	ds_read_b128 v[170:173], v120 offset:18432
	ds_read_b128 v[174:177], v125 offset:41472
	v_mov_b32_e32 v127, v126
	v_pk_mul_f32 v[66:67], v[126:127], v[66:67]
	v_pk_mul_f32 v[64:65], v[128:129], v[64:65]
	v_pk_mul_f32 v[54:55], v[126:127], v[54:55]
	v_pk_mul_f32 v[52:53], v[128:129], v[52:53]
	s_waitcnt lgkmcnt(0)
	v_mfma_f32_16x16x32_bf16 v[64:67], v[170:173], v[174:177], v[64:67]
	ds_read_b128 v[174:177], v166 offset:43776
	s_waitcnt lgkmcnt(0)
	v_mfma_f32_16x16x32_bf16 v[52:55], v[170:173], v[174:177], v[52:55]
	ds_read_b128 v[170:173], v167 offset:18432
	ds_read_b128 v[174:177], v168 offset:41472
	s_waitcnt lgkmcnt(0)
	v_mfma_f32_16x16x32_bf16 v[64:67], v[170:173], v[174:177], v[64:67]
	ds_read_b128 v[174:177], v169 offset:43776
	s_waitcnt lgkmcnt(0)
	v_mfma_f32_16x16x32_bf16 v[52:55], v[170:173], v[174:177], v[52:55]
	s_add_i32 s40, s16, -5
	s_cmp_ge_u32 s40, s63
	s_cbranch_scc0 .LBB0_427

.LBB0_429:
	s_or_b64 exec, exec, s[40:41]
	s_add_i32 s40, s16, -1
	s_cmp_ge_u32 s40, s63
	s_cbranch_scc1 .LBB0_431
	v_add_u32_e32 v60, s62, v124
	v_lshl_add_u64 v[72:73], v[136:137], 0, s[38:39]
	v_add_u32_e32 v60, 0x180, v60
	v_add_co_u32_e32 v84, vcc, 0x4000, v72
	v_mad_i64_i32 v[68:69], s[40:41], v60, s47, v[130:131]
	s_nop 0
	v_addc_co_u32_e32 v85, vcc, 0, v73, vcc
	v_add_u32_e32 v88, s62, v160
	global_load_dwordx4 v[60:63], v[68:69], off offset:1536
	s_nop 0
	global_load_dwordx4 v[68:71], v[68:69], off offset:1664
	s_nop 0
	global_load_dwordx4 v[72:75], v[84:85], off
	global_load_dwordx4 v[76:79], v[84:85], off offset:16
	global_load_dwordx4 v[80:83], v[84:85], off offset:32
	s_nop 0
	global_load_dwordx4 v[84:87], v[84:85], off offset:48
	v_add_u32_e32 v88, 0x180, v88
	v_mad_i64_i32 v[88:89], s[40:41], v88, s47, v[132:133]
	global_load_dwordx4 v[88:91], v[88:89], off offset:3072
.LBB0_431:
	v_add_co_u32_e32 v172, vcc, s56, v146
	v_cvt_pk_bf16_f32 v170, v64, v65
	v_cvt_pk_bf16_f32 v171, v66, v67
	v_addc_co_u32_e32 v173, vcc, 0, v147, vcc
	s_waitcnt lgkmcnt(0)
	s_barrier
	global_store_dwordx2 v[172:173], v[170:171], off
	v_add_co_u32_e32 v172, vcc, s56, v148
	v_cvt_pk_bf16_f32 v170, v52, v53
	v_cvt_pk_bf16_f32 v171, v54, v55
	v_addc_co_u32_e32 v173, vcc, 0, v149, vcc
	global_store_dwordx2 v[172:173], v[170:171], off
	ds_read_b128 v[170:173], v120
	ds_read_b128 v[174:177], v125 offset:36864
	v_mov_b32_e32 v127, v126
	v_pk_mul_f32 v[66:67], v[126:127], v[66:67]
	v_pk_mul_f32 v[64:65], v[128:129], v[64:65]
	v_pk_mul_f32 v[54:55], v[126:127], v[54:55]
	v_pk_mul_f32 v[52:53], v[128:129], v[52:53]
	s_waitcnt lgkmcnt(0)
	v_mfma_f32_16x16x32_bf16 v[64:67], v[170:173], v[174:177], v[64:67]
	ds_read_b128 v[174:177], v166 offset:39168
	s_waitcnt lgkmcnt(0)
	v_mfma_f32_16x16x32_bf16 v[52:55], v[170:173], v[174:177], v[52:55]
	ds_read_b128 v[170:173], v167
	ds_read_b128 v[174:177], v168 offset:36864
	s_waitcnt lgkmcnt(0)
	v_mfma_f32_16x16x32_bf16 v[64:67], v[170:173], v[174:177], v[64:67]
	ds_read_b128 v[174:177], v169 offset:39168
	s_waitcnt lgkmcnt(0)
	v_mfma_f32_16x16x32_bf16 v[52:55], v[170:173], v[174:177], v[52:55]
	s_add_i32 s40, s16, -4
	s_cmp_ge_u32 s40, s63
	s_cbranch_scc1 .LBB0_414

.LBB0_434:
	s_or_b64 exec, exec, s[40:41]
	s_cmp_ge_u32 s16, s63
	s_cbranch_scc1 .LBB0_413
	v_add_u32_e32 v92, s62, v124
	v_lshl_add_u64 v[100:101], v[138:139], 0, s[38:39]
	v_add_u32_e32 v92, 0x1c0, v92
	v_add_co_u32_e32 v112, vcc, 0x4000, v100
	v_mad_i64_i32 v[96:97], s[40:41], v92, s47, v[130:131]
	s_nop 0
	v_addc_co_u32_e32 v113, vcc, 0, v101, vcc
	v_add_u32_e32 v116, s62, v160
	global_load_dwordx4 v[92:95], v[96:97], off offset:1536
	s_nop 0
	global_load_dwordx4 v[96:99], v[96:97], off offset:1664
	s_nop 0
	global_load_dwordx4 v[104:107], v[112:113], off
	global_load_dwordx4 v[100:103], v[112:113], off offset:16
	global_load_dwordx4 v[108:111], v[112:113], off offset:32
	s_nop 0
	global_load_dwordx4 v[112:115], v[112:113], off offset:48
	v_add_u32_e32 v116, 0x1c0, v116
	v_mad_i64_i32 v[116:117], s[40:41], v116, s47, v[132:133]
	global_load_dwordx4 v[116:119], v[116:117], off offset:3072
	s_branch .LBB0_413

.LBB0_490:
	s_or_b64 exec, exec, s[0:1]
	v_lshlrev_b32_e32 v70, 7, v6
	v_lshlrev_b32_e32 v2, 3, v5
	v_ashrrev_i32_e32 v71, 31, v70
	v_and_b32_e32 v7, 56, v2
	v_bfe_u32 v13, v5, 3, 5
	v_lshlrev_b64 v[72:73], 1, v[70:71]
	v_lshlrev_b32_e32 v0, 3, v7
	v_mov_b32_e32 v1, v65
	v_or_b32_e32 v8, v3, v13
	v_lshl_add_u64 v[0:1], s[40:41], 0, v[0:1]
	v_lshlrev_b32_e32 v8, 9, v8
	v_mov_b32_e32 v9, v65
	v_lshl_add_u64 v[18:19], s[38:39], 0, v[72:73]
	v_lshlrev_b32_e32 v64, 1, v7
	v_lshl_add_u64 v[38:39], v[0:1], 0, v[8:9]
	v_lshl_add_u64 v[42:43], v[18:19], 0, v[64:65]
	v_add_u32_e32 v7, v68, v13
	global_load_dwordx4 v[8:11], v[38:39], off
	global_load_dwordx4 v[14:17], v[38:39], off offset:16
	global_load_dwordx4 v[18:21], v[38:39], off offset:32
	v_mad_i64_i32 v[34:35], s[0:1], v7, s57, v[42:43]
	global_load_dwordx4 v[22:25], v[34:35], off
	global_load_dwordx4 v[26:29], v[34:35], off offset:128
	global_load_dwordx4 v[30:33], v[34:35], off offset:1536
	s_nop 0
	global_load_dwordx4 v[34:37], v[34:35], off offset:1664
	s_nop 0
	global_load_dwordx4 v[38:41], v[38:39], off offset:48
	v_or_b32_sdwa v140, v5, s61 dst_sel:DWORD dst_unused:UNUSED_PAD src0_sel:BYTE_0 src1_sel:DWORD
	v_lshrrev_b32_e32 v141, 3, v140
	v_add_u32_e32 v142, v68, v141
	v_mad_i64_i32 v[134:135], s[0:1], v142, s57, v[42:43]
	v_or_b32_e32 v143, v3, v141
	v_lshlrev_b32_e32 v136, 9, v143
	v_mov_b32_e32 v137, v65
	v_lshl_add_u64 v[136:137], v[0:1], 0, v[136:137]
	global_load_dwordx4 v[160:163], v[134:135], off
	global_load_dwordx4 v[164:167], v[134:135], off offset:128
	global_load_dwordx4 v[168:171], v[134:135], off offset:1536
	global_load_dwordx4 v[172:175], v[134:135], off offset:1664
	global_load_dwordx4 v[176:179], v[136:137], off
	global_load_dwordx4 v[180:183], v[136:137], off offset:16
	global_load_dwordx4 v[184:187], v[136:137], off offset:32
	global_load_dwordx4 v[188:191], v[136:137], off offset:48
	v_bfe_u32 v140, v5, 4, 4
	v_add_u32_e32 v140, v68, v140
	v_mad_i64_i32 v[138:139], s[0:1], v140, s57, v[66:67]
	v_lshl_add_u64 v[138:139], v[138:139], 0, v[72:73]
	v_lshlrev_b32_e32 v140, 3, v5
	v_and_b32_e32 v140, 0x78, v140
	v_lshlrev_b32_e32 v140, 1, v140
	v_mov_b32_e32 v141, v65
	v_lshl_add_u64 v[138:139], v[138:139], 0, v[140:141]
	v_mov_b32_e32 v140, 0x1a000
	global_load_dwordx4 v[192:195], v[138:139], off offset:3072
	v_lshl_add_u64 v[138:139], v[138:139], 0, v[140:141]
	global_load_dwordx4 v[196:199], v[138:139], off offset:3072
	v_lshl_add_u64 v[138:139], v[138:139], 0, v[140:141]
	global_load_dwordx4 v[200:203], v[138:139], off offset:3072
	v_lshl_add_u64 v[138:139], v[138:139], 0, v[140:141]
	global_load_dwordx4 v[204:207], v[138:139], off offset:3072
	v_mul_u32_u24_e32 v7, 0x88, v13
	v_mad_i32_i24 v4, v4, s52, 0
	v_lshlrev_b32_e32 v7, 1, v7
	v_add3_u32 v7, v4, v7, v64
	s_add_i32 s2, s2, s84
	s_waitcnt vmcnt(12) lgkmcnt(0)
	v_mov_b32_e32 v44, v8
	v_mov_b32_e32 v45, v10
	v_mov_b32_e32 v10, v9
	v_mov_b32_e32 v8, v14
	v_mov_b32_e32 v9, v16
	v_mov_b32_e32 v16, v15
	v_mov_b32_e32 v14, v18
	v_mov_b32_e32 v15, v20
	v_mov_b32_e32 v20, v19
	v_lshlrev_b32_e32 v18, 16, v22
	v_and_b32_e32 v19, 0xffff0000, v22
	v_lshlrev_b32_e32 v22, 16, v23
	v_and_b32_e32 v23, 0xffff0000, v23
	v_lshlrev_b32_e32 v48, 16, v26
	v_and_b32_e32 v49, 0xffff0000, v26
	v_lshlrev_b32_e32 v26, 16, v27
	v_and_b32_e32 v27, 0xffff0000, v27
	v_lshlrev_b32_e32 v52, 16, v30
	v_and_b32_e32 v53, 0xffff0000, v30
	v_lshlrev_b32_e32 v30, 16, v31
	v_and_b32_e32 v31, 0xffff0000, v31
	v_lshlrev_b32_e32 v56, 16, v34
	v_and_b32_e32 v57, 0xffff0000, v34
	v_lshlrev_b32_e32 v34, 16, v35
	v_and_b32_e32 v35, 0xffff0000, v35
	v_pk_mul_f32 v[76:77], v[16:17], v[26:27]
	v_pk_mul_f32 v[84:85], v[16:17], v[22:23]
	v_pk_mul_f32 v[86:87], v[16:17], v[34:35]
	v_pk_mul_f32 v[16:17], v[16:17], v[30:31]
	v_lshlrev_b32_e32 v46, 16, v24
	v_and_b32_e32 v47, 0xffff0000, v24
	v_lshlrev_b32_e32 v50, 16, v28
	v_and_b32_e32 v51, 0xffff0000, v28
	v_pk_mul_f32 v[60:61], v[10:11], v[48:49]
	v_pk_mul_f32 v[62:63], v[10:11], v[18:19]
	v_pk_mul_f32 v[74:75], v[10:11], v[56:57]
	v_pk_mul_f32 v[10:11], v[10:11], v[52:53]
	v_pk_fma_f32 v[22:23], v[8:9], v[22:23], v[76:77] neg_lo:[0,0,1] neg_hi:[0,0,1]
	v_pk_fma_f32 v[26:27], v[8:9], v[26:27], v[84:85]
	v_pk_fma_f32 v[30:31], v[8:9], v[30:31], v[86:87] neg_lo:[0,0,1] neg_hi:[0,0,1]
	v_pk_fma_f32 v[8:9], v[8:9], v[34:35], v[16:17]
	v_lshlrev_b32_e32 v58, 16, v36
	v_and_b32_e32 v59, 0xffff0000, v36
	v_pk_mul_f32 v[88:89], v[20:21], v[50:51]
	v_pk_fma_f32 v[18:19], v[44:45], v[18:19], v[60:61] neg_lo:[0,0,1] neg_hi:[0,0,1]
	v_pk_fma_f32 v[48:49], v[44:45], v[48:49], v[62:63]
	v_pk_fma_f32 v[52:53], v[44:45], v[52:53], v[74:75] neg_lo:[0,0,1] neg_hi:[0,0,1]
	v_pk_fma_f32 v[10:11], v[44:45], v[56:57], v[10:11]
	v_pk_mul_f32 v[44:45], v[8:9], s[44:45] op_sel_hi:[1,0]
	v_pk_mul_f32 v[8:9], v[20:21], v[46:47]
	v_lshlrev_b32_e32 v54, 16, v32
	v_and_b32_e32 v55, 0xffff0000, v32
	v_pk_mul_f32 v[34:35], v[10:11], s[44:45] op_sel_hi:[1,0]
	v_pk_fma_f32 v[10:11], v[14:15], v[46:47], v[88:89] neg_lo:[0,0,1] neg_hi:[0,0,1]
	v_pk_fma_f32 v[46:47], v[14:15], v[50:51], v[8:9]
	v_pk_mul_f32 v[8:9], v[20:21], v[58:59]
	v_lshlrev_b32_e32 v28, 16, v29
	v_pk_fma_f32 v[8:9], v[14:15], v[54:55], v[8:9] neg_lo:[0,0,1] neg_hi:[0,0,1]
	v_and_b32_e32 v29, 0xffff0000, v29
	v_pk_mul_f32 v[50:51], v[8:9], s[44:45] op_sel_hi:[1,0]
	v_pk_mul_f32 v[8:9], v[20:21], v[54:55]
	v_lshlrev_b32_e32 v24, 16, v25
	v_pk_fma_f32 v[8:9], v[14:15], v[58:59], v[8:9]
	v_and_b32_e32 v25, 0xffff0000, v25
	v_pk_mul_f32 v[14:15], v[8:9], s[44:45] op_sel_hi:[1,0]
	v_mov_b32_e32 v9, v40
	v_mov_b32_e32 v40, v39
	v_mov_b32_e32 v8, v38
	v_pk_mul_f32 v[20:21], v[40:41], v[28:29]
	v_lshlrev_b32_e32 v36, 16, v37
	v_and_b32_e32 v37, 0xffff0000, v37
	v_pk_fma_f32 v[20:21], v[8:9], v[24:25], v[20:21] neg_lo:[0,0,1] neg_hi:[0,0,1]
	v_pk_mul_f32 v[24:25], v[40:41], v[24:25]
	v_lshlrev_b32_e32 v32, 16, v33
	v_and_b32_e32 v33, 0xffff0000, v33
	v_pk_fma_f32 v[24:25], v[8:9], v[28:29], v[24:25]
	v_pk_mul_f32 v[28:29], v[40:41], v[36:37]
	v_cvt_pk_bf16_f32 v10, v10, v11
	v_pk_fma_f32 v[28:29], v[8:9], v[32:33], v[28:29] neg_lo:[0,0,1] neg_hi:[0,0,1]
	v_pk_mul_f32 v[32:33], v[40:41], v[32:33]
	v_cvt_pk_bf16_f32 v11, v20, v21
	v_pk_fma_f32 v[8:9], v[8:9], v[36:37], v[32:33]
	v_pk_mul_f32 v[16:17], v[52:53], s[44:45] op_sel_hi:[1,0]
	v_pk_mul_f32 v[32:33], v[8:9], s[44:45] op_sel_hi:[1,0]
	v_cvt_pk_bf16_f32 v8, v18, v19
	v_cvt_pk_bf16_f32 v9, v22, v23
	v_pk_mul_f32 v[30:31], v[30:31], s[44:45] op_sel_hi:[1,0]
	v_pk_mul_f32 v[28:29], v[28:29], s[44:45] op_sel_hi:[1,0]
	ds_write_b128 v7, v[8:11]
	v_cvt_pk_bf16_f32 v8, v48, v49
	v_cvt_pk_bf16_f32 v9, v26, v27
	v_cvt_pk_bf16_f32 v10, v46, v47
	v_cvt_pk_bf16_f32 v11, v24, v25
	ds_write_b128 v7, v[8:11] offset:128
	v_cvt_pk_bf16_f32 v8, v16, v17
	v_cvt_pk_bf16_f32 v9, v30, v31
	v_cvt_pk_bf16_f32 v10, v50, v51
	v_cvt_pk_bf16_f32 v11, v28, v29
	ds_write_b128 v7, v[8:11] offset:17408
	v_cvt_pk_bf16_f32 v8, v34, v35
	v_cvt_pk_bf16_f32 v9, v44, v45
	v_cvt_pk_bf16_f32 v10, v14, v15
	v_cvt_pk_bf16_f32 v11, v32, v33
	ds_write_b128 v7, v[8:11] offset:17536
	v_or_b32_sdwa v7, v5, s61 dst_sel:DWORD dst_unused:UNUSED_PAD src0_sel:BYTE_0 src1_sel:DWORD
	v_lshrrev_b32_e32 v13, 3, v7
	v_add_u32_e32 v8, v68, v13
	v_or_b32_e32 v3, v3, v13
	v_mad_i64_i32 v[22:23], s[0:1], v8, s57, v[42:43]
	v_lshlrev_b32_e32 v26, 9, v3
	v_mov_b32_e32 v27, v65
	s_nop 0
	v_lshl_add_u64 v[0:1], v[0:1], 0, v[26:27]
	v_mul_u32_u24_e32 v3, 0x88, v13
	v_lshlrev_b32_e32 v3, 1, v3
	v_add3_u32 v3, v4, v3, v64
	v_lshrrev_b32_e32 v7, 4, v7
	s_waitcnt vmcnt(4) lgkmcnt(0)
	v_mov_b64_e32 v[8:9], v[160:161]
	v_mov_b64_e32 v[10:11], v[162:163]
	v_mov_b64_e32 v[14:15], v[164:165]
	v_mov_b64_e32 v[16:17], v[166:167]
	v_mov_b64_e32 v[18:19], v[168:169]
	v_mov_b64_e32 v[20:21], v[170:171]
	v_mov_b64_e32 v[22:23], v[172:173]
	v_mov_b64_e32 v[24:25], v[174:175]
	v_mov_b64_e32 v[26:27], v[176:177]
	v_mov_b64_e32 v[28:29], v[178:179]
	v_mov_b64_e32 v[30:31], v[180:181]
	v_mov_b64_e32 v[32:33], v[182:183]
	v_mov_b64_e32 v[34:35], v[184:185]
	v_mov_b64_e32 v[36:37], v[186:187]
	v_mov_b64_e32 v[38:39], v[188:189]
	v_mov_b64_e32 v[40:41], v[190:191]
	v_lshlrev_b32_e32 v0, 16, v8
	v_lshlrev_b32_e32 v44, 16, v14
	v_and_b32_e32 v45, 0xffff0000, v14
	v_mov_b32_e32 v57, v28
	v_mov_b32_e32 v28, v27
	v_and_b32_e32 v1, 0xffff0000, v8
	v_mov_b32_e32 v56, v26
	v_pk_mul_f32 v[26:27], v[28:29], v[44:45]
	v_lshlrev_b32_e32 v52, 16, v22
	v_and_b32_e32 v53, 0xffff0000, v22
	v_pk_fma_f32 v[26:27], v[56:57], v[0:1], v[26:27] neg_lo:[0,0,1] neg_hi:[0,0,1]
	v_pk_mul_f32 v[0:1], v[28:29], v[0:1]
	v_lshlrev_b32_e32 v48, 16, v18
	v_and_b32_e32 v49, 0xffff0000, v18
	v_pk_fma_f32 v[0:1], v[56:57], v[44:45], v[0:1]
	v_pk_mul_f32 v[44:45], v[28:29], v[52:53]
	v_lshlrev_b32_e32 v14, 16, v15
	v_and_b32_e32 v15, 0xffff0000, v15
	v_pk_fma_f32 v[44:45], v[56:57], v[48:49], v[44:45] neg_lo:[0,0,1] neg_hi:[0,0,1]
	v_pk_mul_f32 v[28:29], v[28:29], v[48:49]
	v_mov_b32_e32 v49, v32
	v_mov_b32_e32 v32, v31
	v_lshlrev_b32_e32 v8, 16, v9
	v_and_b32_e32 v9, 0xffff0000, v9
	v_mov_b32_e32 v48, v30
	v_pk_mul_f32 v[30:31], v[32:33], v[14:15]
	v_lshlrev_b32_e32 v22, 16, v23
	v_and_b32_e32 v23, 0xffff0000, v23
	v_pk_fma_f32 v[30:31], v[48:49], v[8:9], v[30:31] neg_lo:[0,0,1] neg_hi:[0,0,1]
	v_pk_mul_f32 v[8:9], v[32:33], v[8:9]
	v_lshlrev_b32_e32 v18, 16, v19
	v_and_b32_e32 v19, 0xffff0000, v19
	v_pk_fma_f32 v[14:15], v[48:49], v[14:15], v[8:9]
	v_pk_mul_f32 v[8:9], v[32:33], v[22:23]
	v_pk_fma_f32 v[28:29], v[56:57], v[52:53], v[28:29]
	v_pk_fma_f32 v[8:9], v[48:49], v[18:19], v[8:9] neg_lo:[0,0,1] neg_hi:[0,0,1]
	v_lshlrev_b32_e32 v42, 16, v10
	v_pk_mul_f32 v[52:53], v[8:9], s[44:45] op_sel_hi:[1,0]
	v_pk_mul_f32 v[8:9], v[32:33], v[18:19]
	v_and_b32_e32 v43, 0xffff0000, v10
	v_pk_fma_f32 v[8:9], v[48:49], v[22:23], v[8:9]
	v_lshlrev_b32_e32 v46, 16, v16
	v_and_b32_e32 v47, 0xffff0000, v16
	v_lshlrev_b32_e32 v50, 16, v20
	v_and_b32_e32 v51, 0xffff0000, v20
	v_lshlrev_b32_e32 v54, 16, v24
	v_and_b32_e32 v55, 0xffff0000, v24
	v_pk_mul_f32 v[18:19], v[8:9], s[44:45] op_sel_hi:[1,0]
	v_mov_b32_e32 v9, v36
	v_mov_b32_e32 v36, v35
	v_mov_b32_e32 v8, v34
	v_pk_mul_f32 v[22:23], v[36:37], v[46:47]
	v_pk_mul_f32 v[32:33], v[36:37], v[42:43]
	v_pk_mul_f32 v[34:35], v[36:37], v[54:55]
	v_pk_mul_f32 v[36:37], v[36:37], v[50:51]
	v_pk_fma_f32 v[22:23], v[8:9], v[42:43], v[22:23] neg_lo:[0,0,1] neg_hi:[0,0,1]
	v_pk_fma_f32 v[32:33], v[8:9], v[46:47], v[32:33]
	v_pk_fma_f32 v[34:35], v[8:9], v[50:51], v[34:35] neg_lo:[0,0,1] neg_hi:[0,0,1]
	v_pk_fma_f32 v[8:9], v[8:9], v[54:55], v[36:37]
	v_lshlrev_b32_e32 v16, 16, v17
	v_and_b32_e32 v17, 0xffff0000, v17
	v_pk_mul_f32 v[36:37], v[8:9], s[44:45] op_sel_hi:[1,0]
	v_mov_b32_e32 v9, v40
	v_mov_b32_e32 v40, v39
	v_lshlrev_b32_e32 v10, 16, v11
	v_and_b32_e32 v11, 0xffff0000, v11
	v_mov_b32_e32 v8, v38
	v_pk_mul_f32 v[38:39], v[40:41], v[16:17]
	v_lshlrev_b32_e32 v24, 16, v25
	v_and_b32_e32 v25, 0xffff0000, v25
	v_pk_fma_f32 v[38:39], v[8:9], v[10:11], v[38:39] neg_lo:[0,0,1] neg_hi:[0,0,1]
	v_pk_mul_f32 v[10:11], v[40:41], v[10:11]
	v_lshlrev_b32_e32 v20, 16, v21
	v_and_b32_e32 v21, 0xffff0000, v21
	v_pk_fma_f32 v[16:17], v[8:9], v[16:17], v[10:11]
	v_pk_mul_f32 v[10:11], v[40:41], v[24:25]
	v_pk_mul_f32 v[44:45], v[44:45], s[44:45] op_sel_hi:[1,0]
	v_pk_fma_f32 v[10:11], v[8:9], v[20:21], v[10:11] neg_lo:[0,0,1] neg_hi:[0,0,1]
	v_pk_mul_f32 v[34:35], v[34:35], s[44:45] op_sel_hi:[1,0]
	v_pk_mul_f32 v[42:43], v[10:11], s[44:45] op_sel_hi:[1,0]
	v_pk_mul_f32 v[10:11], v[40:41], v[20:21]
	v_pk_mul_f32 v[28:29], v[28:29], s[44:45] op_sel_hi:[1,0]
	v_pk_fma_f32 v[8:9], v[8:9], v[24:25], v[10:11]
	v_cvt_pk_bf16_f32 v10, v22, v23
	v_pk_mul_f32 v[20:21], v[8:9], s[44:45] op_sel_hi:[1,0]
	v_cvt_pk_bf16_f32 v8, v26, v27
	v_cvt_pk_bf16_f32 v9, v30, v31
	v_cvt_pk_bf16_f32 v11, v38, v39
	ds_write_b128 v3, v[8:11]
	v_cvt_pk_bf16_f32 v8, v0, v1
	v_cvt_pk_bf16_f32 v9, v14, v15
	v_cvt_pk_bf16_f32 v10, v32, v33
	v_cvt_pk_bf16_f32 v11, v16, v17
	ds_write_b128 v3, v[8:11] offset:128
	v_cvt_pk_bf16_f32 v8, v44, v45
	v_cvt_pk_bf16_f32 v9, v52, v53
	v_cvt_pk_bf16_f32 v10, v34, v35
	v_cvt_pk_bf16_f32 v11, v42, v43
	ds_write_b128 v3, v[8:11] offset:17408
	v_cvt_pk_bf16_f32 v8, v28, v29
	v_cvt_pk_bf16_f32 v9, v18, v19
	v_cvt_pk_bf16_f32 v10, v36, v37
	v_cvt_pk_bf16_f32 v11, v20, v21
	ds_write_b128 v3, v[8:11] offset:17536
	v_bfe_u32 v9, v5, 4, 4
	v_add_u32_e32 v10, v68, v9
	v_and_b32_e32 v8, 0x78, v2
	v_mad_i64_i32 v[0:1], s[0:1], v10, s57, v[66:67]
	v_lshl_add_u64 v[0:1], v[0:1], 0, v[72:73]
	v_lshlrev_b32_e32 v64, 1, v8
	v_lshl_add_u64 v[0:1], v[0:1], 0, v[64:65]
	v_mul_u32_u24_e32 v8, 0x48, v8
	v_lshlrev_b32_e32 v11, 1, v8
	v_lshlrev_b32_e32 v9, 1, v9
	v_add_u32_e32 v14, v4, v11
	v_add3_u32 v13, v4, v9, v11
	v_add_u32_e32 v15, v14, v9
	v_add_u32_e32 v8, 32, v10
	v_mad_i64_i32 v[8:9], s[0:1], v8, s57, v[66:67]
	v_lshl_add_u64 v[8:9], v[8:9], 0, v[72:73]
	v_lshl_add_u64 v[8:9], v[8:9], 0, v[64:65]
	v_and_b32_e32 v20, 15, v5
	v_bfe_u32 v21, v5, 4, 2
	v_lshrrev_b32_e32 v5, 2, v5
	v_and_or_b32 v76, v5, 48, v20
	v_lshlrev_b32_e32 v5, 2, v21
	v_lshlrev_b32_e32 v74, 4, v21
	v_sub_u32_e32 v69, v76, v5
	v_add_u32_e32 v16, -2, v69
	v_cvt_f32_i32_e32 v16, v16
	v_add_u32_e32 v17, -3, v69
	v_subrev_u32_e32 v22, 17, v69
	v_subrev_u32_e32 v23, 18, v69
	v_subrev_u32_e32 v24, 19, v69
	v_subrev_u32_e32 v25, 33, v69
	v_cvt_f32_i32_e32 v17, v17
	v_cvt_f32_i32_e32 v22, v22
	v_cvt_f32_i32_e32 v23, v23
	v_cvt_f32_i32_e32 v24, v24
	v_cvt_f32_i32_e32 v25, v25
	v_subrev_u32_e32 v26, 34, v69
	v_subrev_u32_e32 v27, 35, v69
	v_cvt_f32_i32_e32 v26, v26
	v_cvt_f32_i32_e32 v34, v27
	v_subrev_u32_e32 v28, 49, v69
	s_add_i32 s45, s45, s48
	s_cmpk_gt_i32 s2, 0x62f
	s_waitcnt vmcnt(3) lgkmcnt(0)
	v_mov_b64_e32 v[0:1], v[192:193]
	v_mov_b64_e32 v[2:3], v[194:195]
	ds_write_b16 v13, v0 offset:34816
	ds_write_b16_d16_hi v15, v0 offset:34960
	ds_write_b16 v13, v1 offset:35104
	ds_write_b16_d16_hi v15, v1 offset:35248
	ds_write_b16 v13, v2 offset:35392
	ds_write_b16_d16_hi v15, v2 offset:35536
	ds_write_b16 v13, v3 offset:35680
	ds_write_b16_d16_hi v15, v3 offset:35824
	v_add_u32_e32 v0, v68, v7
	v_mad_i64_i32 v[0:1], s[0:1], v0, s57, v[66:67]
	v_lshl_add_u64 v[0:1], v[0:1], 0, v[72:73]
	v_lshl_add_u64 v[0:1], v[0:1], 0, v[64:65]
	v_lshlrev_b32_e32 v7, 1, v7
	v_add3_u32 v11, v4, v7, v11
	v_add_u32_e32 v7, v14, v7
	s_waitcnt vmcnt(2) lgkmcnt(0)
	v_mov_b64_e32 v[0:1], v[196:197]
	v_mov_b64_e32 v[2:3], v[198:199]
	ds_write_b16 v11, v0 offset:34816
	ds_write_b16_d16_hi v7, v0 offset:34960
	ds_write_b16 v11, v1 offset:35104
	ds_write_b16_d16_hi v7, v1 offset:35248
	ds_write_b16 v11, v2 offset:35392
	ds_write_b16_d16_hi v7, v2 offset:35536
	ds_write_b16 v11, v3 offset:35680
	ds_write_b16_d16_hi v7, v3 offset:35824
	v_cvt_f32_i32_e32 v8, v6
	v_add_u32_e32 v6, 48, v10
	v_mad_i64_i32 v[6:7], s[0:1], v6, s57, v[66:67]
	v_lshl_add_u64 v[6:7], v[6:7], 0, v[72:73]
	v_lshl_add_u64 v[6:7], v[6:7], 0, v[64:65]
	s_waitcnt vmcnt(1) lgkmcnt(0)
	v_mov_b64_e32 v[0:1], v[200:201]
	v_mov_b64_e32 v[2:3], v[202:203]
	ds_write_b16 v13, v0 offset:34880
	ds_write_b16_d16_hi v15, v0 offset:35024
	ds_write_b16 v13, v1 offset:35168
	ds_write_b16_d16_hi v15, v1 offset:35312
	ds_write_b16 v13, v2 offset:35456
	ds_write_b16_d16_hi v15, v2 offset:35600
	ds_write_b16 v13, v3 offset:35744
	ds_write_b16_d16_hi v15, v3 offset:35888
	v_sub_f32_e32 v8, 0xc0a00000, v8
	v_cmp_gt_f32_e32 vcc, s53, v8
	v_add_u32_e32 v9, v4, v74
	v_xad_u32 v10, v5, -1, v76
	v_cndmask_b32_e32 v29, 0, v78, vcc
	v_add_f32_e32 v8, v8, v29
	v_exp_f32_e32 v6, v8
	v_cndmask_b32_e32 v7, 0, v79, vcc
	v_mad_u32_u24 v18, v76, s62, v9
	v_mad_u32_u24 v19, v20, s62, v9
	v_ldexp_f32 v6, v6, v7
	v_sub_f32_e32 v6, 1.0, v6
	v_cmp_gt_f32_e32 vcc, s54, v6
	v_cvt_f32_i32_e32 v9, v69
	v_cvt_f32_i32_e32 v10, v10
	v_cndmask_b32_e64 v7, 0, 32, vcc
	v_ldexp_f32 v6, v6, v7
	v_log_f32_e32 v6, v6
	v_cndmask_b32_e32 v7, 0, v80, vcc
	v_or_b32_e32 v14, 32, v5
	s_waitcnt vmcnt(0) lgkmcnt(0)
	v_mov_b64_e32 v[0:1], v[204:205]
	v_mov_b64_e32 v[2:3], v[206:207]
	ds_write_b16 v13, v0 offset:34912
	ds_write_b16_d16_hi v15, v0 offset:35056
	ds_write_b16 v13, v1 offset:35200
	ds_write_b16_d16_hi v15, v1 offset:35344
	ds_write_b16 v13, v2 offset:35488
	ds_write_b16_d16_hi v15, v2 offset:35632
	ds_write_b16 v13, v3 offset:35776
	ds_write_b16_d16_hi v15, v3 offset:35920
	v_mul_f32_e32 v8, 0x3f317217, v6
	v_fma_f32 v8, v6, s55, -v8
	v_fmac_f32_e32 v8, 0x3377d1cf, v6
	v_fmac_f32_e32 v8, 0x3f317217, v6
	v_cmp_lt_f32_e64 vcc, |v6|, s56
	s_waitcnt lgkmcnt(0)
	s_barrier
	v_cndmask_b32_e32 v6, v6, v8, vcc
	v_sub_f32_e32 v6, v6, v7
	ds_read_b128 v[0:3], v19 offset:17408
	v_sub_u32_e32 v14, v76, v14
	v_mul_f32_e32 v83, 0x3fb8aa3b, v6
	v_cvt_f32_i32_e32 v14, v14
	v_mul_f32_e64 v6, |v9|, v83
	v_mul_f32_e64 v7, |v10|, v83
	v_mul_f32_e64 v8, |v16|, v83
	v_cmp_gt_f32_e32 vcc, s53, v6
	v_cmp_gt_f32_e64 s[0:1], s53, v7
	v_cmp_gt_f32_e64 s[4:5], s53, v8
	v_or_b32_e32 v11, 16, v5
	v_or_b32_e32 v5, 48, v5
	v_cndmask_b32_e32 v6, 0, v78, vcc
	v_cndmask_b32_e64 v7, 0, v78, s[0:1]
	v_cndmask_b32_e64 v8, 0, v78, s[4:5]
	v_sub_u32_e32 v11, v76, v11
	v_sub_u32_e32 v5, v76, v5
	v_fma_f32 v42, |v9|, v83, v6
	v_fma_f32 v10, |v10|, v83, v7
	v_fma_f32 v43, |v16|, v83, v8
	ds_read_b128 v[56:59], v18
	ds_read_b128 v[6:9], v19 offset:21760
	v_cvt_f32_i32_e32 v11, v11
	v_cvt_f32_i32_e32 v5, v5
	v_mul_f32_e64 v27, |v17|, v83
	v_mul_f32_e64 v29, |v22|, v83
	v_mul_f32_e64 v30, |v23|, v83
	v_mul_f32_e64 v31, |v24|, v83
	v_mul_f32_e64 v32, |v14|, v83
	v_mul_f32_e64 v33, |v25|, v83
	v_cmp_gt_f32_e64 s[6:7], s53, v27
	v_cmp_gt_f32_e64 s[10:11], s53, v29
	v_cmp_gt_f32_e64 s[12:13], s53, v30
	v_cmp_gt_f32_e64 s[14:15], s53, v31
	v_cmp_gt_f32_e64 s[16:17], s53, v32
	v_cmp_gt_f32_e64 s[18:19], s53, v33
	v_cndmask_b32_e64 v27, 0, v78, s[6:7]
	v_cndmask_b32_e64 v29, 0, v78, s[10:11]
	v_cndmask_b32_e64 v30, 0, v78, s[12:13]
	v_cndmask_b32_e64 v31, 0, v78, s[14:15]
	v_cndmask_b32_e64 v32, 0, v78, s[16:17]
	v_cndmask_b32_e64 v33, 0, v78, s[18:19]
	v_fma_f32 v44, |v17|, v83, v27
	v_fma_f32 v45, |v22|, v83, v29
	v_fma_f32 v48, |v23|, v83, v30
	v_fma_f32 v49, |v24|, v83, v31
	v_fma_f32 v50, |v14|, v83, v32
	v_fma_f32 v13, |v25|, v83, v33
	ds_read_b128 v[60:63], v18 offset:64
	ds_read_b128 v[14:17], v19 offset:17472
	ds_read_b128 v[22:25], v19 offset:26112
	s_waitcnt lgkmcnt(4)
	v_mfma_f32_16x16x32_bf16 v[0:3], v[0:3], v[56:59], 0
	v_cvt_f32_i32_e32 v64, v28
	v_mul_f32_e64 v28, |v11|, v83
	v_mul_f32_e64 v35, |v26|, v83
	v_mul_f32_e64 v36, |v34|, v83
	v_mul_f32_e64 v37, |v5|, v83
	v_cmp_gt_f32_e64 s[8:9], s53, v28
	v_cmp_gt_f32_e64 s[20:21], s53, v35
	v_cmp_gt_f32_e64 s[22:23], s53, v36
	v_cmp_gt_f32_e64 s[24:25], s53, v37
	v_cndmask_b32_e64 v28, 0, v78, s[8:9]
	v_cndmask_b32_e64 v35, 0, v78, s[20:21]
	v_cndmask_b32_e64 v36, 0, v78, s[22:23]
	v_cndmask_b32_e64 v38, 0, v78, s[24:25]
	v_fma_f32 v11, |v11|, v83, v28
	v_fma_f32 v91, |v26|, v83, v35
	ds_read_b128 v[26:29], v19 offset:21824
	ds_read_b128 v[30:33], v19 offset:30464
	v_fma_f32 v93, |v34|, v83, v36
	ds_read_b128 v[34:37], v19 offset:26176
	v_fma_f32 v5, |v5|, v83, v38
	ds_read_b128 v[38:41], v19 offset:30528
	s_waitcnt lgkmcnt(5)
	v_mfma_f32_16x16x32_bf16 v[0:3], v[14:17], v[60:63], v[0:3]
	ds_read_b128 v[14:17], v19 offset:17536
	v_exp_f32_e32 v102, v48
	v_exp_f32_e32 v103, v49
	v_mfma_f32_16x16x32_bf16 v[6:9], v[6:9], v[56:59], 0
	v_exp_f32_e32 v104, v50
	v_exp_f32_e32 v96, v42
	v_exp_f32_e32 v97, v10
	s_waitcnt lgkmcnt(5)
	v_mfma_f32_16x16x32_bf16 v[22:25], v[22:25], v[56:59], 0
	v_exp_f32_e32 v98, v43
	v_exp_f32_e32 v99, v44
	v_exp_f32_e32 v101, v45
	s_waitcnt lgkmcnt(3)
	v_mfma_f32_16x16x32_bf16 v[30:33], v[30:33], v[56:59], 0
	v_mul_f32_e64 v75, |v64|, v83
	v_cndmask_b32_e32 v46, 0, v79, vcc
	v_cndmask_b32_e64 v47, 0, v79, s[0:1]
	v_mfma_f32_16x16x32_bf16 v[6:9], v[26:29], v[60:63], v[6:9]
	ds_read_b128 v[52:55], v18 offset:128
	ds_read_b128 v[26:29], v19 offset:21888
	v_exp_f32_e32 v100, v11
	v_ldexp_f32 v10, v96, v46
	s_waitcnt lgkmcnt(4)
	v_mfma_f32_16x16x32_bf16 v[22:25], v[34:37], v[60:63], v[22:25]
	v_ldexp_f32 v11, v97, v47
	v_cmp_gt_f32_e32 vcc, s53, v75
	v_cndmask_b32_e64 v77, 0, v79, s[4:5]
	s_waitcnt lgkmcnt(3)
	v_mfma_f32_16x16x32_bf16 v[30:33], v[38:41], v[60:63], v[30:33]
	ds_read_b128 v[48:51], v18 offset:192
	ds_read_b128 v[34:37], v19 offset:17600
	ds_read_b128 v[38:41], v19 offset:26240
	v_cndmask_b32_e64 v84, 0, v79, s[6:7]
	v_ldexp_f32 v18, v98, v77
	s_waitcnt lgkmcnt(4)
	v_mfma_f32_16x16x32_bf16 v[0:3], v[14:17], v[52:55], v[0:3]
	ds_read_b128 v[14:17], v19 offset:21952
	ds_read_b128 v[42:45], v19 offset:30592
	v_exp_f32_e32 v13, v13
	v_exp_f32_e32 v91, v91
	s_waitcnt lgkmcnt(3)
	v_mfma_f32_16x16x32_bf16 v[0:3], v[34:37], v[48:51], v[0:3]
	v_exp_f32_e32 v93, v93
	v_cndmask_b32_e64 v90, 0, v79, s[18:19]
	v_cndmask_b32_e64 v89, 0, v79, s[16:17]
	v_mfma_f32_16x16x32_bf16 v[6:9], v[26:29], v[52:55], v[6:9]
	ds_read_b128 v[26:29], v19 offset:26304
	s_nop 2
	v_pk_mul_f32 v[10:11], v[10:11], v[0:1]
	v_cndmask_b32_e32 v0, 0, v78, vcc
	v_fma_f32 v0, |v64|, v83, v0
	v_subrev_u32_e32 v1, 50, v69
	s_waitcnt lgkmcnt(3)
	v_mfma_f32_16x16x32_bf16 v[22:25], v[38:41], v[52:55], v[22:25]
	v_exp_f32_e32 v0, v0
	v_cvt_f32_i32_e32 v1, v1
	ds_read_b128 v[38:41], v19 offset:30656
	v_ldexp_f32 v19, v99, v84
	v_pk_mul_f32 v[18:19], v[18:19], v[2:3]
	v_cndmask_b32_e32 v2, 0, v79, vcc
	s_waitcnt lgkmcnt(3)
	v_mfma_f32_16x16x32_bf16 v[6:9], v[14:17], v[48:51], v[6:9]
	v_lshlrev_b32_e32 v64, 3, v21
	v_cndmask_b32_e64 v92, 0, v79, s[20:21]
	v_cndmask_b32_e64 v94, 0, v79, s[22:23]
	s_waitcnt lgkmcnt(1)
	v_mfma_f32_16x16x32_bf16 v[14:17], v[26:29], v[48:51], v[22:25]
	v_ldexp_f32 v29, v0, v2
	v_mul_f32_e64 v0, |v1|, v83
	v_cmp_gt_f32_e32 vcc, s53, v0
	v_mfma_f32_16x16x32_bf16 v[30:33], v[42:45], v[52:55], v[30:33]
	v_ldexp_f32 v43, v13, v90
	v_cndmask_b32_e32 v0, 0, v78, vcc
	v_fma_f32 v13, |v1|, v83, v0
	v_mul_u32_u24_e32 v0, 0x90, v20
	v_add3_u32 v21, v4, v64, v0
	v_exp_f32_e32 v5, v5
	v_ldexp_f32 v42, v104, v89
	v_ldexp_f32 v26, v91, v92
	v_ldexp_f32 v27, v93, v94
	v_add_u32_e32 v92, 0x9800, v21
	v_pk_mul_f32 v[46:47], v[42:43], v[14:15]
	v_pk_mul_f32 v[90:91], v[26:27], v[16:17]
	ds_read2_b64 v[14:17], v92 offset0:64 offset1:68
	v_exp_f32_e32 v13, v13
	v_cndmask_b32_e64 v95, 0, v79, s[24:25]
	v_ldexp_f32 v28, v5, v95
	v_cvt_pk_bf16_f32 v5, v18, v19
	v_cndmask_b32_e32 v18, 0, v79, vcc
	v_ldexp_f32 v18, v13, v18
	v_subrev_u32_e32 v13, 51, v69
	v_cndmask_b32_e64 v85, 0, v79, s[8:9]
	v_cndmask_b32_e64 v86, 0, v79, s[10:11]
	v_cndmask_b32_e64 v87, 0, v79, s[12:13]
	v_cndmask_b32_e64 v88, 0, v79, s[14:15]
	s_waitcnt lgkmcnt(1)
	v_mfma_f32_16x16x32_bf16 v[22:25], v[38:41], v[48:51], v[30:33]
	v_cvt_f32_i32_e32 v13, v13
	v_ldexp_f32 v34, v100, v85
	v_ldexp_f32 v35, v101, v86
	v_ldexp_f32 v36, v102, v87
	v_ldexp_f32 v37, v103, v88
	v_pk_mul_f32 v[6:7], v[34:35], v[6:7]
	v_pk_mul_f32 v[30:31], v[36:37], v[8:9]
	v_add_u32_e32 v75, 0x8800, v21
	v_cvt_pk_bf16_f32 v4, v10, v11
	v_add_u32_e32 v77, 0x9000, v21
	v_cvt_pk_bf16_f32 v6, v6, v7
	v_cvt_pk_bf16_f32 v7, v30, v31
	v_add_u32_e32 v93, 0xa000, v21
	v_add_u32_e32 v94, 0xa800, v21
	v_add_u32_e32 v69, 0xb000, v21
	v_add_u32_e32 v95, 0xb800, v21
	v_add_u32_e32 v96, 0xc000, v21
	v_pk_mul_f32 v[22:23], v[28:29], v[22:23]
	ds_read2_b64 v[0:3], v75 offset1:4
	ds_read2_b64 v[8:11], v77 offset0:32 offset1:36
	ds_read2_b64 v[26:29], v93 offset0:96 offset1:100
	ds_read2_b64 v[30:33], v94 offset0:128 offset1:132
	s_waitcnt lgkmcnt(4)
	v_mfma_f32_16x16x32_bf16 v[34:37], v[14:17], v[4:7], 0
	ds_read2_b64 v[14:17], v69 offset0:160 offset1:164
	v_mul_f32_e64 v19, |v13|, v83
	ds_read2_b64 v[38:41], v95 offset0:192 offset1:196
	ds_read2_b64 v[42:45], v96 offset0:224 offset1:228
	v_cmp_gt_f32_e32 vcc, s53, v19
	s_waitcnt lgkmcnt(6)
	v_mfma_f32_16x16x32_bf16 v[0:3], v[0:3], v[4:7], 0
	v_cvt_pk_bf16_f32 v89, v90, v91
	v_cndmask_b32_e32 v19, 0, v78, vcc
	v_fma_f32 v13, |v13|, v83, v19
	v_exp_f32_e32 v13, v13
	v_cndmask_b32_e32 v19, 0, v79, vcc
	s_waitcnt lgkmcnt(5)
	v_mfma_f32_16x16x32_bf16 v[8:11], v[8:11], v[4:7], 0
	v_cvt_pk_bf16_f32 v90, v22, v23
	v_ldexp_f32 v19, v13, v19
	v_pk_mul_f32 v[18:19], v[18:19], v[24:25]
	s_waitcnt lgkmcnt(4)
	v_mfma_f32_16x16x32_bf16 v[26:29], v[26:29], v[4:7], 0
	ds_read2_b64 v[22:25], v92 offset0:72 offset1:76
	v_cvt_pk_bf16_f32 v88, v46, v47
	v_cvt_pk_bf16_f32 v91, v18, v19
	s_waitcnt lgkmcnt(4)
	v_mfma_f32_16x16x32_bf16 v[30:33], v[30:33], v[4:7], 0
	v_ashrrev_i32_e32 v13, 31, v12
	v_lshlrev_b64 v[12:13], 15, v[12:13]
	v_lshlrev_b32_e32 v20, 8, v20
	s_waitcnt lgkmcnt(3)
	v_mfma_f32_16x16x32_bf16 v[84:87], v[14:17], v[4:7], 0
	ds_read2_b64 v[14:17], v75 offset0:8 offset1:12
	v_mov_b32_e32 v75, v65
	v_mov_b32_e32 v21, v65
	s_waitcnt lgkmcnt(3)
	v_mfma_f32_16x16x32_bf16 v[38:41], v[38:41], v[4:7], 0
	v_readlane_b32 s4, v255, 2
	v_readlane_b32 s6, v255, 4
	v_readlane_b32 s7, v255, 5
	s_waitcnt lgkmcnt(2)
	v_mfma_f32_16x16x32_bf16 v[42:45], v[42:45], v[4:7], 0
	ds_read2_b64 v[4:7], v77 offset0:40 offset1:44
	v_mov_b32_e32 v77, v65
	v_readlane_b32 s5, v255, 3
	s_waitcnt lgkmcnt(1)
	v_mfma_f32_16x16x32_bf16 v[16:19], v[14:17], v[88:91], v[0:3]
	v_readlane_b32 s8, v255, 6
	v_readlane_b32 s9, v255, 7
	v_readlane_b32 s10, v255, 8
	s_waitcnt lgkmcnt(0)
	v_mfma_f32_16x16x32_bf16 v[0:3], v[4:7], v[88:91], v[8:11]
	v_readlane_b32 s11, v255, 9
	s_nop 1
	ds_read2_b64 v[8:11], v93 offset0:104 offset1:108
	v_readlane_b32 s12, v255, 10
	v_mfma_f32_16x16x32_bf16 v[4:7], v[22:25], v[88:91], v[34:37]
	ds_read2_b64 v[22:25], v94 offset0:136 offset1:140
	v_readlane_b32 s13, v255, 11
	v_readlane_b32 s14, v255, 12
	s_waitcnt lgkmcnt(1)
	v_mfma_f32_16x16x32_bf16 v[8:11], v[8:11], v[88:91], v[26:29]
	s_nop 2
	v_lshl_add_u64 v[26:27], s[42:43], 0, v[12:13]
	v_lshl_add_u64 v[26:27], v[26:27], 0, v[74:75]
	v_lshl_add_u64 v[108:109], v[26:27], 0, v[20:21]
	s_waitcnt lgkmcnt(0)
	v_mfma_f32_16x16x32_bf16 v[12:15], v[22:25], v[88:91], v[30:33]
	ds_read2_b64 v[22:25], v69 offset0:168 offset1:172
	v_add_co_u32_e32 v134, vcc, s63, v108
	s_nop 1
	v_addc_co_u32_e32 v135, vcc, 0, v109, vcc
	v_add_co_u32_e32 v136, vcc, s64, v108
	s_nop 1
	v_addc_co_u32_e32 v137, vcc, 0, v109, vcc
	v_add_co_u32_e32 v138, vcc, s65, v108
	s_nop 1
	v_addc_co_u32_e32 v139, vcc, 0, v109, vcc
	v_add_co_u32_e32 v140, vcc, s66, v108
	s_nop 1
	v_addc_co_u32_e32 v141, vcc, 0, v109, vcc
	v_add_co_u32_e32 v142, vcc, s67, v108
	s_nop 1
	v_addc_co_u32_e32 v143, vcc, 0, v109, vcc
	v_add_co_u32_e32 v150, vcc, s68, v108
	s_nop 1
	v_addc_co_u32_e32 v151, vcc, 0, v109, vcc
	v_add_co_u32_e32 v152, vcc, s69, v108
	s_nop 1
	v_addc_co_u32_e32 v153, vcc, 0, v109, vcc
	global_load_dwordx4 v[160:163], v[108:109], off
	global_load_dwordx4 v[164:167], v[108:109], off offset:64
	global_load_dwordx4 v[168:171], v[108:109], off offset:128
	global_load_dwordx4 v[172:175], v[108:109], off offset:192
	global_load_dwordx4 v[176:179], v[134:135], off
	global_load_dwordx4 v[180:183], v[134:135], off offset:64
	global_load_dwordx4 v[184:187], v[134:135], off offset:128
	global_load_dwordx4 v[188:191], v[134:135], off offset:192
	global_load_dwordx4 v[192:195], v[136:137], off
	global_load_dwordx4 v[196:199], v[136:137], off offset:64
	global_load_dwordx4 v[200:203], v[136:137], off offset:128
	global_load_dwordx4 v[204:207], v[136:137], off offset:192
	global_load_dwordx4 v[208:211], v[138:139], off
	global_load_dwordx4 v[212:215], v[138:139], off offset:64
	global_load_dwordx4 v[216:219], v[138:139], off offset:128
	global_load_dwordx4 v[220:223], v[138:139], off offset:192
	global_load_dwordx4 v[224:227], v[140:141], off
	global_load_dwordx4 v[228:231], v[140:141], off offset:64
	global_load_dwordx4 v[232:235], v[140:141], off offset:128
	global_load_dwordx4 v[236:239], v[140:141], off offset:192
	global_load_dwordx4 v[240:243], v[142:143], off
	global_load_dwordx4 v[244:247], v[142:143], off offset:64
	global_load_dwordx4 v[248:251], v[142:143], off offset:128
	ds_read2_b64 v[30:33], v95 offset0:200 offset1:204
	s_waitcnt lgkmcnt(0)
	v_mfma_f32_16x16x32_bf16 v[20:23], v[22:25], v[88:91], v[84:87]
	v_ashrrev_i32_e32 v69, 31, v68
	v_mfma_f32_16x16x32_bf16 v[84:87], v[30:33], v[88:91], v[38:41]
	ds_read2_b64 v[30:33], v96 offset0:232 offset1:236
	s_waitcnt lgkmcnt(0)
	v_mfma_f32_16x16x32_bf16 v[88:91], v[30:33], v[88:91], v[42:45]
	s_nop 0
	s_waitcnt lgkmcnt(0)
	global_load_dwordx4 v[96:99], v[142:143], off offset:192
	global_load_dwordx4 v[100:103], v[150:151], off
	global_load_dwordx4 v[104:107], v[150:151], off offset:64
	s_waitcnt vmcnt(22)
	v_mfma_f32_16x16x32_bf16 v[36:39], v[160:163], v[56:59], 0
	v_mfma_f32_16x16x32_bf16 v[36:39], v[164:167], v[60:63], v[36:39]
	v_mfma_f32_16x16x32_bf16 v[36:39], v[168:171], v[52:55], v[36:39]
	v_mfma_f32_16x16x32_bf16 v[36:39], v[172:175], v[48:51], v[36:39]
	global_load_dwordx4 v[160:163], v[150:151], off offset:128
	global_load_dwordx4 v[164:167], v[150:151], off offset:192
	global_load_dwordx4 v[168:171], v[152:153], off
	global_load_dwordx4 v[172:175], v[152:153], off offset:64
	s_waitcnt vmcnt(22)
	v_mfma_f32_16x16x32_bf16 v[24:27], v[176:179], v[56:59], 0
	v_mfma_f32_16x16x32_bf16 v[24:27], v[180:183], v[60:63], v[24:27]
	v_mfma_f32_16x16x32_bf16 v[24:27], v[184:187], v[52:55], v[24:27]
	v_mfma_f32_16x16x32_bf16 v[24:27], v[188:191], v[48:51], v[24:27]
	global_load_dwordx4 v[176:179], v[152:153], off offset:128
	global_load_dwordx4 v[180:183], v[152:153], off offset:192
	s_waitcnt vmcnt(20)
	v_mfma_f32_16x16x32_bf16 v[28:31], v[192:195], v[56:59], 0
	v_mfma_f32_16x16x32_bf16 v[28:31], v[196:199], v[60:63], v[28:31]
	v_mfma_f32_16x16x32_bf16 v[28:31], v[200:203], v[52:55], v[28:31]
	v_mfma_f32_16x16x32_bf16 v[28:31], v[204:207], v[48:51], v[28:31]
	s_waitcnt vmcnt(16)
	v_mfma_f32_16x16x32_bf16 v[32:35], v[208:211], v[56:59], 0
	v_mfma_f32_16x16x32_bf16 v[32:35], v[212:215], v[60:63], v[32:35]
	v_mfma_f32_16x16x32_bf16 v[32:35], v[216:219], v[52:55], v[32:35]
	v_mfma_f32_16x16x32_bf16 v[32:35], v[220:223], v[48:51], v[32:35]
	s_waitcnt vmcnt(12)
	v_mfma_f32_16x16x32_bf16 v[40:43], v[224:227], v[56:59], 0
	v_mfma_f32_16x16x32_bf16 v[40:43], v[228:231], v[60:63], v[40:43]
	v_mfma_f32_16x16x32_bf16 v[40:43], v[232:235], v[52:55], v[40:43]
	v_mfma_f32_16x16x32_bf16 v[40:43], v[236:239], v[48:51], v[40:43]
	s_waitcnt vmcnt(8)
	v_mfma_f32_16x16x32_bf16 v[44:47], v[240:243], v[56:59], 0
	v_mfma_f32_16x16x32_bf16 v[44:47], v[244:247], v[60:63], v[44:47]
	v_mfma_f32_16x16x32_bf16 v[44:47], v[248:251], v[52:55], v[44:47]
	v_mfma_f32_16x16x32_bf16 v[44:47], v[96:99], v[48:51], v[44:47]
	s_waitcnt vmcnt(4)
	v_mfma_f32_16x16x32_bf16 v[92:95], v[100:103], v[56:59], 0
	v_mfma_f32_16x16x32_bf16 v[92:95], v[104:107], v[60:63], v[92:95]
	v_mfma_f32_16x16x32_bf16 v[92:95], v[160:163], v[52:55], v[92:95]
	v_mfma_f32_16x16x32_bf16 v[92:95], v[164:167], v[48:51], v[92:95]
	s_waitcnt vmcnt(0)
	v_mfma_f32_16x16x32_bf16 v[56:59], v[168:171], v[56:59], 0
	v_mfma_f32_16x16x32_bf16 v[56:59], v[172:175], v[60:63], v[56:59]
	v_mfma_f32_16x16x32_bf16 v[52:55], v[176:179], v[52:55], v[56:59]
	v_mfma_f32_16x16x32_bf16 v[48:51], v[180:183], v[48:51], v[52:55]
	v_readlane_b32 s15, v255, 13
	v_readlane_b32 s16, v255, 14
	v_readlane_b32 s17, v255, 15
	v_readlane_b32 s18, v255, 16
	v_readlane_b32 s19, v255, 17
	s_waitcnt lgkmcnt(0)
	s_nop 5
	s_waitcnt lgkmcnt(0)
	s_nop 2
	s_nop 2
	s_waitcnt lgkmcnt(0)
	s_nop 0
	s_nop 3
	s_waitcnt lgkmcnt(0)
	s_waitcnt lgkmcnt(0)
	s_waitcnt lgkmcnt(0)
	s_nop 0
	s_waitcnt lgkmcnt(0)
	s_nop 0
	s_waitcnt lgkmcnt(0)
	s_waitcnt lgkmcnt(0)
	s_nop 0
	s_waitcnt lgkmcnt(0)
	v_lshl_add_u64 v[100:101], v[68:69], 0, v[76:77]
	v_mad_u64_u32 v[60:61], s[0:1], v100, s57, v[66:67]
	v_mad_i32_i24 v61, v101, s57, v61
	v_lshl_add_u64 v[60:61], v[60:61], 0, v[72:73]
	v_lshl_add_u64 v[102:103], v[60:61], 0, v[64:65]
	v_add_co_u32_e32 v60, vcc, s63, v102
	s_waitcnt lgkmcnt(0)
	v_addc_co_u32_e32 v61, vcc, 0, v103, vcc
	global_load_dwordx2 v[68:69], v[60:61], off offset:512
	s_nop 0
	v_add_u32_e32 v56, 1, v76
	v_cvt_f32_ubyte0_e32 v56, v56
	v_mul_f32_e32 v57, v83, v56
	v_cmp_gt_f32_e32 vcc, s53, v57
	s_waitcnt vmcnt(0) lgkmcnt(0)
	v_lshlrev_b32_e32 v77, 16, v68
	v_cndmask_b32_e32 v57, 0, v78, vcc
	v_fmac_f32_e32 v57, v83, v56
	v_exp_f32_e32 v56, v57
	v_cndmask_b32_e32 v52, 0, v79, vcc
	v_and_b32_e32 v68, 0xffff0000, v68
	v_cmp_lt_i32_e32 vcc, v157, v156
	v_ldexp_f32 v62, v56, v52
	v_pk_fma_f32 v[58:59], v[62:63], v[50:51], v[90:91] op_sel_hi:[0,1,1]
	v_lshlrev_b64 v[50:51], 11, v[100:101]
	v_lshl_add_u64 v[50:51], s[30:31], 0, v[50:51]
	v_lshl_add_u64 v[52:53], v[50:51], 0, v[72:73]
	v_mul_f32_e32 v72, 0xbfb8aa3b, v77
	v_pk_fma_f32 v[54:55], v[62:63], v[92:93], v[84:85] op_sel_hi:[0,1,1]
	v_exp_f32_e32 v84, v72
	v_mul_f32_e32 v72, 0xbfb8aa3b, v68
	v_exp_f32_e32 v85, v72
	v_pk_fma_f32 v[60:61], v[62:63], v[48:49], v[88:89] op_sel_hi:[0,1,1]
	v_cndmask_b32_e32 v48, v155, v157, vcc
	v_cmp_lt_i32_e32 vcc, v158, v156
	v_lshlrev_b32_e32 v76, 2, v48
	v_pk_fma_f32 v[56:57], v[62:63], v[94:95], v[86:87] op_sel_hi:[0,1,1]
	v_cndmask_b32_e32 v48, v155, v158, vcc
	v_lshlrev_b32_e32 v63, 2, v48
	v_pk_fma_f32 v[18:19], v[62:63], v[38:39], v[18:19] op_sel_hi:[0,1,1]
	v_pk_add_f32 v[38:39], v[84:85], 1.0 op_sel_hi:[1,0]
	v_lshlrev_b32_e32 v83, 16, v69
	v_and_b32_e32 v86, 0xffff0000, v69
	v_div_scale_f32 v69, s[0:1], v39, v39, v68
	v_rcp_f32_e32 v84, v69
	v_pk_fma_f32 v[16:17], v[62:63], v[36:37], v[16:17] op_sel_hi:[0,1,1]
	v_add_f32_e32 v36, 0, v16
	v_add_f32_e32 v85, v17, v36
	v_fma_f32 v36, -v69, v84, 1.0
	v_fmac_f32_e32 v84, v36, v84
	v_div_scale_f32 v36, vcc, v68, v39, v68
	v_mul_f32_e32 v37, v36, v84
	v_fma_f32 v87, -v69, v37, v36
	v_fmac_f32_e32 v37, v87, v84
	v_div_scale_f32 v87, s[0:1], v38, v38, v77
	v_rcp_f32_e32 v88, v87
	v_fma_f32 v36, -v69, v37, v36
	v_div_fmas_f32 v36, v36, v84, v37
	v_div_fixup_f32 v37, v36, v39, v68
	v_fma_f32 v36, -v87, v88, 1.0
	v_fmac_f32_e32 v88, v36, v88
	v_div_scale_f32 v36, vcc, v77, v38, v77
	v_mul_f32_e32 v39, v36, v88
	v_fma_f32 v68, -v87, v39, v36
	v_fmac_f32_e32 v39, v68, v88
	v_fma_f32 v36, -v87, v39, v36
	v_div_fmas_f32 v36, v36, v88, v39
	v_div_fixup_f32 v36, v36, v38, v77
	v_add_f32_e32 v38, v18, v85
	v_add_f32_e32 v38, v19, v38
	v_pk_fma_f32 v[0:1], v[62:63], v[24:25], v[0:1] op_sel_hi:[0,1,1]
	v_add_f32_e32 v24, v38, v0
	v_pk_fma_f32 v[2:3], v[62:63], v[26:27], v[2:3] op_sel_hi:[0,1,1]
	v_add_f32_e32 v24, v1, v24
	v_add_f32_e32 v24, v2, v24
	v_add_f32_e32 v24, v3, v24
	v_pk_fma_f32 v[4:5], v[62:63], v[28:29], v[4:5] op_sel_hi:[0,1,1]
	v_add_f32_e32 v24, v24, v4
	v_pk_fma_f32 v[6:7], v[62:63], v[30:31], v[6:7] op_sel_hi:[0,1,1]
	v_add_f32_e32 v24, v5, v24
	v_add_f32_e32 v24, v6, v24
	v_add_f32_e32 v24, v7, v24
	v_pk_fma_f32 v[8:9], v[62:63], v[32:33], v[8:9] op_sel_hi:[0,1,1]
	v_add_f32_e32 v24, v24, v8
	v_pk_fma_f32 v[10:11], v[62:63], v[34:35], v[10:11] op_sel_hi:[0,1,1]
	v_add_f32_e32 v24, v9, v24
	v_add_f32_e32 v24, v10, v24
	v_add_f32_e32 v24, v11, v24
	v_pk_fma_f32 v[12:13], v[62:63], v[40:41], v[12:13] op_sel_hi:[0,1,1]
	v_add_f32_e32 v24, v24, v12
	v_pk_fma_f32 v[14:15], v[62:63], v[42:43], v[14:15] op_sel_hi:[0,1,1]
	v_add_f32_e32 v24, v13, v24
	v_lshl_add_u64 v[48:49], v[70:71], 2, s[6:7]
	v_add_f32_e32 v24, v14, v24
	v_lshl_add_u64 v[48:49], v[48:49], 0, v[74:75]
	v_add_f32_e32 v28, v15, v24
	v_pk_fma_f32 v[26:27], v[62:63], v[44:45], v[20:21] op_sel_hi:[0,1,1]
	global_load_dwordx4 v[72:75], v[48:49], off
	v_add_f32_e32 v20, v28, v26
	v_pk_fma_f32 v[24:25], v[62:63], v[46:47], v[22:23] op_sel_hi:[0,1,1]
	v_add_f32_e32 v20, v27, v20
	v_add_f32_e32 v20, v24, v20
	v_add_f32_e32 v20, v25, v20
	v_add_f32_e32 v20, v20, v54
	v_add_f32_e32 v20, v55, v20
	v_mul_f32_e32 v68, 0xbfb8aa3b, v83
	v_mul_f32_e32 v69, 0xbfb8aa3b, v86
	v_add_f32_e32 v20, v56, v20
	v_exp_f32_e32 v68, v68
	v_exp_f32_e32 v69, v69
	v_add_f32_e32 v20, v57, v20
	v_add_f32_e32 v20, v20, v60
	v_add_f32_e32 v20, v61, v20
	v_add_f32_e32 v20, v58, v20
	v_pk_add_f32 v[68:69], v[68:69], 1.0 op_sel_hi:[1,0]
	v_add_f32_e32 v20, v59, v20
	v_div_scale_f32 v39, s[0:1], v69, v69, v86
	ds_bpermute_b32 v21, v76, v20
	v_rcp_f32_e32 v84, v39
	v_lshl_add_u64 v[50:51], v[102:103], 0, s[46:47]
	global_load_dwordx2 v[70:71], v[50:51], off offset:224
	global_load_dwordx2 v[30:31], v[50:51], off offset:32
	v_fma_f32 v77, -v39, v84, 1.0
	s_waitcnt lgkmcnt(0)
	v_add_f32_e32 v20, v20, v21
	v_fmac_f32_e32 v84, v77, v84
	v_div_scale_f32 v77, vcc, v86, v69, v86
	ds_bpermute_b32 v21, v63, v20
	v_mul_f32_e32 v85, v77, v84
	v_fma_f32 v87, -v39, v85, v77
	v_fmac_f32_e32 v85, v87, v84
	v_fma_f32 v22, -v39, v85, v77
	v_div_fmas_f32 v22, v22, v84, v85
	s_waitcnt lgkmcnt(0)
	v_add_f32_e32 v20, v20, v21
	v_div_fixup_f32 v29, v22, v69, v86
	v_mul_f32_e32 v28, 0x3c000000, v20
	v_pk_add_f32 v[32:33], v[16:17], v[28:29] op_sel_hi:[1,0] neg_lo:[0,1] neg_hi:[0,1]
	v_pk_add_f32 v[38:39], v[18:19], v[28:29] op_sel_hi:[1,0] neg_lo:[0,1] neg_hi:[0,1]
	v_pk_mul_f32 v[34:35], v[32:33], v[32:33]
	v_pk_mul_f32 v[40:41], v[38:39], v[38:39]
	v_pk_add_f32 v[42:43], v[0:1], v[28:29] op_sel_hi:[1,0] neg_lo:[0,1] neg_hi:[0,1]
	v_pk_add_f32 v[46:47], v[2:3], v[28:29] op_sel_hi:[1,0] neg_lo:[0,1] neg_hi:[0,1]
	v_pk_add_f32 v[84:85], v[4:5], v[28:29] op_sel_hi:[1,0] neg_lo:[0,1] neg_hi:[0,1]
	v_pk_add_f32 v[88:89], v[6:7], v[28:29] op_sel_hi:[1,0] neg_lo:[0,1] neg_hi:[0,1]
	v_pk_add_f32 v[22:23], v[8:9], v[28:29] op_sel_hi:[1,0] neg_lo:[0,1] neg_hi:[0,1]
	v_pk_add_f32 v[20:21], v[10:11], v[28:29] op_sel_hi:[1,0] neg_lo:[0,1] neg_hi:[0,1]
	v_pk_add_f32 v[18:19], v[12:13], v[28:29] op_sel_hi:[1,0] neg_lo:[0,1] neg_hi:[0,1]
	v_pk_add_f32 v[16:17], v[14:15], v[28:29] op_sel_hi:[1,0] neg_lo:[0,1] neg_hi:[0,1]
	v_pk_add_f32 v[14:15], v[26:27], v[28:29] op_sel_hi:[1,0] neg_lo:[0,1] neg_hi:[0,1]
	v_pk_add_f32 v[12:13], v[24:25], v[28:29] op_sel_hi:[1,0] neg_lo:[0,1] neg_hi:[0,1]
	v_pk_add_f32 v[4:5], v[60:61], v[28:29] op_sel_hi:[1,0] neg_lo:[0,1] neg_hi:[0,1]
	v_pk_add_f32 v[0:1], v[58:59], v[28:29] op_sel_hi:[1,0] neg_lo:[0,1] neg_hi:[0,1]
	v_pk_add_f32 v[8:9], v[56:57], v[28:29] op_sel_hi:[1,0] neg_lo:[0,1] neg_hi:[0,1]
	v_pk_add_f32 v[10:11], v[54:55], v[28:29] op_sel_hi:[1,0] neg_lo:[0,1] neg_hi:[0,1]
	v_add_f32_e32 v28, v34, v35
	v_add_f32_e32 v28, v40, v28
	v_pk_mul_f32 v[44:45], v[42:43], v[42:43]
	v_add_f32_e32 v28, v41, v28
	v_add_f32_e32 v28, v44, v28
	v_pk_mul_f32 v[2:3], v[46:47], v[46:47]
	v_add_f32_e32 v28, v45, v28
	v_add_f32_e32 v2, v2, v28
	v_pk_mul_f32 v[86:87], v[84:85], v[84:85]
	v_add_f32_e32 v2, v3, v2
	v_add_f32_e32 v2, v86, v2
	v_pk_mul_f32 v[6:7], v[88:89], v[88:89]
	v_add_f32_e32 v2, v87, v2
	v_add_f32_e32 v2, v6, v2
	v_pk_mul_f32 v[90:91], v[22:23], v[22:23]
	v_add_f32_e32 v2, v7, v2
	v_add_f32_e32 v2, v90, v2
	v_pk_mul_f32 v[92:93], v[20:21], v[20:21]
	v_add_f32_e32 v2, v91, v2
	v_add_f32_e32 v2, v92, v2
	v_pk_mul_f32 v[94:95], v[18:19], v[18:19]
	v_add_f32_e32 v2, v93, v2
	v_add_f32_e32 v2, v94, v2
	v_pk_mul_f32 v[96:97], v[16:17], v[16:17]
	v_add_f32_e32 v2, v95, v2
	v_add_f32_e32 v2, v96, v2
	v_pk_mul_f32 v[26:27], v[14:15], v[14:15]
	v_add_f32_e32 v2, v97, v2
	v_add_f32_e32 v2, v26, v2
	v_pk_mul_f32 v[24:25], v[12:13], v[12:13]
	v_add_f32_e32 v2, v27, v2
	v_add_f32_e32 v2, v24, v2
	v_pk_mul_f32 v[54:55], v[10:11], v[10:11]
	v_add_f32_e32 v2, v25, v2
	v_add_f32_e32 v2, v54, v2
	v_pk_mul_f32 v[56:57], v[8:9], v[8:9]
	v_add_f32_e32 v2, v55, v2
	v_add_f32_e32 v2, v56, v2
	v_pk_mul_f32 v[60:61], v[4:5], v[4:5]
	v_add_f32_e32 v2, v57, v2
	v_add_f32_e32 v2, v60, v2
	v_pk_mul_f32 v[58:59], v[0:1], v[0:1]
	v_add_f32_e32 v2, v61, v2
	v_add_f32_e32 v2, v58, v2
	v_add_f32_e32 v2, v59, v2
	ds_bpermute_b32 v3, v76, v2
	v_div_scale_f32 v62, s[0:1], v68, v68, v83
	v_rcp_f32_e32 v69, v62
	s_waitcnt vmcnt(0)
	v_lshlrev_b32_e32 v40, 16, v31
	s_waitcnt lgkmcnt(0)
	v_add_f32_e32 v2, v2, v3
	ds_bpermute_b32 v3, v63, v2
	v_fma_f32 v6, -v62, v69, 1.0
	v_fmac_f32_e32 v69, v6, v69
	v_div_scale_f32 v6, vcc, v83, v68, v83
	s_waitcnt lgkmcnt(0)
	v_add_f32_e32 v2, v2, v3
	v_fmamk_f32 v2, v2, 0x3c000000, v81
	v_mul_f32_e32 v7, v6, v69
	v_mul_f32_e32 v3, 0x4b800000, v2
	v_cmp_gt_f32_e64 s[0:1], s54, v2
	v_fma_f32 v24, -v62, v7, v6
	v_fmac_f32_e32 v7, v24, v69
	v_cndmask_b32_e64 v2, v2, v3, s[0:1]
	v_rsq_f32_e32 v24, v2
	v_fma_f32 v6, -v62, v7, v6
	v_div_fmas_f32 v2, v6, v69, v7
	v_div_fixup_f32 v28, v2, v68, v83
	v_mul_f32_e32 v6, 0x45800000, v24
	v_cndmask_b32_e64 v6, v24, v6, s[0:1]
	v_pk_mul_f32 v[24:25], v[32:33], v[6:7] op_sel_hi:[1,0]
	v_pk_mul_f32 v[26:27], v[38:39], v[6:7] op_sel_hi:[1,0]
	v_pk_mul_f32 v[24:25], v[72:73], v[24:25]
	v_pk_mul_f32 v[26:27], v[74:75], v[26:27]
	v_pk_mul_f32 v[24:25], v[36:37], v[24:25]
	v_pk_mul_f32 v[26:27], v[28:29], v[26:27]
	v_lshl_add_u64 v[2:3], v[52:53], 0, v[64:65]
	v_cvt_pk_bf16_f32 v24, v24, v25
	v_cvt_pk_bf16_f32 v25, v26, v27
	global_store_dwordx2 v[2:3], v[24:25], off
	global_load_dwordx4 v[24:27], v[48:49], off offset:64
	s_nop 0
	global_load_dwordx2 v[28:29], v[50:51], off offset:64
	global_load_dwordx2 v[32:33], v[50:51], off offset:96
	global_load_dwordx2 v[34:35], v[50:51], off offset:128
	v_lshlrev_b32_e32 v7, 16, v30
	v_and_b32_e32 v30, 0xffff0000, v30
	v_mul_f32_e32 v36, 0xbfb8aa3b, v7
	v_mul_f32_e32 v37, 0xbfb8aa3b, v30
	v_exp_f32_e32 v36, v36
	v_exp_f32_e32 v37, v37
	v_and_b32_e32 v41, 0xffff0000, v31
	v_pk_add_f32 v[36:37], v[36:37], 1.0 op_sel_hi:[1,0]
	s_nop 0
	v_div_scale_f32 v38, s[0:1], v37, v37, v30
	v_rcp_f32_e32 v39, v38
	s_nop 0
	v_fma_f32 v31, -v38, v39, 1.0
	v_fmac_f32_e32 v39, v31, v39
	v_div_scale_f32 v31, vcc, v30, v37, v30
	v_mul_f32_e32 v44, v31, v39
	v_fma_f32 v45, -v38, v44, v31
	v_fmac_f32_e32 v44, v45, v39
	v_div_scale_f32 v45, s[0:1], v36, v36, v7
	v_rcp_f32_e32 v52, v45
	v_fma_f32 v31, -v38, v44, v31
	v_div_fmas_f32 v31, v31, v39, v44
	v_mul_f32_e32 v38, 0xbfb8aa3b, v40
	v_mul_f32_e32 v39, 0xbfb8aa3b, v41
	v_exp_f32_e32 v38, v38
	v_exp_f32_e32 v39, v39
	v_div_fixup_f32 v31, v31, v37, v30
	v_fma_f32 v30, -v45, v52, 1.0
	v_fmac_f32_e32 v52, v30, v52
	v_div_scale_f32 v30, vcc, v7, v36, v7
	v_mul_f32_e32 v37, v30, v52
	v_fma_f32 v44, -v45, v37, v30
	v_pk_add_f32 v[38:39], v[38:39], 1.0 op_sel_hi:[1,0]
	v_fmac_f32_e32 v37, v44, v52
	v_div_scale_f32 v44, s[0:1], v39, v39, v41
	v_fma_f32 v30, -v45, v37, v30
	v_rcp_f32_e32 v45, v44
	v_div_fmas_f32 v30, v30, v52, v37
	v_div_fixup_f32 v30, v30, v36, v7
	v_fma_f32 v7, -v44, v45, 1.0
	v_fmac_f32_e32 v45, v7, v45
	v_div_scale_f32 v7, vcc, v41, v39, v41
	v_mul_f32_e32 v36, v7, v45
	v_fma_f32 v37, -v44, v36, v7
	v_fmac_f32_e32 v36, v37, v45
	v_fma_f32 v7, -v44, v36, v7
	v_div_scale_f32 v44, s[0:1], v38, v38, v40
	v_rcp_f32_e32 v52, v44
	v_div_fmas_f32 v7, v7, v45, v36
	v_div_fixup_f32 v37, v7, v39, v41
	v_fma_f32 v7, -v44, v52, 1.0
	v_fmac_f32_e32 v52, v7, v52
	v_div_scale_f32 v7, vcc, v40, v38, v40
	v_mul_f32_e32 v36, v7, v52
	v_fma_f32 v39, -v44, v36, v7
	v_fmac_f32_e32 v36, v39, v52
	v_fma_f32 v7, -v44, v36, v7
	v_div_fmas_f32 v7, v7, v52, v36
	v_div_fixup_f32 v36, v7, v38, v40
	v_pk_mul_f32 v[38:39], v[42:43], v[6:7] op_sel_hi:[1,0]
	s_waitcnt vmcnt(0)
	v_pk_mul_f32 v[24:25], v[24:25], v[38:39]
	s_nop 0
	v_pk_mul_f32 v[24:25], v[30:31], v[24:25]
	v_pk_mul_f32 v[30:31], v[46:47], v[6:7] op_sel_hi:[1,0]
	v_cvt_pk_bf16_f32 v24, v24, v25
	v_pk_mul_f32 v[26:27], v[26:27], v[30:31]
	s_waitcnt lgkmcnt(0)
	v_lshlrev_b32_e32 v7, 16, v28
	v_pk_mul_f32 v[26:27], v[36:37], v[26:27]
	v_and_b32_e32 v28, 0xffff0000, v28
	v_cvt_pk_bf16_f32 v25, v26, v27
	global_store_dwordx2 v[2:3], v[24:25], off offset:32
	global_load_dwordx4 v[24:27], v[48:49], off offset:128
	v_mul_f32_e32 v30, 0xbfb8aa3b, v7
	v_mul_f32_e32 v31, 0xbfb8aa3b, v28
	v_exp_f32_e32 v30, v30
	v_exp_f32_e32 v31, v31
	v_lshlrev_b32_e32 v38, 16, v29
	v_and_b32_e32 v39, 0xffff0000, v29
	v_pk_add_f32 v[30:31], v[30:31], 1.0 op_sel_hi:[1,0]
	s_nop 0
	v_div_scale_f32 v36, s[0:1], v31, v31, v28
	v_rcp_f32_e32 v37, v36
	s_nop 0
	v_fma_f32 v29, -v36, v37, 1.0
	v_fmac_f32_e32 v37, v29, v37
	v_div_scale_f32 v29, vcc, v28, v31, v28
	v_mul_f32_e32 v40, v29, v37
	v_fma_f32 v41, -v36, v40, v29
	v_fmac_f32_e32 v40, v41, v37
	v_div_scale_f32 v41, s[0:1], v30, v30, v7
	v_rcp_f32_e32 v42, v41
	v_fma_f32 v29, -v36, v40, v29
	v_div_fmas_f32 v29, v29, v37, v40
	v_mul_f32_e32 v36, 0xbfb8aa3b, v38
	v_mul_f32_e32 v37, 0xbfb8aa3b, v39
	v_exp_f32_e32 v36, v36
	v_exp_f32_e32 v37, v37
	v_div_fixup_f32 v29, v29, v31, v28
	v_fma_f32 v28, -v41, v42, 1.0
	v_fmac_f32_e32 v42, v28, v42
	v_div_scale_f32 v28, vcc, v7, v30, v7
	v_mul_f32_e32 v31, v28, v42
	v_fma_f32 v40, -v41, v31, v28
	v_pk_add_f32 v[36:37], v[36:37], 1.0 op_sel_hi:[1,0]
	v_fmac_f32_e32 v31, v40, v42
	v_div_scale_f32 v40, s[0:1], v37, v37, v39
	v_fma_f32 v28, -v41, v31, v28
	v_rcp_f32_e32 v41, v40
	v_div_fmas_f32 v28, v28, v42, v31
	v_div_fixup_f32 v28, v28, v30, v7
	v_fma_f32 v7, -v40, v41, 1.0
	v_fmac_f32_e32 v41, v7, v41
	v_div_scale_f32 v7, vcc, v39, v37, v39
	v_mul_f32_e32 v30, v7, v41
	v_fma_f32 v31, -v40, v30, v7
	v_fmac_f32_e32 v30, v31, v41
	v_fma_f32 v7, -v40, v30, v7
	v_div_scale_f32 v40, s[0:1], v36, v36, v38
	v_rcp_f32_e32 v42, v40
	v_div_fmas_f32 v7, v7, v41, v30
	v_div_fixup_f32 v31, v7, v37, v39
	v_fma_f32 v7, -v40, v42, 1.0
	v_fmac_f32_e32 v42, v7, v42
	v_div_scale_f32 v7, vcc, v38, v36, v38
	v_mul_f32_e32 v30, v7, v42
	v_fma_f32 v37, -v40, v30, v7
	v_fmac_f32_e32 v30, v37, v42
	v_fma_f32 v7, -v40, v30, v7
	v_div_fmas_f32 v7, v7, v42, v30
	v_div_fixup_f32 v30, v7, v36, v38
	v_pk_mul_f32 v[36:37], v[84:85], v[6:7] op_sel_hi:[1,0]
	s_waitcnt vmcnt(0)
	v_pk_mul_f32 v[24:25], v[24:25], v[36:37]
	s_nop 0
	v_pk_mul_f32 v[24:25], v[28:29], v[24:25]
	v_pk_mul_f32 v[28:29], v[88:89], v[6:7] op_sel_hi:[1,0]
	v_cvt_pk_bf16_f32 v24, v24, v25
	v_pk_mul_f32 v[26:27], v[26:27], v[28:29]
	v_lshlrev_b32_e32 v7, 16, v32
	v_pk_mul_f32 v[26:27], v[30:31], v[26:27]
	v_and_b32_e32 v30, 0xffff0000, v32
	v_cvt_pk_bf16_f32 v25, v26, v27
	global_store_dwordx2 v[2:3], v[24:25], off offset:64
	global_load_dwordx4 v[24:27], v[48:49], off offset:192
	v_mul_f32_e32 v28, 0xbfb8aa3b, v7
	v_mul_f32_e32 v29, 0xbfb8aa3b, v30
	v_exp_f32_e32 v28, v28
	v_exp_f32_e32 v29, v29
	v_lshlrev_b32_e32 v36, 16, v33
	v_and_b32_e32 v33, 0xffff0000, v33
	v_pk_add_f32 v[28:29], v[28:29], 1.0 op_sel_hi:[1,0]
	s_nop 0
	v_div_scale_f32 v31, s[0:1], v29, v29, v30
	v_rcp_f32_e32 v32, v31
	s_nop 0
	v_fma_f32 v37, -v31, v32, 1.0
	v_fmac_f32_e32 v32, v37, v32
	v_div_scale_f32 v37, vcc, v30, v29, v30
	v_mul_f32_e32 v38, v37, v32
	v_fma_f32 v39, -v31, v38, v37
	v_fmac_f32_e32 v38, v39, v32
	v_fma_f32 v31, -v31, v38, v37
	v_div_scale_f32 v37, s[0:1], v28, v28, v7
	v_rcp_f32_e32 v39, v37
	v_div_fmas_f32 v31, v31, v32, v38
	v_div_fixup_f32 v29, v31, v29, v30
	v_mul_f32_e32 v31, 0xbfb8aa3b, v33
	v_fma_f32 v30, -v37, v39, 1.0
	v_fmac_f32_e32 v39, v30, v39
	v_mul_f32_e32 v30, 0xbfb8aa3b, v36
	v_exp_f32_e32 v30, v30
	v_exp_f32_e32 v31, v31
	v_div_scale_f32 v32, vcc, v7, v28, v7
	v_mul_f32_e32 v38, v32, v39
	v_fma_f32 v40, -v37, v38, v32
	v_fmac_f32_e32 v38, v40, v39
	v_pk_add_f32 v[30:31], v[30:31], 1.0 op_sel_hi:[1,0]
	v_fma_f32 v32, -v37, v38, v32
	v_div_scale_f32 v37, s[0:1], v31, v31, v33
	v_rcp_f32_e32 v40, v37
	v_div_fmas_f32 v32, v32, v39, v38
	v_div_fixup_f32 v28, v32, v28, v7
	v_fma_f32 v7, -v37, v40, 1.0
	v_fmac_f32_e32 v40, v7, v40
	v_div_scale_f32 v7, vcc, v33, v31, v33
	v_mul_f32_e32 v32, v7, v40
	v_fma_f32 v38, -v37, v32, v7
	v_fmac_f32_e32 v32, v38, v40
	v_fma_f32 v7, -v37, v32, v7
	v_div_scale_f32 v37, s[0:1], v30, v30, v36
	v_rcp_f32_e32 v38, v37
	v_div_fmas_f32 v7, v7, v40, v32
	v_div_fixup_f32 v31, v7, v31, v33
	v_fma_f32 v7, -v37, v38, 1.0
	v_fmac_f32_e32 v38, v7, v38
	v_div_scale_f32 v7, vcc, v36, v30, v36
	v_mul_f32_e32 v32, v7, v38
	v_fma_f32 v33, -v37, v32, v7
	v_fmac_f32_e32 v32, v33, v38
	v_fma_f32 v7, -v37, v32, v7
	v_div_fmas_f32 v7, v7, v38, v32
	v_pk_mul_f32 v[22:23], v[22:23], v[6:7] op_sel_hi:[1,0]
	v_pk_mul_f32 v[20:21], v[20:21], v[6:7] op_sel_hi:[1,0]
	v_div_fixup_f32 v30, v7, v30, v36
	v_lshlrev_b32_e32 v7, 16, v34
	v_and_b32_e32 v32, 0xffff0000, v35
	s_waitcnt vmcnt(0)
	v_pk_mul_f32 v[22:23], v[24:25], v[22:23]
	v_pk_mul_f32 v[20:21], v[26:27], v[20:21]
	v_pk_mul_f32 v[22:23], v[28:29], v[22:23]
	v_pk_mul_f32 v[20:21], v[30:31], v[20:21]
	v_cvt_pk_bf16_f32 v22, v22, v23
	v_cvt_pk_bf16_f32 v23, v20, v21
	global_store_dwordx2 v[2:3], v[22:23], off offset:96
	global_load_dwordx4 v[20:23], v[48:49], off offset:256
	v_and_b32_e32 v28, 0xffff0000, v34
	v_mul_f32_e32 v24, 0xbfb8aa3b, v7
	v_mul_f32_e32 v25, 0xbfb8aa3b, v28
	v_exp_f32_e32 v24, v24
	v_exp_f32_e32 v25, v25
	global_load_dwordx2 v[26:27], v[50:51], off offset:160
	v_lshlrev_b32_e32 v31, 16, v35
	v_pk_add_f32 v[24:25], v[24:25], 1.0 op_sel_hi:[1,0]
	s_nop 0
	v_div_scale_f32 v29, s[0:1], v25, v25, v28
	v_rcp_f32_e32 v30, v29
	s_nop 0
	v_fma_f32 v33, -v29, v30, 1.0
	v_fmac_f32_e32 v30, v33, v30
	v_div_scale_f32 v33, vcc, v28, v25, v28
	v_mul_f32_e32 v34, v33, v30
	v_fma_f32 v35, -v29, v34, v33
	v_fmac_f32_e32 v34, v35, v30
	v_fma_f32 v29, -v29, v34, v33
	v_div_scale_f32 v33, s[0:1], v24, v24, v7
	v_rcp_f32_e32 v35, v33
	v_div_fmas_f32 v29, v29, v30, v34
	v_div_fixup_f32 v25, v29, v25, v28
	v_mul_f32_e32 v29, 0xbfb8aa3b, v32
	v_fma_f32 v28, -v33, v35, 1.0
	v_fmac_f32_e32 v35, v28, v35
	v_mul_f32_e32 v28, 0xbfb8aa3b, v31
	v_exp_f32_e32 v28, v28
	v_exp_f32_e32 v29, v29
	v_div_scale_f32 v30, vcc, v7, v24, v7
	v_mul_f32_e32 v34, v30, v35
	v_fma_f32 v36, -v33, v34, v30
	v_fmac_f32_e32 v34, v36, v35
	v_pk_add_f32 v[28:29], v[28:29], 1.0 op_sel_hi:[1,0]
	v_fma_f32 v30, -v33, v34, v30
	v_div_scale_f32 v33, s[0:1], v29, v29, v32
	v_rcp_f32_e32 v36, v33
	v_div_fmas_f32 v30, v30, v35, v34
	v_div_fixup_f32 v24, v30, v24, v7
	v_fma_f32 v7, -v33, v36, 1.0
	v_fmac_f32_e32 v36, v7, v36
	v_div_scale_f32 v7, vcc, v32, v29, v32
	v_mul_f32_e32 v30, v7, v36
	v_fma_f32 v34, -v33, v30, v7
	v_fmac_f32_e32 v30, v34, v36
	v_fma_f32 v7, -v33, v30, v7
	v_div_scale_f32 v33, s[0:1], v28, v28, v31
	v_rcp_f32_e32 v34, v33
	v_div_fmas_f32 v7, v7, v36, v30
	v_div_fixup_f32 v29, v7, v29, v32
	v_fma_f32 v7, -v33, v34, 1.0
	v_fmac_f32_e32 v34, v7, v34
	v_div_scale_f32 v7, vcc, v31, v28, v31
	v_mul_f32_e32 v30, v7, v34
	v_fma_f32 v32, -v33, v30, v7
	v_fmac_f32_e32 v30, v32, v34
	v_fma_f32 v7, -v33, v30, v7
	v_div_fmas_f32 v7, v7, v34, v30
	v_pk_mul_f32 v[18:19], v[18:19], v[6:7] op_sel_hi:[1,0]
	v_pk_mul_f32 v[16:17], v[16:17], v[6:7] op_sel_hi:[1,0]
	v_div_fixup_f32 v28, v7, v28, v31
	s_waitcnt vmcnt(0)
	v_pk_mul_f32 v[18:19], v[20:21], v[18:19]
	v_pk_mul_f32 v[16:17], v[22:23], v[16:17]
	v_pk_mul_f32 v[18:19], v[24:25], v[18:19]
	v_pk_mul_f32 v[16:17], v[28:29], v[16:17]
	v_cvt_pk_bf16_f32 v18, v18, v19
	v_cvt_pk_bf16_f32 v19, v16, v17
	global_store_dwordx2 v[2:3], v[18:19], off offset:128
	global_load_dwordx4 v[16:19], v[48:49], off offset:320
	s_nop 0
	global_load_dwordx2 v[20:21], v[50:51], off offset:192
	s_waitcnt lgkmcnt(0)
	v_lshlrev_b32_e32 v7, 16, v26
	v_and_b32_e32 v24, 0xffff0000, v26
	v_mul_f32_e32 v22, 0xbfb8aa3b, v7
	v_mul_f32_e32 v23, 0xbfb8aa3b, v24
	v_exp_f32_e32 v22, v22
	v_exp_f32_e32 v23, v23
	v_lshlrev_b32_e32 v28, 16, v27
	v_and_b32_e32 v27, 0xffff0000, v27
	v_pk_add_f32 v[22:23], v[22:23], 1.0 op_sel_hi:[1,0]
	s_nop 0
	v_div_scale_f32 v25, s[0:1], v23, v23, v24
	v_rcp_f32_e32 v26, v25
	s_nop 0
	v_fma_f32 v29, -v25, v26, 1.0
	v_fmac_f32_e32 v26, v29, v26
	v_div_scale_f32 v29, vcc, v24, v23, v24
	v_mul_f32_e32 v30, v29, v26
	v_fma_f32 v31, -v25, v30, v29
	v_fmac_f32_e32 v30, v31, v26
	v_fma_f32 v25, -v25, v30, v29
	v_div_scale_f32 v29, s[0:1], v22, v22, v7
	v_rcp_f32_e32 v31, v29
	v_div_fmas_f32 v25, v25, v26, v30
	v_div_fixup_f32 v23, v25, v23, v24
	v_mul_f32_e32 v25, 0xbfb8aa3b, v27
	v_fma_f32 v24, -v29, v31, 1.0
	v_fmac_f32_e32 v31, v24, v31
	v_mul_f32_e32 v24, 0xbfb8aa3b, v28
	v_exp_f32_e32 v24, v24
	v_exp_f32_e32 v25, v25
	v_div_scale_f32 v26, vcc, v7, v22, v7
	v_mul_f32_e32 v30, v26, v31
	v_fma_f32 v32, -v29, v30, v26
	v_fmac_f32_e32 v30, v32, v31
	v_pk_add_f32 v[24:25], v[24:25], 1.0 op_sel_hi:[1,0]
	v_fma_f32 v26, -v29, v30, v26
	v_div_scale_f32 v29, s[0:1], v25, v25, v27
	v_rcp_f32_e32 v32, v29
	v_div_fmas_f32 v26, v26, v31, v30
	v_div_fixup_f32 v22, v26, v22, v7
	v_fma_f32 v7, -v29, v32, 1.0
	v_fmac_f32_e32 v32, v7, v32
	v_div_scale_f32 v7, vcc, v27, v25, v27
	v_mul_f32_e32 v26, v7, v32
	v_fma_f32 v30, -v29, v26, v7
	v_fmac_f32_e32 v26, v30, v32
	v_fma_f32 v7, -v29, v26, v7
	v_div_scale_f32 v29, s[0:1], v24, v24, v28
	v_rcp_f32_e32 v30, v29
	v_div_fmas_f32 v7, v7, v32, v26
	v_div_fixup_f32 v25, v7, v25, v27
	v_fma_f32 v7, -v29, v30, 1.0
	v_fmac_f32_e32 v30, v7, v30
	v_div_scale_f32 v7, vcc, v28, v24, v28
	v_mul_f32_e32 v26, v7, v30
	v_fma_f32 v27, -v29, v26, v7
	v_fmac_f32_e32 v26, v27, v30
	v_fma_f32 v7, -v29, v26, v7
	v_div_fmas_f32 v7, v7, v30, v26
	v_pk_mul_f32 v[14:15], v[14:15], v[6:7] op_sel_hi:[1,0]
	v_pk_mul_f32 v[12:13], v[12:13], v[6:7] op_sel_hi:[1,0]
	v_div_fixup_f32 v24, v7, v24, v28
	s_waitcnt vmcnt(0)
	v_pk_mul_f32 v[14:15], v[16:17], v[14:15]
	v_pk_mul_f32 v[12:13], v[18:19], v[12:13]
	v_pk_mul_f32 v[14:15], v[22:23], v[14:15]
	v_pk_mul_f32 v[12:13], v[24:25], v[12:13]
	v_cvt_pk_bf16_f32 v14, v14, v15
	v_cvt_pk_bf16_f32 v15, v12, v13
	global_store_dwordx2 v[2:3], v[14:15], off offset:160
	global_load_dwordx4 v[12:15], v[48:49], off offset:384
	v_lshlrev_b32_e32 v7, 16, v20
	v_and_b32_e32 v18, 0xffff0000, v20
	v_mul_f32_e32 v16, 0xbfb8aa3b, v7
	v_mul_f32_e32 v17, 0xbfb8aa3b, v18
	v_exp_f32_e32 v16, v16
	v_exp_f32_e32 v17, v17
	v_pk_mul_f32 v[10:11], v[10:11], v[6:7] op_sel_hi:[1,0]
	v_pk_add_f32 v[16:17], v[16:17], 1.0 op_sel_hi:[1,0]
	s_nop 0
	v_div_scale_f32 v19, s[0:1], v17, v17, v18
	v_rcp_f32_e32 v20, v19
	s_waitcnt vmcnt(0)
	v_pk_mul_f32 v[10:11], v[10:11], v[12:13]
	v_fma_f32 v12, -v19, v20, 1.0
	v_fmac_f32_e32 v20, v12, v20
	v_div_scale_f32 v12, vcc, v18, v17, v18
	v_mul_f32_e32 v13, v12, v20
	v_fma_f32 v22, -v19, v13, v12
	v_fmac_f32_e32 v13, v22, v20
	v_fma_f32 v12, -v19, v13, v12
	v_div_scale_f32 v19, s[0:1], v16, v16, v7
	v_rcp_f32_e32 v22, v19
	v_div_fmas_f32 v12, v12, v20, v13
	v_div_fixup_f32 v13, v12, v17, v18
	v_lshlrev_b32_e32 v20, 16, v21
	v_fma_f32 v12, -v19, v22, 1.0
	v_fmac_f32_e32 v22, v12, v22
	v_div_scale_f32 v12, vcc, v7, v16, v7
	v_mul_f32_e32 v17, v12, v22
	v_fma_f32 v18, -v19, v17, v12
	v_fmac_f32_e32 v17, v18, v22
	v_and_b32_e32 v21, 0xffff0000, v21
	v_fma_f32 v12, -v19, v17, v12
	v_mul_f32_e32 v18, 0xbfb8aa3b, v20
	v_mul_f32_e32 v19, 0xbfb8aa3b, v21
	v_exp_f32_e32 v18, v18
	v_exp_f32_e32 v19, v19
	v_div_fmas_f32 v12, v12, v22, v17
	v_div_fixup_f32 v12, v12, v16, v7
	v_pk_mul_f32 v[10:11], v[10:11], v[12:13]
	v_pk_add_f32 v[16:17], v[18:19], 1.0 op_sel_hi:[1,0]
	v_cvt_pk_bf16_f32 v10, v10, v11
	v_div_scale_f32 v7, s[0:1], v17, v17, v21
	v_rcp_f32_e32 v18, v7
	v_pk_mul_f32 v[8:9], v[8:9], v[6:7] op_sel_hi:[1,0]
	v_fma_f32 v12, -v7, v18, 1.0
	v_fmac_f32_e32 v18, v12, v18
	v_div_scale_f32 v12, vcc, v21, v17, v21
	v_mul_f32_e32 v13, v12, v18
	v_pk_mul_f32 v[8:9], v[8:9], v[14:15]
	v_fma_f32 v14, -v7, v13, v12
	v_fmac_f32_e32 v13, v14, v18
	v_fma_f32 v7, -v7, v13, v12
	v_div_scale_f32 v12, s[0:1], v16, v16, v20
	v_rcp_f32_e32 v14, v12
	v_div_fmas_f32 v7, v7, v18, v13
	v_div_fixup_f32 v13, v7, v17, v21
	v_and_b32_e32 v18, 0xffff0000, v71
	v_fma_f32 v7, -v12, v14, 1.0
	v_fmac_f32_e32 v14, v7, v14
	v_div_scale_f32 v7, vcc, v20, v16, v20
	v_mul_f32_e32 v15, v7, v14
	v_fma_f32 v17, -v12, v15, v7
	v_fmac_f32_e32 v15, v17, v14
	v_fma_f32 v7, -v12, v15, v7
	v_div_fmas_f32 v7, v7, v14, v15
	v_div_fixup_f32 v12, v7, v16, v20
	v_pk_mul_f32 v[8:9], v[8:9], v[12:13]
	v_lshlrev_b32_e32 v7, 16, v70
	v_cvt_pk_bf16_f32 v11, v8, v9
	global_store_dwordx2 v[2:3], v[10:11], off offset:192
	global_load_dwordx4 v[8:11], v[48:49], off offset:448
	v_and_b32_e32 v14, 0xffff0000, v70
	v_mul_f32_e32 v12, 0xbfb8aa3b, v7
	v_mul_f32_e32 v13, 0xbfb8aa3b, v14
	v_exp_f32_e32 v12, v12
	v_exp_f32_e32 v13, v13
	v_pk_mul_f32 v[4:5], v[4:5], v[6:7] op_sel_hi:[1,0]
	v_pk_add_f32 v[12:13], v[12:13], 1.0 op_sel_hi:[1,0]
	s_nop 0
	v_div_scale_f32 v15, s[0:1], v13, v13, v14
	v_rcp_f32_e32 v16, v15
	s_waitcnt vmcnt(0)
	v_pk_mul_f32 v[4:5], v[4:5], v[8:9]
	v_fma_f32 v8, -v15, v16, 1.0
	v_fmac_f32_e32 v16, v8, v16
	v_div_scale_f32 v8, vcc, v14, v13, v14
	v_mul_f32_e32 v9, v8, v16
	v_fma_f32 v17, -v15, v9, v8
	v_fmac_f32_e32 v9, v17, v16
	v_fma_f32 v8, -v15, v9, v8
	v_div_scale_f32 v15, s[0:1], v12, v12, v7
	v_rcp_f32_e32 v17, v15
	v_div_fmas_f32 v8, v8, v16, v9
	v_div_fixup_f32 v9, v8, v13, v14
	v_lshlrev_b32_e32 v16, 16, v71
	v_fma_f32 v8, -v15, v17, 1.0
	v_fmac_f32_e32 v17, v8, v17
	v_div_scale_f32 v8, vcc, v7, v12, v7
	v_mul_f32_e32 v13, v8, v17
	v_fma_f32 v14, -v15, v13, v8
	v_fmac_f32_e32 v13, v14, v17
	v_fma_f32 v8, -v15, v13, v8
	v_mul_f32_e32 v14, 0xbfb8aa3b, v16
	v_mul_f32_e32 v15, 0xbfb8aa3b, v18
	v_exp_f32_e32 v14, v14
	v_exp_f32_e32 v15, v15
	v_div_fmas_f32 v8, v8, v17, v13
	v_div_fixup_f32 v8, v8, v12, v7
	v_pk_mul_f32 v[4:5], v[4:5], v[8:9]
	v_pk_add_f32 v[12:13], v[14:15], 1.0 op_sel_hi:[1,0]
	v_cvt_pk_bf16_f32 v4, v4, v5
	v_div_scale_f32 v7, s[0:1], v13, v13, v18
	v_rcp_f32_e32 v14, v7
	v_pk_mul_f32 v[0:1], v[0:1], v[6:7] op_sel_hi:[1,0]
	v_fma_f32 v6, -v7, v14, 1.0
	v_fmac_f32_e32 v14, v6, v14
	v_div_scale_f32 v6, vcc, v18, v13, v18
	v_mul_f32_e32 v8, v6, v14
	v_fma_f32 v9, -v7, v8, v6
	v_fmac_f32_e32 v8, v9, v14
	v_div_scale_f32 v9, s[0:1], v12, v12, v16
	v_pk_mul_f32 v[0:1], v[0:1], v[10:11]
	v_rcp_f32_e32 v10, v9
	v_fma_f32 v6, -v7, v8, v6
	v_div_fmas_f32 v6, v6, v14, v8
	v_div_fixup_f32 v7, v6, v13, v18
	v_fma_f32 v6, -v9, v10, 1.0
	v_fmac_f32_e32 v10, v6, v10
	v_div_scale_f32 v6, vcc, v16, v12, v16
	v_mul_f32_e32 v8, v6, v10
	v_fma_f32 v11, -v9, v8, v6
	v_fmac_f32_e32 v8, v11, v10
	v_fma_f32 v6, -v9, v8, v6
	v_div_fmas_f32 v6, v6, v10, v8
	v_div_fixup_f32 v6, v6, v12, v16
	v_pk_mul_f32 v[0:1], v[0:1], v[6:7]
	s_nop 0
	v_cvt_pk_bf16_f32 v5, v0, v1
	global_store_dwordx2 v[2:3], v[4:5], off offset:224
	s_waitcnt lgkmcnt(0)
	s_barrier
	s_cbranch_scc1 .LBB0_495

.LBB0_501:
	v_mov_b32_e32 v0, v154
	s_nop 0
	v_cmp_eq_u32_e32 vcc, 0, v0
	s_and_saveexec_b64 s[0:1], vcc
	s_cbranch_execz .LBB0_503
	v_mov_b64_e32 v[0:1], s[28:29]
	global_atomic_add v0, v[0:1], v76, off offset:8 sc0
	v_mov_b32_e32 v1, s42
	s_waitcnt vmcnt(0) lgkmcnt(0)
	ds_write_b32 v1, v0

.LBB0_508:
	s_ashr_i32 s31, s30, 31
	s_and_b32 s27, s27, 3
	s_lshl_b64 s[48:49], s[30:31], 17
	s_add_u32 s31, s2, s48
	s_addc_u32 s39, s21, s49
	s_lshl_b32 s6, s27, 7
	s_add_u32 s48, s31, s6
	v_lshrrev_b32_e32 v18, 4, v0
	s_addc_u32 s49, s39, 0
	s_lshl_b32 s30, s30, 2
	s_or_b32 s30, s30, s27
	v_xor_b32_e32 v3, v18, v0
	s_ashr_i32 s31, s30, 31
	v_lshlrev_b32_e32 v3, 4, v3
	s_lshl_b64 s[30:31], s[30:31], 15
	v_and_b32_e32 v16, 0x70, v3
	v_ashrrev_i32_e32 v6, 5, v0
	v_and_b32_e32 v3, 31, v0
	s_add_u32 s30, s40, s30
	v_readfirstlane_b32 s27, v0
	v_ashrrev_i32_e32 v2, 3, v0
	v_bitop3_b32 v3, v6, v3, 15 bitop3:0x6c
	s_addc_u32 s31, s41, s31
	s_lshl_b32 s27, s27, 4
	v_lshl_add_u64 v[4:5], s[48:49], 0, v[16:17]
	v_lshlrev_b32_e32 v16, 4, v3
	v_ashrrev_i32_e32 v3, 31, v2
	s_and_b32 s27, s27, 0xfffffc00
	v_lshlrev_b64 v[2:3], 9, v[2:3]
	v_ashrrev_i32_e32 v7, 31, v6
	s_waitcnt vmcnt(0) lgkmcnt(0)
	s_barrier
	s_add_i32 s27, s27, 0
	v_lshl_add_u64 v[8:9], s[30:31], 0, v[16:17]
	v_lshl_add_u64 v[2:3], v[4:5], 0, v[2:3]
	s_mov_b32 s31, m0
	s_mov_b32 m0, s27
	s_nop 0
	global_load_lds_dwordx4 v[2:3], off
	s_mov_b32 m0, s31
	v_lshlrev_b64 v[4:5], 9, v[6:7]
	s_add_i32 s30, s27, 0x8000
	v_lshl_add_u64 v[4:5], v[8:9], 0, v[4:5]
	s_mov_b32 s31, m0
	s_mov_b32 m0, s30
	s_nop 0
	global_load_lds_dwordx4 v[4:5], off
	s_mov_b32 m0, s31
	v_lshl_add_u64 v[6:7], v[2:3], 0, s[8:9]
	s_add_i32 s30, s27, 0x2000
	s_mov_b32 s31, m0
	s_mov_b32 m0, s30
	s_nop 0
	global_load_lds_dwordx4 v[6:7], off
	s_mov_b32 m0, s31
	v_lshl_add_u64 v[6:7], v[4:5], 0, s[10:11]
	s_add_i32 s30, s27, 0xa000
	s_mov_b32 s31, m0
	s_mov_b32 m0, s30
	s_nop 0
	global_load_lds_dwordx4 v[6:7], off
	s_mov_b32 m0, s31
	v_lshl_add_u64 v[6:7], v[2:3], 0, s[12:13]
	s_add_i32 s30, s27, 0x4000
	s_mov_b32 s31, m0
	s_mov_b32 m0, s30
	s_nop 0
	global_load_lds_dwordx4 v[6:7], off
	s_mov_b32 m0, s31
	v_lshl_add_u64 v[6:7], v[4:5], 0, s[14:15]
	s_add_i32 s30, s27, 0xc000
	s_mov_b32 s31, m0
	s_mov_b32 m0, s30
	s_nop 0
	global_load_lds_dwordx4 v[6:7], off
	s_mov_b32 m0, s31
	v_lshl_add_u64 v[2:3], v[2:3], 0, s[16:17]
	v_ashrrev_i32_e32 v1, 6, v0
	s_add_i32 s30, s27, 0x6000
	s_mov_b32 s31, m0
	s_mov_b32 m0, s30
	s_nop 0
	global_load_lds_dwordx4 v[2:3], off
	s_mov_b32 m0, s31
	v_lshl_add_u64 v[2:3], v[4:5], 0, s[18:19]
	s_add_i32 s27, s27, 0xe000
	s_mov_b32 s30, m0
	s_mov_b32 m0, s27
	s_nop 0
	global_load_lds_dwordx4 v[2:3], off
	s_mov_b32 m0, s30
	v_lshlrev_b32_e32 v2, 4, v1
	v_and_b32_e32 v3, 48, v2
	v_and_b32_e32 v19, 15, v0
	v_cndmask_b32_e64 v2, v3, v2, s[0:1]
	s_ashr_i32 s27, s26, 31
	v_ashrrev_i32_e32 v3, 31, v2
	v_or_b32_e32 v2, v2, v19
	v_lshl_add_u64 v[2:3], v[2:3], 0, s[26:27]
	v_mov_b64_e32 v[4:5], s[4:5]
	v_mad_u64_u32 v[4:5], s[26:27], v2, s44, v[4:5]
	v_bfe_u32 v20, v0, 4, 2
	v_mad_i32_i24 v5, v3, s44, v5
	v_lshl_add_u64 v[4:5], v[4:5], 0, s[6:7]
	v_lshlrev_b32_e32 v16, 4, v20
	v_lshl_add_u64 v[4:5], v[4:5], 0, v[16:17]
	global_load_dwordx4 v[12:15], v[4:5], off
	global_load_dwordx4 v[8:11], v[4:5], off offset:64
	v_bfe_u32 v5, v0, 1, 3
	v_bfe_u32 v7, v18, 1, 1
	v_bitop3_b32 v18, v18, v5, 3 bitop3:0x6c
	v_lshlrev_b32_e32 v22, 4, v18
	v_bitop3_b32 v18, v7, v0, 15 bitop3:0x78
	v_lshlrev_b32_e32 v23, 4, v18
	v_bitop3_b32 v18, v7, v19, 2 bitop3:0x36
	v_lshlrev_b32_e32 v24, 4, v18
	v_bitop3_b32 v18, v7, v19, 4 bitop3:0x36
	v_lshlrev_b32_e32 v25, 4, v18
	v_bitop3_b32 v18, v7, v19, 6 bitop3:0x36
	v_lshlrev_b32_e32 v26, 4, v18
	v_bitop3_b32 v18, v7, v19, 8 bitop3:0x36
	v_lshlrev_b32_e32 v27, 4, v18
	v_bitop3_b32 v18, v7, v19, 10 bitop3:0x36
	v_lshlrev_b32_e32 v28, 4, v18
	v_bitop3_b32 v18, v7, v19, 12 bitop3:0x36
	v_lshlrev_b32_e32 v29, 4, v18
	v_bitop3_b32 v18, v7, v19, 14 bitop3:0x36
	v_lshlrev_b32_e32 v30, 4, v18
	v_bitop3_b32 v18, v7, v19, 16 bitop3:0x36
	v_lshlrev_b32_e32 v31, 4, v18
	v_bitop3_b32 v18, v7, v19, 18 bitop3:0x36
	v_lshlrev_b32_e32 v32, 4, v18
	v_bitop3_b32 v18, v7, v19, 20 bitop3:0x36
	v_lshrrev_b32_e32 v4, 1, v0
	v_lshlrev_b32_e32 v33, 4, v18
	v_bitop3_b32 v18, v7, v19, 22 bitop3:0x36
	v_cmp_gt_i32_e32 vcc, 4, v1
	v_lshl_add_u32 v6, v19, 7, 0
	v_mul_u32_u24_e32 v1, 0x180, v19
	v_and_b32_e32 v4, 8, v4
	v_lshlrev_b32_e32 v34, 4, v18
	v_bitop3_b32 v18, v7, v19, 24 bitop3:0x36
	v_add3_u32 v4, v6, v1, v4
	v_mad_u64_u32 v[0:1], s[26:27], v2, s44, 0
	v_lshlrev_b32_e32 v35, 4, v18
	v_bitop3_b32 v18, v7, v19, 26 bitop3:0x36
	v_mad_i32_i24 v1, v3, s44, v1
	v_lshlrev_b32_e32 v36, 4, v18
	v_bitop3_b32 v18, v7, v19, 28 bitop3:0x36
	v_or_b32_e32 v0, v0, v16
	v_bitop3_b32 v5, v20, v5, 4 bitop3:0x36
	v_lshlrev_b32_e32 v37, 4, v18
	v_bitop3_b32 v7, v7, v19, 30 bitop3:0x36
	v_lshl_add_u64 v[18:19], s[28:29], 0, v[0:1]
	v_lshlrev_b64 v[0:1], 11, v[2:3]
	v_lshlrev_b32_e32 v5, 4, v5
	s_waitcnt vmcnt(0) lgkmcnt(0)
	s_waitcnt vmcnt(0)
	v_lshlrev_b32_e32 v7, 4, v7
	v_lshl_or_b32 v0, v20, 3, v0
	v_lshl_add_u64 v[20:21], s[28:29], 0, v[0:1]
	v_add_u32_e32 v78, v6, v22
	v_add_u32_e32 v79, v6, v5
	v_add_u32_e32 v80, v4, v23
	v_add_u32_e32 v81, v4, v24
	v_add_u32_e32 v82, v4, v25
	v_add_u32_e32 v83, v4, v26
	v_add_u32_e32 v84, v4, v27
	v_add_u32_e32 v85, v4, v28
	v_add_u32_e32 v86, v4, v29
	v_add_u32_e32 v87, v4, v30
	v_add_u32_e32 v88, v4, v31
	v_add_u32_e32 v89, v4, v32
	v_add_u32_e32 v90, v4, v33
	v_add_u32_e32 v91, v4, v34
	v_add_u32_e32 v92, v4, v35
	v_add_u32_e32 v93, v4, v36
	v_add_u32_e32 v94, v4, v37
	v_add_u32_e32 v95, v4, v7
	v_mov_b64_e32 v[0:1], v[12:13]
	v_mov_b64_e32 v[4:5], v[8:9]
	s_or_b64 s[0:1], s[0:1], vcc
	s_mov_b32 s30, 0
	v_mov_b64_e32 v[2:3], v[14:15]
	v_mov_b64_e32 v[6:7], v[10:11]
	s_barrier
	s_branch .LBB0_510

.LBB0_510:
	s_add_i32 s30, s30, 1
	s_cmp_ge_u32 s30, s38
	s_cbranch_scc1 .LBB0_512
	v_lshl_add_u64 v[0:1], v[18:19], 0, s[6:7]
	v_add_co_u32_e32 v4, vcc, 0xc995000, v0
	s_nop 1
	v_addc_co_u32_e32 v5, vcc, 0, v1, vcc
	global_load_dwordx4 v[0:3], v[4:5], off offset:2048
	s_nop 0
	global_load_dwordx4 v[4:7], v[4:5], off offset:2112
.LBB0_512:
	s_and_saveexec_b64 s[26:27], s[0:1]
	s_cbranch_execz .LBB0_509
	ds_read_b128 v[22:25], v78
	ds_read_b128 v[26:29], v78 offset:2048
	ds_read_b128 v[30:33], v79
	ds_read_b128 v[34:37], v79 offset:2048
	v_cmp_lt_i32_e32 vcc, v157, v156
	s_waitcnt lgkmcnt(0)
	v_mfma_f32_16x16x32_bf16 v[22:25], v[22:25], v[12:15], 0
	v_mfma_f32_16x16x32_bf16 v[26:29], v[26:29], v[12:15], 0
	v_mfma_f32_16x16x32_bf16 v[22:25], v[30:33], v[8:11], v[22:25]
	ds_read_b128 v[30:33], v79 offset:4096
	ds_read_b128 v[38:41], v78 offset:4096
	ds_read_b128 v[42:45], v78 offset:6144
	v_mfma_f32_16x16x32_bf16 v[26:29], v[34:37], v[8:11], v[26:29]
	s_nop 3
	v_max_f32_e32 v16, v25, v25
	v_max_f32_e32 v34, v24, v24
	v_max_f32_e32 v16, v34, v16
	v_max3_f32 v16, v22, v23, v16
	v_max_f32_e32 v35, v29, v29
	v_max_f32_e32 v36, v28, v28
	v_max_f32_e32 v46, v36, v35
	s_waitcnt lgkmcnt(0)
	v_mfma_f32_16x16x32_bf16 v[34:37], v[38:41], v[12:15], 0
	v_max3_f32 v38, v26, v27, v46
	v_max3_f32 v16, v16, s45, v38
	ds_read_b128 v[38:41], v79 offset:6144
	v_mfma_f32_16x16x32_bf16 v[30:33], v[30:33], v[8:11], v[34:37]
	s_nop 7
	v_max_f32_e32 v34, v33, v33
	v_max_f32_e32 v35, v32, v32
	v_max_f32_e32 v46, v35, v34
	v_mfma_f32_16x16x32_bf16 v[34:37], v[42:45], v[12:15], 0
	v_max3_f32 v54, v30, v31, v46
	ds_read_b128 v[42:45], v78 offset:8192
	ds_read_b128 v[46:49], v79 offset:8192
	s_waitcnt lgkmcnt(0)
	v_mfma_f32_16x16x32_bf16 v[34:37], v[38:41], v[8:11], v[34:37]
	ds_read_b128 v[38:41], v78 offset:10240
	v_mfma_f32_16x16x32_bf16 v[42:45], v[42:45], v[12:15], 0
	v_mfma_f32_16x16x32_bf16 v[42:45], v[46:49], v[8:11], v[42:45]
	s_nop 4
	v_max_f32_e32 v50, v37, v37
	v_max_f32_e32 v51, v36, v36
	v_max_f32_e32 v50, v51, v50
	v_max3_f32 v55, v34, v35, v50
	ds_read_b128 v[50:53], v79 offset:10240
	v_max_f32_e32 v46, v45, v45
	v_max_f32_e32 v47, v44, v44
	v_max_f32_e32 v46, v47, v46
	v_max3_f32 v58, v42, v43, v46
	ds_read_b128 v[46:49], v78 offset:12288
	s_waitcnt lgkmcnt(0)
	v_mfma_f32_16x16x32_bf16 v[38:41], v[38:41], v[12:15], 0
	v_max3_f32 v16, v16, v54, v55
	v_mfma_f32_16x16x32_bf16 v[38:41], v[50:53], v[8:11], v[38:41]
	ds_read_b128 v[50:53], v79 offset:12288
	v_mfma_f32_16x16x32_bf16 v[46:49], v[46:49], v[12:15], 0
	s_nop 5
	v_max_f32_e32 v54, v41, v41
	v_max_f32_e32 v55, v40, v40
	v_max_f32_e32 v59, v55, v54
	ds_read_b128 v[54:57], v78 offset:14336
	v_max3_f32 v59, v38, v39, v59
	v_max3_f32 v16, v16, v58, v59
	ds_read_b128 v[58:61], v79 offset:14336
	s_waitcnt lgkmcnt(0)
	v_mfma_f32_16x16x32_bf16 v[46:49], v[50:53], v[8:11], v[46:49]
	s_nop 7
	v_max_f32_e32 v50, v49, v49
	v_max_f32_e32 v51, v48, v48
	v_max_f32_e32 v62, v51, v50
	v_mfma_f32_16x16x32_bf16 v[50:53], v[54:57], v[12:15], 0
	v_max3_f32 v66, v46, v47, v62
	ds_read_b128 v[54:57], v78 offset:16384
	ds_read_b128 v[62:65], v79 offset:16384
	v_mfma_f32_16x16x32_bf16 v[96:99], v[58:61], v[8:11], v[50:53]
	s_waitcnt lgkmcnt(0)
	v_mfma_f32_16x16x32_bf16 v[54:57], v[54:57], v[12:15], 0
	s_nop 1
	ds_read_b128 v[50:53], v78 offset:18432
	s_nop 2
	v_max_f32_e32 v58, v99, v99
	v_max_f32_e32 v59, v98, v98
	v_max_f32_e32 v58, v59, v58
	v_mfma_f32_16x16x32_bf16 v[100:103], v[62:65], v[8:11], v[54:57]
	v_max3_f32 v67, v96, v97, v58
	ds_read_b128 v[58:61], v79 offset:18432
	v_max3_f32 v16, v16, v66, v67
	s_nop 4
	v_max_f32_e32 v54, v103, v103
	v_max_f32_e32 v55, v102, v102
	v_max_f32_e32 v54, v55, v54
	v_max3_f32 v62, v100, v101, v54
	ds_read_b128 v[54:57], v78 offset:20480
	s_waitcnt lgkmcnt(0)
	v_mfma_f32_16x16x32_bf16 v[50:53], v[50:53], v[12:15], 0
	v_mfma_f32_16x16x32_bf16 v[104:107], v[58:61], v[8:11], v[50:53]
	v_mfma_f32_16x16x32_bf16 v[54:57], v[54:57], v[12:15], 0
	s_nop 5
	ds_read_b128 v[50:53], v79 offset:20480
	v_max_f32_e32 v58, v107, v107
	v_max_f32_e32 v59, v106, v106
	v_max_f32_e32 v63, v59, v58
	ds_read_b128 v[58:61], v78 offset:22528
	v_max3_f32 v63, v104, v105, v63
	v_max3_f32 v16, v16, v62, v63
	ds_read_b128 v[62:65], v79 offset:22528
	s_waitcnt lgkmcnt(0)
	v_mfma_f32_16x16x32_bf16 v[108:111], v[50:53], v[8:11], v[54:57]
	s_nop 7
	v_max_f32_e32 v50, v111, v111
	v_max_f32_e32 v51, v110, v110
	v_max_f32_e32 v54, v51, v50
	v_mfma_f32_16x16x32_bf16 v[50:53], v[58:61], v[12:15], 0
	v_max3_f32 v66, v108, v109, v54
	ds_read_b128 v[54:57], v78 offset:24576
	ds_read_b128 v[58:61], v79 offset:24576
	v_mfma_f32_16x16x32_bf16 v[112:115], v[62:65], v[8:11], v[50:53]
	s_nop 3
	ds_read_b128 v[50:53], v78 offset:26624
	s_waitcnt lgkmcnt(0)
	v_mfma_f32_16x16x32_bf16 v[54:57], v[54:57], v[12:15], 0
	s_nop 0
	v_max_f32_e32 v62, v115, v115
	v_max_f32_e32 v63, v114, v114
	v_max_f32_e32 v62, v63, v62
	v_max3_f32 v67, v112, v113, v62
	ds_read_b128 v[62:65], v79 offset:26624
	v_mfma_f32_16x16x32_bf16 v[116:119], v[58:61], v[8:11], v[54:57]
	v_max3_f32 v16, v16, v66, v67
	s_nop 1
	ds_read_b128 v[54:57], v78 offset:28672
	v_mfma_f32_16x16x32_bf16 v[50:53], v[50:53], v[12:15], 0
	s_nop 2
	v_max_f32_e32 v58, v119, v119
	v_max_f32_e32 v59, v118, v118
	v_max_f32_e32 v66, v59, v58
	s_waitcnt lgkmcnt(0)
	v_mfma_f32_16x16x32_bf16 v[120:123], v[62:65], v[8:11], v[50:53]
	ds_read_b128 v[58:61], v79 offset:28672
	v_max3_f32 v66, v116, v117, v66
	s_nop 0
	ds_read_b128 v[50:53], v78 offset:30720
	v_mfma_f32_16x16x32_bf16 v[54:57], v[54:57], v[12:15], 0
	s_nop 2
	v_max_f32_e32 v62, v123, v123
	v_max_f32_e32 v63, v122, v122
	v_max_f32_e32 v67, v63, v62
	ds_read_b128 v[62:65], v79 offset:30720
	s_waitcnt lgkmcnt(0)
	v_mfma_f32_16x16x32_bf16 v[12:15], v[50:53], v[12:15], 0
	v_mfma_f32_16x16x32_bf16 v[124:127], v[58:61], v[8:11], v[54:57]
	v_mfma_f32_16x16x32_bf16 v[8:11], v[62:65], v[8:11], v[12:15]
	s_nop 1
	v_max3_f32 v54, v120, v121, v67
	v_max3_f32 v16, v16, v66, v54
	s_nop 2
	v_max_f32_e32 v54, v127, v127
	v_max_f32_e32 v50, v126, v126
	v_max_f32_e32 v50, v50, v54
	v_max_f32_e32 v12, v11, v11
	v_max_f32_e32 v13, v10, v10
	v_max_f32_e32 v12, v13, v12
	v_max3_f32 v50, v124, v125, v50
	v_max3_f32 v12, v8, v9, v12
	v_cndmask_b32_e32 v13, v155, v157, vcc
	v_max3_f32 v12, v16, v50, v12
	v_lshlrev_b32_e32 v16, 2, v13
	ds_bpermute_b32 v13, v16, v12
	v_cmp_lt_i32_e32 vcc, v158, v156
	s_waitcnt lgkmcnt(0)
	v_max_f32_e32 v13, v13, v13
	v_max_f32_e32 v12, v12, v13
	v_cndmask_b32_e32 v13, v155, v158, vcc
	v_lshlrev_b32_e32 v132, 2, v13
	ds_bpermute_b32 v13, v132, v12
	s_waitcnt lgkmcnt(0)
	v_max_f32_e32 v13, v13, v13
	v_max_f32_e32 v13, v12, v13
	v_mov_b32_e32 v12, v11
	v_pk_mul_f32 v[128:129], v[12:13], s[20:21] op_sel_hi:[1,0]
	s_nop 0
	v_fma_f32 v11, v22, s20, -v129
	v_exp_f32_e32 v70, v11
	v_fma_f32 v11, v23, s20, -v129
	v_exp_f32_e32 v71, v11
	v_fma_f32 v11, v24, s20, -v129
	v_exp_f32_e32 v130, v11
	v_fma_f32 v11, v25, s20, -v129
	v_exp_f32_e32 v131, v11
	v_fma_f32 v12, v26, s20, -v129
	v_add_f32_e32 v11, 0, v70
	v_exp_f32_e32 v72, v12
	v_fma_f32 v12, v27, s20, -v129
	v_add_f32_e32 v11, v71, v11
	v_exp_f32_e32 v73, v12
	v_fma_f32 v12, v28, s20, -v129
	v_add_f32_e32 v11, v130, v11
	v_exp_f32_e32 v74, v12
	v_fma_f32 v12, v29, s20, -v129
	v_add_f32_e32 v11, v131, v11
	v_exp_f32_e32 v75, v12
	v_fma_f32 v12, v30, s20, -v129
	v_add_f32_e32 v11, v72, v11
	v_exp_f32_e32 v62, v12
	v_fma_f32 v12, v31, s20, -v129
	v_add_f32_e32 v11, v73, v11
	v_exp_f32_e32 v63, v12
	v_fma_f32 v12, v32, s20, -v129
	v_add_f32_e32 v11, v74, v11
	v_exp_f32_e32 v68, v12
	v_fma_f32 v12, v33, s20, -v129
	v_add_f32_e32 v11, v75, v11
	v_exp_f32_e32 v69, v12
	v_fma_f32 v12, v34, s20, -v129
	v_add_f32_e32 v11, v62, v11
	v_exp_f32_e32 v64, v12
	v_fma_f32 v12, v35, s20, -v129
	v_add_f32_e32 v11, v63, v11
	v_exp_f32_e32 v65, v12
	v_fma_f32 v12, v36, s20, -v129
	v_add_f32_e32 v11, v68, v11
	v_exp_f32_e32 v66, v12
	v_fma_f32 v12, v37, s20, -v129
	v_add_f32_e32 v11, v69, v11
	v_exp_f32_e32 v67, v12
	v_fma_f32 v12, v42, s20, -v129
	v_add_f32_e32 v11, v64, v11
	v_exp_f32_e32 v54, v12
	v_fma_f32 v12, v43, s20, -v129
	v_add_f32_e32 v11, v65, v11
	v_exp_f32_e32 v55, v12
	v_fma_f32 v12, v44, s20, -v129
	v_add_f32_e32 v11, v66, v11
	v_exp_f32_e32 v60, v12
	v_fma_f32 v12, v45, s20, -v129
	v_add_f32_e32 v11, v67, v11
	v_exp_f32_e32 v61, v12
	v_fma_f32 v12, v38, s20, -v129
	v_add_f32_e32 v11, v54, v11
	v_exp_f32_e32 v56, v12
	v_fma_f32 v12, v39, s20, -v129
	v_add_f32_e32 v11, v55, v11
	v_exp_f32_e32 v57, v12
	v_fma_f32 v12, v40, s20, -v129
	v_add_f32_e32 v11, v60, v11
	v_exp_f32_e32 v58, v12
	v_fma_f32 v12, v41, s20, -v129
	v_add_f32_e32 v11, v61, v11
	v_exp_f32_e32 v59, v12
	v_fma_f32 v12, v46, s20, -v129
	v_add_f32_e32 v11, v56, v11
	v_exp_f32_e32 v46, v12
	v_fma_f32 v12, v47, s20, -v129
	v_add_f32_e32 v11, v57, v11
	v_exp_f32_e32 v47, v12
	v_fma_f32 v12, v48, s20, -v129
	v_add_f32_e32 v11, v58, v11
	v_exp_f32_e32 v52, v12
	v_fma_f32 v12, v49, s20, -v129
	v_add_f32_e32 v11, v59, v11
	v_exp_f32_e32 v53, v12
	v_fma_f32 v12, v96, s20, -v129
	v_add_f32_e32 v11, v46, v11
	v_exp_f32_e32 v48, v12
	v_fma_f32 v12, v97, s20, -v129
	v_add_f32_e32 v11, v47, v11
	v_exp_f32_e32 v49, v12
	v_fma_f32 v12, v98, s20, -v129
	v_add_f32_e32 v11, v52, v11
	v_exp_f32_e32 v50, v12
	v_fma_f32 v12, v99, s20, -v129
	v_add_f32_e32 v11, v53, v11
	v_exp_f32_e32 v51, v12
	v_fma_f32 v12, v100, s20, -v129
	v_add_f32_e32 v11, v48, v11
	v_exp_f32_e32 v38, v12
	v_fma_f32 v12, v101, s20, -v129
	v_add_f32_e32 v11, v49, v11
	v_exp_f32_e32 v39, v12
	v_fma_f32 v12, v102, s20, -v129
	v_add_f32_e32 v11, v50, v11
	v_exp_f32_e32 v44, v12
	v_fma_f32 v12, v103, s20, -v129
	v_add_f32_e32 v11, v51, v11
	v_exp_f32_e32 v45, v12
	v_fma_f32 v12, v104, s20, -v129
	v_add_f32_e32 v11, v38, v11
	v_exp_f32_e32 v40, v12
	v_fma_f32 v12, v105, s20, -v129
	v_add_f32_e32 v11, v39, v11
	v_exp_f32_e32 v41, v12
	v_fma_f32 v12, v106, s20, -v129
	v_add_f32_e32 v11, v44, v11
	v_exp_f32_e32 v42, v12
	v_fma_f32 v12, v107, s20, -v129
	v_add_f32_e32 v11, v45, v11
	v_exp_f32_e32 v43, v12
	v_fma_f32 v12, v108, s20, -v129
	v_add_f32_e32 v11, v40, v11
	v_exp_f32_e32 v30, v12
	v_fma_f32 v12, v109, s20, -v129
	v_add_f32_e32 v11, v41, v11
	v_exp_f32_e32 v31, v12
	v_fma_f32 v12, v110, s20, -v129
	v_add_f32_e32 v11, v42, v11
	v_exp_f32_e32 v36, v12
	v_fma_f32 v12, v111, s20, -v129
	v_add_f32_e32 v11, v43, v11
	v_exp_f32_e32 v37, v12
	v_fma_f32 v12, v112, s20, -v129
	v_add_f32_e32 v11, v30, v11
	v_exp_f32_e32 v32, v12
	v_fma_f32 v12, v113, s20, -v129
	v_add_f32_e32 v11, v31, v11
	v_exp_f32_e32 v33, v12
	v_fma_f32 v12, v114, s20, -v129
	v_add_f32_e32 v11, v36, v11
	v_exp_f32_e32 v34, v12
	v_fma_f32 v12, v115, s20, -v129
	v_add_f32_e32 v11, v37, v11
	v_exp_f32_e32 v35, v12
	v_fma_f32 v12, v116, s20, -v129
	v_add_f32_e32 v11, v32, v11
	v_exp_f32_e32 v22, v12
	v_fma_f32 v12, v117, s20, -v129
	v_add_f32_e32 v11, v33, v11
	v_exp_f32_e32 v23, v12
	v_fma_f32 v12, v118, s20, -v129
	v_add_f32_e32 v11, v34, v11
	v_exp_f32_e32 v28, v12
	v_fma_f32 v12, v119, s20, -v129
	v_add_f32_e32 v11, v35, v11
	v_exp_f32_e32 v29, v12
	v_fma_f32 v12, v120, s20, -v129
	v_add_f32_e32 v11, v22, v11
	v_exp_f32_e32 v24, v12
	v_fma_f32 v12, v121, s20, -v129
	v_add_f32_e32 v11, v23, v11
	v_exp_f32_e32 v25, v12
	v_fma_f32 v12, v122, s20, -v129
	v_add_f32_e32 v11, v28, v11
	v_exp_f32_e32 v26, v12
	v_fma_f32 v12, v123, s20, -v129
	v_add_f32_e32 v11, v29, v11
	v_exp_f32_e32 v27, v12
	v_fma_f32 v12, v124, s20, -v129
	v_add_f32_e32 v11, v24, v11
	v_exp_f32_e32 v12, v12
	v_fma_f32 v13, v125, s20, -v129
	v_add_f32_e32 v11, v25, v11
	v_exp_f32_e32 v13, v13
	v_fma_f32 v14, v126, s20, -v129
	v_add_f32_e32 v11, v26, v11
	v_exp_f32_e32 v14, v14
	v_fma_f32 v15, v127, s20, -v129
	v_add_f32_e32 v11, v27, v11
	v_exp_f32_e32 v15, v15
	v_add_f32_e32 v11, v12, v11
	v_fma_f32 v8, v8, s20, -v129
	v_add_f32_e32 v11, v13, v11
	v_exp_f32_e32 v8, v8
	v_fma_f32 v9, v9, s20, -v129
	v_add_f32_e32 v11, v14, v11
	v_exp_f32_e32 v9, v9
	v_fma_f32 v10, v10, s20, -v129
	v_add_f32_e32 v96, v15, v11
	v_exp_f32_e32 v10, v10
	v_sub_f32_e32 v11, v128, v129
	v_exp_f32_e32 v11, v11
	v_add_f32_e32 v96, v8, v96
	v_add_f32_e32 v96, v9, v96
	v_add_f32_e32 v96, v10, v96
	v_add_f32_e32 v96, v11, v96
	ds_bpermute_b32 v16, v16, v96
	s_waitcnt lgkmcnt(0)
	v_add_f32_e32 v16, v96, v16
	ds_bpermute_b32 v96, v132, v16
	s_waitcnt lgkmcnt(0)
	v_add_f32_e32 v16, v16, v96
	v_div_scale_f32 v96, s[48:49], v16, v16, 1.0
	v_rcp_f32_e32 v97, v96
	s_nop 0
	v_fma_f32 v98, -v96, v97, 1.0
	v_fmac_f32_e32 v97, v98, v97
	v_div_scale_f32 v98, vcc, 1.0, v16, 1.0
	v_mul_f32_e32 v99, v98, v97
	v_fma_f32 v100, -v96, v99, v98
	v_fmac_f32_e32 v99, v100, v97
	v_fma_f32 v96, -v96, v99, v98
	v_div_fmas_f32 v96, v96, v97, v99
	v_div_fixup_f32 v16, v96, v16, 1.0
	ds_read2st64_b64 v[96:99], v80 offset0:64 offset1:80
	ds_read2st64_b64 v[100:103], v81 offset0:64 offset1:80
	v_pk_mul_f32 v[106:107], v[130:131], v[16:17] op_sel_hi:[1,0]
	v_pk_mul_f32 v[104:105], v[70:71], v[16:17] op_sel_hi:[1,0]
	v_pk_mul_f32 v[108:109], v[72:73], v[16:17] op_sel_hi:[1,0]
	s_waitcnt lgkmcnt(0)
	v_mov_b32_e32 v70, v96
	v_mov_b32_e32 v71, v97
	v_mov_b32_e32 v72, v100
	v_mov_b32_e32 v73, v101
	v_cvt_pk_bf16_f32 v104, v104, v105
	v_cvt_pk_bf16_f32 v105, v106, v107
	v_cvt_pk_bf16_f32 v106, v108, v109
	v_mov_b32_e32 v100, v98
	v_mov_b32_e32 v101, v99
	ds_read2st64_b64 v[96:99], v80 offset0:96 offset1:112
	ds_read2st64_b64 v[108:111], v81 offset0:96 offset1:112
	v_pk_mul_f32 v[74:75], v[74:75], v[16:17] op_sel_hi:[1,0]
	v_pk_mul_f32 v[118:119], v[64:65], v[16:17] op_sel_hi:[1,0]
	v_cvt_pk_bf16_f32 v107, v74, v75
	s_waitcnt lgkmcnt(0)
	v_mov_b32_e32 v112, v96
	v_mov_b32_e32 v113, v97
	v_mov_b32_e32 v114, v108
	v_mov_b32_e32 v115, v109
	v_mov_b32_e32 v108, v98
	v_mov_b32_e32 v109, v99
	v_mfma_f32_16x16x32_bf16 v[70:73], v[70:73], v[104:107], 0
	v_mul_f32_e64 v74, v62, v16
	v_mul_f32_e64 v75, v63, v16
	v_pk_mul_f32 v[68:69], v[68:69], v[16:17] op_sel_hi:[1,0]
	v_pk_mul_f32 v[116:117], v[66:67], v[16:17] op_sel_hi:[1,0]
	v_mfma_f32_16x16x32_bf16 v[100:103], v[100:103], v[104:107], 0
	v_cvt_pk_bf16_f32 v66, v74, v75
	v_cvt_pk_bf16_f32 v67, v68, v69
	v_cvt_pk_bf16_f32 v68, v118, v119
	v_mfma_f32_16x16x32_bf16 v[112:115], v[112:115], v[104:107], 0
	v_cvt_pk_bf16_f32 v69, v116, v117
	v_pk_mul_f32 v[74:75], v[54:55], v[16:17] op_sel_hi:[1,0]
	v_pk_mul_f32 v[60:61], v[60:61], v[16:17] op_sel_hi:[1,0]
	v_mfma_f32_16x16x32_bf16 v[96:99], v[108:111], v[104:107], 0
	ds_read2st64_b64 v[104:107], v82 offset0:64 offset1:80
	ds_read2st64_b64 v[108:111], v83 offset0:64 offset1:80
	v_pk_mul_f32 v[52:53], v[52:53], v[16:17] op_sel_hi:[1,0]
	v_pk_mul_f32 v[44:45], v[44:45], v[16:17] op_sel_hi:[1,0]
	v_pk_mul_f32 v[36:37], v[36:37], v[16:17] op_sel_hi:[1,0]
	s_waitcnt lgkmcnt(0)
	v_mov_b32_e32 v62, v104
	v_mov_b32_e32 v63, v105
	v_mov_b32_e32 v64, v108
	v_mov_b32_e32 v65, v109
	v_mov_b32_e32 v108, v106
	v_mov_b32_e32 v109, v107
	v_mfma_f32_16x16x32_bf16 v[62:65], v[62:65], v[66:69], v[70:73]
	s_nop 2
	ds_read2st64_b64 v[70:73], v82 offset0:96 offset1:112
	ds_read2st64_b64 v[104:107], v83 offset0:96 offset1:112
	v_pk_mul_f32 v[28:29], v[28:29], v[16:17] op_sel_hi:[1,0]
	v_mfma_f32_16x16x32_bf16 v[100:103], v[108:111], v[66:69], v[100:103]
	s_waitcnt lgkmcnt(0)
	v_mov_b32_e32 v108, v70
	v_mov_b32_e32 v109, v71
	v_mov_b32_e32 v110, v104
	v_mov_b32_e32 v111, v105
	v_mov_b32_e32 v104, v72
	v_mov_b32_e32 v105, v73
	v_mfma_f32_16x16x32_bf16 v[108:111], v[108:111], v[66:69], v[112:115]
	ds_read2st64_b64 v[70:73], v84 offset0:64 offset1:80
	s_waitcnt lgkmcnt(0)
	v_mov_b32_e32 v54, v70
	v_mfma_f32_16x16x32_bf16 v[66:69], v[104:107], v[66:69], v[96:99]
	v_mul_f32_e64 v106, v56, v16
	v_mul_f32_e64 v107, v57, v16
	v_mov_b32_e32 v55, v71
	v_pk_mul_f32 v[104:105], v[58:59], v[16:17] op_sel_hi:[1,0]
	ds_read2st64_b64 v[96:99], v85 offset0:64 offset1:80
	v_cvt_pk_bf16_f32 v58, v74, v75
	v_cvt_pk_bf16_f32 v59, v60, v61
	v_cvt_pk_bf16_f32 v60, v106, v107
	v_cvt_pk_bf16_f32 v61, v104, v105
	s_waitcnt lgkmcnt(0)
	v_mov_b32_e32 v56, v96
	v_mov_b32_e32 v57, v97
	v_mov_b32_e32 v96, v72
	v_mov_b32_e32 v97, v73
	v_mfma_f32_16x16x32_bf16 v[54:57], v[54:57], v[58:61], v[62:65]
	s_nop 2
	ds_read2st64_b64 v[62:65], v84 offset0:96 offset1:112
	ds_read2st64_b64 v[70:73], v85 offset0:96 offset1:112
	v_pk_mul_f32 v[74:75], v[48:49], v[16:17] op_sel_hi:[1,0]
	v_mfma_f32_16x16x32_bf16 v[96:99], v[96:99], v[58:61], v[100:103]
	s_waitcnt lgkmcnt(0)
	s_nop 1
	v_mov_b32_e32 v100, v62
	v_mov_b32_e32 v101, v63
	v_mov_b32_e32 v102, v70
	v_mov_b32_e32 v103, v71
	v_mov_b32_e32 v70, v64
	v_mov_b32_e32 v71, v65
	v_mfma_f32_16x16x32_bf16 v[100:103], v[100:103], v[58:61], v[108:111]
	ds_read2st64_b64 v[62:65], v86 offset0:64 offset1:80
	v_mfma_f32_16x16x32_bf16 v[58:61], v[70:73], v[58:61], v[66:69]
	v_mul_f32_e64 v70, v46, v16
	v_mul_f32_e64 v71, v47, v16
	s_waitcnt lgkmcnt(0)
	v_mov_b32_e32 v46, v62
	v_mov_b32_e32 v47, v63
	ds_read2st64_b64 v[66:69], v87 offset0:64 offset1:80
	v_pk_mul_f32 v[72:73], v[50:51], v[16:17] op_sel_hi:[1,0]
	v_cvt_pk_bf16_f32 v50, v70, v71
	v_cvt_pk_bf16_f32 v51, v52, v53
	v_cvt_pk_bf16_f32 v52, v74, v75
	s_waitcnt lgkmcnt(0)
	v_mov_b32_e32 v48, v66
	v_mov_b32_e32 v49, v67
	v_cvt_pk_bf16_f32 v53, v72, v73
	v_mov_b32_e32 v66, v64
	v_mov_b32_e32 v67, v65
	v_mfma_f32_16x16x32_bf16 v[46:49], v[46:49], v[50:53], v[54:57]
	s_nop 2
	ds_read2st64_b64 v[54:57], v86 offset0:96 offset1:112
	ds_read2st64_b64 v[62:65], v87 offset0:96 offset1:112
	v_pk_mul_f32 v[74:75], v[40:41], v[16:17] op_sel_hi:[1,0]
	s_waitcnt lgkmcnt(0)
	v_mov_b32_e32 v70, v54
	v_mov_b32_e32 v71, v55
	v_mov_b32_e32 v72, v62
	v_mov_b32_e32 v73, v63
	v_mov_b32_e32 v62, v56
	v_mov_b32_e32 v63, v57
	v_mfma_f32_16x16x32_bf16 v[66:69], v[66:69], v[50:53], v[96:99]
	ds_read2st64_b64 v[54:57], v88 offset0:64 offset1:80
	v_mfma_f32_16x16x32_bf16 v[70:73], v[70:73], v[50:53], v[100:103]
	v_mfma_f32_16x16x32_bf16 v[50:53], v[62:65], v[50:53], v[58:61]
	v_mul_f32_e64 v62, v38, v16
	v_mul_f32_e64 v63, v39, v16
	s_waitcnt lgkmcnt(0)
	v_mov_b32_e32 v38, v54
	v_mov_b32_e32 v39, v55
	ds_read2st64_b64 v[58:61], v89 offset0:64 offset1:80
	v_pk_mul_f32 v[64:65], v[42:43], v[16:17] op_sel_hi:[1,0]
	v_cvt_pk_bf16_f32 v42, v62, v63
	v_cvt_pk_bf16_f32 v43, v44, v45
	v_cvt_pk_bf16_f32 v44, v74, v75
	s_waitcnt lgkmcnt(0)
	v_mov_b32_e32 v40, v58
	v_mov_b32_e32 v41, v59
	v_cvt_pk_bf16_f32 v45, v64, v65
	v_mov_b32_e32 v58, v56
	v_mov_b32_e32 v59, v57
	v_mfma_f32_16x16x32_bf16 v[38:41], v[38:41], v[42:45], v[46:49]
	s_nop 2
	ds_read2st64_b64 v[46:49], v88 offset0:96 offset1:112
	ds_read2st64_b64 v[54:57], v89 offset0:96 offset1:112
	s_waitcnt lgkmcnt(0)
	v_mov_b32_e32 v62, v46
	v_mov_b32_e32 v63, v47
	v_mov_b32_e32 v64, v54
	v_mov_b32_e32 v65, v55
	v_mov_b32_e32 v54, v48
	v_mov_b32_e32 v55, v49
	v_mfma_f32_16x16x32_bf16 v[58:61], v[58:61], v[42:45], v[66:69]
	ds_read2st64_b64 v[46:49], v90 offset0:64 offset1:80
	v_mfma_f32_16x16x32_bf16 v[62:65], v[62:65], v[42:45], v[70:73]
	s_nop 0
	v_mul_f32_e64 v66, v32, v16
	v_mul_f32_e64 v67, v33, v16
	v_mfma_f32_16x16x32_bf16 v[42:45], v[54:57], v[42:45], v[50:53]
	v_mul_f32_e64 v54, v30, v16
	v_mul_f32_e64 v55, v31, v16
	s_waitcnt lgkmcnt(0)
	v_mov_b32_e32 v30, v46
	v_mov_b32_e32 v31, v47
	ds_read2st64_b64 v[50:53], v91 offset0:64 offset1:80
	v_pk_mul_f32 v[56:57], v[34:35], v[16:17] op_sel_hi:[1,0]
	v_cvt_pk_bf16_f32 v34, v54, v55
	v_cvt_pk_bf16_f32 v35, v36, v37
	v_cvt_pk_bf16_f32 v36, v66, v67
	s_waitcnt lgkmcnt(0)
	v_mov_b32_e32 v32, v50
	v_mov_b32_e32 v33, v51
	v_cvt_pk_bf16_f32 v37, v56, v57
	v_mov_b32_e32 v50, v48
	v_mov_b32_e32 v51, v49
	v_mfma_f32_16x16x32_bf16 v[30:33], v[30:33], v[34:37], v[38:41]
	s_nop 2
	ds_read2st64_b64 v[38:41], v90 offset0:96 offset1:112
	ds_read2st64_b64 v[46:49], v91 offset0:96 offset1:112
	s_waitcnt lgkmcnt(0)
	v_mov_b32_e32 v54, v38
	v_mov_b32_e32 v55, v39
	v_mov_b32_e32 v56, v46
	v_mov_b32_e32 v57, v47
	v_mov_b32_e32 v46, v40
	v_mov_b32_e32 v47, v41
	v_mfma_f32_16x16x32_bf16 v[50:53], v[50:53], v[34:37], v[58:61]
	ds_read2st64_b64 v[38:41], v92 offset0:64 offset1:80
	v_mfma_f32_16x16x32_bf16 v[54:57], v[54:57], v[34:37], v[62:65]
	s_nop 0
	v_mul_f32_e64 v58, v24, v16
	v_mul_f32_e64 v59, v25, v16
	v_mfma_f32_16x16x32_bf16 v[34:37], v[46:49], v[34:37], v[42:45]
	v_mul_f32_e64 v46, v22, v16
	v_mul_f32_e64 v47, v23, v16
	s_waitcnt lgkmcnt(0)
	v_mov_b32_e32 v22, v38
	v_mov_b32_e32 v23, v39
	ds_read2st64_b64 v[42:45], v93 offset0:64 offset1:80
	v_pk_mul_f32 v[48:49], v[26:27], v[16:17] op_sel_hi:[1,0]
	v_cvt_pk_bf16_f32 v26, v46, v47
	v_cvt_pk_bf16_f32 v27, v28, v29
	v_cvt_pk_bf16_f32 v28, v58, v59
	s_waitcnt lgkmcnt(0)
	v_mov_b32_e32 v24, v42
	v_mov_b32_e32 v25, v43
	v_cvt_pk_bf16_f32 v29, v48, v49
	v_mov_b32_e32 v42, v40
	v_mov_b32_e32 v43, v41
	v_mfma_f32_16x16x32_bf16 v[22:25], v[22:25], v[26:29], v[30:33]
	s_nop 2
	ds_read2st64_b64 v[30:33], v92 offset0:96 offset1:112
	ds_read2st64_b64 v[38:41], v93 offset0:96 offset1:112
	s_waitcnt lgkmcnt(0)
	v_mov_b32_e32 v46, v30
	v_mov_b32_e32 v47, v31
	v_mov_b32_e32 v48, v38
	v_mov_b32_e32 v49, v39
	v_mov_b32_e32 v38, v32
	v_mov_b32_e32 v39, v33
	v_mfma_f32_16x16x32_bf16 v[42:45], v[42:45], v[26:29], v[50:53]
	ds_read2st64_b64 v[30:33], v94 offset0:64 offset1:80
	v_mfma_f32_16x16x32_bf16 v[46:49], v[46:49], v[26:29], v[54:57]
	v_mfma_f32_16x16x32_bf16 v[26:29], v[38:41], v[26:29], v[34:37]
	v_mul_f32_e64 v38, v10, v16
	v_mul_f32_e64 v39, v11, v16
	v_pk_mul_f32 v[40:41], v[8:9], v[16:17] op_sel_hi:[1,0]
	s_waitcnt lgkmcnt(0)
	v_mov_b32_e32 v8, v30
	v_pk_mul_f32 v[36:37], v[14:15], v[16:17] op_sel_hi:[1,0]
	v_pk_mul_f32 v[34:35], v[12:13], v[16:17] op_sel_hi:[1,0]
	ds_read2st64_b64 v[12:15], v95 offset0:64 offset1:80
	v_mov_b32_e32 v9, v31
	v_cvt_pk_bf16_f32 v34, v34, v35
	v_cvt_pk_bf16_f32 v35, v36, v37
	v_cvt_pk_bf16_f32 v36, v40, v41
	s_waitcnt lgkmcnt(0)
	v_mov_b32_e32 v10, v12
	v_mov_b32_e32 v11, v13
	v_cvt_pk_bf16_f32 v37, v38, v39
	v_mov_b32_e32 v12, v32
	v_mov_b32_e32 v13, v33
	v_mfma_f32_16x16x32_bf16 v[8:11], v[8:11], v[34:37], v[22:25]
	s_nop 2
	ds_read2st64_b64 v[22:25], v94 offset0:96 offset1:112
	ds_read2st64_b64 v[30:33], v95 offset0:96 offset1:112
	s_nop 2
	v_cvt_pk_bf16_f32 v8, v8, v9
	s_waitcnt lgkmcnt(0)
	v_mov_b32_e32 v38, v22
	v_mov_b32_e32 v39, v23
	v_mov_b32_e32 v40, v30
	v_mov_b32_e32 v41, v31
	v_mov_b32_e32 v30, v24
	v_mov_b32_e32 v31, v25
	v_mfma_f32_16x16x32_bf16 v[12:15], v[12:15], v[34:37], v[42:45]
	v_cvt_pk_bf16_f32 v9, v10, v11
	v_mfma_f32_16x16x32_bf16 v[38:41], v[38:41], v[34:37], v[46:49]
	v_mfma_f32_16x16x32_bf16 v[22:25], v[30:33], v[34:37], v[26:29]
	s_nop 2
	v_lshl_add_u64 v[26:27], v[20:21], 0, s[6:7]
	v_add_co_u32_e32 v10, vcc, s46, v26
	s_nop 1
	v_addc_co_u32_e32 v11, vcc, 0, v27, vcc
	global_store_dwordx2 v[10:11], v[8:9], off offset:1536
	v_cvt_pk_bf16_f32 v8, v12, v13
	v_cvt_pk_bf16_f32 v9, v14, v15
	global_store_dwordx2 v[10:11], v[8:9], off offset:1568
	v_cvt_pk_bf16_f32 v8, v38, v39
	v_cvt_pk_bf16_f32 v9, v40, v41
	global_store_dwordx2 v[10:11], v[8:9], off offset:1600
	v_cvt_pk_bf16_f32 v8, v22, v23
	v_cvt_pk_bf16_f32 v9, v24, v25
	global_store_dwordx2 v[10:11], v[8:9], off offset:1632
	s_branch .LBB0_509

.LBB0_686:
	s_or_b64 exec, exec, s[38:39]
	v_mul_f32_e32 v131, 0xbfb8aa3b, v124
	v_exp_f32_e32 v132, v131
	v_mul_f32_e32 v131, 0xbfb8aa3b, v125
	v_exp_f32_e32 v133, v131
	v_or_b32_e32 v130, s30, v146
	s_lshl_b32 s38, s56, 7
	v_lshlrev_b32_e32 v131, 4, v145
	v_pk_add_f32 v[132:133], v[132:133], 1.0 op_sel_hi:[1,0]
	v_lshlrev_b32_e32 v134, 2, v144
	v_or3_b32 v134, v131, s38, v134
	v_add_u32_e32 v130, v130, v147
	v_ashrrev_i32_e32 v135, 31, v134
	v_div_scale_f32 v139, s[30:31], v132, v132, v124
	v_rcp_f32_e32 v140, v139
	v_rcp_f32_e32 v131, v133
	s_nop 0
	v_mul_f32_e32 v125, v125, v131
	v_fma_f32 v131, -v139, v140, 1.0
	v_fmac_f32_e32 v140, v131, v140
	v_mul_f32_e32 v136, 0xbfb8aa3b, v126
	v_mul_f32_e32 v137, 0xbfb8aa3b, v127
	v_exp_f32_e32 v136, v136
	v_exp_f32_e32 v137, v137
	v_rcp_f32_e32 v131, v132
	s_nop 0
	v_mul_f32_e32 v124, v124, v131
	v_pk_add_f32 v[136:137], v[136:137], 1.0 op_sel_hi:[1,0]
	v_pk_mul_f32 v[120:121], v[120:121], v[124:125]
	v_div_scale_f32 v133, s[30:31], v137, v137, v127
	v_rcp_f32_e32 v138, v133
	v_cvt_pk_bf16_f32 v132, v120, v121
	v_fma_f32 v120, -v133, v138, 1.0
	v_fmac_f32_e32 v138, v120, v138
	v_rcp_f32_e32 v120, v137
	s_nop 0
	v_mul_f32_e32 v121, v127, v120
	v_rcp_f32_e32 v120, v136
	s_nop 0
	v_mul_f32_e32 v120, v126, v120
	v_pk_mul_f32 v[120:121], v[122:123], v[120:121]
	v_lshlrev_b64 v[122:123], 1, v[134:135]
	v_cvt_pk_bf16_f32 v133, v120, v121
	v_mov_b64_e32 v[120:121], s[6:7]
	v_mad_i64_i32 v[124:125], s[30:31], v130, s53, v[120:121]
	v_lshl_add_u64 v[124:125], v[124:125], 0, v[122:123]
	global_store_dwordx2 v[124:125], v[132:133], off
	v_mul_f32_e32 v126, 0xbfb8aa3b, v116
	v_mul_f32_e32 v127, 0xbfb8aa3b, v117
	v_exp_f32_e32 v126, v126
	v_exp_f32_e32 v127, v127
	v_or_b32_e32 v134, 16, v130
	v_pk_add_f32 v[126:127], v[126:127], 1.0 op_sel_hi:[1,0]
	s_nop 0
	v_div_scale_f32 v136, s[30:31], v126, v126, v116
	v_rcp_f32_e32 v137, v136
	v_rcp_f32_e32 v131, v127
	s_nop 0
	v_mul_f32_e32 v117, v117, v131
	v_fma_f32 v127, -v136, v137, 1.0
	v_fmac_f32_e32 v137, v127, v137
	v_mul_f32_e32 v132, 0xbfb8aa3b, v118
	v_mul_f32_e32 v133, 0xbfb8aa3b, v119
	v_exp_f32_e32 v132, v132
	v_exp_f32_e32 v133, v133
	v_rcp_f32_e32 v127, v126
	s_nop 0
	v_mul_f32_e32 v116, v116, v127
	v_pk_add_f32 v[132:133], v[132:133], 1.0 op_sel_hi:[1,0]
	v_pk_mul_f32 v[112:113], v[112:113], v[116:117]
	v_div_scale_f32 v131, s[30:31], v133, v133, v119
	v_rcp_f32_e32 v135, v131
	v_cvt_pk_bf16_f32 v116, v112, v113
	v_fma_f32 v112, -v131, v135, 1.0
	v_fmac_f32_e32 v135, v112, v135
	v_rcp_f32_e32 v112, v133
	s_nop 0
	v_mul_f32_e32 v113, v119, v112
	v_rcp_f32_e32 v112, v132
	s_nop 0
	v_mul_f32_e32 v112, v118, v112
	v_pk_mul_f32 v[112:113], v[114:115], v[112:113]
	s_nop 0
	v_cvt_pk_bf16_f32 v117, v112, v113
	v_mad_i64_i32 v[112:113], s[30:31], v134, s53, v[120:121]
	v_lshl_add_u64 v[112:113], v[112:113], 0, v[122:123]
	global_store_dwordx2 v[112:113], v[116:117], off
	v_mul_f32_e32 v114, 0xbfb8aa3b, v108
	v_mul_f32_e32 v115, 0xbfb8aa3b, v109
	v_exp_f32_e32 v114, v114
	v_exp_f32_e32 v115, v115
	v_or_b32_e32 v118, 32, v130
	v_pk_add_f32 v[114:115], v[114:115], 1.0 op_sel_hi:[1,0]
	s_nop 0
	v_rcp_f32_e32 v116, v115
	s_nop 0
	v_mul_f32_e32 v109, v109, v116
	v_mul_f32_e32 v117, 0xbfb8aa3b, v111
	v_mul_f32_e32 v116, 0xbfb8aa3b, v110
	v_exp_f32_e32 v116, v116
	v_exp_f32_e32 v117, v117
	v_rcp_f32_e32 v115, v114
	s_nop 0
	v_mul_f32_e32 v108, v108, v115
	v_pk_add_f32 v[116:117], v[116:117], 1.0 op_sel_hi:[1,0]
	v_pk_mul_f32 v[104:105], v[104:105], v[108:109]
	s_nop 0
	v_cvt_pk_bf16_f32 v108, v104, v105
	v_rcp_f32_e32 v104, v117
	s_nop 0
	v_mul_f32_e32 v105, v111, v104
	v_rcp_f32_e32 v104, v116
	s_nop 0
	v_mul_f32_e32 v104, v110, v104
	v_pk_mul_f32 v[104:105], v[106:107], v[104:105]
	s_nop 0
	v_cvt_pk_bf16_f32 v109, v104, v105
	v_mad_i64_i32 v[104:105], s[30:31], v118, s53, v[120:121]
	v_lshl_add_u64 v[104:105], v[104:105], 0, v[122:123]
	global_store_dwordx2 v[104:105], v[108:109], off
	v_mul_f32_e32 v106, 0xbfb8aa3b, v100
	v_mul_f32_e32 v107, 0xbfb8aa3b, v101
	v_exp_f32_e32 v106, v106
	v_exp_f32_e32 v107, v107
	v_or_b32_e32 v110, 48, v130
	v_pk_add_f32 v[106:107], v[106:107], 1.0 op_sel_hi:[1,0]
	s_nop 0
	v_rcp_f32_e32 v108, v107
	s_nop 0
	v_mul_f32_e32 v101, v101, v108
	v_mul_f32_e32 v109, 0xbfb8aa3b, v103
	v_mul_f32_e32 v108, 0xbfb8aa3b, v102
	v_exp_f32_e32 v108, v108
	v_exp_f32_e32 v109, v109
	v_rcp_f32_e32 v107, v106
	s_nop 0
	v_mul_f32_e32 v100, v100, v107
	v_pk_add_f32 v[108:109], v[108:109], 1.0 op_sel_hi:[1,0]
	v_pk_mul_f32 v[96:97], v[96:97], v[100:101]
	s_nop 0
	v_cvt_pk_bf16_f32 v100, v96, v97
	v_rcp_f32_e32 v96, v109
	s_nop 0
	v_mul_f32_e32 v97, v103, v96
	v_rcp_f32_e32 v96, v108
	s_nop 0
	v_mul_f32_e32 v96, v102, v96
	v_pk_mul_f32 v[96:97], v[98:99], v[96:97]
	s_nop 0
	v_cvt_pk_bf16_f32 v101, v96, v97
	v_mad_i64_i32 v[96:97], s[30:31], v110, s53, v[120:121]
	v_lshl_add_u64 v[96:97], v[96:97], 0, v[122:123]
	global_store_dwordx2 v[96:97], v[100:101], off
	v_mul_f32_e32 v98, 0xbfb8aa3b, v92
	v_mul_f32_e32 v99, 0xbfb8aa3b, v93
	v_exp_f32_e32 v98, v98
	v_exp_f32_e32 v99, v99
	s_nop 0
	v_pk_add_f32 v[98:99], v[98:99], 1.0 op_sel_hi:[1,0]
	s_nop 0
	v_rcp_f32_e32 v100, v99
	s_nop 0
	v_mul_f32_e32 v93, v93, v100
	v_mul_f32_e32 v101, 0xbfb8aa3b, v95
	v_mul_f32_e32 v100, 0xbfb8aa3b, v94
	v_exp_f32_e32 v100, v100
	v_exp_f32_e32 v101, v101
	v_rcp_f32_e32 v99, v98
	s_nop 0
	v_mul_f32_e32 v92, v92, v99
	v_pk_add_f32 v[100:101], v[100:101], 1.0 op_sel_hi:[1,0]
	v_pk_mul_f32 v[88:89], v[88:89], v[92:93]
	s_nop 0
	v_cvt_pk_bf16_f32 v88, v88, v89
	v_rcp_f32_e32 v89, v101
	s_nop 0
	v_mul_f32_e32 v93, v95, v89
	v_rcp_f32_e32 v89, v100
	s_nop 0
	v_mul_f32_e32 v92, v94, v89
	v_pk_mul_f32 v[90:91], v[90:91], v[92:93]
	s_nop 0
	v_cvt_pk_bf16_f32 v89, v90, v91
	global_store_dwordx2 v[124:125], v[88:89], off offset:128
	v_mul_f32_e32 v88, 0xbfb8aa3b, v84
	v_mul_f32_e32 v89, 0xbfb8aa3b, v85
	v_exp_f32_e32 v88, v88
	v_exp_f32_e32 v89, v89
	s_nop 0
	v_pk_add_f32 v[88:89], v[88:89], 1.0 op_sel_hi:[1,0]
	s_nop 0
	v_rcp_f32_e32 v90, v89
	s_nop 0
	v_mul_f32_e32 v85, v85, v90
	v_mul_f32_e32 v91, 0xbfb8aa3b, v87
	v_mul_f32_e32 v90, 0xbfb8aa3b, v86
	v_exp_f32_e32 v90, v90
	v_exp_f32_e32 v91, v91
	v_rcp_f32_e32 v89, v88
	s_nop 0
	v_mul_f32_e32 v84, v84, v89
	v_pk_add_f32 v[90:91], v[90:91], 1.0 op_sel_hi:[1,0]
	v_pk_mul_f32 v[80:81], v[80:81], v[84:85]
	s_nop 0
	v_cvt_pk_bf16_f32 v80, v80, v81
	v_rcp_f32_e32 v81, v91
	s_nop 0
	v_mul_f32_e32 v85, v87, v81
	v_rcp_f32_e32 v81, v90
	s_nop 0
	v_mul_f32_e32 v84, v86, v81
	v_pk_mul_f32 v[82:83], v[82:83], v[84:85]
	s_nop 0
	v_cvt_pk_bf16_f32 v81, v82, v83
	global_store_dwordx2 v[112:113], v[80:81], off offset:128
	v_mul_f32_e32 v80, 0xbfb8aa3b, v76
	v_mul_f32_e32 v81, 0xbfb8aa3b, v77
	v_exp_f32_e32 v80, v80
	v_exp_f32_e32 v81, v81
	s_nop 0
	v_pk_add_f32 v[80:81], v[80:81], 1.0 op_sel_hi:[1,0]
	s_nop 0
	v_rcp_f32_e32 v82, v81
	s_nop 0
	v_mul_f32_e32 v77, v77, v82
	v_mul_f32_e32 v83, 0xbfb8aa3b, v79
	v_mul_f32_e32 v82, 0xbfb8aa3b, v78
	v_exp_f32_e32 v82, v82
	v_exp_f32_e32 v83, v83
	v_rcp_f32_e32 v81, v80
	s_nop 0
	v_mul_f32_e32 v76, v76, v81
	v_pk_add_f32 v[82:83], v[82:83], 1.0 op_sel_hi:[1,0]
	v_pk_mul_f32 v[72:73], v[72:73], v[76:77]
	s_nop 0
	v_cvt_pk_bf16_f32 v72, v72, v73
	v_rcp_f32_e32 v73, v83
	s_nop 0
	v_mul_f32_e32 v77, v79, v73
	v_rcp_f32_e32 v73, v82
	s_nop 0
	v_mul_f32_e32 v76, v78, v73
	v_pk_mul_f32 v[74:75], v[74:75], v[76:77]
	s_nop 0
	v_cvt_pk_bf16_f32 v73, v74, v75
	global_store_dwordx2 v[104:105], v[72:73], off offset:128
	v_mul_f32_e32 v72, 0xbfb8aa3b, v68
	v_mul_f32_e32 v73, 0xbfb8aa3b, v69
	v_exp_f32_e32 v72, v72
	v_exp_f32_e32 v73, v73
	s_nop 0
	v_pk_add_f32 v[72:73], v[72:73], 1.0 op_sel_hi:[1,0]
	s_nop 0
	v_rcp_f32_e32 v74, v73
	s_nop 0
	v_mul_f32_e32 v69, v69, v74
	v_mul_f32_e32 v75, 0xbfb8aa3b, v71
	v_mul_f32_e32 v74, 0xbfb8aa3b, v70
	v_exp_f32_e32 v74, v74
	v_exp_f32_e32 v75, v75
	v_rcp_f32_e32 v73, v72
	s_nop 0
	v_mul_f32_e32 v68, v68, v73
	v_pk_add_f32 v[74:75], v[74:75], 1.0 op_sel_hi:[1,0]
	v_pk_mul_f32 v[64:65], v[64:65], v[68:69]
	s_nop 0
	v_cvt_pk_bf16_f32 v64, v64, v65
	v_rcp_f32_e32 v65, v75
	s_nop 0
	v_mul_f32_e32 v69, v71, v65
	v_rcp_f32_e32 v65, v74
	s_nop 0
	v_mul_f32_e32 v68, v70, v65
	v_pk_mul_f32 v[66:67], v[66:67], v[68:69]
	s_nop 0
	v_cvt_pk_bf16_f32 v65, v66, v67
	global_store_dwordx2 v[96:97], v[64:65], off offset:128
	v_mul_f32_e32 v64, 0xbfb8aa3b, v60
	v_mul_f32_e32 v65, 0xbfb8aa3b, v61
	v_exp_f32_e32 v64, v64
	v_exp_f32_e32 v65, v65
	v_add_u32_e32 v68, 0x80, v130
	v_pk_add_f32 v[64:65], v[64:65], 1.0 op_sel_hi:[1,0]
	s_nop 0
	v_rcp_f32_e32 v66, v65
	s_nop 0
	v_mul_f32_e32 v61, v61, v66
	v_mul_f32_e32 v67, 0xbfb8aa3b, v63
	v_mul_f32_e32 v66, 0xbfb8aa3b, v62
	v_exp_f32_e32 v66, v66
	v_exp_f32_e32 v67, v67
	v_rcp_f32_e32 v65, v64
	s_nop 0
	v_mul_f32_e32 v60, v60, v65
	v_pk_add_f32 v[66:67], v[66:67], 1.0 op_sel_hi:[1,0]
	v_pk_mul_f32 v[56:57], v[56:57], v[60:61]
	s_nop 0
	v_cvt_pk_bf16_f32 v60, v56, v57
	v_rcp_f32_e32 v56, v67
	s_nop 0
	v_mul_f32_e32 v57, v63, v56
	v_rcp_f32_e32 v56, v66
	s_nop 0
	v_mul_f32_e32 v56, v62, v56
	v_pk_mul_f32 v[56:57], v[58:59], v[56:57]
	s_nop 0
	v_cvt_pk_bf16_f32 v61, v56, v57
	v_mad_i64_i32 v[56:57], s[30:31], v68, s53, v[120:121]
	v_lshl_add_u64 v[56:57], v[56:57], 0, v[122:123]
	global_store_dwordx2 v[56:57], v[60:61], off
	v_mul_f32_e32 v58, 0xbfb8aa3b, v52
	v_mul_f32_e32 v59, 0xbfb8aa3b, v53
	v_exp_f32_e32 v58, v58
	v_exp_f32_e32 v59, v59
	v_add_u32_e32 v62, 0x90, v130
	v_pk_add_f32 v[58:59], v[58:59], 1.0 op_sel_hi:[1,0]
	s_nop 0
	v_rcp_f32_e32 v60, v59
	s_nop 0
	v_mul_f32_e32 v53, v53, v60
	v_mul_f32_e32 v61, 0xbfb8aa3b, v55
	v_mul_f32_e32 v60, 0xbfb8aa3b, v54
	v_exp_f32_e32 v60, v60
	v_exp_f32_e32 v61, v61
	v_rcp_f32_e32 v59, v58
	s_nop 0
	v_mul_f32_e32 v52, v52, v59
	v_pk_add_f32 v[60:61], v[60:61], 1.0 op_sel_hi:[1,0]
	v_pk_mul_f32 v[48:49], v[48:49], v[52:53]
	s_nop 0
	v_cvt_pk_bf16_f32 v52, v48, v49
	v_rcp_f32_e32 v48, v61
	s_nop 0
	v_mul_f32_e32 v49, v55, v48
	v_rcp_f32_e32 v48, v60
	s_nop 0
	v_mul_f32_e32 v48, v54, v48
	v_pk_mul_f32 v[48:49], v[50:51], v[48:49]
	s_nop 0
	v_cvt_pk_bf16_f32 v53, v48, v49
	v_mad_i64_i32 v[48:49], s[30:31], v62, s53, v[120:121]
	v_lshl_add_u64 v[48:49], v[48:49], 0, v[122:123]
	global_store_dwordx2 v[48:49], v[52:53], off
	v_mul_f32_e32 v50, 0xbfb8aa3b, v44
	v_mul_f32_e32 v51, 0xbfb8aa3b, v45
	v_exp_f32_e32 v50, v50
	v_exp_f32_e32 v51, v51
	v_add_u32_e32 v54, 0xa0, v130
	v_pk_add_f32 v[50:51], v[50:51], 1.0 op_sel_hi:[1,0]
	s_nop 0
	v_rcp_f32_e32 v52, v51
	s_nop 0
	v_mul_f32_e32 v45, v45, v52
	v_mul_f32_e32 v53, 0xbfb8aa3b, v47
	v_mul_f32_e32 v52, 0xbfb8aa3b, v46
	v_exp_f32_e32 v52, v52
	v_exp_f32_e32 v53, v53
	v_rcp_f32_e32 v51, v50
	s_nop 0
	v_mul_f32_e32 v44, v44, v51
	v_pk_add_f32 v[52:53], v[52:53], 1.0 op_sel_hi:[1,0]
	v_pk_mul_f32 v[40:41], v[40:41], v[44:45]
	s_nop 0
	v_cvt_pk_bf16_f32 v44, v40, v41
	v_rcp_f32_e32 v40, v53
	s_nop 0
	v_mul_f32_e32 v41, v47, v40
	v_rcp_f32_e32 v40, v52
	s_nop 0
	v_mul_f32_e32 v40, v46, v40
	v_pk_mul_f32 v[40:41], v[42:43], v[40:41]
	s_nop 0
	v_cvt_pk_bf16_f32 v45, v40, v41
	v_mad_i64_i32 v[40:41], s[30:31], v54, s53, v[120:121]
	v_lshl_add_u64 v[40:41], v[40:41], 0, v[122:123]
	global_store_dwordx2 v[40:41], v[44:45], off
	v_mul_f32_e32 v42, 0xbfb8aa3b, v36
	v_mul_f32_e32 v43, 0xbfb8aa3b, v37
	v_exp_f32_e32 v42, v42
	v_exp_f32_e32 v43, v43
	v_add_u32_e32 v46, 0xb0, v130
	v_pk_add_f32 v[42:43], v[42:43], 1.0 op_sel_hi:[1,0]
	s_nop 0
	v_rcp_f32_e32 v44, v43
	s_nop 0
	v_mul_f32_e32 v37, v37, v44
	v_mul_f32_e32 v45, 0xbfb8aa3b, v39
	v_mul_f32_e32 v44, 0xbfb8aa3b, v38
	v_exp_f32_e32 v44, v44
	v_exp_f32_e32 v45, v45
	v_rcp_f32_e32 v43, v42
	s_nop 0
	v_mul_f32_e32 v36, v36, v43
	v_pk_add_f32 v[44:45], v[44:45], 1.0 op_sel_hi:[1,0]
	v_pk_mul_f32 v[32:33], v[32:33], v[36:37]
	s_nop 0
	v_cvt_pk_bf16_f32 v36, v32, v33
	v_rcp_f32_e32 v32, v45
	s_nop 0
	v_mul_f32_e32 v33, v39, v32
	v_rcp_f32_e32 v32, v44
	s_nop 0
	v_mul_f32_e32 v32, v38, v32
	v_pk_mul_f32 v[32:33], v[34:35], v[32:33]
	s_nop 0
	v_cvt_pk_bf16_f32 v37, v32, v33
	v_mad_i64_i32 v[32:33], s[30:31], v46, s53, v[120:121]
	v_lshl_add_u64 v[32:33], v[32:33], 0, v[122:123]
	global_store_dwordx2 v[32:33], v[36:37], off
	v_mul_f32_e32 v34, 0xbfb8aa3b, v28
	v_mul_f32_e32 v35, 0xbfb8aa3b, v29
	v_exp_f32_e32 v34, v34
	v_exp_f32_e32 v35, v35
	s_nop 0
	v_pk_add_f32 v[34:35], v[34:35], 1.0 op_sel_hi:[1,0]
	s_nop 0
	v_rcp_f32_e32 v36, v35
	s_nop 0
	v_mul_f32_e32 v29, v29, v36
	v_mul_f32_e32 v37, 0xbfb8aa3b, v31
	v_mul_f32_e32 v36, 0xbfb8aa3b, v30
	v_exp_f32_e32 v36, v36
	v_exp_f32_e32 v37, v37
	v_rcp_f32_e32 v35, v34
	s_nop 0
	v_mul_f32_e32 v28, v28, v35
	v_pk_add_f32 v[36:37], v[36:37], 1.0 op_sel_hi:[1,0]
	v_pk_mul_f32 v[24:25], v[24:25], v[28:29]
	s_nop 0
	v_cvt_pk_bf16_f32 v24, v24, v25
	v_rcp_f32_e32 v25, v37
	s_nop 0
	v_mul_f32_e32 v29, v31, v25
	v_rcp_f32_e32 v25, v36
	s_nop 0
	v_mul_f32_e32 v28, v30, v25
	v_pk_mul_f32 v[26:27], v[26:27], v[28:29]
	s_nop 0
	v_cvt_pk_bf16_f32 v25, v26, v27
	global_store_dwordx2 v[56:57], v[24:25], off offset:128
	v_mul_f32_e32 v24, 0xbfb8aa3b, v20
	v_mul_f32_e32 v25, 0xbfb8aa3b, v21
	v_exp_f32_e32 v24, v24
	v_exp_f32_e32 v25, v25
	s_nop 0
	v_pk_add_f32 v[24:25], v[24:25], 1.0 op_sel_hi:[1,0]
	s_nop 0
	v_rcp_f32_e32 v26, v25
	s_nop 0
	v_mul_f32_e32 v21, v21, v26
	v_mul_f32_e32 v27, 0xbfb8aa3b, v23
	v_mul_f32_e32 v26, 0xbfb8aa3b, v22
	v_exp_f32_e32 v26, v26
	v_exp_f32_e32 v27, v27
	v_rcp_f32_e32 v25, v24
	s_nop 0
	v_mul_f32_e32 v20, v20, v25
	v_pk_add_f32 v[26:27], v[26:27], 1.0 op_sel_hi:[1,0]
	v_pk_mul_f32 v[16:17], v[16:17], v[20:21]
	s_nop 0
	v_cvt_pk_bf16_f32 v16, v16, v17
	v_rcp_f32_e32 v17, v27
	s_nop 0
	v_mul_f32_e32 v21, v23, v17
	v_rcp_f32_e32 v17, v26
	s_nop 0
	v_mul_f32_e32 v20, v22, v17
	v_pk_mul_f32 v[18:19], v[18:19], v[20:21]
	s_nop 0
	v_cvt_pk_bf16_f32 v17, v18, v19
	global_store_dwordx2 v[48:49], v[16:17], off offset:128
	v_mul_f32_e32 v16, 0xbfb8aa3b, v12
	v_mul_f32_e32 v17, 0xbfb8aa3b, v13
	v_exp_f32_e32 v16, v16
	v_exp_f32_e32 v17, v17
	s_nop 0
	v_pk_add_f32 v[16:17], v[16:17], 1.0 op_sel_hi:[1,0]
	s_nop 0
	v_rcp_f32_e32 v18, v17
	s_nop 0
	v_mul_f32_e32 v13, v13, v18
	v_mul_f32_e32 v19, 0xbfb8aa3b, v15
	v_mul_f32_e32 v18, 0xbfb8aa3b, v14
	v_exp_f32_e32 v18, v18
	v_exp_f32_e32 v19, v19
	v_rcp_f32_e32 v17, v16
	s_nop 0
	v_mul_f32_e32 v12, v12, v17
	v_pk_add_f32 v[18:19], v[18:19], 1.0 op_sel_hi:[1,0]
	v_pk_mul_f32 v[8:9], v[8:9], v[12:13]
	s_nop 0
	v_cvt_pk_bf16_f32 v8, v8, v9
	v_rcp_f32_e32 v9, v19
	s_nop 0
	v_mul_f32_e32 v13, v15, v9
	v_rcp_f32_e32 v9, v18
	s_nop 0
	v_mul_f32_e32 v12, v14, v9
	v_pk_mul_f32 v[10:11], v[10:11], v[12:13]
	s_nop 0
	v_cvt_pk_bf16_f32 v9, v10, v11
	global_store_dwordx2 v[40:41], v[8:9], off offset:128
	v_mul_f32_e32 v8, 0xbfb8aa3b, v4
	v_mul_f32_e32 v9, 0xbfb8aa3b, v5
	v_exp_f32_e32 v8, v8
	v_exp_f32_e32 v9, v9
	s_nop 0
	v_pk_add_f32 v[8:9], v[8:9], 1.0 op_sel_hi:[1,0]
	s_nop 0
	v_rcp_f32_e32 v10, v9
	s_nop 0
	v_mul_f32_e32 v5, v5, v10
	v_mul_f32_e32 v11, 0xbfb8aa3b, v7
	v_mul_f32_e32 v10, 0xbfb8aa3b, v6
	v_exp_f32_e32 v10, v10
	v_exp_f32_e32 v11, v11
	v_rcp_f32_e32 v9, v8
	s_nop 0
	v_mul_f32_e32 v4, v4, v9
	v_pk_add_f32 v[10:11], v[10:11], 1.0 op_sel_hi:[1,0]
	v_pk_mul_f32 v[0:1], v[0:1], v[4:5]
	s_nop 0
	v_cvt_pk_bf16_f32 v0, v0, v1
	v_div_scale_f32 v8, s[30:31], v10, v10, v6
	v_rcp_f32_e32 v1, v11
	s_nop 0
	v_mul_f32_e32 v5, v7, v1
	v_rcp_f32_e32 v1, v10
	s_nop 0
	v_mul_f32_e32 v4, v6, v1
	v_pk_mul_f32 v[2:3], v[2:3], v[4:5]
	s_nop 0
	v_cvt_pk_bf16_f32 v1, v2, v3
	global_store_dwordx2 v[32:33], v[0:1], off offset:128
	s_andn2_b64 vcc, exec, s[0:1]
	s_mov_b32 s56, s54
	s_mov_b32 s38, s55
	s_cbranch_vccz .LBB0_695

.LBB0_868:
	global_load_dwordx4 v[6:9], v[2:3], off offset:-8
	v_mul_hi_u32 v10, v0, s2
	v_lshrrev_b32_e32 v12, 17, v10
	v_mul_hi_i32_i24_e32 v11, 0xffe80000, v12
	v_mul_i32_i24_e32 v10, 0xffe80000, v12
	v_lshl_add_u64 v[0:1], v[0:1], 0, s[8:9]
	v_mad_u64_u32 v[10:11], s[20:21], v12, s5, v[10:11]
	v_cmp_lt_u64_e32 vcc, s[16:17], v[0:1]
	v_lshl_add_u64 v[10:11], v[4:5], 0, v[10:11]
	s_or_b64 s[14:15], vcc, s[14:15]
	v_add_co_u32_e32 v10, vcc, -4, v10
	v_lshl_add_u64 v[2:3], v[2:3], 0, s[10:11]
	v_lshl_add_u64 v[4:5], v[4:5], 0, s[12:13]
	v_addc_co_u32_e32 v11, vcc, -1, v11, vcc
	s_waitcnt vmcnt(0)
	v_cvt_pk_bf16_f32 v6, v6, v7
	v_cvt_pk_bf16_f32 v7, v8, v9
	global_store_dwordx2 v[10:11], v[6:7], off
	s_andn2_b64 exec, exec, s[14:15]
	s_cbranch_execnz .LBB0_868

.LBB0_872:
	s_waitcnt vmcnt(0)
	ds_write2_b32 v56, v0, v1 offset1:1
	ds_write2_b32 v56, v2, v3 offset0:2 offset1:3
	v_add_u32_e32 v0, 0x1040, v56
	ds_write2_b32 v0, v4, v5 offset1:1
	v_add_u32_e32 v0, 0x1048, v56
	ds_write2_b32 v0, v6, v7 offset1:1
	v_add_u32_e32 v0, 0x2080, v56
	ds_write2_b32 v0, v8, v9 offset1:1
	v_add_u32_e32 v0, 0x2088, v56
	ds_write2_b32 v0, v10, v11 offset1:1
	v_add_u32_e32 v0, 0x30c0, v56
	ds_write2_b32 v0, v12, v13 offset1:1
	v_add_u32_e32 v0, 0x30c8, v56
	ds_write2_b32 v0, v14, v15 offset1:1
	s_waitcnt lgkmcnt(0)
	s_barrier
	ds_read2_b32 v[0:1], v51 offset1:130
	ds_read2_b32 v[2:3], v52 offset0:65 offset1:195
	v_add_u32_e32 v4, 0x400, v52
	v_add_u32_e32 v6, 0x800, v51
	v_add_u32_e32 v8, 0x800, v52
	v_add_u32_e32 v10, 0xc00, v51
	s_waitcnt lgkmcnt(0)
	v_cvt_pk_bf16_f32 v0, v0, v2
	v_add_u32_e32 v2, 0x400, v51
	v_add_u32_e32 v12, 0xc00, v52
	v_cvt_pk_bf16_f32 v1, v1, v3
	ds_read2_b32 v[2:3], v2 offset0:4 offset1:134
	ds_read2_b32 v[4:5], v4 offset0:69 offset1:199
	ds_read2_b32 v[6:7], v6 offset0:8 offset1:138
	ds_read2_b32 v[8:9], v8 offset0:73 offset1:203
	ds_read2_b32 v[10:11], v10 offset0:12 offset1:142
	ds_read2_b32 v[12:13], v12 offset0:77 offset1:207
	v_or_b32_e32 v14, v48, v50
	v_mul_u32_u24_e32 v32, 0x880, v14
	s_waitcnt lgkmcnt(4)
	v_cvt_pk_bf16_f32 v2, v2, v4
	v_cvt_pk_bf16_f32 v3, v3, v5
	s_waitcnt lgkmcnt(2)
	v_cvt_pk_bf16_f32 v4, v6, v8
	v_cvt_pk_bf16_f32 v5, v7, v9
	s_waitcnt lgkmcnt(0)
	v_cvt_pk_bf16_f32 v6, v10, v12
	v_cvt_pk_bf16_f32 v7, v11, v13
	v_or_b32_e32 v8, v43, v53
	v_lshl_add_u64 v[10:11], v[36:37], 0, v[32:33]
	v_mov_b32_e32 v9, v33
	v_lshl_add_u64 v[8:9], v[8:9], 1, v[10:11]
	v_mov_b32_e32 v43, v33
	s_add_i32 s2, s2, s4
	v_lshl_add_u64 v[8:9], v[8:9], 0, v[42:43]
	s_add_i32 s14, s13, s2
	global_store_dwordx2 v[8:9], v[0:1], off
	global_store_dwordx2 v[8:9], v[2:3], off offset:16
	global_store_dwordx2 v[8:9], v[4:5], off offset:32
	global_store_dwordx2 v[8:9], v[6:7], off offset:48
	v_add_u32_e32 v54, s10, v54
	v_add_u32_e32 v55, s11, v55
	s_cmpk_lt_i32 s14, 0x600
	v_mov_b32_e32 v48, v39
	v_mov_b32_e32 v43, v57
	v_mov_b64_e32 v[36:37], v[44:45]
	v_mov_b64_e32 v[0:1], v[16:17]
	v_mov_b64_e32 v[2:3], v[18:19]
	v_mov_b64_e32 v[4:5], v[20:21]
	v_mov_b64_e32 v[6:7], v[22:23]
	v_mov_b64_e32 v[8:9], v[24:25]
	v_mov_b64_e32 v[10:11], v[26:27]
	v_mov_b64_e32 v[12:13], v[28:29]
	v_mov_b64_e32 v[14:15], v[30:31]
	s_waitcnt lgkmcnt(0)
	s_barrier
	s_cbranch_scc0 .LBB0_875

.LBB0_889:
	s_or_b64 exec, exec, s[6:7]
	v_or_b32_e32 v132, s4, v163
	v_add_u32_e32 v134, v132, v146
	v_lshlrev_b32_e32 v142, 2, v130
	v_cmp_gt_u32_e64 s[30:31], 2, v130
	v_add_u32_e32 v130, 0xffff8000, v134
	v_lshrrev_b32_e32 v143, 6, v130
	v_mad_u64_u32 v[136:137], s[4:5], v130, s63, 0
	v_lshlrev_b32_e32 v130, 1, v163
	v_mad_i64_i32 v[138:139], s[4:5], v134, s63, 0
	v_lshlrev_b32_e32 v132, 5, v145
	v_and_b32_e32 v162, 24, v130
	s_movk_i32 s4, 0xfc3
	v_or3_b32 v132, v132, s84, v142
	v_ashrrev_i32_e32 v135, 31, v134
	v_and_b32_e32 v164, 3, v144
	v_ashrrev_i32_e32 v130, 12, v134
	v_and_or_b32 v174, v134, s4, v162
	s_movk_i32 s4, 0x2ff
	s_movk_i32 s8, 0x5ff
	v_lshlrev_b64 v[140:141], 11, v[134:135]
	v_cmp_lt_i32_e64 s[20:21], s2, v134
	v_cmp_gt_i32_e64 s[6:7], s61, v134
	v_mul_lo_u32 v175, v143, 6
	v_or_b32_e32 v173, v162, v164
	v_mul_i32_i24_e32 v172, 6, v130
	v_cmp_lt_i32_e64 s[4:5], s4, v132
	v_cmp_lt_i32_e64 s[12:13], s8, v132
	s_and_saveexec_b64 s[8:9], s[12:13]
	s_xor_b64 s[8:9], exec, s[8:9]
	s_cbranch_execz .LBB0_898
	s_cmpk_gt_u32 s84, 0x8ff
	s_mov_b64 s[10:11], -1
	s_cbranch_scc0 .LBB0_892
	v_lshl_add_u64 v[148:149], s[54:55], 0, v[140:141]
	v_mov_b32_e32 v133, v131
	v_lshl_add_u64 v[148:149], v[132:133], 1, v[148:149]
	v_add_co_u32_e32 v148, vcc, 0xfffff400, v148
	v_cvt_pk_bf16_f32 v146, v124, v125
	v_cvt_pk_bf16_f32 v147, v126, v127
	v_addc_co_u32_e32 v149, vcc, -1, v149, vcc
	global_store_dwordx2 v[148:149], v[146:147], off
	s_mov_b64 s[10:11], 0
.LBB0_892:
	s_andn2_b64 vcc, exec, s[10:11]
	s_cbranch_vccnz .LBB0_898
	v_add_u32_e32 v130, 0xfffffa00, v132
	v_lshrrev_b32_e32 v135, 7, v130
	v_and_b32_e32 v133, 0x6c, v132
	s_and_saveexec_b64 s[10:11], s[20:21]
	s_xor_b64 s[10:11], exec, s[10:11]
	s_cbranch_execz .LBB0_895
	v_lshl_add_u64 v[146:147], s[68:69], 0, v[136:137]
	v_lshl_add_u64 v[146:147], v[130:131], 2, v[146:147]
	v_add_u32_e32 v130, v135, v175
	global_store_dwordx4 v[146:147], v[124:127], off
	v_lshlrev_b64 v[146:147], 7, v[130:131]
	v_or_b32_e32 v130, v146, v133
	v_mov_b64_e32 v[148:149], s[48:49]
	v_mad_u64_u32 v[148:149], s[14:15], v130, s51, v[148:149]
	v_mad_u32_u24 v149, v147, s51, v149
	v_lshlrev_b32_e32 v130, 1, v173
	v_cvt_pk_bf16_f32 v124, v124, s0
	v_lshl_add_u64 v[146:147], v[148:149], 0, v[130:131]
	global_store_short v[146:147], v124, off offset:2048
	v_add_co_u32_e32 v124, vcc, 0x1000, v146
	v_cvt_pk_bf16_f32 v130, v125, s0
	s_nop 0
	v_addc_co_u32_e32 v125, vcc, 0, v147, vcc
	v_cvt_pk_bf16_f32 v126, v126, s0
	global_store_short v[124:125], v130, off offset:128
	global_store_short v[124:125], v126, off offset:2304
	v_add_co_u32_e32 v124, vcc, 0x2000, v146
	v_cvt_pk_bf16_f32 v126, v127, s0
	s_nop 0
	v_addc_co_u32_e32 v125, vcc, 0, v147, vcc
	global_store_short v[124:125], v126, off offset:384
.LBB0_895:
	s_andn2_saveexec_b64 s[10:11], s[10:11]
	s_cbranch_execz .LBB0_897
	v_lshl_add_u64 v[146:147], s[70:71], 0, v[138:139]
	v_lshl_add_u64 v[146:147], v[130:131], 2, v[146:147]
	global_store_dwordx4 v[146:147], v[124:127], off
	v_add_u32_e32 v146, v135, v172
	v_ashrrev_i32_e32 v147, 31, v146
	v_lshlrev_b32_e32 v130, 1, v174
	v_lshl_add_u64 v[148:149], s[46:47], 0, v[130:131]
	v_lshlrev_b64 v[146:147], 20, v[146:147]
	v_lshlrev_b32_e32 v130, 13, v133
	v_lshl_add_u64 v[146:147], v[148:149], 0, v[146:147]
	v_cvt_pk_bf16_f32 v124, v124, s0
	v_lshl_add_u64 v[146:147], v[146:147], 0, v[130:131]
	s_movk_i32 s14, 0x2000
	global_store_short v[146:147], v124, off
	v_add_co_u32_e32 v124, vcc, s14, v146
	v_cvt_pk_bf16_f32 v130, v125, s0
	s_nop 0
	v_addc_co_u32_e32 v125, vcc, 0, v147, vcc
	global_store_short v[124:125], v130, off
	v_add_co_u32_e32 v124, vcc, 0x4000, v146
	v_cvt_pk_bf16_f32 v126, v126, s0
	s_nop 0
	v_addc_co_u32_e32 v125, vcc, 0, v147, vcc
	global_store_short v[124:125], v126, off
	v_add_co_u32_e32 v124, vcc, 0x6000, v146
	v_cvt_pk_bf16_f32 v126, v127, s0
	s_nop 0
	v_addc_co_u32_e32 v125, vcc, 0, v147, vcc
	global_store_short v[124:125], v126, off

.LBB0_898:
	s_or_saveexec_b64 s[8:9], s[8:9]
	v_and_b32_e32 v130, 0xfcf, v134
	v_or_b32_e32 v165, 0x400, v163
	v_cndmask_b32_e64 v130, v165, v130, s[6:7]
	v_lshlrev_b32_e32 v187, 3, v130
	v_mul_lo_u32 v130, v143, s88
	v_or_b32_e32 v130, v130, v163
	v_add_u32_e32 v130, 0x400, v130
	v_bfe_u32 v160, v144, 6, 1
	v_and_b32_e32 v135, 4, v142
	v_mad_u64_u32 v[144:145], s[6:7], v130, s89, 0
	v_mad_i64_i32 v[142:143], s[6:7], v134, s62, 0
	s_xor_b64 exec, exec, s[8:9]
	s_cbranch_execz .LBB0_910
	v_cmp_eq_u32_e32 vcc, 0, v160
	s_and_saveexec_b64 s[6:7], vcc
	s_cbranch_execz .LBB0_901
	v_cmp_lt_i32_e32 vcc, v158, v156
	s_nop 1
	v_cndmask_b32_e32 v130, v155, v158, vcc
	v_lshlrev_b32_e32 v130, 2, v130
	ds_bpermute_b32 v150, v130, v124
	ds_bpermute_b32 v151, v130, v125
	ds_bpermute_b32 v152, v130, v126
	ds_bpermute_b32 v153, v130, v127
	v_lshlrev_b32_e32 v130, 3, v187
	v_lshl_add_u64 v[146:147], s[52:53], 0, v[130:131]
	v_lshlrev_b32_e32 v130, 3, v135
	v_lshl_add_u64 v[166:167], v[146:147], 0, v[130:131]
	global_load_dwordx4 v[146:149], v[166:167], off
	s_waitcnt vmcnt(0) lgkmcnt(0)
	v_mov_b32_e32 v169, v148
	v_mov_b32_e32 v148, v147
	v_mov_b32_e32 v168, v146
	v_pk_mul_f32 v[146:147], v[148:149], v[150:151]
	s_nop 0
	v_cndmask_b32_e64 v147, v147, -v147, s[30:31]
	v_cndmask_b32_e64 v146, v146, -v146, s[30:31]
	v_pk_fma_f32 v[124:125], v[124:125], v[168:169], v[146:147]
	global_load_dwordx4 v[146:149], v[166:167], off offset:16
	s_waitcnt vmcnt(0) lgkmcnt(0)
	v_mov_b32_e32 v151, v148
	v_mov_b32_e32 v148, v147
	v_mov_b32_e32 v150, v146
	v_pk_mul_f32 v[146:147], v[148:149], v[152:153]
	s_nop 0
	v_cndmask_b32_e64 v147, v147, -v147, s[30:31]
	v_cndmask_b32_e64 v146, v146, -v146, s[30:31]
	v_pk_fma_f32 v[126:127], v[126:127], v[150:151], v[146:147]
.LBB0_901:
	s_or_b64 exec, exec, s[6:7]
	v_cvt_pk_bf16_f32 v146, v124, v125
	v_cvt_pk_bf16_f32 v147, v126, v127
	s_and_saveexec_b64 s[6:7], s[4:5]
	s_xor_b64 s[6:7], exec, s[6:7]
	s_cbranch_execz .LBB0_907
	v_add_u32_e32 v130, 0xfffffd00, v132
	s_and_saveexec_b64 s[10:11], s[20:21]
	s_xor_b64 s[10:11], exec, s[10:11]
	s_cbranch_execz .LBB0_904
	v_lshl_add_u64 v[148:149], s[56:57], 0, v[144:145]
	v_lshl_add_u64 v[148:149], v[130:131], 1, v[148:149]
	global_store_dwordx2 v[148:149], v[146:147], off
	v_lshl_add_u64 v[146:147], s[72:73], 0, v[136:137]
	v_lshl_add_u64 v[146:147], v[130:131], 2, v[146:147]
	global_store_dwordx4 v[146:147], v[124:127], off
.LBB0_904:
	s_andn2_saveexec_b64 s[10:11], s[10:11]
	s_cbranch_execz .LBB0_906
	v_lshl_add_u64 v[148:149], v[142:143], 1, s[44:45]
	v_lshl_add_u64 v[148:149], v[130:131], 1, v[148:149]
	global_store_dwordx2 v[148:149], v[146:147], off
	v_lshl_add_u64 v[146:147], v[142:143], 2, s[74:75]
	v_lshl_add_u64 v[146:147], v[130:131], 2, v[146:147]
	global_store_dwordx4 v[146:147], v[124:127], off

.LBB0_907:
	s_andn2_saveexec_b64 s[6:7], s[6:7]
	s_cbranch_execz .LBB0_909
	v_lshl_add_u64 v[124:125], s[54:55], 0, v[140:141]
	v_ashrrev_i32_e32 v133, 31, v132
	v_lshl_add_u64 v[124:125], v[132:133], 1, v[124:125]
	global_store_dwordx2 v[124:125], v[146:147], off

.LBB0_910:
	s_or_b64 exec, exec, s[8:9]
	v_or_b32_e32 v161, 16, v132
	s_movk_i32 s6, 0x2ff
	v_cmp_lt_i32_e64 s[10:11], s6, v161
	s_movk_i32 s6, 0x5ff
	v_cmp_lt_i32_e64 s[16:17], s6, v161
	s_and_saveexec_b64 s[6:7], s[16:17]
	s_xor_b64 s[6:7], exec, s[6:7]
	s_cbranch_execz .LBB0_919
	s_cmpk_lt_u32 s84, 0x900
	s_mov_b64 s[8:9], -1
	s_cbranch_scc1 .LBB0_913
	v_lshl_add_u64 v[126:127], s[54:55], 0, v[140:141]
	v_mov_b32_e32 v133, v131
	v_lshl_add_u64 v[126:127], v[132:133], 1, v[126:127]
	v_add_co_u32_e32 v126, vcc, 0xfffff420, v126
	v_cvt_pk_bf16_f32 v124, v120, v121
	v_cvt_pk_bf16_f32 v125, v122, v123
	v_addc_co_u32_e32 v127, vcc, -1, v127, vcc
	s_mov_b64 s[8:9], 0
	global_store_dwordx2 v[126:127], v[124:125], off
.LBB0_913:
	s_andn2_b64 vcc, exec, s[8:9]
	s_cbranch_vccnz .LBB0_919
	v_add_u32_e32 v130, 0xfffffa10, v132
	v_lshrrev_b32_e32 v125, 7, v130
	v_and_b32_e32 v124, 0x7c, v161
	s_and_saveexec_b64 s[8:9], s[20:21]
	s_xor_b64 s[8:9], exec, s[8:9]
	s_cbranch_execz .LBB0_916
	v_lshl_add_u64 v[126:127], s[68:69], 0, v[136:137]
	v_lshl_add_u64 v[126:127], v[130:131], 2, v[126:127]
	v_add_u32_e32 v130, v125, v175
	global_store_dwordx4 v[126:127], v[120:123], off
	v_lshlrev_b64 v[126:127], 7, v[130:131]
	v_or_b32_e32 v126, v126, v124
	v_mov_b64_e32 v[124:125], s[48:49]
	v_mad_u64_u32 v[124:125], s[14:15], v126, s51, v[124:125]
	v_mad_u32_u24 v125, v127, s51, v125
	v_lshlrev_b32_e32 v130, 1, v173
	v_cvt_pk_bf16_f32 v120, v120, s0
	v_lshl_add_u64 v[124:125], v[124:125], 0, v[130:131]
	global_store_short v[124:125], v120, off offset:2048
	v_add_co_u32_e32 v120, vcc, 0x1000, v124
	v_cvt_pk_bf16_f32 v126, v121, s0
	s_nop 0
	v_addc_co_u32_e32 v121, vcc, 0, v125, vcc
	v_cvt_pk_bf16_f32 v122, v122, s0
	global_store_short v[120:121], v126, off offset:128
	global_store_short v[120:121], v122, off offset:2304
	v_add_co_u32_e32 v120, vcc, 0x2000, v124
	v_cvt_pk_bf16_f32 v122, v123, s0
	s_nop 0
	v_addc_co_u32_e32 v121, vcc, 0, v125, vcc
	global_store_short v[120:121], v122, off offset:384
.LBB0_916:
	s_andn2_saveexec_b64 s[8:9], s[8:9]
	s_cbranch_execz .LBB0_918
	v_lshl_add_u64 v[126:127], s[70:71], 0, v[138:139]
	v_lshl_add_u64 v[126:127], v[130:131], 2, v[126:127]
	global_store_dwordx4 v[126:127], v[120:123], off
	v_add_u32_e32 v126, v125, v172
	v_ashrrev_i32_e32 v127, 31, v126
	v_lshlrev_b32_e32 v130, 1, v174
	v_lshl_add_u64 v[146:147], s[46:47], 0, v[130:131]
	v_lshlrev_b64 v[126:127], 20, v[126:127]
	v_lshlrev_b32_e32 v130, 13, v124
	v_lshl_add_u64 v[124:125], v[146:147], 0, v[126:127]
	v_cvt_pk_bf16_f32 v120, v120, s0
	v_lshl_add_u64 v[124:125], v[124:125], 0, v[130:131]
	s_movk_i32 s14, 0x2000
	global_store_short v[124:125], v120, off
	v_add_co_u32_e32 v120, vcc, s14, v124
	v_cvt_pk_bf16_f32 v126, v121, s0
	s_nop 0
	v_addc_co_u32_e32 v121, vcc, 0, v125, vcc
	global_store_short v[120:121], v126, off
	v_add_co_u32_e32 v120, vcc, 0x4000, v124
	v_cvt_pk_bf16_f32 v122, v122, s0
	s_nop 0
	v_addc_co_u32_e32 v121, vcc, 0, v125, vcc
	global_store_short v[120:121], v122, off
	v_add_co_u32_e32 v120, vcc, 0x6000, v124
	v_cvt_pk_bf16_f32 v122, v123, s0
	s_nop 0
	v_addc_co_u32_e32 v121, vcc, 0, v125, vcc
	global_store_short v[120:121], v122, off

.LBB0_919:
	s_andn2_saveexec_b64 s[6:7], s[6:7]
	s_cbranch_execz .LBB0_929
	v_cvt_pk_bf16_f32 v124, v120, v121
	v_cvt_pk_bf16_f32 v125, v122, v123
	s_and_saveexec_b64 s[8:9], s[10:11]
	s_xor_b64 s[8:9], exec, s[8:9]
	s_cbranch_execz .LBB0_926
	v_add_u32_e32 v130, 0xfffffd10, v132
	s_and_saveexec_b64 s[14:15], s[20:21]
	s_xor_b64 s[14:15], exec, s[14:15]
	s_cbranch_execz .LBB0_923
	v_lshl_add_u64 v[126:127], s[56:57], 0, v[144:145]
	v_lshl_add_u64 v[126:127], v[130:131], 1, v[126:127]
	global_store_dwordx2 v[126:127], v[124:125], off
	v_lshl_add_u64 v[124:125], s[72:73], 0, v[136:137]
	v_lshl_add_u64 v[124:125], v[130:131], 2, v[124:125]
	global_store_dwordx4 v[124:125], v[120:123], off
.LBB0_923:
	s_andn2_saveexec_b64 s[14:15], s[14:15]
	s_cbranch_execz .LBB0_925
	v_lshl_add_u64 v[126:127], v[142:143], 1, s[44:45]
	v_lshl_add_u64 v[126:127], v[130:131], 1, v[126:127]
	global_store_dwordx2 v[126:127], v[124:125], off
	v_lshl_add_u64 v[124:125], v[142:143], 2, s[74:75]
	v_lshl_add_u64 v[124:125], v[130:131], 2, v[124:125]
	global_store_dwordx4 v[124:125], v[120:123], off

.LBB0_926:
	s_andn2_saveexec_b64 s[8:9], s[8:9]
	s_cbranch_execz .LBB0_928
	v_lshl_add_u64 v[120:121], s[54:55], 0, v[140:141]
	v_ashrrev_i32_e32 v133, 31, v132
	v_lshl_add_u64 v[120:121], v[132:133], 1, v[120:121]
	global_store_dwordx2 v[120:121], v[124:125], off offset:32

.LBB0_929:
	s_or_b64 exec, exec, s[6:7]
	v_or_b32_e32 v126, 16, v134
	v_lshlrev_b32_e32 v122, 1, v134
	v_ashrrev_i32_e32 v127, 31, v126
	v_add_u32_e32 v120, 0xffff8010, v134
	v_and_b32_e32 v152, 24, v122
	v_lshlrev_b64 v[124:125], 11, v[126:127]
	v_lshrrev_b32_e32 v127, 6, v120
	v_or_b32_e32 v179, v164, v152
	v_cmp_lt_i32_e64 s[22:23], s2, v126
	v_cmp_gt_i32_e64 s[6:7], s61, v126
	v_mad_u64_u32 v[120:121], s[8:9], v120, s63, 0
	v_mul_lo_u32 v184, v127, 6
	v_or_b32_e32 v177, 4, v179
	v_mad_i64_i32 v[122:123], s[8:9], v126, s63, 0
	v_or_b32_e32 v176, 4, v174
	s_and_saveexec_b64 s[8:9], s[12:13]
	s_xor_b64 s[8:9], exec, s[8:9]
	s_cbranch_execz .LBB0_938
	s_cmpk_lt_u32 s84, 0x900
	s_mov_b64 s[14:15], -1
	s_cbranch_scc1 .LBB0_932
	v_lshl_add_u64 v[148:149], s[54:55], 0, v[124:125]
	v_mov_b32_e32 v133, v131
	v_lshl_add_u64 v[148:149], v[132:133], 1, v[148:149]
	v_add_co_u32_e32 v148, vcc, 0xfffff400, v148
	v_cvt_pk_bf16_f32 v146, v116, v117
	v_cvt_pk_bf16_f32 v147, v118, v119
	v_addc_co_u32_e32 v149, vcc, -1, v149, vcc
	s_mov_b64 s[14:15], 0
	global_store_dwordx2 v[148:149], v[146:147], off
.LBB0_932:
	s_andn2_b64 vcc, exec, s[14:15]
	s_cbranch_vccnz .LBB0_938
	v_add_u32_e32 v130, 0xfffffa00, v132
	v_lshrrev_b32_e32 v146, 7, v130
	v_and_b32_e32 v133, 0x6c, v132
	s_and_saveexec_b64 s[14:15], s[22:23]
	s_xor_b64 s[14:15], exec, s[14:15]
	s_cbranch_execz .LBB0_935
	v_lshl_add_u64 v[148:149], s[68:69], 0, v[120:121]
	v_lshl_add_u64 v[148:149], v[130:131], 2, v[148:149]
	v_add_u32_e32 v130, v146, v184
	v_lshlrev_b64 v[146:147], 7, v[130:131]
	global_store_dwordx4 v[148:149], v[116:119], off
	v_or_b32_e32 v130, v146, v133
	v_mov_b64_e32 v[148:149], s[48:49]
	v_mad_u64_u32 v[148:149], s[18:19], v130, s51, v[148:149]
	v_mad_u32_u24 v149, v147, s51, v149
	v_lshlrev_b32_e32 v130, 1, v179
	v_cvt_pk_bf16_f32 v116, v116, s0
	v_lshl_add_u64 v[146:147], v[148:149], 0, v[130:131]
	v_lshlrev_b32_e32 v130, 1, v177
	global_store_short v[146:147], v116, off offset:2056
	v_cvt_pk_bf16_f32 v133, v117, s0
	v_lshl_add_u64 v[116:117], v[148:149], 0, v[130:131]
	v_add_co_u32_e32 v146, vcc, 0x1000, v116
	v_cvt_pk_bf16_f32 v118, v118, s0
	s_nop 0
	v_addc_co_u32_e32 v147, vcc, 0, v117, vcc
	v_add_co_u32_e32 v116, vcc, 0x2000, v116
	global_store_short v[146:147], v118, off offset:2304
	v_cvt_pk_bf16_f32 v118, v119, s0
	v_addc_co_u32_e32 v117, vcc, 0, v117, vcc
	global_store_short v[146:147], v133, off offset:128
	global_store_short v[116:117], v118, off offset:384
.LBB0_935:
	s_andn2_saveexec_b64 s[14:15], s[14:15]
	s_cbranch_execz .LBB0_937
	v_add_u32_e32 v146, v146, v172
	v_ashrrev_i32_e32 v147, 31, v146
	v_lshl_add_u64 v[148:149], s[70:71], 0, v[122:123]
	v_lshlrev_b64 v[146:147], 20, v[146:147]
	v_lshl_add_u64 v[148:149], v[130:131], 2, v[148:149]
	v_lshlrev_b32_e32 v130, 13, v133
	v_lshl_add_u64 v[146:147], s[46:47], 0, v[146:147]
	v_lshl_add_u64 v[146:147], v[146:147], 0, v[130:131]
	v_lshlrev_b32_e32 v130, 1, v176
	global_store_dwordx4 v[148:149], v[116:119], off
	v_lshl_add_u64 v[146:147], v[146:147], 0, v[130:131]
	s_movk_i32 s18, 0x2000
	v_cvt_pk_bf16_f32 v116, v116, s0
	global_store_short v[146:147], v116, off
	v_add_co_u32_e32 v116, vcc, s18, v146
	v_cvt_pk_bf16_f32 v130, v117, s0
	s_nop 0
	v_addc_co_u32_e32 v117, vcc, 0, v147, vcc
	global_store_short v[116:117], v130, off
	v_add_co_u32_e32 v116, vcc, 0x4000, v146
	v_cvt_pk_bf16_f32 v118, v118, s0
	s_nop 0
	v_addc_co_u32_e32 v117, vcc, 0, v147, vcc
	global_store_short v[116:117], v118, off
	v_add_co_u32_e32 v116, vcc, 0x6000, v146
	v_cvt_pk_bf16_f32 v118, v119, s0
	s_nop 0
	v_addc_co_u32_e32 v117, vcc, 0, v147, vcc
	global_store_short v[116:117], v118, off

.LBB0_938:
	s_or_saveexec_b64 s[8:9], s[8:9]
	v_or_b32_e32 v168, 16, v163
	s_movk_i32 s14, 0xfdf
	v_mul_lo_u32 v127, v127, s88
	v_bitop3_b32 v130, v134, s14, 16 bitop3:0xc8
	v_or_b32_e32 v171, 0x410, v163
	v_or_b32_e32 v127, v127, v168
	v_cndmask_b32_e64 v130, v171, v130, s[6:7]
	v_add_u32_e32 v127, 0x400, v127
	v_lshlrev_b32_e32 v189, 3, v130
	v_mad_u64_u32 v[146:147], s[6:7], v127, s89, 0
	v_mad_i64_i32 v[126:127], s[6:7], v126, s62, 0
	s_xor_b64 exec, exec, s[8:9]
	s_cbranch_execz .LBB0_950
	v_cmp_eq_u32_e32 vcc, 0, v160
	s_and_saveexec_b64 s[6:7], vcc
	s_cbranch_execz .LBB0_941
	v_cmp_lt_i32_e32 vcc, v158, v156
	s_nop 1
	v_cndmask_b32_e32 v130, v155, v158, vcc
	v_lshlrev_b32_e32 v130, 2, v130
	ds_bpermute_b32 v166, v130, v116
	ds_bpermute_b32 v167, v130, v117
	ds_bpermute_b32 v180, v130, v118
	ds_bpermute_b32 v181, v130, v119
	v_lshlrev_b32_e32 v130, 3, v189
	v_lshl_add_u64 v[148:149], s[52:53], 0, v[130:131]
	v_lshlrev_b32_e32 v130, 3, v135
	v_lshl_add_u64 v[182:183], v[148:149], 0, v[130:131]
	global_load_dwordx4 v[148:151], v[182:183], off
	s_waitcnt vmcnt(0) lgkmcnt(0)
	v_mov_b32_e32 v191, v150
	v_mov_b32_e32 v150, v149
	v_mov_b32_e32 v190, v148
	v_pk_mul_f32 v[148:149], v[150:151], v[166:167]
	s_nop 0
	v_cndmask_b32_e64 v149, v149, -v149, s[30:31]
	v_cndmask_b32_e64 v148, v148, -v148, s[30:31]
	v_pk_fma_f32 v[116:117], v[116:117], v[190:191], v[148:149]
	global_load_dwordx4 v[148:151], v[182:183], off offset:16
	s_waitcnt vmcnt(0) lgkmcnt(0)
	v_mov_b32_e32 v167, v150
	v_mov_b32_e32 v150, v149
	v_mov_b32_e32 v166, v148
	v_pk_mul_f32 v[148:149], v[150:151], v[180:181]
	s_nop 0
	v_cndmask_b32_e64 v149, v149, -v149, s[30:31]
	v_cndmask_b32_e64 v148, v148, -v148, s[30:31]
	v_pk_fma_f32 v[118:119], v[118:119], v[166:167], v[148:149]
.LBB0_941:
	s_or_b64 exec, exec, s[6:7]
	v_cvt_pk_bf16_f32 v148, v116, v117
	v_cvt_pk_bf16_f32 v149, v118, v119
	s_and_saveexec_b64 s[6:7], s[4:5]
	s_xor_b64 s[6:7], exec, s[6:7]
	s_cbranch_execz .LBB0_947
	v_add_u32_e32 v130, 0xfffffd00, v132
	s_and_saveexec_b64 s[14:15], s[22:23]
	s_xor_b64 s[14:15], exec, s[14:15]
	s_cbranch_execz .LBB0_944
	v_lshl_add_u64 v[150:151], s[56:57], 0, v[146:147]
	v_lshl_add_u64 v[150:151], v[130:131], 1, v[150:151]
	global_store_dwordx2 v[150:151], v[148:149], off
	v_lshl_add_u64 v[148:149], s[72:73], 0, v[120:121]
	v_lshl_add_u64 v[148:149], v[130:131], 2, v[148:149]
	global_store_dwordx4 v[148:149], v[116:119], off
.LBB0_944:
	s_andn2_saveexec_b64 s[14:15], s[14:15]
	s_cbranch_execz .LBB0_946
	v_lshl_add_u64 v[150:151], v[126:127], 1, s[44:45]
	v_lshl_add_u64 v[150:151], v[130:131], 1, v[150:151]
	global_store_dwordx2 v[150:151], v[148:149], off
	v_lshl_add_u64 v[148:149], v[126:127], 2, s[74:75]
	v_lshl_add_u64 v[148:149], v[130:131], 2, v[148:149]
	global_store_dwordx4 v[148:149], v[116:119], off

.LBB0_947:
	s_andn2_saveexec_b64 s[6:7], s[6:7]
	s_cbranch_execz .LBB0_949
	v_lshl_add_u64 v[116:117], s[54:55], 0, v[124:125]
	v_ashrrev_i32_e32 v133, 31, v132
	v_lshl_add_u64 v[116:117], v[132:133], 1, v[116:117]
	global_store_dwordx2 v[116:117], v[148:149], off

.LBB0_950:
	s_or_b64 exec, exec, s[8:9]
	s_and_saveexec_b64 s[6:7], s[16:17]
	s_xor_b64 s[6:7], exec, s[6:7]
	s_cbranch_execz .LBB0_959
	s_cmpk_lt_u32 s84, 0x900
	s_mov_b64 s[8:9], -1
	s_cbranch_scc1 .LBB0_953
	v_lshl_add_u64 v[118:119], s[54:55], 0, v[124:125]
	v_mov_b32_e32 v133, v131
	v_lshl_add_u64 v[118:119], v[132:133], 1, v[118:119]
	v_add_co_u32_e32 v118, vcc, 0xfffff420, v118
	v_cvt_pk_bf16_f32 v116, v112, v113
	v_cvt_pk_bf16_f32 v117, v114, v115
	v_addc_co_u32_e32 v119, vcc, -1, v119, vcc
	s_mov_b64 s[8:9], 0
	global_store_dwordx2 v[118:119], v[116:117], off
.LBB0_953:
	s_andn2_b64 vcc, exec, s[8:9]
	s_cbranch_vccnz .LBB0_959
	v_add_u32_e32 v130, 0xfffffa10, v132
	v_lshrrev_b32_e32 v117, 7, v130
	v_and_b32_e32 v116, 0x7c, v161
	s_and_saveexec_b64 s[8:9], s[22:23]
	s_xor_b64 s[8:9], exec, s[8:9]
	s_cbranch_execz .LBB0_956
	v_lshl_add_u64 v[118:119], s[68:69], 0, v[120:121]
	v_lshl_add_u64 v[118:119], v[130:131], 2, v[118:119]
	v_add_u32_e32 v130, v117, v184
	global_store_dwordx4 v[118:119], v[112:115], off
	v_lshlrev_b64 v[118:119], 7, v[130:131]
	v_or_b32_e32 v118, v118, v116
	v_mov_b64_e32 v[116:117], s[48:49]
	v_mad_u64_u32 v[116:117], s[14:15], v118, s51, v[116:117]
	v_mad_u32_u24 v117, v119, s51, v117
	v_lshlrev_b32_e32 v130, 1, v179
	v_cvt_pk_bf16_f32 v112, v112, s0
	v_lshl_add_u64 v[118:119], v[116:117], 0, v[130:131]
	v_lshlrev_b32_e32 v130, 1, v177
	global_store_short v[118:119], v112, off offset:2056
	v_cvt_pk_bf16_f32 v118, v113, s0
	v_lshl_add_u64 v[112:113], v[116:117], 0, v[130:131]
	v_add_co_u32_e32 v116, vcc, 0x1000, v112
	v_cvt_pk_bf16_f32 v114, v114, s0
	s_nop 0
	v_addc_co_u32_e32 v117, vcc, 0, v113, vcc
	v_add_co_u32_e32 v112, vcc, 0x2000, v112
	global_store_short v[116:117], v114, off offset:2304
	v_cvt_pk_bf16_f32 v114, v115, s0
	v_addc_co_u32_e32 v113, vcc, 0, v113, vcc
	global_store_short v[116:117], v118, off offset:128
	global_store_short v[112:113], v114, off offset:384
.LBB0_956:
	s_andn2_saveexec_b64 s[8:9], s[8:9]
	s_cbranch_execz .LBB0_958
	v_lshl_add_u64 v[118:119], s[70:71], 0, v[122:123]
	v_lshl_add_u64 v[118:119], v[130:131], 2, v[118:119]
	global_store_dwordx4 v[118:119], v[112:115], off
	v_add_u32_e32 v118, v117, v172
	v_ashrrev_i32_e32 v119, 31, v118
	v_lshlrev_b64 v[118:119], 20, v[118:119]
	v_lshlrev_b32_e32 v130, 13, v116
	v_lshl_add_u64 v[116:117], s[46:47], 0, v[118:119]
	v_lshl_add_u64 v[116:117], v[116:117], 0, v[130:131]
	v_lshlrev_b32_e32 v130, 1, v176
	v_cvt_pk_bf16_f32 v112, v112, s0
	v_lshl_add_u64 v[116:117], v[116:117], 0, v[130:131]
	s_movk_i32 s14, 0x2000
	global_store_short v[116:117], v112, off
	v_add_co_u32_e32 v112, vcc, s14, v116
	v_cvt_pk_bf16_f32 v118, v113, s0
	s_nop 0
	v_addc_co_u32_e32 v113, vcc, 0, v117, vcc
	global_store_short v[112:113], v118, off
	v_add_co_u32_e32 v112, vcc, 0x4000, v116
	v_cvt_pk_bf16_f32 v114, v114, s0
	s_nop 0
	v_addc_co_u32_e32 v113, vcc, 0, v117, vcc
	global_store_short v[112:113], v114, off
	v_add_co_u32_e32 v112, vcc, 0x6000, v116
	v_cvt_pk_bf16_f32 v114, v115, s0
	s_nop 0
	v_addc_co_u32_e32 v113, vcc, 0, v117, vcc
	global_store_short v[112:113], v114, off

.LBB0_959:
	s_andn2_saveexec_b64 s[6:7], s[6:7]
	s_cbranch_execz .LBB0_969
	v_cvt_pk_bf16_f32 v116, v112, v113
	v_cvt_pk_bf16_f32 v117, v114, v115
	s_and_saveexec_b64 s[8:9], s[10:11]
	s_xor_b64 s[8:9], exec, s[8:9]
	s_cbranch_execz .LBB0_966
	v_add_u32_e32 v130, 0xfffffd10, v132
	s_and_saveexec_b64 s[14:15], s[22:23]
	s_xor_b64 s[14:15], exec, s[14:15]
	s_cbranch_execz .LBB0_963
	v_lshl_add_u64 v[118:119], s[56:57], 0, v[146:147]
	v_lshl_add_u64 v[118:119], v[130:131], 1, v[118:119]
	global_store_dwordx2 v[118:119], v[116:117], off
	v_lshl_add_u64 v[116:117], s[72:73], 0, v[120:121]
	v_lshl_add_u64 v[116:117], v[130:131], 2, v[116:117]
	global_store_dwordx4 v[116:117], v[112:115], off
.LBB0_963:
	s_andn2_saveexec_b64 s[14:15], s[14:15]
	s_cbranch_execz .LBB0_965
	v_lshl_add_u64 v[118:119], v[126:127], 1, s[44:45]
	v_lshl_add_u64 v[118:119], v[130:131], 1, v[118:119]
	global_store_dwordx2 v[118:119], v[116:117], off
	v_lshl_add_u64 v[116:117], v[126:127], 2, s[74:75]
	v_lshl_add_u64 v[116:117], v[130:131], 2, v[116:117]
	global_store_dwordx4 v[116:117], v[112:115], off

.LBB0_966:
	s_andn2_saveexec_b64 s[8:9], s[8:9]
	s_cbranch_execz .LBB0_968
	v_lshl_add_u64 v[112:113], s[54:55], 0, v[124:125]
	v_ashrrev_i32_e32 v133, 31, v132
	v_lshl_add_u64 v[112:113], v[132:133], 1, v[112:113]
	global_store_dwordx2 v[112:113], v[116:117], off offset:32

.LBB0_969:
	s_or_b64 exec, exec, s[6:7]
	v_or_b32_e32 v118, 32, v134
	v_ashrrev_i32_e32 v119, 31, v118
	v_add_u32_e32 v112, 0xffff8020, v134
	v_lshlrev_b64 v[116:117], 11, v[118:119]
	v_lshrrev_b32_e32 v119, 6, v112
	v_mad_u64_u32 v[112:113], s[8:9], v112, s63, 0
	v_mad_i64_i32 v[114:115], s[8:9], v118, s63, 0
	s_movk_i32 s8, 0xfe3
	v_cmp_lt_i32_e64 s[26:27], s2, v118
	v_cmp_gt_i32_e64 s[6:7], s61, v118
	v_mul_lo_u32 v186, v119, 6
	v_and_or_b32 v183, v118, 35, v152
	v_and_or_b32 v182, v118, s8, v162
	s_and_saveexec_b64 s[8:9], s[12:13]
	s_xor_b64 s[8:9], exec, s[8:9]
	s_cbranch_execz .LBB0_978
	s_cmpk_lt_u32 s84, 0x900
	s_mov_b64 s[14:15], -1
	s_cbranch_scc1 .LBB0_972
	v_lshl_add_u64 v[150:151], s[54:55], 0, v[116:117]
	v_mov_b32_e32 v133, v131
	v_lshl_add_u64 v[150:151], v[132:133], 1, v[150:151]
	v_add_co_u32_e32 v150, vcc, 0xfffff400, v150
	v_cvt_pk_bf16_f32 v148, v108, v109
	v_cvt_pk_bf16_f32 v149, v110, v111
	v_addc_co_u32_e32 v151, vcc, -1, v151, vcc
	s_mov_b64 s[14:15], 0
	global_store_dwordx2 v[150:151], v[148:149], off
.LBB0_972:
	s_andn2_b64 vcc, exec, s[14:15]
	s_cbranch_vccnz .LBB0_978
	v_add_u32_e32 v130, 0xfffffa00, v132
	v_lshrrev_b32_e32 v148, 7, v130
	v_and_b32_e32 v133, 0x6c, v132
	s_and_saveexec_b64 s[14:15], s[26:27]
	s_xor_b64 s[14:15], exec, s[14:15]
	s_cbranch_execz .LBB0_975
	v_lshl_add_u64 v[150:151], s[68:69], 0, v[112:113]
	v_lshl_add_u64 v[150:151], v[130:131], 2, v[150:151]
	v_add_u32_e32 v130, v148, v186
	v_lshlrev_b64 v[148:149], 7, v[130:131]
	global_store_dwordx4 v[150:151], v[108:111], off
	v_or_b32_e32 v130, v148, v133
	v_mov_b64_e32 v[150:151], s[48:49]
	v_mad_u64_u32 v[150:151], s[18:19], v130, s51, v[150:151]
	v_mad_u32_u24 v151, v149, s51, v151
	v_lshlrev_b32_e32 v130, 1, v183
	v_cvt_pk_bf16_f32 v108, v108, s0
	v_lshl_add_u64 v[148:149], v[150:151], 0, v[130:131]
	global_store_short v[148:149], v108, off offset:2048
	v_add_co_u32_e32 v108, vcc, 0x1000, v148
	v_cvt_pk_bf16_f32 v130, v109, s0
	s_nop 0
	v_addc_co_u32_e32 v109, vcc, 0, v149, vcc
	v_cvt_pk_bf16_f32 v110, v110, s0
	global_store_short v[108:109], v130, off offset:128
	global_store_short v[108:109], v110, off offset:2304
	v_add_co_u32_e32 v108, vcc, 0x2000, v148
	v_cvt_pk_bf16_f32 v110, v111, s0
	s_nop 0
	v_addc_co_u32_e32 v109, vcc, 0, v149, vcc
	global_store_short v[108:109], v110, off offset:384
.LBB0_975:
	s_andn2_saveexec_b64 s[14:15], s[14:15]
	s_cbranch_execz .LBB0_977
	v_lshl_add_u64 v[150:151], s[70:71], 0, v[114:115]
	v_add_u32_e32 v148, v148, v172
	v_lshl_add_u64 v[150:151], v[130:131], 2, v[150:151]
	v_ashrrev_i32_e32 v149, 31, v148
	v_lshlrev_b32_e32 v130, 1, v182
	global_store_dwordx4 v[150:151], v[108:111], off
	v_lshl_add_u64 v[150:151], s[46:47], 0, v[130:131]
	v_lshlrev_b64 v[148:149], 20, v[148:149]
	v_lshlrev_b32_e32 v130, 13, v133
	v_lshl_add_u64 v[148:149], v[150:151], 0, v[148:149]
	v_cvt_pk_bf16_f32 v108, v108, s0
	v_lshl_add_u64 v[148:149], v[148:149], 0, v[130:131]
	s_movk_i32 s18, 0x2000
	global_store_short v[148:149], v108, off
	v_add_co_u32_e32 v108, vcc, s18, v148
	v_cvt_pk_bf16_f32 v130, v109, s0
	s_nop 0
	v_addc_co_u32_e32 v109, vcc, 0, v149, vcc
	global_store_short v[108:109], v130, off
	v_add_co_u32_e32 v108, vcc, 0x4000, v148
	v_cvt_pk_bf16_f32 v110, v110, s0
	s_nop 0
	v_addc_co_u32_e32 v109, vcc, 0, v149, vcc
	global_store_short v[108:109], v110, off
	v_add_co_u32_e32 v108, vcc, 0x6000, v148
	v_cvt_pk_bf16_f32 v110, v111, s0
	s_nop 0
	v_addc_co_u32_e32 v109, vcc, 0, v149, vcc
	global_store_short v[108:109], v110, off

.LBB0_978:
	s_or_saveexec_b64 s[8:9], s[8:9]
	v_or_b32_e32 v166, 32, v163
	s_movk_i32 s14, 0xfef
	v_mul_lo_u32 v119, v119, s88
	v_bitop3_b32 v130, v134, s14, 32 bitop3:0xc8
	v_or_b32_e32 v169, 0x420, v163
	v_or_b32_e32 v119, v119, v166
	v_cndmask_b32_e64 v130, v169, v130, s[6:7]
	v_add_u32_e32 v119, 0x400, v119
	v_lshlrev_b32_e32 v188, 3, v130
	v_mad_u64_u32 v[148:149], s[6:7], v119, s89, 0
	v_mad_i64_i32 v[118:119], s[6:7], v118, s62, 0
	s_xor_b64 exec, exec, s[8:9]
	s_cbranch_execz .LBB0_990
	v_cmp_eq_u32_e32 vcc, 0, v160
	s_and_saveexec_b64 s[6:7], vcc
	s_cbranch_execz .LBB0_981
	v_cmp_lt_i32_e32 vcc, v158, v156
	s_nop 1
	v_cndmask_b32_e32 v130, v155, v158, vcc
	v_lshlrev_b32_e32 v130, 2, v130
	ds_bpermute_b32 v150, v130, v108
	ds_bpermute_b32 v151, v130, v109
	ds_bpermute_b32 v180, v130, v110
	ds_bpermute_b32 v181, v130, v111
	v_lshlrev_b32_e32 v130, 3, v188
	v_lshl_add_u64 v[190:191], s[52:53], 0, v[130:131]
	v_lshlrev_b32_e32 v130, 3, v135
	v_lshl_add_u64 v[194:195], v[190:191], 0, v[130:131]
	global_load_dwordx4 v[190:193], v[194:195], off
	s_waitcnt vmcnt(0) lgkmcnt(0)
	v_mov_b32_e32 v197, v192
	v_mov_b32_e32 v192, v191
	v_mov_b32_e32 v196, v190
	v_pk_mul_f32 v[150:151], v[192:193], v[150:151]
	global_load_dwordx4 v[190:193], v[194:195], off offset:16
	v_cndmask_b32_e64 v151, v151, -v151, s[30:31]
	v_cndmask_b32_e64 v150, v150, -v150, s[30:31]
	v_pk_fma_f32 v[108:109], v[108:109], v[196:197], v[150:151]
	s_waitcnt vmcnt(0) lgkmcnt(0)
	v_mov_b32_e32 v151, v192
	v_mov_b32_e32 v192, v191
	v_pk_mul_f32 v[180:181], v[192:193], v[180:181]
	v_mov_b32_e32 v150, v190
	v_cndmask_b32_e64 v181, v181, -v181, s[30:31]
	v_cndmask_b32_e64 v180, v180, -v180, s[30:31]
	v_pk_fma_f32 v[110:111], v[110:111], v[150:151], v[180:181]
.LBB0_981:
	s_or_b64 exec, exec, s[6:7]
	v_cvt_pk_bf16_f32 v150, v108, v109
	v_cvt_pk_bf16_f32 v151, v110, v111
	s_and_saveexec_b64 s[6:7], s[4:5]
	s_xor_b64 s[6:7], exec, s[6:7]
	s_cbranch_execz .LBB0_987
	v_add_u32_e32 v130, 0xfffffd00, v132
	s_and_saveexec_b64 s[14:15], s[26:27]
	s_xor_b64 s[14:15], exec, s[14:15]
	s_cbranch_execz .LBB0_984
	v_lshl_add_u64 v[180:181], s[56:57], 0, v[148:149]
	v_lshl_add_u64 v[180:181], v[130:131], 1, v[180:181]
	global_store_dwordx2 v[180:181], v[150:151], off
	v_lshl_add_u64 v[150:151], s[72:73], 0, v[112:113]
	v_lshl_add_u64 v[150:151], v[130:131], 2, v[150:151]
	global_store_dwordx4 v[150:151], v[108:111], off
.LBB0_984:
	s_andn2_saveexec_b64 s[14:15], s[14:15]
	s_cbranch_execz .LBB0_986
	v_lshl_add_u64 v[180:181], v[118:119], 1, s[44:45]
	v_lshl_add_u64 v[180:181], v[130:131], 1, v[180:181]
	global_store_dwordx2 v[180:181], v[150:151], off
	v_lshl_add_u64 v[150:151], v[118:119], 2, s[74:75]
	v_lshl_add_u64 v[150:151], v[130:131], 2, v[150:151]
	global_store_dwordx4 v[150:151], v[108:111], off

.LBB0_987:
	s_andn2_saveexec_b64 s[6:7], s[6:7]
	s_cbranch_execz .LBB0_989
	v_lshl_add_u64 v[108:109], s[54:55], 0, v[116:117]
	v_ashrrev_i32_e32 v133, 31, v132
	v_lshl_add_u64 v[108:109], v[132:133], 1, v[108:109]
	global_store_dwordx2 v[108:109], v[150:151], off

.LBB0_990:
	s_or_b64 exec, exec, s[8:9]
	s_and_saveexec_b64 s[6:7], s[16:17]
	s_xor_b64 s[6:7], exec, s[6:7]
	s_cbranch_execz .LBB0_999
	s_cmpk_lt_u32 s84, 0x900
	s_mov_b64 s[8:9], -1
	s_cbranch_scc1 .LBB0_993
	v_lshl_add_u64 v[110:111], s[54:55], 0, v[116:117]
	v_mov_b32_e32 v133, v131
	v_lshl_add_u64 v[110:111], v[132:133], 1, v[110:111]
	v_add_co_u32_e32 v110, vcc, 0xfffff420, v110
	v_cvt_pk_bf16_f32 v108, v104, v105
	v_cvt_pk_bf16_f32 v109, v106, v107
	v_addc_co_u32_e32 v111, vcc, -1, v111, vcc
	s_mov_b64 s[8:9], 0
	global_store_dwordx2 v[110:111], v[108:109], off
.LBB0_993:
	s_andn2_b64 vcc, exec, s[8:9]
	s_cbranch_vccnz .LBB0_999
	v_add_u32_e32 v130, 0xfffffa10, v132
	v_lshrrev_b32_e32 v109, 7, v130
	v_and_b32_e32 v108, 0x7c, v161
	s_and_saveexec_b64 s[8:9], s[26:27]
	s_xor_b64 s[8:9], exec, s[8:9]
	s_cbranch_execz .LBB0_996
	v_lshl_add_u64 v[110:111], s[68:69], 0, v[112:113]
	v_lshl_add_u64 v[110:111], v[130:131], 2, v[110:111]
	v_add_u32_e32 v130, v109, v186
	global_store_dwordx4 v[110:111], v[104:107], off
	v_lshlrev_b64 v[110:111], 7, v[130:131]
	v_or_b32_e32 v110, v110, v108
	v_mov_b64_e32 v[108:109], s[48:49]
	v_mad_u64_u32 v[108:109], s[14:15], v110, s51, v[108:109]
	v_mad_u32_u24 v109, v111, s51, v109
	v_lshlrev_b32_e32 v130, 1, v183
	v_cvt_pk_bf16_f32 v104, v104, s0
	v_lshl_add_u64 v[108:109], v[108:109], 0, v[130:131]
	global_store_short v[108:109], v104, off offset:2048
	v_add_co_u32_e32 v104, vcc, 0x1000, v108
	v_cvt_pk_bf16_f32 v110, v105, s0
	s_nop 0
	v_addc_co_u32_e32 v105, vcc, 0, v109, vcc
	v_cvt_pk_bf16_f32 v106, v106, s0
	global_store_short v[104:105], v110, off offset:128
	global_store_short v[104:105], v106, off offset:2304
	v_add_co_u32_e32 v104, vcc, 0x2000, v108
	v_cvt_pk_bf16_f32 v106, v107, s0
	s_nop 0
	v_addc_co_u32_e32 v105, vcc, 0, v109, vcc
	global_store_short v[104:105], v106, off offset:384
.LBB0_996:
	s_andn2_saveexec_b64 s[8:9], s[8:9]
	s_cbranch_execz .LBB0_998
	v_lshl_add_u64 v[110:111], s[70:71], 0, v[114:115]
	v_lshl_add_u64 v[110:111], v[130:131], 2, v[110:111]
	global_store_dwordx4 v[110:111], v[104:107], off
	v_add_u32_e32 v110, v109, v172
	v_ashrrev_i32_e32 v111, 31, v110
	v_lshlrev_b32_e32 v130, 1, v182
	v_lshl_add_u64 v[150:151], s[46:47], 0, v[130:131]
	v_lshlrev_b64 v[110:111], 20, v[110:111]
	v_lshlrev_b32_e32 v130, 13, v108
	v_lshl_add_u64 v[108:109], v[150:151], 0, v[110:111]
	v_cvt_pk_bf16_f32 v104, v104, s0
	v_lshl_add_u64 v[108:109], v[108:109], 0, v[130:131]
	s_movk_i32 s14, 0x2000
	global_store_short v[108:109], v104, off
	v_add_co_u32_e32 v104, vcc, s14, v108
	v_cvt_pk_bf16_f32 v110, v105, s0
	s_nop 0
	v_addc_co_u32_e32 v105, vcc, 0, v109, vcc
	global_store_short v[104:105], v110, off
	v_add_co_u32_e32 v104, vcc, 0x4000, v108
	v_cvt_pk_bf16_f32 v106, v106, s0
	s_nop 0
	v_addc_co_u32_e32 v105, vcc, 0, v109, vcc
	global_store_short v[104:105], v106, off
	v_add_co_u32_e32 v104, vcc, 0x6000, v108
	v_cvt_pk_bf16_f32 v106, v107, s0
	s_nop 0
	v_addc_co_u32_e32 v105, vcc, 0, v109, vcc
	global_store_short v[104:105], v106, off

.LBB0_999:
	s_andn2_saveexec_b64 s[6:7], s[6:7]
	s_cbranch_execz .LBB0_1009
	v_cvt_pk_bf16_f32 v108, v104, v105
	v_cvt_pk_bf16_f32 v109, v106, v107
	s_and_saveexec_b64 s[8:9], s[10:11]
	s_xor_b64 s[8:9], exec, s[8:9]
	s_cbranch_execz .LBB0_1006
	v_add_u32_e32 v130, 0xfffffd10, v132
	s_and_saveexec_b64 s[14:15], s[26:27]
	s_xor_b64 s[14:15], exec, s[14:15]
	s_cbranch_execz .LBB0_1003
	v_lshl_add_u64 v[110:111], s[56:57], 0, v[148:149]
	v_lshl_add_u64 v[110:111], v[130:131], 1, v[110:111]
	global_store_dwordx2 v[110:111], v[108:109], off
	v_lshl_add_u64 v[108:109], s[72:73], 0, v[112:113]
	v_lshl_add_u64 v[108:109], v[130:131], 2, v[108:109]
	global_store_dwordx4 v[108:109], v[104:107], off
.LBB0_1003:
	s_andn2_saveexec_b64 s[14:15], s[14:15]
	s_cbranch_execz .LBB0_1005
	v_lshl_add_u64 v[110:111], v[118:119], 1, s[44:45]
	v_lshl_add_u64 v[110:111], v[130:131], 1, v[110:111]
	global_store_dwordx2 v[110:111], v[108:109], off
	v_lshl_add_u64 v[108:109], v[118:119], 2, s[74:75]
	v_lshl_add_u64 v[108:109], v[130:131], 2, v[108:109]
	global_store_dwordx4 v[108:109], v[104:107], off

.LBB0_1006:
	s_andn2_saveexec_b64 s[8:9], s[8:9]
	s_cbranch_execz .LBB0_1008
	v_lshl_add_u64 v[104:105], s[54:55], 0, v[116:117]
	v_ashrrev_i32_e32 v133, 31, v132
	v_lshl_add_u64 v[104:105], v[132:133], 1, v[104:105]
	global_store_dwordx2 v[104:105], v[108:109], off offset:32

.LBB0_1009:
	s_or_b64 exec, exec, s[6:7]
	v_or_b32_e32 v110, 48, v134
	v_ashrrev_i32_e32 v111, 31, v110
	v_add_u32_e32 v104, 0xffff8030, v134
	v_lshlrev_b64 v[108:109], 11, v[110:111]
	v_lshrrev_b32_e32 v111, 6, v104
	v_mad_u64_u32 v[104:105], s[8:9], v104, s63, 0
	v_mad_i64_i32 v[106:107], s[8:9], v110, s63, 0
	s_movk_i32 s8, 0xfe3
	v_and_or_b32 v181, v110, 35, v152
	v_bitop3_b32 v130, v134, s8, 48 bitop3:0xc8
	v_cmp_lt_i32_e64 s[24:25], s2, v110
	v_cmp_gt_i32_e64 s[6:7], s61, v110
	v_mul_lo_u32 v185, v111, 6
	v_or_b32_e32 v180, 4, v181
	v_or3_b32 v178, v162, v130, 4
	s_and_saveexec_b64 s[8:9], s[12:13]
	s_xor_b64 s[8:9], exec, s[8:9]
	s_cbranch_execz .LBB0_1018
	s_cmpk_lt_u32 s84, 0x900
	s_mov_b64 s[14:15], -1
	s_cbranch_scc1 .LBB0_1012
	v_lshl_add_u64 v[152:153], s[54:55], 0, v[108:109]
	v_mov_b32_e32 v133, v131
	v_lshl_add_u64 v[152:153], v[132:133], 1, v[152:153]
	v_add_co_u32_e32 v152, vcc, 0xfffff400, v152
	v_cvt_pk_bf16_f32 v150, v100, v101
	v_cvt_pk_bf16_f32 v151, v102, v103
	v_addc_co_u32_e32 v153, vcc, -1, v153, vcc
	s_mov_b64 s[14:15], 0
	global_store_dwordx2 v[152:153], v[150:151], off
.LBB0_1012:
	s_andn2_b64 vcc, exec, s[14:15]
	s_cbranch_vccnz .LBB0_1018
	v_add_u32_e32 v130, 0xfffffa00, v132
	v_lshrrev_b32_e32 v150, 7, v130
	v_and_b32_e32 v133, 0x6c, v132
	s_and_saveexec_b64 s[14:15], s[24:25]
	s_xor_b64 s[14:15], exec, s[14:15]
	s_cbranch_execz .LBB0_1015
	v_lshl_add_u64 v[152:153], s[68:69], 0, v[104:105]
	v_lshl_add_u64 v[152:153], v[130:131], 2, v[152:153]
	v_add_u32_e32 v130, v150, v185
	v_lshlrev_b64 v[150:151], 7, v[130:131]
	global_store_dwordx4 v[152:153], v[100:103], off
	v_or_b32_e32 v130, v150, v133
	v_mov_b64_e32 v[152:153], s[48:49]
	v_mad_u64_u32 v[152:153], s[18:19], v130, s51, v[152:153]
	v_mad_u32_u24 v153, v151, s51, v153
	v_lshlrev_b32_e32 v130, 1, v181
	v_cvt_pk_bf16_f32 v100, v100, s0
	v_lshl_add_u64 v[150:151], v[152:153], 0, v[130:131]
	v_lshlrev_b32_e32 v130, 1, v180
	global_store_short v[150:151], v100, off offset:2056
	v_cvt_pk_bf16_f32 v133, v101, s0
	v_lshl_add_u64 v[100:101], v[152:153], 0, v[130:131]
	v_add_co_u32_e32 v150, vcc, 0x1000, v100
	v_cvt_pk_bf16_f32 v102, v102, s0
	s_nop 0
	v_addc_co_u32_e32 v151, vcc, 0, v101, vcc
	v_add_co_u32_e32 v100, vcc, 0x2000, v100
	global_store_short v[150:151], v102, off offset:2304
	v_cvt_pk_bf16_f32 v102, v103, s0
	v_addc_co_u32_e32 v101, vcc, 0, v101, vcc
	global_store_short v[150:151], v133, off offset:128
	global_store_short v[100:101], v102, off offset:384
.LBB0_1015:
	s_andn2_saveexec_b64 s[14:15], s[14:15]
	s_cbranch_execz .LBB0_1017
	v_add_u32_e32 v150, v150, v172
	v_ashrrev_i32_e32 v151, 31, v150
	v_lshl_add_u64 v[152:153], s[70:71], 0, v[106:107]
	v_lshlrev_b64 v[150:151], 20, v[150:151]
	v_lshl_add_u64 v[152:153], v[130:131], 2, v[152:153]
	v_lshlrev_b32_e32 v130, 13, v133
	v_lshl_add_u64 v[150:151], s[46:47], 0, v[150:151]
	v_lshl_add_u64 v[150:151], v[150:151], 0, v[130:131]
	v_lshlrev_b32_e32 v130, 1, v178
	global_store_dwordx4 v[152:153], v[100:103], off
	v_lshl_add_u64 v[150:151], v[150:151], 0, v[130:131]
	s_movk_i32 s18, 0x2000
	v_cvt_pk_bf16_f32 v100, v100, s0
	global_store_short v[150:151], v100, off
	v_add_co_u32_e32 v100, vcc, s18, v150
	v_cvt_pk_bf16_f32 v130, v101, s0
	s_nop 0
	v_addc_co_u32_e32 v101, vcc, 0, v151, vcc
	global_store_short v[100:101], v130, off
	v_add_co_u32_e32 v100, vcc, 0x4000, v150
	v_cvt_pk_bf16_f32 v102, v102, s0
	s_nop 0
	v_addc_co_u32_e32 v101, vcc, 0, v151, vcc
	global_store_short v[100:101], v102, off
	v_add_co_u32_e32 v100, vcc, 0x6000, v150
	v_cvt_pk_bf16_f32 v102, v103, s0
	s_nop 0
	v_addc_co_u32_e32 v101, vcc, 0, v151, vcc
	global_store_short v[100:101], v102, off

.LBB0_1018:
	s_or_saveexec_b64 s[8:9], s[8:9]
	v_or_b32_e32 v167, 48, v163
	s_movk_i32 s14, 0xfff
	v_mul_lo_u32 v111, v111, s88
	v_bitop3_b32 v130, v134, s14, 48 bitop3:0xc8
	v_or_b32_e32 v170, 0x430, v163
	v_or_b32_e32 v111, v111, v167
	v_cndmask_b32_e64 v130, v170, v130, s[6:7]
	v_add_u32_e32 v111, 0x400, v111
	v_lshlrev_b32_e32 v190, 3, v130
	v_mad_u64_u32 v[150:151], s[6:7], v111, s89, 0
	v_mad_i64_i32 v[110:111], s[6:7], v110, s62, 0
	s_xor_b64 exec, exec, s[8:9]
	s_cbranch_execz .LBB0_1030
	v_cmp_eq_u32_e32 vcc, 0, v160
	s_and_saveexec_b64 s[6:7], vcc
	s_cbranch_execz .LBB0_1021
	v_cmp_lt_i32_e32 vcc, v158, v156
	s_nop 1
	v_cndmask_b32_e32 v130, v155, v158, vcc
	v_lshlrev_b32_e32 v130, 2, v130
	ds_bpermute_b32 v152, v130, v100
	ds_bpermute_b32 v153, v130, v101
	ds_bpermute_b32 v196, v130, v102
	ds_bpermute_b32 v197, v130, v103
	v_lshlrev_b32_e32 v130, 3, v190
	v_lshl_add_u64 v[192:193], s[52:53], 0, v[130:131]
	v_lshlrev_b32_e32 v130, 3, v135
	v_lshl_add_u64 v[198:199], v[192:193], 0, v[130:131]
	global_load_dwordx4 v[192:195], v[198:199], off
	s_waitcnt vmcnt(0) lgkmcnt(0)
	v_mov_b32_e32 v201, v194
	v_mov_b32_e32 v194, v193
	v_mov_b32_e32 v200, v192
	v_pk_mul_f32 v[152:153], v[194:195], v[152:153]
	global_load_dwordx4 v[192:195], v[198:199], off offset:16
	v_cndmask_b32_e64 v153, v153, -v153, s[30:31]
	v_cndmask_b32_e64 v152, v152, -v152, s[30:31]
	v_pk_fma_f32 v[100:101], v[100:101], v[200:201], v[152:153]
	s_waitcnt vmcnt(0) lgkmcnt(0)
	v_mov_b32_e32 v153, v194
	v_mov_b32_e32 v194, v193
	v_mov_b32_e32 v152, v192
	v_pk_mul_f32 v[192:193], v[194:195], v[196:197]
	s_nop 0
	v_cndmask_b32_e64 v193, v193, -v193, s[30:31]
	v_cndmask_b32_e64 v192, v192, -v192, s[30:31]
	v_pk_fma_f32 v[102:103], v[102:103], v[152:153], v[192:193]
.LBB0_1021:
	s_or_b64 exec, exec, s[6:7]
	v_cvt_pk_bf16_f32 v152, v100, v101
	v_cvt_pk_bf16_f32 v153, v102, v103
	s_and_saveexec_b64 s[6:7], s[4:5]
	s_xor_b64 s[6:7], exec, s[6:7]
	s_cbranch_execz .LBB0_1027
	v_add_u32_e32 v130, 0xfffffd00, v132
	s_and_saveexec_b64 s[14:15], s[24:25]
	s_xor_b64 s[14:15], exec, s[14:15]
	s_cbranch_execz .LBB0_1024
	v_lshl_add_u64 v[192:193], s[56:57], 0, v[150:151]
	v_lshl_add_u64 v[192:193], v[130:131], 1, v[192:193]
	global_store_dwordx2 v[192:193], v[152:153], off
	v_lshl_add_u64 v[152:153], s[72:73], 0, v[104:105]
	v_lshl_add_u64 v[152:153], v[130:131], 2, v[152:153]
	global_store_dwordx4 v[152:153], v[100:103], off
.LBB0_1024:
	s_andn2_saveexec_b64 s[14:15], s[14:15]
	s_cbranch_execz .LBB0_1026
	v_lshl_add_u64 v[192:193], v[110:111], 1, s[44:45]
	v_lshl_add_u64 v[192:193], v[130:131], 1, v[192:193]
	global_store_dwordx2 v[192:193], v[152:153], off
	v_lshl_add_u64 v[152:153], v[110:111], 2, s[74:75]
	v_lshl_add_u64 v[152:153], v[130:131], 2, v[152:153]
	global_store_dwordx4 v[152:153], v[100:103], off

.LBB0_1027:
	s_andn2_saveexec_b64 s[6:7], s[6:7]
	s_cbranch_execz .LBB0_1029
	v_lshl_add_u64 v[100:101], s[54:55], 0, v[108:109]
	v_ashrrev_i32_e32 v133, 31, v132
	v_lshl_add_u64 v[100:101], v[132:133], 1, v[100:101]
	global_store_dwordx2 v[100:101], v[152:153], off

.LBB0_1030:
	s_or_b64 exec, exec, s[8:9]
	s_and_saveexec_b64 s[6:7], s[16:17]
	s_xor_b64 s[6:7], exec, s[6:7]
	s_cbranch_execz .LBB0_1039
	s_cmpk_lt_u32 s84, 0x900
	s_mov_b64 s[8:9], -1
	s_cbranch_scc1 .LBB0_1033
	v_lshl_add_u64 v[102:103], s[54:55], 0, v[108:109]
	v_mov_b32_e32 v133, v131
	v_lshl_add_u64 v[102:103], v[132:133], 1, v[102:103]
	v_add_co_u32_e32 v102, vcc, 0xfffff420, v102
	v_cvt_pk_bf16_f32 v100, v96, v97
	v_cvt_pk_bf16_f32 v101, v98, v99
	v_addc_co_u32_e32 v103, vcc, -1, v103, vcc
	s_mov_b64 s[8:9], 0
	global_store_dwordx2 v[102:103], v[100:101], off
.LBB0_1033:
	s_andn2_b64 vcc, exec, s[8:9]
	s_cbranch_vccnz .LBB0_1039
	v_add_u32_e32 v130, 0xfffffa10, v132
	v_lshrrev_b32_e32 v101, 7, v130
	v_and_b32_e32 v100, 0x7c, v161
	s_and_saveexec_b64 s[8:9], s[24:25]
	s_xor_b64 s[8:9], exec, s[8:9]
	s_cbranch_execz .LBB0_1036
	v_lshl_add_u64 v[102:103], s[68:69], 0, v[104:105]
	v_lshl_add_u64 v[102:103], v[130:131], 2, v[102:103]
	v_add_u32_e32 v130, v101, v185
	global_store_dwordx4 v[102:103], v[96:99], off
	v_lshlrev_b64 v[102:103], 7, v[130:131]
	v_or_b32_e32 v102, v102, v100
	v_mov_b64_e32 v[100:101], s[48:49]
	v_mad_u64_u32 v[100:101], s[14:15], v102, s51, v[100:101]
	v_mad_u32_u24 v101, v103, s51, v101
	v_lshlrev_b32_e32 v130, 1, v181
	v_cvt_pk_bf16_f32 v96, v96, s0
	v_lshl_add_u64 v[102:103], v[100:101], 0, v[130:131]
	v_lshlrev_b32_e32 v130, 1, v180
	global_store_short v[102:103], v96, off offset:2056
	v_cvt_pk_bf16_f32 v102, v97, s0
	v_lshl_add_u64 v[96:97], v[100:101], 0, v[130:131]
	v_add_co_u32_e32 v100, vcc, 0x1000, v96
	v_cvt_pk_bf16_f32 v98, v98, s0
	s_nop 0
	v_addc_co_u32_e32 v101, vcc, 0, v97, vcc
	v_add_co_u32_e32 v96, vcc, 0x2000, v96
	global_store_short v[100:101], v98, off offset:2304
	v_cvt_pk_bf16_f32 v98, v99, s0
	v_addc_co_u32_e32 v97, vcc, 0, v97, vcc
	global_store_short v[100:101], v102, off offset:128
	global_store_short v[96:97], v98, off offset:384
.LBB0_1036:
	s_andn2_saveexec_b64 s[8:9], s[8:9]
	s_cbranch_execz .LBB0_1038
	v_lshl_add_u64 v[102:103], s[70:71], 0, v[106:107]
	v_lshl_add_u64 v[102:103], v[130:131], 2, v[102:103]
	global_store_dwordx4 v[102:103], v[96:99], off
	v_add_u32_e32 v102, v101, v172
	v_ashrrev_i32_e32 v103, 31, v102
	v_lshlrev_b64 v[102:103], 20, v[102:103]
	v_lshlrev_b32_e32 v130, 13, v100
	v_lshl_add_u64 v[100:101], s[46:47], 0, v[102:103]
	v_lshl_add_u64 v[100:101], v[100:101], 0, v[130:131]
	v_lshlrev_b32_e32 v130, 1, v178
	v_cvt_pk_bf16_f32 v96, v96, s0
	v_lshl_add_u64 v[100:101], v[100:101], 0, v[130:131]
	s_movk_i32 s14, 0x2000
	global_store_short v[100:101], v96, off
	v_add_co_u32_e32 v96, vcc, s14, v100
	v_cvt_pk_bf16_f32 v102, v97, s0
	s_nop 0
	v_addc_co_u32_e32 v97, vcc, 0, v101, vcc
	global_store_short v[96:97], v102, off
	v_add_co_u32_e32 v96, vcc, 0x4000, v100
	v_cvt_pk_bf16_f32 v98, v98, s0
	s_nop 0
	v_addc_co_u32_e32 v97, vcc, 0, v101, vcc
	global_store_short v[96:97], v98, off
	v_add_co_u32_e32 v96, vcc, 0x6000, v100
	v_cvt_pk_bf16_f32 v98, v99, s0
	s_nop 0
	v_addc_co_u32_e32 v97, vcc, 0, v101, vcc
	global_store_short v[96:97], v98, off

.LBB0_1039:
	s_andn2_saveexec_b64 s[6:7], s[6:7]
	s_cbranch_execz .LBB0_1049
	v_cvt_pk_bf16_f32 v100, v96, v97
	v_cvt_pk_bf16_f32 v101, v98, v99
	s_and_saveexec_b64 s[8:9], s[10:11]
	s_xor_b64 s[8:9], exec, s[8:9]
	s_cbranch_execz .LBB0_1046
	v_add_u32_e32 v130, 0xfffffd10, v132
	s_and_saveexec_b64 s[14:15], s[24:25]
	s_xor_b64 s[14:15], exec, s[14:15]
	s_cbranch_execz .LBB0_1043
	v_lshl_add_u64 v[102:103], s[56:57], 0, v[150:151]
	v_lshl_add_u64 v[102:103], v[130:131], 1, v[102:103]
	global_store_dwordx2 v[102:103], v[100:101], off
	v_lshl_add_u64 v[100:101], s[72:73], 0, v[104:105]
	v_lshl_add_u64 v[100:101], v[130:131], 2, v[100:101]
	global_store_dwordx4 v[100:101], v[96:99], off
.LBB0_1043:
	s_andn2_saveexec_b64 s[14:15], s[14:15]
	s_cbranch_execz .LBB0_1045
	v_lshl_add_u64 v[102:103], v[110:111], 1, s[44:45]
	v_lshl_add_u64 v[102:103], v[130:131], 1, v[102:103]
	global_store_dwordx2 v[102:103], v[100:101], off
	v_lshl_add_u64 v[100:101], v[110:111], 2, s[74:75]
	v_lshl_add_u64 v[100:101], v[130:131], 2, v[100:101]
	global_store_dwordx4 v[100:101], v[96:99], off

.LBB0_1046:
	s_andn2_saveexec_b64 s[8:9], s[8:9]
	s_cbranch_execz .LBB0_1048
	v_lshl_add_u64 v[96:97], s[54:55], 0, v[108:109]
	v_ashrrev_i32_e32 v133, 31, v132
	v_lshl_add_u64 v[96:97], v[132:133], 1, v[96:97]
	global_store_dwordx2 v[96:97], v[100:101], off offset:32

.LBB0_1049:
	s_or_b64 exec, exec, s[6:7]
	v_or_b32_e32 v96, 0x80, v132
	s_movk_i32 s6, 0x2ff
	s_movk_i32 s8, 0x5ff
	v_cmp_lt_i32_e64 s[6:7], s6, v96
	v_cmp_lt_i32_e64 s[18:19], s8, v96
	s_and_saveexec_b64 s[8:9], s[18:19]
	s_xor_b64 s[8:9], exec, s[8:9]
	s_cbranch_execz .LBB0_1058
	s_cmpk_lt_u32 s84, 0x900
	s_mov_b64 s[14:15], -1
	s_cbranch_scc1 .LBB0_1052
	v_lshl_add_u64 v[98:99], s[54:55], 0, v[140:141]
	v_mov_b32_e32 v133, v131
	v_lshl_add_u64 v[98:99], v[132:133], 1, v[98:99]
	v_add_co_u32_e32 v98, vcc, 0xfffff500, v98
	v_cvt_pk_bf16_f32 v96, v92, v93
	v_cvt_pk_bf16_f32 v97, v94, v95
	v_addc_co_u32_e32 v99, vcc, -1, v99, vcc
	s_mov_b64 s[14:15], 0
	global_store_dwordx2 v[98:99], v[96:97], off
.LBB0_1052:
	s_andn2_b64 vcc, exec, s[14:15]
	s_cbranch_vccnz .LBB0_1058
	v_add_u32_e32 v130, 0xfffffa80, v132
	v_lshrrev_b32_e32 v97, 7, v130
	v_and_b32_e32 v96, 0x6c, v132
	s_and_saveexec_b64 s[14:15], s[20:21]
	s_xor_b64 s[14:15], exec, s[14:15]
	s_cbranch_execz .LBB0_1055
	v_lshl_add_u64 v[98:99], s[68:69], 0, v[136:137]
	v_lshl_add_u64 v[98:99], v[130:131], 2, v[98:99]
	v_add_u32_e32 v130, v97, v175
	global_store_dwordx4 v[98:99], v[92:95], off
	v_lshlrev_b64 v[98:99], 7, v[130:131]
	v_or_b32_e32 v98, v98, v96
	v_mov_b64_e32 v[96:97], s[48:49]
	v_mad_u64_u32 v[96:97], s[28:29], v98, s51, v[96:97]
	v_mad_u32_u24 v97, v99, s51, v97
	v_lshlrev_b32_e32 v130, 1, v173
	v_cvt_pk_bf16_f32 v92, v92, s0
	v_lshl_add_u64 v[96:97], v[96:97], 0, v[130:131]
	global_store_short v[96:97], v92, off offset:2048
	v_add_co_u32_e32 v92, vcc, 0x1000, v96
	v_cvt_pk_bf16_f32 v98, v93, s0
	s_nop 0
	v_addc_co_u32_e32 v93, vcc, 0, v97, vcc
	v_cvt_pk_bf16_f32 v94, v94, s0
	global_store_short v[92:93], v98, off offset:128
	global_store_short v[92:93], v94, off offset:2304
	v_add_co_u32_e32 v92, vcc, 0x2000, v96
	v_cvt_pk_bf16_f32 v94, v95, s0
	s_nop 0
	v_addc_co_u32_e32 v93, vcc, 0, v97, vcc
	global_store_short v[92:93], v94, off offset:384
.LBB0_1055:
	s_andn2_saveexec_b64 s[14:15], s[14:15]
	s_cbranch_execz .LBB0_1057
	v_lshl_add_u64 v[98:99], s[70:71], 0, v[138:139]
	v_lshl_add_u64 v[98:99], v[130:131], 2, v[98:99]
	global_store_dwordx4 v[98:99], v[92:95], off
	v_add_u32_e32 v98, v97, v172
	v_ashrrev_i32_e32 v99, 31, v98
	v_lshlrev_b32_e32 v130, 1, v174
	v_lshl_add_u64 v[100:101], s[46:47], 0, v[130:131]
	v_lshlrev_b64 v[98:99], 20, v[98:99]
	v_lshlrev_b32_e32 v130, 13, v96
	v_lshl_add_u64 v[96:97], v[100:101], 0, v[98:99]
	v_cvt_pk_bf16_f32 v92, v92, s0
	v_lshl_add_u64 v[96:97], v[96:97], 0, v[130:131]
	s_movk_i32 s28, 0x2000
	global_store_short v[96:97], v92, off
	v_add_co_u32_e32 v92, vcc, s28, v96
	v_cvt_pk_bf16_f32 v98, v93, s0
	s_nop 0
	v_addc_co_u32_e32 v93, vcc, 0, v97, vcc
	global_store_short v[92:93], v98, off
	v_add_co_u32_e32 v92, vcc, 0x4000, v96
	v_cvt_pk_bf16_f32 v94, v94, s0
	s_nop 0
	v_addc_co_u32_e32 v93, vcc, 0, v97, vcc
	global_store_short v[92:93], v94, off
	v_add_co_u32_e32 v92, vcc, 0x6000, v96
	v_cvt_pk_bf16_f32 v94, v95, s0
	s_nop 0
	v_addc_co_u32_e32 v93, vcc, 0, v97, vcc
	global_store_short v[92:93], v94, off

.LBB0_1058:
	s_andn2_saveexec_b64 s[8:9], s[8:9]
	s_cbranch_execz .LBB0_1070
	v_cmp_eq_u32_e32 vcc, 0, v160
	s_and_saveexec_b64 s[14:15], vcc
	s_cbranch_execz .LBB0_1061
	v_cmp_lt_i32_e32 vcc, v158, v156
	v_lshlrev_b32_e32 v130, 3, v187
	s_nop 0
	v_cndmask_b32_e32 v96, v155, v158, vcc
	v_lshlrev_b32_e32 v96, 2, v96
	ds_bpermute_b32 v100, v96, v92
	ds_bpermute_b32 v101, v96, v93
	ds_bpermute_b32 v102, v96, v94
	ds_bpermute_b32 v103, v96, v95
	v_lshl_add_u64 v[96:97], s[52:53], 0, v[130:131]
	v_lshlrev_b32_e32 v130, 3, v135
	v_lshl_add_u64 v[152:153], v[96:97], 0, v[130:131]
	global_load_dwordx4 v[96:99], v[152:153], off
	s_waitcnt vmcnt(0) lgkmcnt(0)
	v_mov_b32_e32 v193, v98
	v_mov_b32_e32 v98, v97
	v_mov_b32_e32 v192, v96
	v_pk_mul_f32 v[96:97], v[98:99], v[100:101]
	s_nop 0
	v_cndmask_b32_e64 v97, v97, -v97, s[30:31]
	v_cndmask_b32_e64 v96, v96, -v96, s[30:31]
	v_pk_fma_f32 v[92:93], v[92:93], v[192:193], v[96:97]
	global_load_dwordx4 v[96:99], v[152:153], off offset:16
	s_waitcnt vmcnt(0) lgkmcnt(0)
	v_mov_b32_e32 v101, v98
	v_mov_b32_e32 v98, v97
	v_mov_b32_e32 v100, v96
	v_pk_mul_f32 v[96:97], v[98:99], v[102:103]
	s_nop 0
	v_cndmask_b32_e64 v97, v97, -v97, s[30:31]
	v_cndmask_b32_e64 v96, v96, -v96, s[30:31]
	v_pk_fma_f32 v[94:95], v[94:95], v[100:101], v[96:97]
.LBB0_1061:
	s_or_b64 exec, exec, s[14:15]
	v_cvt_pk_bf16_f32 v96, v92, v93
	v_cvt_pk_bf16_f32 v97, v94, v95
	s_and_saveexec_b64 s[14:15], s[6:7]
	s_xor_b64 s[14:15], exec, s[14:15]
	s_cbranch_execz .LBB0_1067
	v_add_u32_e32 v130, 0xfffffd80, v132
	s_and_saveexec_b64 s[28:29], s[20:21]
	s_xor_b64 s[28:29], exec, s[28:29]
	s_cbranch_execz .LBB0_1064
	v_lshl_add_u64 v[98:99], s[56:57], 0, v[144:145]
	v_lshl_add_u64 v[98:99], v[130:131], 1, v[98:99]
	global_store_dwordx2 v[98:99], v[96:97], off
	v_lshl_add_u64 v[96:97], s[72:73], 0, v[136:137]
	v_lshl_add_u64 v[96:97], v[130:131], 2, v[96:97]
	global_store_dwordx4 v[96:97], v[92:95], off
.LBB0_1064:
	s_andn2_saveexec_b64 s[28:29], s[28:29]
	s_cbranch_execz .LBB0_1066
	v_lshl_add_u64 v[98:99], v[142:143], 1, s[44:45]
	v_lshl_add_u64 v[98:99], v[130:131], 1, v[98:99]
	global_store_dwordx2 v[98:99], v[96:97], off
	v_lshl_add_u64 v[96:97], v[142:143], 2, s[74:75]
	v_lshl_add_u64 v[96:97], v[130:131], 2, v[96:97]
	global_store_dwordx4 v[96:97], v[92:95], off

.LBB0_1067:
	s_andn2_saveexec_b64 s[14:15], s[14:15]
	s_cbranch_execz .LBB0_1069
	v_lshl_add_u64 v[92:93], s[54:55], 0, v[140:141]
	v_ashrrev_i32_e32 v133, 31, v132
	v_lshl_add_u64 v[92:93], v[132:133], 1, v[92:93]
	global_store_dwordx2 v[92:93], v[96:97], off offset:256

.LBB0_1070:
	s_or_b64 exec, exec, s[8:9]
	v_or_b32_e32 v94, 0x90, v132
	s_movk_i32 s8, 0x2ff
	s_movk_i32 s14, 0x5ff
	v_cmp_lt_i32_e64 s[8:9], s8, v94
	v_cmp_lt_i32_e64 s[14:15], s14, v94
	s_and_saveexec_b64 s[28:29], s[14:15]
	s_xor_b64 s[28:29], exec, s[28:29]
	s_cbranch_execz .LBB0_1079
	s_cmpk_lt_u32 s84, 0x900
	s_mov_b64 s[86:87], -1
	s_cbranch_scc1 .LBB0_1073
	v_lshl_add_u64 v[96:97], s[54:55], 0, v[140:141]
	v_mov_b32_e32 v133, v131
	v_lshl_add_u64 v[96:97], v[132:133], 1, v[96:97]
	v_add_co_u32_e32 v96, vcc, 0xfffff520, v96
	v_cvt_pk_bf16_f32 v92, v88, v89
	v_cvt_pk_bf16_f32 v93, v90, v91
	v_addc_co_u32_e32 v97, vcc, -1, v97, vcc
	s_mov_b64 s[86:87], 0
	global_store_dwordx2 v[96:97], v[92:93], off
.LBB0_1073:
	s_andn2_b64 vcc, exec, s[86:87]
	s_cbranch_vccnz .LBB0_1079
	v_add_u32_e32 v130, 0xfffffa90, v132
	v_lshrrev_b32_e32 v93, 7, v130
	v_and_b32_e32 v92, 0x7c, v94
	s_and_saveexec_b64 s[86:87], s[20:21]
	s_xor_b64 s[86:87], exec, s[86:87]
	s_cbranch_execz .LBB0_1076
	v_lshl_add_u64 v[96:97], s[68:69], 0, v[136:137]
	v_lshl_add_u64 v[96:97], v[130:131], 2, v[96:97]
	v_add_u32_e32 v130, v93, v175
	global_store_dwordx4 v[96:97], v[88:91], off
	v_lshlrev_b64 v[96:97], 7, v[130:131]
	v_or_b32_e32 v95, v96, v92
	v_mov_b64_e32 v[92:93], s[48:49]
	v_mad_u64_u32 v[92:93], vcc, v95, s51, v[92:93]
	v_mad_u32_u24 v93, v97, s51, v93
	v_lshlrev_b32_e32 v130, 1, v173
	v_cvt_pk_bf16_f32 v88, v88, s0
	v_lshl_add_u64 v[92:93], v[92:93], 0, v[130:131]
	global_store_short v[92:93], v88, off offset:2048
	v_add_co_u32_e32 v88, vcc, 0x1000, v92
	v_cvt_pk_bf16_f32 v95, v89, s0
	s_nop 0
	v_addc_co_u32_e32 v89, vcc, 0, v93, vcc
	v_cvt_pk_bf16_f32 v90, v90, s0
	global_store_short v[88:89], v95, off offset:128
	global_store_short v[88:89], v90, off offset:2304
	v_add_co_u32_e32 v88, vcc, 0x2000, v92
	v_cvt_pk_bf16_f32 v90, v91, s0
	s_nop 0
	v_addc_co_u32_e32 v89, vcc, 0, v93, vcc
	global_store_short v[88:89], v90, off offset:384
.LBB0_1076:
	s_andn2_saveexec_b64 s[86:87], s[86:87]
	s_cbranch_execz .LBB0_1078
	v_lshl_add_u64 v[96:97], s[70:71], 0, v[138:139]
	v_lshl_add_u64 v[96:97], v[130:131], 2, v[96:97]
	global_store_dwordx4 v[96:97], v[88:91], off
	v_add_u32_e32 v96, v93, v172
	v_ashrrev_i32_e32 v97, 31, v96
	v_lshlrev_b32_e32 v130, 1, v174
	v_lshl_add_u64 v[98:99], s[46:47], 0, v[130:131]
	v_lshlrev_b64 v[96:97], 20, v[96:97]
	v_lshlrev_b32_e32 v130, 13, v92
	v_lshl_add_u64 v[92:93], v[98:99], 0, v[96:97]
	v_cvt_pk_bf16_f32 v88, v88, s0
	v_lshl_add_u64 v[92:93], v[92:93], 0, v[130:131]
	s_movk_i32 s66, 0x2000
	global_store_short v[92:93], v88, off
	v_add_co_u32_e32 v88, vcc, s66, v92
	v_cvt_pk_bf16_f32 v95, v89, s0
	s_nop 0
	v_addc_co_u32_e32 v89, vcc, 0, v93, vcc
	global_store_short v[88:89], v95, off
	v_add_co_u32_e32 v88, vcc, 0x4000, v92
	v_cvt_pk_bf16_f32 v90, v90, s0
	s_nop 0
	v_addc_co_u32_e32 v89, vcc, 0, v93, vcc
	global_store_short v[88:89], v90, off
	v_add_co_u32_e32 v88, vcc, 0x6000, v92
	v_cvt_pk_bf16_f32 v90, v91, s0
	s_nop 0
	v_addc_co_u32_e32 v89, vcc, 0, v93, vcc
	global_store_short v[88:89], v90, off

.LBB0_1079:
	s_andn2_saveexec_b64 s[28:29], s[28:29]
	s_cbranch_execz .LBB0_1089
	v_cvt_pk_bf16_f32 v92, v88, v89
	v_cvt_pk_bf16_f32 v93, v90, v91
	s_and_saveexec_b64 s[86:87], s[8:9]
	s_xor_b64 s[86:87], exec, s[86:87]
	s_cbranch_execz .LBB0_1086
	v_add_u32_e32 v130, 0xfffffd90, v132
	s_and_saveexec_b64 vcc, s[20:21]
	s_xor_b64 s[20:21], exec, vcc
	s_cbranch_execz .LBB0_1083
	v_lshl_add_u64 v[96:97], s[56:57], 0, v[144:145]
	v_lshl_add_u64 v[96:97], v[130:131], 1, v[96:97]
	global_store_dwordx2 v[96:97], v[92:93], off
	v_lshl_add_u64 v[92:93], s[72:73], 0, v[136:137]
	v_lshl_add_u64 v[92:93], v[130:131], 2, v[92:93]
	global_store_dwordx4 v[92:93], v[88:91], off
.LBB0_1083:
	s_andn2_saveexec_b64 s[20:21], s[20:21]
	s_cbranch_execz .LBB0_1085
	v_lshl_add_u64 v[96:97], v[142:143], 1, s[44:45]
	v_lshl_add_u64 v[96:97], v[130:131], 1, v[96:97]
	global_store_dwordx2 v[96:97], v[92:93], off
	v_lshl_add_u64 v[92:93], v[142:143], 2, s[74:75]
	v_lshl_add_u64 v[92:93], v[130:131], 2, v[92:93]
	global_store_dwordx4 v[92:93], v[88:91], off

.LBB0_1086:
	s_andn2_saveexec_b64 s[20:21], s[86:87]
	s_cbranch_execz .LBB0_1088
	v_lshl_add_u64 v[88:89], s[54:55], 0, v[140:141]
	v_ashrrev_i32_e32 v133, 31, v132
	v_lshl_add_u64 v[88:89], v[132:133], 1, v[88:89]
	global_store_dwordx2 v[88:89], v[92:93], off offset:288

.LBB0_1089:
	s_or_b64 exec, exec, s[28:29]
	s_and_saveexec_b64 s[20:21], s[18:19]
	s_xor_b64 s[20:21], exec, s[20:21]
	s_cbranch_execz .LBB0_1098
	s_cmpk_lt_u32 s84, 0x900
	s_mov_b64 s[28:29], -1
	s_cbranch_scc1 .LBB0_1092
	v_lshl_add_u64 v[90:91], s[54:55], 0, v[124:125]
	v_mov_b32_e32 v133, v131
	v_lshl_add_u64 v[90:91], v[132:133], 1, v[90:91]
	v_add_co_u32_e32 v90, vcc, 0xfffff500, v90
	v_cvt_pk_bf16_f32 v88, v84, v85
	v_cvt_pk_bf16_f32 v89, v86, v87
	v_addc_co_u32_e32 v91, vcc, -1, v91, vcc
	s_mov_b64 s[28:29], 0
	global_store_dwordx2 v[90:91], v[88:89], off
.LBB0_1092:
	s_andn2_b64 vcc, exec, s[28:29]
	s_cbranch_vccnz .LBB0_1098
	v_add_u32_e32 v130, 0xfffffa80, v132
	v_lshrrev_b32_e32 v89, 7, v130
	v_and_b32_e32 v88, 0x6c, v132
	s_and_saveexec_b64 s[28:29], s[22:23]
	s_xor_b64 s[28:29], exec, s[28:29]
	s_cbranch_execz .LBB0_1095
	v_lshl_add_u64 v[90:91], s[68:69], 0, v[120:121]
	v_lshl_add_u64 v[90:91], v[130:131], 2, v[90:91]
	v_add_u32_e32 v130, v89, v184
	global_store_dwordx4 v[90:91], v[84:87], off
	v_lshlrev_b64 v[90:91], 7, v[130:131]
	v_or_b32_e32 v90, v90, v88
	v_mov_b64_e32 v[88:89], s[48:49]
	v_mad_u64_u32 v[88:89], s[66:67], v90, s51, v[88:89]
	v_mad_u32_u24 v89, v91, s51, v89
	v_lshlrev_b32_e32 v130, 1, v179
	v_cvt_pk_bf16_f32 v84, v84, s0
	v_lshl_add_u64 v[90:91], v[88:89], 0, v[130:131]
	v_lshlrev_b32_e32 v130, 1, v177
	global_store_short v[90:91], v84, off offset:2056
	v_cvt_pk_bf16_f32 v90, v85, s0
	v_lshl_add_u64 v[84:85], v[88:89], 0, v[130:131]
	v_add_co_u32_e32 v88, vcc, 0x1000, v84
	v_cvt_pk_bf16_f32 v86, v86, s0
	s_nop 0
	v_addc_co_u32_e32 v89, vcc, 0, v85, vcc
	v_add_co_u32_e32 v84, vcc, 0x2000, v84
	global_store_short v[88:89], v86, off offset:2304
	v_cvt_pk_bf16_f32 v86, v87, s0
	v_addc_co_u32_e32 v85, vcc, 0, v85, vcc
	global_store_short v[88:89], v90, off offset:128
	global_store_short v[84:85], v86, off offset:384
.LBB0_1095:
	s_andn2_saveexec_b64 s[28:29], s[28:29]
	s_cbranch_execz .LBB0_1097
	v_lshl_add_u64 v[90:91], s[70:71], 0, v[122:123]
	v_lshl_add_u64 v[90:91], v[130:131], 2, v[90:91]
	global_store_dwordx4 v[90:91], v[84:87], off
	v_add_u32_e32 v90, v89, v172
	v_ashrrev_i32_e32 v91, 31, v90
	v_lshlrev_b64 v[90:91], 20, v[90:91]
	v_lshlrev_b32_e32 v130, 13, v88
	v_lshl_add_u64 v[88:89], s[46:47], 0, v[90:91]
	v_lshl_add_u64 v[88:89], v[88:89], 0, v[130:131]
	v_lshlrev_b32_e32 v130, 1, v176
	v_cvt_pk_bf16_f32 v84, v84, s0
	v_lshl_add_u64 v[88:89], v[88:89], 0, v[130:131]
	s_movk_i32 s66, 0x2000
	global_store_short v[88:89], v84, off
	v_add_co_u32_e32 v84, vcc, s66, v88
	v_cvt_pk_bf16_f32 v90, v85, s0
	s_nop 0
	v_addc_co_u32_e32 v85, vcc, 0, v89, vcc
	global_store_short v[84:85], v90, off
	v_add_co_u32_e32 v84, vcc, 0x4000, v88
	v_cvt_pk_bf16_f32 v86, v86, s0
	s_nop 0
	v_addc_co_u32_e32 v85, vcc, 0, v89, vcc
	global_store_short v[84:85], v86, off
	v_add_co_u32_e32 v84, vcc, 0x6000, v88
	v_cvt_pk_bf16_f32 v86, v87, s0
	s_nop 0
	v_addc_co_u32_e32 v85, vcc, 0, v89, vcc
	global_store_short v[84:85], v86, off

.LBB0_1098:
	s_andn2_saveexec_b64 s[20:21], s[20:21]
	s_cbranch_execz .LBB0_1110
	v_cmp_eq_u32_e32 vcc, 0, v160
	s_and_saveexec_b64 s[28:29], vcc
	s_cbranch_execz .LBB0_1101
	v_cmp_lt_i32_e32 vcc, v158, v156
	v_lshlrev_b32_e32 v130, 3, v189
	s_nop 0
	v_cndmask_b32_e32 v88, v155, v158, vcc
	v_lshlrev_b32_e32 v88, 2, v88
	ds_bpermute_b32 v92, v88, v84
	ds_bpermute_b32 v93, v88, v85
	ds_bpermute_b32 v96, v88, v86
	ds_bpermute_b32 v97, v88, v87
	v_lshl_add_u64 v[88:89], s[52:53], 0, v[130:131]
	v_lshlrev_b32_e32 v130, 3, v135
	v_lshl_add_u64 v[98:99], v[88:89], 0, v[130:131]
	global_load_dwordx4 v[88:91], v[98:99], off
	s_waitcnt vmcnt(0) lgkmcnt(0)
	v_mov_b32_e32 v101, v90
	v_mov_b32_e32 v90, v89
	v_mov_b32_e32 v100, v88
	v_pk_mul_f32 v[88:89], v[90:91], v[92:93]
	s_nop 0
	v_cndmask_b32_e64 v89, v89, -v89, s[30:31]
	v_cndmask_b32_e64 v88, v88, -v88, s[30:31]
	v_pk_fma_f32 v[84:85], v[84:85], v[100:101], v[88:89]
	global_load_dwordx4 v[88:91], v[98:99], off offset:16
	s_waitcnt vmcnt(0) lgkmcnt(0)
	v_mov_b32_e32 v93, v90
	v_mov_b32_e32 v90, v89
	v_mov_b32_e32 v92, v88
	v_pk_mul_f32 v[88:89], v[90:91], v[96:97]
	s_nop 0
	v_cndmask_b32_e64 v89, v89, -v89, s[30:31]
	v_cndmask_b32_e64 v88, v88, -v88, s[30:31]
	v_pk_fma_f32 v[86:87], v[86:87], v[92:93], v[88:89]
.LBB0_1101:
	s_or_b64 exec, exec, s[28:29]
	v_cvt_pk_bf16_f32 v88, v84, v85
	v_cvt_pk_bf16_f32 v89, v86, v87
	s_and_saveexec_b64 s[28:29], s[6:7]
	s_xor_b64 s[28:29], exec, s[28:29]
	s_cbranch_execz .LBB0_1107
	v_add_u32_e32 v130, 0xfffffd80, v132
	s_and_saveexec_b64 s[66:67], s[22:23]
	s_xor_b64 s[86:87], exec, s[66:67]
	s_cbranch_execz .LBB0_1104
	v_lshl_add_u64 v[90:91], s[56:57], 0, v[146:147]
	v_lshl_add_u64 v[90:91], v[130:131], 1, v[90:91]
	global_store_dwordx2 v[90:91], v[88:89], off
	v_lshl_add_u64 v[88:89], s[72:73], 0, v[120:121]
	v_lshl_add_u64 v[88:89], v[130:131], 2, v[88:89]
	global_store_dwordx4 v[88:89], v[84:87], off
.LBB0_1104:
	s_andn2_saveexec_b64 s[86:87], s[86:87]
	s_cbranch_execz .LBB0_1106
	v_lshl_add_u64 v[90:91], v[126:127], 1, s[44:45]
	v_lshl_add_u64 v[90:91], v[130:131], 1, v[90:91]
	global_store_dwordx2 v[90:91], v[88:89], off
	v_lshl_add_u64 v[88:89], v[126:127], 2, s[74:75]
	v_lshl_add_u64 v[88:89], v[130:131], 2, v[88:89]
	global_store_dwordx4 v[88:89], v[84:87], off

.LBB0_1107:
	s_andn2_saveexec_b64 s[28:29], s[28:29]
	s_cbranch_execz .LBB0_1109
	v_lshl_add_u64 v[84:85], s[54:55], 0, v[124:125]
	v_ashrrev_i32_e32 v133, 31, v132
	v_lshl_add_u64 v[84:85], v[132:133], 1, v[84:85]
	global_store_dwordx2 v[84:85], v[88:89], off offset:256

.LBB0_1110:
	s_or_b64 exec, exec, s[20:21]
	s_and_saveexec_b64 s[20:21], s[14:15]
	s_xor_b64 s[20:21], exec, s[20:21]
	s_cbranch_execz .LBB0_1119
	s_cmpk_lt_u32 s84, 0x900
	s_mov_b64 s[28:29], -1
	s_cbranch_scc1 .LBB0_1113
	v_lshl_add_u64 v[86:87], s[54:55], 0, v[124:125]
	v_mov_b32_e32 v133, v131
	v_lshl_add_u64 v[86:87], v[132:133], 1, v[86:87]
	v_add_co_u32_e32 v86, vcc, 0xfffff520, v86
	v_cvt_pk_bf16_f32 v84, v80, v81
	v_cvt_pk_bf16_f32 v85, v82, v83
	v_addc_co_u32_e32 v87, vcc, -1, v87, vcc
	s_mov_b64 s[28:29], 0
	global_store_dwordx2 v[86:87], v[84:85], off
.LBB0_1113:
	s_andn2_b64 vcc, exec, s[28:29]
	s_cbranch_vccnz .LBB0_1119
	v_add_u32_e32 v130, 0xfffffa90, v132
	v_lshrrev_b32_e32 v85, 7, v130
	v_and_b32_e32 v84, 0x7c, v94
	s_and_saveexec_b64 s[28:29], s[22:23]
	s_xor_b64 s[28:29], exec, s[28:29]
	s_cbranch_execz .LBB0_1116
	v_lshl_add_u64 v[86:87], s[68:69], 0, v[120:121]
	v_lshl_add_u64 v[86:87], v[130:131], 2, v[86:87]
	v_add_u32_e32 v130, v85, v184
	global_store_dwordx4 v[86:87], v[80:83], off
	v_lshlrev_b64 v[86:87], 7, v[130:131]
	v_or_b32_e32 v86, v86, v84
	v_mov_b64_e32 v[84:85], s[48:49]
	v_mad_u64_u32 v[84:85], s[66:67], v86, s51, v[84:85]
	v_mad_u32_u24 v85, v87, s51, v85
	v_lshlrev_b32_e32 v130, 1, v179
	v_cvt_pk_bf16_f32 v80, v80, s0
	v_lshl_add_u64 v[86:87], v[84:85], 0, v[130:131]
	v_lshlrev_b32_e32 v130, 1, v177
	global_store_short v[86:87], v80, off offset:2056
	v_cvt_pk_bf16_f32 v86, v81, s0
	v_lshl_add_u64 v[80:81], v[84:85], 0, v[130:131]
	v_add_co_u32_e32 v84, vcc, 0x1000, v80
	v_cvt_pk_bf16_f32 v82, v82, s0
	s_nop 0
	v_addc_co_u32_e32 v85, vcc, 0, v81, vcc
	v_add_co_u32_e32 v80, vcc, 0x2000, v80
	global_store_short v[84:85], v82, off offset:2304
	v_cvt_pk_bf16_f32 v82, v83, s0
	v_addc_co_u32_e32 v81, vcc, 0, v81, vcc
	global_store_short v[84:85], v86, off offset:128
	global_store_short v[80:81], v82, off offset:384
.LBB0_1116:
	s_andn2_saveexec_b64 s[28:29], s[28:29]
	s_cbranch_execz .LBB0_1118
	v_lshl_add_u64 v[86:87], s[70:71], 0, v[122:123]
	v_lshl_add_u64 v[86:87], v[130:131], 2, v[86:87]
	global_store_dwordx4 v[86:87], v[80:83], off
	v_add_u32_e32 v86, v85, v172
	v_ashrrev_i32_e32 v87, 31, v86
	v_lshlrev_b64 v[86:87], 20, v[86:87]
	v_lshlrev_b32_e32 v130, 13, v84
	v_lshl_add_u64 v[84:85], s[46:47], 0, v[86:87]
	v_lshl_add_u64 v[84:85], v[84:85], 0, v[130:131]
	v_lshlrev_b32_e32 v130, 1, v176
	v_cvt_pk_bf16_f32 v80, v80, s0
	v_lshl_add_u64 v[84:85], v[84:85], 0, v[130:131]
	s_movk_i32 s66, 0x2000
	global_store_short v[84:85], v80, off
	v_add_co_u32_e32 v80, vcc, s66, v84
	v_cvt_pk_bf16_f32 v86, v81, s0
	s_nop 0
	v_addc_co_u32_e32 v81, vcc, 0, v85, vcc
	global_store_short v[80:81], v86, off
	v_add_co_u32_e32 v80, vcc, 0x4000, v84
	v_cvt_pk_bf16_f32 v82, v82, s0
	s_nop 0
	v_addc_co_u32_e32 v81, vcc, 0, v85, vcc
	global_store_short v[80:81], v82, off
	v_add_co_u32_e32 v80, vcc, 0x6000, v84
	v_cvt_pk_bf16_f32 v82, v83, s0
	s_nop 0
	v_addc_co_u32_e32 v81, vcc, 0, v85, vcc
	global_store_short v[80:81], v82, off

.LBB0_1119:
	s_andn2_saveexec_b64 s[20:21], s[20:21]
	s_cbranch_execz .LBB0_1129
	v_cvt_pk_bf16_f32 v84, v80, v81
	v_cvt_pk_bf16_f32 v85, v82, v83
	s_and_saveexec_b64 s[28:29], s[8:9]
	s_xor_b64 s[28:29], exec, s[28:29]
	s_cbranch_execz .LBB0_1126
	v_add_u32_e32 v130, 0xfffffd90, v132
	s_and_saveexec_b64 s[66:67], s[22:23]
	s_xor_b64 s[22:23], exec, s[66:67]
	s_cbranch_execz .LBB0_1123
	v_lshl_add_u64 v[86:87], s[56:57], 0, v[146:147]
	v_lshl_add_u64 v[86:87], v[130:131], 1, v[86:87]
	global_store_dwordx2 v[86:87], v[84:85], off
	v_lshl_add_u64 v[84:85], s[72:73], 0, v[120:121]
	v_lshl_add_u64 v[84:85], v[130:131], 2, v[84:85]
	global_store_dwordx4 v[84:85], v[80:83], off
.LBB0_1123:
	s_andn2_saveexec_b64 s[22:23], s[22:23]
	s_cbranch_execz .LBB0_1125
	v_lshl_add_u64 v[86:87], v[126:127], 1, s[44:45]
	v_lshl_add_u64 v[86:87], v[130:131], 1, v[86:87]
	global_store_dwordx2 v[86:87], v[84:85], off
	v_lshl_add_u64 v[84:85], v[126:127], 2, s[74:75]
	v_lshl_add_u64 v[84:85], v[130:131], 2, v[84:85]
	global_store_dwordx4 v[84:85], v[80:83], off

.LBB0_1126:
	s_andn2_saveexec_b64 s[22:23], s[28:29]
	s_cbranch_execz .LBB0_1128
	v_lshl_add_u64 v[80:81], s[54:55], 0, v[124:125]
	v_ashrrev_i32_e32 v133, 31, v132
	v_lshl_add_u64 v[80:81], v[132:133], 1, v[80:81]
	global_store_dwordx2 v[80:81], v[84:85], off offset:288

.LBB0_1129:
	s_or_b64 exec, exec, s[20:21]
	s_and_saveexec_b64 s[20:21], s[18:19]
	s_xor_b64 s[20:21], exec, s[20:21]
	s_cbranch_execz .LBB0_1138
	s_cmpk_lt_u32 s84, 0x900
	s_mov_b64 s[22:23], -1
	s_cbranch_scc1 .LBB0_1132
	v_lshl_add_u64 v[82:83], s[54:55], 0, v[116:117]
	v_mov_b32_e32 v133, v131
	v_lshl_add_u64 v[82:83], v[132:133], 1, v[82:83]
	v_add_co_u32_e32 v82, vcc, 0xfffff500, v82
	v_cvt_pk_bf16_f32 v80, v76, v77
	v_cvt_pk_bf16_f32 v81, v78, v79
	v_addc_co_u32_e32 v83, vcc, -1, v83, vcc
	s_mov_b64 s[22:23], 0
	global_store_dwordx2 v[82:83], v[80:81], off
.LBB0_1132:
	s_andn2_b64 vcc, exec, s[22:23]
	s_cbranch_vccnz .LBB0_1138
	v_add_u32_e32 v130, 0xfffffa80, v132
	v_lshrrev_b32_e32 v81, 7, v130
	v_and_b32_e32 v80, 0x6c, v132
	s_and_saveexec_b64 s[22:23], s[26:27]
	s_xor_b64 s[22:23], exec, s[22:23]
	s_cbranch_execz .LBB0_1135
	v_lshl_add_u64 v[82:83], s[68:69], 0, v[112:113]
	v_lshl_add_u64 v[82:83], v[130:131], 2, v[82:83]
	v_add_u32_e32 v130, v81, v186
	global_store_dwordx4 v[82:83], v[76:79], off
	v_lshlrev_b64 v[82:83], 7, v[130:131]
	v_or_b32_e32 v82, v82, v80
	v_mov_b64_e32 v[80:81], s[48:49]
	v_mad_u64_u32 v[80:81], s[28:29], v82, s51, v[80:81]
	v_mad_u32_u24 v81, v83, s51, v81
	v_lshlrev_b32_e32 v130, 1, v183
	v_cvt_pk_bf16_f32 v76, v76, s0
	v_lshl_add_u64 v[80:81], v[80:81], 0, v[130:131]
	global_store_short v[80:81], v76, off offset:2048
	v_add_co_u32_e32 v76, vcc, 0x1000, v80
	v_cvt_pk_bf16_f32 v82, v77, s0
	s_nop 0
	v_addc_co_u32_e32 v77, vcc, 0, v81, vcc
	v_cvt_pk_bf16_f32 v78, v78, s0
	global_store_short v[76:77], v82, off offset:128
	global_store_short v[76:77], v78, off offset:2304
	v_add_co_u32_e32 v76, vcc, 0x2000, v80
	v_cvt_pk_bf16_f32 v78, v79, s0
	s_nop 0
	v_addc_co_u32_e32 v77, vcc, 0, v81, vcc
	global_store_short v[76:77], v78, off offset:384
.LBB0_1135:
	s_andn2_saveexec_b64 s[22:23], s[22:23]
	s_cbranch_execz .LBB0_1137
	v_lshl_add_u64 v[82:83], s[70:71], 0, v[114:115]
	v_lshl_add_u64 v[82:83], v[130:131], 2, v[82:83]
	global_store_dwordx4 v[82:83], v[76:79], off
	v_add_u32_e32 v82, v81, v172
	v_ashrrev_i32_e32 v83, 31, v82
	v_lshlrev_b32_e32 v130, 1, v182
	v_lshl_add_u64 v[84:85], s[46:47], 0, v[130:131]
	v_lshlrev_b64 v[82:83], 20, v[82:83]
	v_lshlrev_b32_e32 v130, 13, v80
	v_lshl_add_u64 v[80:81], v[84:85], 0, v[82:83]
	v_cvt_pk_bf16_f32 v76, v76, s0
	v_lshl_add_u64 v[80:81], v[80:81], 0, v[130:131]
	s_movk_i32 s28, 0x2000
	global_store_short v[80:81], v76, off
	v_add_co_u32_e32 v76, vcc, s28, v80
	v_cvt_pk_bf16_f32 v82, v77, s0
	s_nop 0
	v_addc_co_u32_e32 v77, vcc, 0, v81, vcc
	global_store_short v[76:77], v82, off
	v_add_co_u32_e32 v76, vcc, 0x4000, v80
	v_cvt_pk_bf16_f32 v78, v78, s0
	s_nop 0
	v_addc_co_u32_e32 v77, vcc, 0, v81, vcc
	global_store_short v[76:77], v78, off
	v_add_co_u32_e32 v76, vcc, 0x6000, v80
	v_cvt_pk_bf16_f32 v78, v79, s0
	s_nop 0
	v_addc_co_u32_e32 v77, vcc, 0, v81, vcc
	global_store_short v[76:77], v78, off

.LBB0_1138:
	s_andn2_saveexec_b64 s[20:21], s[20:21]
	s_cbranch_execz .LBB0_1150
	v_cmp_eq_u32_e32 vcc, 0, v160
	s_and_saveexec_b64 s[22:23], vcc
	s_cbranch_execz .LBB0_1141
	v_cmp_lt_i32_e32 vcc, v158, v156
	v_lshlrev_b32_e32 v130, 3, v188
	s_nop 0
	v_cndmask_b32_e32 v80, v155, v158, vcc
	v_lshlrev_b32_e32 v80, 2, v80
	ds_bpermute_b32 v84, v80, v76
	ds_bpermute_b32 v85, v80, v77
	ds_bpermute_b32 v86, v80, v78
	ds_bpermute_b32 v87, v80, v79
	v_lshl_add_u64 v[80:81], s[52:53], 0, v[130:131]
	v_lshlrev_b32_e32 v130, 3, v135
	v_lshl_add_u64 v[88:89], v[80:81], 0, v[130:131]
	global_load_dwordx4 v[80:83], v[88:89], off
	s_waitcnt vmcnt(0) lgkmcnt(0)
	v_mov_b32_e32 v91, v82
	v_mov_b32_e32 v82, v81
	v_mov_b32_e32 v90, v80
	v_pk_mul_f32 v[80:81], v[82:83], v[84:85]
	s_nop 0
	v_cndmask_b32_e64 v81, v81, -v81, s[30:31]
	v_cndmask_b32_e64 v80, v80, -v80, s[30:31]
	v_pk_fma_f32 v[76:77], v[76:77], v[90:91], v[80:81]
	global_load_dwordx4 v[80:83], v[88:89], off offset:16
	s_waitcnt vmcnt(0) lgkmcnt(0)
	v_mov_b32_e32 v85, v82
	v_mov_b32_e32 v82, v81
	v_mov_b32_e32 v84, v80
	v_pk_mul_f32 v[80:81], v[82:83], v[86:87]
	s_nop 0
	v_cndmask_b32_e64 v81, v81, -v81, s[30:31]
	v_cndmask_b32_e64 v80, v80, -v80, s[30:31]
	v_pk_fma_f32 v[78:79], v[78:79], v[84:85], v[80:81]
.LBB0_1141:
	s_or_b64 exec, exec, s[22:23]
	v_cvt_pk_bf16_f32 v80, v76, v77
	v_cvt_pk_bf16_f32 v81, v78, v79
	s_and_saveexec_b64 s[22:23], s[6:7]
	s_xor_b64 s[22:23], exec, s[22:23]
	s_cbranch_execz .LBB0_1147
	v_add_u32_e32 v130, 0xfffffd80, v132
	s_and_saveexec_b64 s[28:29], s[26:27]
	s_xor_b64 s[28:29], exec, s[28:29]
	s_cbranch_execz .LBB0_1144
	v_lshl_add_u64 v[82:83], s[56:57], 0, v[148:149]
	v_lshl_add_u64 v[82:83], v[130:131], 1, v[82:83]
	global_store_dwordx2 v[82:83], v[80:81], off
	v_lshl_add_u64 v[80:81], s[72:73], 0, v[112:113]
	v_lshl_add_u64 v[80:81], v[130:131], 2, v[80:81]
	global_store_dwordx4 v[80:81], v[76:79], off
.LBB0_1144:
	s_andn2_saveexec_b64 s[28:29], s[28:29]
	s_cbranch_execz .LBB0_1146
	v_lshl_add_u64 v[82:83], v[118:119], 1, s[44:45]
	v_lshl_add_u64 v[82:83], v[130:131], 1, v[82:83]
	global_store_dwordx2 v[82:83], v[80:81], off
	v_lshl_add_u64 v[80:81], v[118:119], 2, s[74:75]
	v_lshl_add_u64 v[80:81], v[130:131], 2, v[80:81]
	global_store_dwordx4 v[80:81], v[76:79], off

.LBB0_1147:
	s_andn2_saveexec_b64 s[22:23], s[22:23]
	s_cbranch_execz .LBB0_1149
	v_lshl_add_u64 v[76:77], s[54:55], 0, v[116:117]
	v_ashrrev_i32_e32 v133, 31, v132
	v_lshl_add_u64 v[76:77], v[132:133], 1, v[76:77]
	global_store_dwordx2 v[76:77], v[80:81], off offset:256

.LBB0_1150:
	s_or_b64 exec, exec, s[20:21]
	s_and_saveexec_b64 s[20:21], s[14:15]
	s_xor_b64 s[20:21], exec, s[20:21]
	s_cbranch_execz .LBB0_1159
	s_cmpk_lt_u32 s84, 0x900
	s_mov_b64 s[22:23], -1
	s_cbranch_scc1 .LBB0_1153
	v_lshl_add_u64 v[78:79], s[54:55], 0, v[116:117]
	v_mov_b32_e32 v133, v131
	v_lshl_add_u64 v[78:79], v[132:133], 1, v[78:79]
	v_add_co_u32_e32 v78, vcc, 0xfffff520, v78
	v_cvt_pk_bf16_f32 v76, v72, v73
	v_cvt_pk_bf16_f32 v77, v74, v75
	v_addc_co_u32_e32 v79, vcc, -1, v79, vcc
	s_mov_b64 s[22:23], 0
	global_store_dwordx2 v[78:79], v[76:77], off
.LBB0_1153:
	s_andn2_b64 vcc, exec, s[22:23]
	s_cbranch_vccnz .LBB0_1159
	v_add_u32_e32 v130, 0xfffffa90, v132
	v_lshrrev_b32_e32 v77, 7, v130
	v_and_b32_e32 v76, 0x7c, v94
	s_and_saveexec_b64 s[22:23], s[26:27]
	s_xor_b64 s[22:23], exec, s[22:23]
	s_cbranch_execz .LBB0_1156
	v_lshl_add_u64 v[78:79], s[68:69], 0, v[112:113]
	v_lshl_add_u64 v[78:79], v[130:131], 2, v[78:79]
	v_add_u32_e32 v130, v77, v186
	global_store_dwordx4 v[78:79], v[72:75], off
	v_lshlrev_b64 v[78:79], 7, v[130:131]
	v_or_b32_e32 v78, v78, v76
	v_mov_b64_e32 v[76:77], s[48:49]
	v_mad_u64_u32 v[76:77], s[28:29], v78, s51, v[76:77]
	v_mad_u32_u24 v77, v79, s51, v77
	v_lshlrev_b32_e32 v130, 1, v183
	v_cvt_pk_bf16_f32 v72, v72, s0
	v_lshl_add_u64 v[76:77], v[76:77], 0, v[130:131]
	global_store_short v[76:77], v72, off offset:2048
	v_add_co_u32_e32 v72, vcc, 0x1000, v76
	v_cvt_pk_bf16_f32 v78, v73, s0
	s_nop 0
	v_addc_co_u32_e32 v73, vcc, 0, v77, vcc
	v_cvt_pk_bf16_f32 v74, v74, s0
	global_store_short v[72:73], v78, off offset:128
	global_store_short v[72:73], v74, off offset:2304
	v_add_co_u32_e32 v72, vcc, 0x2000, v76
	v_cvt_pk_bf16_f32 v74, v75, s0
	s_nop 0
	v_addc_co_u32_e32 v73, vcc, 0, v77, vcc
	global_store_short v[72:73], v74, off offset:384
.LBB0_1156:
	s_andn2_saveexec_b64 s[22:23], s[22:23]
	s_cbranch_execz .LBB0_1158
	v_lshl_add_u64 v[78:79], s[70:71], 0, v[114:115]
	v_lshl_add_u64 v[78:79], v[130:131], 2, v[78:79]
	global_store_dwordx4 v[78:79], v[72:75], off
	v_add_u32_e32 v78, v77, v172
	v_ashrrev_i32_e32 v79, 31, v78
	v_lshlrev_b32_e32 v130, 1, v182
	v_lshl_add_u64 v[80:81], s[46:47], 0, v[130:131]
	v_lshlrev_b64 v[78:79], 20, v[78:79]
	v_lshlrev_b32_e32 v130, 13, v76
	v_lshl_add_u64 v[76:77], v[80:81], 0, v[78:79]
	v_cvt_pk_bf16_f32 v72, v72, s0
	v_lshl_add_u64 v[76:77], v[76:77], 0, v[130:131]
	s_movk_i32 s28, 0x2000
	global_store_short v[76:77], v72, off
	v_add_co_u32_e32 v72, vcc, s28, v76
	v_cvt_pk_bf16_f32 v78, v73, s0
	s_nop 0
	v_addc_co_u32_e32 v73, vcc, 0, v77, vcc
	global_store_short v[72:73], v78, off
	v_add_co_u32_e32 v72, vcc, 0x4000, v76
	v_cvt_pk_bf16_f32 v74, v74, s0
	s_nop 0
	v_addc_co_u32_e32 v73, vcc, 0, v77, vcc
	global_store_short v[72:73], v74, off
	v_add_co_u32_e32 v72, vcc, 0x6000, v76
	v_cvt_pk_bf16_f32 v74, v75, s0
	s_nop 0
	v_addc_co_u32_e32 v73, vcc, 0, v77, vcc
	global_store_short v[72:73], v74, off

.LBB0_1159:
	s_andn2_saveexec_b64 s[20:21], s[20:21]
	s_cbranch_execz .LBB0_1169
	v_cvt_pk_bf16_f32 v76, v72, v73
	v_cvt_pk_bf16_f32 v77, v74, v75
	s_and_saveexec_b64 s[22:23], s[8:9]
	s_xor_b64 s[22:23], exec, s[22:23]
	s_cbranch_execz .LBB0_1166
	v_add_u32_e32 v130, 0xfffffd90, v132
	s_and_saveexec_b64 s[28:29], s[26:27]
	s_xor_b64 s[26:27], exec, s[28:29]
	s_cbranch_execz .LBB0_1163
	v_lshl_add_u64 v[78:79], s[56:57], 0, v[148:149]
	v_lshl_add_u64 v[78:79], v[130:131], 1, v[78:79]
	global_store_dwordx2 v[78:79], v[76:77], off
	v_lshl_add_u64 v[76:77], s[72:73], 0, v[112:113]
	v_lshl_add_u64 v[76:77], v[130:131], 2, v[76:77]
	global_store_dwordx4 v[76:77], v[72:75], off
.LBB0_1163:
	s_andn2_saveexec_b64 s[26:27], s[26:27]
	s_cbranch_execz .LBB0_1165
	v_lshl_add_u64 v[78:79], v[118:119], 1, s[44:45]
	v_lshl_add_u64 v[78:79], v[130:131], 1, v[78:79]
	global_store_dwordx2 v[78:79], v[76:77], off
	v_lshl_add_u64 v[76:77], v[118:119], 2, s[74:75]
	v_lshl_add_u64 v[76:77], v[130:131], 2, v[76:77]
	global_store_dwordx4 v[76:77], v[72:75], off

.LBB0_1166:
	s_andn2_saveexec_b64 s[22:23], s[22:23]
	s_cbranch_execz .LBB0_1168
	v_lshl_add_u64 v[72:73], s[54:55], 0, v[116:117]
	v_ashrrev_i32_e32 v133, 31, v132
	v_lshl_add_u64 v[72:73], v[132:133], 1, v[72:73]
	global_store_dwordx2 v[72:73], v[76:77], off offset:288

.LBB0_1169:
	s_or_b64 exec, exec, s[20:21]
	s_and_saveexec_b64 s[20:21], s[18:19]
	s_xor_b64 s[20:21], exec, s[20:21]
	s_cbranch_execz .LBB0_1178
	s_cmpk_lt_u32 s84, 0x900
	s_mov_b64 s[22:23], -1
	s_cbranch_scc1 .LBB0_1172
	v_lshl_add_u64 v[74:75], s[54:55], 0, v[108:109]
	v_mov_b32_e32 v133, v131
	v_lshl_add_u64 v[74:75], v[132:133], 1, v[74:75]
	v_add_co_u32_e32 v74, vcc, 0xfffff500, v74
	v_cvt_pk_bf16_f32 v72, v68, v69
	v_cvt_pk_bf16_f32 v73, v70, v71
	v_addc_co_u32_e32 v75, vcc, -1, v75, vcc
	s_mov_b64 s[22:23], 0
	global_store_dwordx2 v[74:75], v[72:73], off
.LBB0_1172:
	s_andn2_b64 vcc, exec, s[22:23]
	s_cbranch_vccnz .LBB0_1178
	v_add_u32_e32 v130, 0xfffffa80, v132
	v_lshrrev_b32_e32 v73, 7, v130
	v_and_b32_e32 v72, 0x6c, v132
	s_and_saveexec_b64 s[22:23], s[24:25]
	s_xor_b64 s[22:23], exec, s[22:23]
	s_cbranch_execz .LBB0_1175
	v_lshl_add_u64 v[74:75], s[68:69], 0, v[104:105]
	v_lshl_add_u64 v[74:75], v[130:131], 2, v[74:75]
	v_add_u32_e32 v130, v73, v185
	global_store_dwordx4 v[74:75], v[68:71], off
	v_lshlrev_b64 v[74:75], 7, v[130:131]
	v_or_b32_e32 v74, v74, v72
	v_mov_b64_e32 v[72:73], s[48:49]
	v_mad_u64_u32 v[72:73], s[26:27], v74, s51, v[72:73]
	v_mad_u32_u24 v73, v75, s51, v73
	v_lshlrev_b32_e32 v130, 1, v181
	v_cvt_pk_bf16_f32 v68, v68, s0
	v_lshl_add_u64 v[74:75], v[72:73], 0, v[130:131]
	v_lshlrev_b32_e32 v130, 1, v180
	global_store_short v[74:75], v68, off offset:2056
	v_cvt_pk_bf16_f32 v74, v69, s0
	v_lshl_add_u64 v[68:69], v[72:73], 0, v[130:131]
	v_add_co_u32_e32 v72, vcc, 0x1000, v68
	v_cvt_pk_bf16_f32 v70, v70, s0
	s_nop 0
	v_addc_co_u32_e32 v73, vcc, 0, v69, vcc
	v_add_co_u32_e32 v68, vcc, 0x2000, v68
	global_store_short v[72:73], v70, off offset:2304
	v_cvt_pk_bf16_f32 v70, v71, s0
	v_addc_co_u32_e32 v69, vcc, 0, v69, vcc
	global_store_short v[72:73], v74, off offset:128
	global_store_short v[68:69], v70, off offset:384
.LBB0_1175:
	s_andn2_saveexec_b64 s[22:23], s[22:23]
	s_cbranch_execz .LBB0_1177
	v_lshl_add_u64 v[74:75], s[70:71], 0, v[106:107]
	v_lshl_add_u64 v[74:75], v[130:131], 2, v[74:75]
	global_store_dwordx4 v[74:75], v[68:71], off
	v_add_u32_e32 v74, v73, v172
	v_ashrrev_i32_e32 v75, 31, v74
	v_lshlrev_b64 v[74:75], 20, v[74:75]
	v_lshlrev_b32_e32 v130, 13, v72
	v_lshl_add_u64 v[72:73], s[46:47], 0, v[74:75]
	v_lshl_add_u64 v[72:73], v[72:73], 0, v[130:131]
	v_lshlrev_b32_e32 v130, 1, v178
	v_cvt_pk_bf16_f32 v68, v68, s0
	v_lshl_add_u64 v[72:73], v[72:73], 0, v[130:131]
	s_movk_i32 s26, 0x2000
	global_store_short v[72:73], v68, off
	v_add_co_u32_e32 v68, vcc, s26, v72
	v_cvt_pk_bf16_f32 v74, v69, s0
	s_nop 0
	v_addc_co_u32_e32 v69, vcc, 0, v73, vcc
	global_store_short v[68:69], v74, off
	v_add_co_u32_e32 v68, vcc, 0x4000, v72
	v_cvt_pk_bf16_f32 v70, v70, s0
	s_nop 0
	v_addc_co_u32_e32 v69, vcc, 0, v73, vcc
	global_store_short v[68:69], v70, off
	v_add_co_u32_e32 v68, vcc, 0x6000, v72
	v_cvt_pk_bf16_f32 v70, v71, s0
	s_nop 0
	v_addc_co_u32_e32 v69, vcc, 0, v73, vcc
	global_store_short v[68:69], v70, off

.LBB0_1178:
	s_andn2_saveexec_b64 s[20:21], s[20:21]
	s_cbranch_execz .LBB0_1190
	v_cmp_eq_u32_e32 vcc, 0, v160
	s_and_saveexec_b64 s[22:23], vcc
	s_cbranch_execz .LBB0_1181
	v_cmp_lt_i32_e32 vcc, v158, v156
	v_lshlrev_b32_e32 v130, 3, v190
	s_nop 0
	v_cndmask_b32_e32 v72, v155, v158, vcc
	v_lshlrev_b32_e32 v72, 2, v72
	ds_bpermute_b32 v76, v72, v68
	ds_bpermute_b32 v77, v72, v69
	ds_bpermute_b32 v78, v72, v70
	ds_bpermute_b32 v79, v72, v71
	v_lshl_add_u64 v[72:73], s[52:53], 0, v[130:131]
	v_lshlrev_b32_e32 v130, 3, v135
	v_lshl_add_u64 v[80:81], v[72:73], 0, v[130:131]
	global_load_dwordx4 v[72:75], v[80:81], off
	s_waitcnt vmcnt(0) lgkmcnt(0)
	v_mov_b32_e32 v83, v74
	v_mov_b32_e32 v74, v73
	v_mov_b32_e32 v82, v72
	v_pk_mul_f32 v[72:73], v[74:75], v[76:77]
	s_nop 0
	v_cndmask_b32_e64 v73, v73, -v73, s[30:31]
	v_cndmask_b32_e64 v72, v72, -v72, s[30:31]
	v_pk_fma_f32 v[68:69], v[68:69], v[82:83], v[72:73]
	global_load_dwordx4 v[72:75], v[80:81], off offset:16
	s_waitcnt vmcnt(0) lgkmcnt(0)
	v_mov_b32_e32 v77, v74
	v_mov_b32_e32 v74, v73
	v_mov_b32_e32 v76, v72
	v_pk_mul_f32 v[72:73], v[74:75], v[78:79]
	s_nop 0
	v_cndmask_b32_e64 v73, v73, -v73, s[30:31]
	v_cndmask_b32_e64 v72, v72, -v72, s[30:31]
	v_pk_fma_f32 v[70:71], v[70:71], v[76:77], v[72:73]
.LBB0_1181:
	s_or_b64 exec, exec, s[22:23]
	v_cvt_pk_bf16_f32 v72, v68, v69
	v_cvt_pk_bf16_f32 v73, v70, v71
	s_and_saveexec_b64 s[22:23], s[6:7]
	s_xor_b64 s[22:23], exec, s[22:23]
	s_cbranch_execz .LBB0_1187
	v_add_u32_e32 v130, 0xfffffd80, v132
	s_and_saveexec_b64 s[26:27], s[24:25]
	s_xor_b64 s[26:27], exec, s[26:27]
	s_cbranch_execz .LBB0_1184
	v_lshl_add_u64 v[74:75], s[56:57], 0, v[150:151]
	v_lshl_add_u64 v[74:75], v[130:131], 1, v[74:75]
	global_store_dwordx2 v[74:75], v[72:73], off
	v_lshl_add_u64 v[72:73], s[72:73], 0, v[104:105]
	v_lshl_add_u64 v[72:73], v[130:131], 2, v[72:73]
	global_store_dwordx4 v[72:73], v[68:71], off
.LBB0_1184:
	s_andn2_saveexec_b64 s[26:27], s[26:27]
	s_cbranch_execz .LBB0_1186
	v_lshl_add_u64 v[74:75], v[110:111], 1, s[44:45]
	v_lshl_add_u64 v[74:75], v[130:131], 1, v[74:75]
	global_store_dwordx2 v[74:75], v[72:73], off
	v_lshl_add_u64 v[72:73], v[110:111], 2, s[74:75]
	v_lshl_add_u64 v[72:73], v[130:131], 2, v[72:73]
	global_store_dwordx4 v[72:73], v[68:71], off

.LBB0_1187:
	s_andn2_saveexec_b64 s[22:23], s[22:23]
	s_cbranch_execz .LBB0_1189
	v_lshl_add_u64 v[68:69], s[54:55], 0, v[108:109]
	v_ashrrev_i32_e32 v133, 31, v132
	v_lshl_add_u64 v[68:69], v[132:133], 1, v[68:69]
	global_store_dwordx2 v[68:69], v[72:73], off offset:256

.LBB0_1190:
	s_or_b64 exec, exec, s[20:21]
	s_and_saveexec_b64 s[20:21], s[14:15]
	s_xor_b64 s[20:21], exec, s[20:21]
	s_cbranch_execz .LBB0_1199
	s_cmpk_lt_u32 s84, 0x900
	s_mov_b64 s[22:23], -1
	s_cbranch_scc1 .LBB0_1193
	v_lshl_add_u64 v[70:71], s[54:55], 0, v[108:109]
	v_mov_b32_e32 v133, v131
	v_lshl_add_u64 v[70:71], v[132:133], 1, v[70:71]
	v_add_co_u32_e32 v70, vcc, 0xfffff520, v70
	v_cvt_pk_bf16_f32 v68, v64, v65
	v_cvt_pk_bf16_f32 v69, v66, v67
	v_addc_co_u32_e32 v71, vcc, -1, v71, vcc
	s_mov_b64 s[22:23], 0
	global_store_dwordx2 v[70:71], v[68:69], off
.LBB0_1193:
	s_andn2_b64 vcc, exec, s[22:23]
	s_cbranch_vccnz .LBB0_1199
	v_add_u32_e32 v130, 0xfffffa90, v132
	v_lshrrev_b32_e32 v69, 7, v130
	v_and_b32_e32 v68, 0x7c, v94
	s_and_saveexec_b64 s[22:23], s[24:25]
	s_xor_b64 s[22:23], exec, s[22:23]
	s_cbranch_execz .LBB0_1196
	v_lshl_add_u64 v[70:71], s[68:69], 0, v[104:105]
	v_lshl_add_u64 v[70:71], v[130:131], 2, v[70:71]
	v_add_u32_e32 v130, v69, v185
	global_store_dwordx4 v[70:71], v[64:67], off
	v_lshlrev_b64 v[70:71], 7, v[130:131]
	v_or_b32_e32 v70, v70, v68
	v_mov_b64_e32 v[68:69], s[48:49]
	v_mad_u64_u32 v[68:69], s[26:27], v70, s51, v[68:69]
	v_mad_u32_u24 v69, v71, s51, v69
	v_lshlrev_b32_e32 v130, 1, v181
	v_cvt_pk_bf16_f32 v64, v64, s0
	v_lshl_add_u64 v[70:71], v[68:69], 0, v[130:131]
	v_lshlrev_b32_e32 v130, 1, v180
	global_store_short v[70:71], v64, off offset:2056
	v_cvt_pk_bf16_f32 v70, v65, s0
	v_lshl_add_u64 v[64:65], v[68:69], 0, v[130:131]
	v_add_co_u32_e32 v68, vcc, 0x1000, v64
	v_cvt_pk_bf16_f32 v66, v66, s0
	s_nop 0
	v_addc_co_u32_e32 v69, vcc, 0, v65, vcc
	v_add_co_u32_e32 v64, vcc, 0x2000, v64
	global_store_short v[68:69], v66, off offset:2304
	v_cvt_pk_bf16_f32 v66, v67, s0
	v_addc_co_u32_e32 v65, vcc, 0, v65, vcc
	global_store_short v[68:69], v70, off offset:128
	global_store_short v[64:65], v66, off offset:384
.LBB0_1196:
	s_andn2_saveexec_b64 s[22:23], s[22:23]
	s_cbranch_execz .LBB0_1198
	v_lshl_add_u64 v[70:71], s[70:71], 0, v[106:107]
	v_lshl_add_u64 v[70:71], v[130:131], 2, v[70:71]
	global_store_dwordx4 v[70:71], v[64:67], off
	v_add_u32_e32 v70, v69, v172
	v_ashrrev_i32_e32 v71, 31, v70
	v_lshlrev_b64 v[70:71], 20, v[70:71]
	v_lshlrev_b32_e32 v130, 13, v68
	v_lshl_add_u64 v[68:69], s[46:47], 0, v[70:71]
	v_lshl_add_u64 v[68:69], v[68:69], 0, v[130:131]
	v_lshlrev_b32_e32 v130, 1, v178
	v_cvt_pk_bf16_f32 v64, v64, s0
	v_lshl_add_u64 v[68:69], v[68:69], 0, v[130:131]
	s_movk_i32 s26, 0x2000
	global_store_short v[68:69], v64, off
	v_add_co_u32_e32 v64, vcc, s26, v68
	v_cvt_pk_bf16_f32 v70, v65, s0
	s_nop 0
	v_addc_co_u32_e32 v65, vcc, 0, v69, vcc
	global_store_short v[64:65], v70, off
	v_add_co_u32_e32 v64, vcc, 0x4000, v68
	v_cvt_pk_bf16_f32 v66, v66, s0
	s_nop 0
	v_addc_co_u32_e32 v65, vcc, 0, v69, vcc
	global_store_short v[64:65], v66, off
	v_add_co_u32_e32 v64, vcc, 0x6000, v68
	v_cvt_pk_bf16_f32 v66, v67, s0
	s_nop 0
	v_addc_co_u32_e32 v65, vcc, 0, v69, vcc
	global_store_short v[64:65], v66, off

.LBB0_1199:
	s_andn2_saveexec_b64 s[20:21], s[20:21]
	s_cbranch_execz .LBB0_1209
	v_cvt_pk_bf16_f32 v68, v64, v65
	v_cvt_pk_bf16_f32 v69, v66, v67
	s_and_saveexec_b64 s[22:23], s[8:9]
	s_xor_b64 s[22:23], exec, s[22:23]
	s_cbranch_execz .LBB0_1206
	v_add_u32_e32 v130, 0xfffffd90, v132
	s_and_saveexec_b64 s[26:27], s[24:25]
	s_xor_b64 s[24:25], exec, s[26:27]
	s_cbranch_execz .LBB0_1203
	v_lshl_add_u64 v[70:71], s[56:57], 0, v[150:151]
	v_lshl_add_u64 v[70:71], v[130:131], 1, v[70:71]
	global_store_dwordx2 v[70:71], v[68:69], off
	v_lshl_add_u64 v[68:69], s[72:73], 0, v[104:105]
	v_lshl_add_u64 v[68:69], v[130:131], 2, v[68:69]
	global_store_dwordx4 v[68:69], v[64:67], off
.LBB0_1203:
	s_andn2_saveexec_b64 s[24:25], s[24:25]
	s_cbranch_execz .LBB0_1205
	v_lshl_add_u64 v[70:71], v[110:111], 1, s[44:45]
	v_lshl_add_u64 v[70:71], v[130:131], 1, v[70:71]
	global_store_dwordx2 v[70:71], v[68:69], off
	v_lshl_add_u64 v[68:69], v[110:111], 2, s[74:75]
	v_lshl_add_u64 v[68:69], v[130:131], 2, v[68:69]
	global_store_dwordx4 v[68:69], v[64:67], off

.LBB0_1206:
	s_andn2_saveexec_b64 s[22:23], s[22:23]
	s_cbranch_execz .LBB0_1208
	v_lshl_add_u64 v[64:65], s[54:55], 0, v[108:109]
	v_ashrrev_i32_e32 v133, 31, v132
	v_lshl_add_u64 v[64:65], v[132:133], 1, v[64:65]
	global_store_dwordx2 v[64:65], v[68:69], off offset:288

.LBB0_1209:
	s_or_b64 exec, exec, s[20:21]
	v_add_u32_e32 v70, 0x80, v134
	v_ashrrev_i32_e32 v71, 31, v70
	v_add_u32_e32 v64, 0xffff8080, v134
	v_lshlrev_b32_e32 v66, 1, v70
	v_lshlrev_b64 v[68:69], 11, v[70:71]
	v_lshrrev_b32_e32 v71, 6, v64
	v_mad_u64_u32 v[64:65], s[22:23], v64, s63, 0
	v_and_or_b32 v92, v66, 24, v164
	v_mad_i64_i32 v[66:67], s[22:23], v70, s63, 0
	v_ashrrev_i32_e32 v72, 12, v70
	s_movk_i32 s22, 0xfc3
	v_cmp_lt_i32_e64 s[24:25], s2, v70
	v_cmp_gt_i32_e64 s[20:21], s61, v70
	v_mul_lo_u32 v99, v71, 6
	v_mul_i32_i24_e32 v93, 6, v72
	v_and_or_b32 v91, v70, s22, v162
	s_and_saveexec_b64 s[22:23], s[12:13]
	s_xor_b64 s[22:23], exec, s[22:23]
	s_cbranch_execz .LBB0_1218
	s_cmpk_lt_u32 s84, 0x900
	s_mov_b64 s[26:27], -1
	s_cbranch_scc1 .LBB0_1212
	v_lshl_add_u64 v[74:75], s[54:55], 0, v[68:69]
	v_mov_b32_e32 v133, v131
	v_lshl_add_u64 v[74:75], v[132:133], 1, v[74:75]
	v_add_co_u32_e32 v74, vcc, 0xfffff400, v74
	v_cvt_pk_bf16_f32 v72, v60, v61
	v_cvt_pk_bf16_f32 v73, v62, v63
	v_addc_co_u32_e32 v75, vcc, -1, v75, vcc
	s_mov_b64 s[26:27], 0
	global_store_dwordx2 v[74:75], v[72:73], off
.LBB0_1212:
	s_andn2_b64 vcc, exec, s[26:27]
	s_cbranch_vccnz .LBB0_1218
	v_add_u32_e32 v130, 0xfffffa00, v132
	v_lshrrev_b32_e32 v73, 7, v130
	v_and_b32_e32 v72, 0x6c, v132
	s_and_saveexec_b64 s[26:27], s[24:25]
	s_xor_b64 s[26:27], exec, s[26:27]
	s_cbranch_execz .LBB0_1215
	v_lshl_add_u64 v[74:75], s[68:69], 0, v[64:65]
	v_lshl_add_u64 v[74:75], v[130:131], 2, v[74:75]
	v_add_u32_e32 v130, v73, v99
	global_store_dwordx4 v[74:75], v[60:63], off
	v_lshlrev_b64 v[74:75], 7, v[130:131]
	v_or_b32_e32 v74, v74, v72
	v_mov_b64_e32 v[72:73], s[48:49]
	v_mad_u64_u32 v[72:73], s[28:29], v74, s51, v[72:73]
	v_mad_u32_u24 v73, v75, s51, v73
	v_lshlrev_b32_e32 v130, 1, v92
	v_cvt_pk_bf16_f32 v60, v60, s0
	v_lshl_add_u64 v[72:73], v[72:73], 0, v[130:131]
	global_store_short v[72:73], v60, off offset:2048
	v_add_co_u32_e32 v60, vcc, 0x1000, v72
	v_cvt_pk_bf16_f32 v74, v61, s0
	s_nop 0
	v_addc_co_u32_e32 v61, vcc, 0, v73, vcc
	v_cvt_pk_bf16_f32 v62, v62, s0
	global_store_short v[60:61], v74, off offset:128
	global_store_short v[60:61], v62, off offset:2304
	v_add_co_u32_e32 v60, vcc, 0x2000, v72
	v_cvt_pk_bf16_f32 v62, v63, s0
	s_nop 0
	v_addc_co_u32_e32 v61, vcc, 0, v73, vcc
	global_store_short v[60:61], v62, off offset:384
.LBB0_1215:
	s_andn2_saveexec_b64 s[26:27], s[26:27]
	s_cbranch_execz .LBB0_1217
	v_lshl_add_u64 v[74:75], s[70:71], 0, v[66:67]
	v_lshl_add_u64 v[74:75], v[130:131], 2, v[74:75]
	global_store_dwordx4 v[74:75], v[60:63], off
	v_add_u32_e32 v74, v73, v93
	v_ashrrev_i32_e32 v75, 31, v74
	v_lshlrev_b32_e32 v130, 1, v91
	v_lshl_add_u64 v[76:77], s[46:47], 0, v[130:131]
	v_lshlrev_b64 v[74:75], 20, v[74:75]
	v_lshlrev_b32_e32 v130, 13, v72
	v_lshl_add_u64 v[72:73], v[76:77], 0, v[74:75]
	v_cvt_pk_bf16_f32 v60, v60, s0
	v_lshl_add_u64 v[72:73], v[72:73], 0, v[130:131]
	s_movk_i32 s28, 0x2000
	global_store_short v[72:73], v60, off
	v_add_co_u32_e32 v60, vcc, s28, v72
	v_cvt_pk_bf16_f32 v74, v61, s0
	s_nop 0
	v_addc_co_u32_e32 v61, vcc, 0, v73, vcc
	global_store_short v[60:61], v74, off
	v_add_co_u32_e32 v60, vcc, 0x4000, v72
	v_cvt_pk_bf16_f32 v62, v62, s0
	s_nop 0
	v_addc_co_u32_e32 v61, vcc, 0, v73, vcc
	global_store_short v[60:61], v62, off
	v_add_co_u32_e32 v60, vcc, 0x6000, v72
	v_cvt_pk_bf16_f32 v62, v63, s0
	s_nop 0
	v_addc_co_u32_e32 v61, vcc, 0, v73, vcc
	global_store_short v[60:61], v62, off

.LBB0_1218:
	s_or_saveexec_b64 s[22:23], s[22:23]
	v_mul_lo_u32 v71, v71, s88
	v_and_b32_e32 v72, 0xfcf, v70
	v_or_b32_e32 v71, v71, v163
	v_cndmask_b32_e64 v72, v165, v72, s[20:21]
	v_add_u32_e32 v71, 0x400, v71
	v_lshlrev_b32_e32 v101, 3, v72
	v_mad_u64_u32 v[74:75], s[20:21], v71, s89, 0
	v_mad_i64_i32 v[70:71], s[20:21], v70, s62, 0
	s_xor_b64 exec, exec, s[22:23]
	s_cbranch_execz .LBB0_1230
	v_cmp_eq_u32_e32 vcc, 0, v160
	s_and_saveexec_b64 s[20:21], vcc
	s_cbranch_execz .LBB0_1221
	v_cmp_lt_i32_e32 vcc, v158, v156
	v_lshlrev_b32_e32 v130, 3, v101
	s_nop 0
	v_cndmask_b32_e32 v72, v155, v158, vcc
	v_lshlrev_b32_e32 v76, 2, v72
	ds_bpermute_b32 v72, v76, v60
	ds_bpermute_b32 v73, v76, v61
	ds_bpermute_b32 v80, v76, v62
	ds_bpermute_b32 v81, v76, v63
	v_lshl_add_u64 v[76:77], s[52:53], 0, v[130:131]
	v_lshlrev_b32_e32 v130, 3, v135
	v_lshl_add_u64 v[82:83], v[76:77], 0, v[130:131]
	global_load_dwordx4 v[76:79], v[82:83], off
	s_waitcnt vmcnt(0) lgkmcnt(0)
	v_mov_b32_e32 v85, v78
	v_mov_b32_e32 v78, v77
	v_mov_b32_e32 v84, v76
	v_pk_mul_f32 v[72:73], v[78:79], v[72:73]
	global_load_dwordx4 v[76:79], v[82:83], off offset:16
	v_cndmask_b32_e64 v73, v73, -v73, s[30:31]
	v_cndmask_b32_e64 v72, v72, -v72, s[30:31]
	v_pk_fma_f32 v[60:61], v[60:61], v[84:85], v[72:73]
	s_waitcnt vmcnt(0) lgkmcnt(0)
	v_mov_b32_e32 v73, v78
	v_mov_b32_e32 v78, v77
	v_mov_b32_e32 v72, v76
	v_pk_mul_f32 v[76:77], v[78:79], v[80:81]
	s_nop 0
	v_cndmask_b32_e64 v77, v77, -v77, s[30:31]
	v_cndmask_b32_e64 v76, v76, -v76, s[30:31]
	v_pk_fma_f32 v[62:63], v[62:63], v[72:73], v[76:77]
.LBB0_1221:
	s_or_b64 exec, exec, s[20:21]
	v_cvt_pk_bf16_f32 v72, v60, v61
	v_cvt_pk_bf16_f32 v73, v62, v63
	s_and_saveexec_b64 s[20:21], s[4:5]
	s_xor_b64 s[20:21], exec, s[20:21]
	s_cbranch_execz .LBB0_1227
	v_add_u32_e32 v130, 0xfffffd00, v132
	s_and_saveexec_b64 s[26:27], s[24:25]
	s_xor_b64 s[26:27], exec, s[26:27]
	s_cbranch_execz .LBB0_1224
	v_lshl_add_u64 v[76:77], s[56:57], 0, v[74:75]
	v_lshl_add_u64 v[76:77], v[130:131], 1, v[76:77]
	global_store_dwordx2 v[76:77], v[72:73], off
	v_lshl_add_u64 v[72:73], s[72:73], 0, v[64:65]
	v_lshl_add_u64 v[72:73], v[130:131], 2, v[72:73]
	global_store_dwordx4 v[72:73], v[60:63], off
.LBB0_1224:
	s_andn2_saveexec_b64 s[26:27], s[26:27]
	s_cbranch_execz .LBB0_1226
	v_lshl_add_u64 v[76:77], v[70:71], 1, s[44:45]
	v_lshl_add_u64 v[76:77], v[130:131], 1, v[76:77]
	global_store_dwordx2 v[76:77], v[72:73], off
	v_lshl_add_u64 v[72:73], v[70:71], 2, s[74:75]
	v_lshl_add_u64 v[72:73], v[130:131], 2, v[72:73]
	global_store_dwordx4 v[72:73], v[60:63], off

.LBB0_1227:
	s_andn2_saveexec_b64 s[20:21], s[20:21]
	s_cbranch_execz .LBB0_1229
	v_lshl_add_u64 v[60:61], s[54:55], 0, v[68:69]
	v_ashrrev_i32_e32 v133, 31, v132
	v_lshl_add_u64 v[60:61], v[132:133], 1, v[60:61]
	global_store_dwordx2 v[60:61], v[72:73], off

.LBB0_1230:
	s_or_b64 exec, exec, s[22:23]
	s_and_saveexec_b64 s[20:21], s[16:17]
	s_xor_b64 s[20:21], exec, s[20:21]
	s_cbranch_execz .LBB0_1239
	s_cmpk_lt_u32 s84, 0x900
	s_mov_b64 s[22:23], -1
	s_cbranch_scc1 .LBB0_1233
	v_lshl_add_u64 v[62:63], s[54:55], 0, v[68:69]
	v_mov_b32_e32 v133, v131
	v_lshl_add_u64 v[62:63], v[132:133], 1, v[62:63]
	v_add_co_u32_e32 v62, vcc, 0xfffff420, v62
	v_cvt_pk_bf16_f32 v60, v56, v57
	v_cvt_pk_bf16_f32 v61, v58, v59
	v_addc_co_u32_e32 v63, vcc, -1, v63, vcc
	s_mov_b64 s[22:23], 0
	global_store_dwordx2 v[62:63], v[60:61], off
.LBB0_1233:
	s_andn2_b64 vcc, exec, s[22:23]
	s_cbranch_vccnz .LBB0_1239
	v_add_u32_e32 v130, 0xfffffa10, v132
	v_lshrrev_b32_e32 v61, 7, v130
	v_and_b32_e32 v60, 0x7c, v161
	s_and_saveexec_b64 s[22:23], s[24:25]
	s_xor_b64 s[22:23], exec, s[22:23]
	s_cbranch_execz .LBB0_1236
	v_lshl_add_u64 v[62:63], s[68:69], 0, v[64:65]
	v_lshl_add_u64 v[62:63], v[130:131], 2, v[62:63]
	v_add_u32_e32 v130, v61, v99
	global_store_dwordx4 v[62:63], v[56:59], off
	v_lshlrev_b64 v[62:63], 7, v[130:131]
	v_or_b32_e32 v62, v62, v60
	v_mov_b64_e32 v[60:61], s[48:49]
	v_mad_u64_u32 v[60:61], s[26:27], v62, s51, v[60:61]
	v_mad_u32_u24 v61, v63, s51, v61
	v_lshlrev_b32_e32 v130, 1, v92
	v_cvt_pk_bf16_f32 v56, v56, s0
	v_lshl_add_u64 v[60:61], v[60:61], 0, v[130:131]
	global_store_short v[60:61], v56, off offset:2048
	v_add_co_u32_e32 v56, vcc, 0x1000, v60
	v_cvt_pk_bf16_f32 v62, v57, s0
	s_nop 0
	v_addc_co_u32_e32 v57, vcc, 0, v61, vcc
	v_cvt_pk_bf16_f32 v58, v58, s0
	global_store_short v[56:57], v62, off offset:128
	global_store_short v[56:57], v58, off offset:2304
	v_add_co_u32_e32 v56, vcc, 0x2000, v60
	v_cvt_pk_bf16_f32 v58, v59, s0
	s_nop 0
	v_addc_co_u32_e32 v57, vcc, 0, v61, vcc
	global_store_short v[56:57], v58, off offset:384
.LBB0_1236:
	s_andn2_saveexec_b64 s[22:23], s[22:23]
	s_cbranch_execz .LBB0_1238
	v_lshl_add_u64 v[62:63], s[70:71], 0, v[66:67]
	v_lshl_add_u64 v[62:63], v[130:131], 2, v[62:63]
	global_store_dwordx4 v[62:63], v[56:59], off
	v_add_u32_e32 v62, v61, v93
	v_ashrrev_i32_e32 v63, 31, v62
	v_lshlrev_b32_e32 v130, 1, v91
	v_lshl_add_u64 v[72:73], s[46:47], 0, v[130:131]
	v_lshlrev_b64 v[62:63], 20, v[62:63]
	v_lshlrev_b32_e32 v130, 13, v60
	v_lshl_add_u64 v[60:61], v[72:73], 0, v[62:63]
	v_cvt_pk_bf16_f32 v56, v56, s0
	v_lshl_add_u64 v[60:61], v[60:61], 0, v[130:131]
	s_movk_i32 s26, 0x2000
	global_store_short v[60:61], v56, off
	v_add_co_u32_e32 v56, vcc, s26, v60
	v_cvt_pk_bf16_f32 v62, v57, s0
	s_nop 0
	v_addc_co_u32_e32 v57, vcc, 0, v61, vcc
	global_store_short v[56:57], v62, off
	v_add_co_u32_e32 v56, vcc, 0x4000, v60
	v_cvt_pk_bf16_f32 v58, v58, s0
	s_nop 0
	v_addc_co_u32_e32 v57, vcc, 0, v61, vcc
	global_store_short v[56:57], v58, off
	v_add_co_u32_e32 v56, vcc, 0x6000, v60
	v_cvt_pk_bf16_f32 v58, v59, s0
	s_nop 0
	v_addc_co_u32_e32 v57, vcc, 0, v61, vcc
	global_store_short v[56:57], v58, off

.LBB0_1239:
	s_andn2_saveexec_b64 s[20:21], s[20:21]
	s_cbranch_execz .LBB0_1249
	v_cvt_pk_bf16_f32 v60, v56, v57
	v_cvt_pk_bf16_f32 v61, v58, v59
	s_and_saveexec_b64 s[22:23], s[10:11]
	s_xor_b64 s[22:23], exec, s[22:23]
	s_cbranch_execz .LBB0_1246
	v_add_u32_e32 v130, 0xfffffd10, v132
	s_and_saveexec_b64 s[26:27], s[24:25]
	s_xor_b64 s[26:27], exec, s[26:27]
	s_cbranch_execz .LBB0_1243
	v_lshl_add_u64 v[62:63], s[56:57], 0, v[74:75]
	v_lshl_add_u64 v[62:63], v[130:131], 1, v[62:63]
	global_store_dwordx2 v[62:63], v[60:61], off
	v_lshl_add_u64 v[60:61], s[72:73], 0, v[64:65]
	v_lshl_add_u64 v[60:61], v[130:131], 2, v[60:61]
	global_store_dwordx4 v[60:61], v[56:59], off
.LBB0_1243:
	s_andn2_saveexec_b64 s[26:27], s[26:27]
	s_cbranch_execz .LBB0_1245
	v_lshl_add_u64 v[62:63], v[70:71], 1, s[44:45]
	v_lshl_add_u64 v[62:63], v[130:131], 1, v[62:63]
	global_store_dwordx2 v[62:63], v[60:61], off
	v_lshl_add_u64 v[60:61], v[70:71], 2, s[74:75]
	v_lshl_add_u64 v[60:61], v[130:131], 2, v[60:61]
	global_store_dwordx4 v[60:61], v[56:59], off

.LBB0_1246:
	s_andn2_saveexec_b64 s[22:23], s[22:23]
	s_cbranch_execz .LBB0_1248
	v_lshl_add_u64 v[56:57], s[54:55], 0, v[68:69]
	v_ashrrev_i32_e32 v133, 31, v132
	v_lshl_add_u64 v[56:57], v[132:133], 1, v[56:57]
	global_store_dwordx2 v[56:57], v[60:61], off offset:32

.LBB0_1249:
	s_or_b64 exec, exec, s[20:21]
	v_add_u32_e32 v62, 0x90, v134
	v_ashrrev_i32_e32 v63, 31, v62
	v_add_u32_e32 v56, 0xffff8090, v134
	v_lshlrev_b32_e32 v58, 1, v62
	v_ashrrev_i32_e32 v72, 12, v62
	v_lshlrev_b64 v[60:61], 11, v[62:63]
	v_lshrrev_b32_e32 v63, 6, v56
	v_and_or_b32 v88, v58, 24, v164
	v_mul_i32_i24_e32 v90, 6, v72
	v_and_b32_e32 v72, 0xfc3, v62
	v_cmp_lt_i32_e64 s[22:23], s2, v62
	v_cmp_gt_i32_e64 s[20:21], s61, v62
	v_mad_u64_u32 v[56:57], s[26:27], v56, s63, 0
	v_mul_lo_u32 v98, v63, 6
	v_or_b32_e32 v87, 4, v88
	v_mad_i64_i32 v[58:59], s[26:27], v62, s63, 0
	v_or3_b32 v85, v162, v72, 4
	s_and_saveexec_b64 s[26:27], s[12:13]
	s_xor_b64 s[26:27], exec, s[26:27]
	s_cbranch_execz .LBB0_1258
	s_cmpk_lt_u32 s84, 0x900
	s_mov_b64 s[28:29], -1
	s_cbranch_scc1 .LBB0_1252
	v_lshl_add_u64 v[76:77], s[54:55], 0, v[60:61]
	v_mov_b32_e32 v133, v131
	v_lshl_add_u64 v[76:77], v[132:133], 1, v[76:77]
	v_add_co_u32_e32 v76, vcc, 0xfffff400, v76
	v_cvt_pk_bf16_f32 v72, v52, v53
	v_cvt_pk_bf16_f32 v73, v54, v55
	v_addc_co_u32_e32 v77, vcc, -1, v77, vcc
	s_mov_b64 s[28:29], 0
	global_store_dwordx2 v[76:77], v[72:73], off
.LBB0_1252:
	s_andn2_b64 vcc, exec, s[28:29]
	s_cbranch_vccnz .LBB0_1258
	v_add_u32_e32 v130, 0xfffffa00, v132
	v_lshrrev_b32_e32 v73, 7, v130
	v_and_b32_e32 v72, 0x6c, v132
	s_and_saveexec_b64 s[28:29], s[22:23]
	s_xor_b64 s[28:29], exec, s[28:29]
	s_cbranch_execz .LBB0_1255
	v_lshl_add_u64 v[76:77], s[68:69], 0, v[56:57]
	v_lshl_add_u64 v[76:77], v[130:131], 2, v[76:77]
	v_add_u32_e32 v130, v73, v98
	global_store_dwordx4 v[76:77], v[52:55], off
	v_lshlrev_b64 v[76:77], 7, v[130:131]
	v_or_b32_e32 v76, v76, v72
	v_mov_b64_e32 v[72:73], s[48:49]
	v_mad_u64_u32 v[72:73], s[66:67], v76, s51, v[72:73]
	v_mad_u32_u24 v73, v77, s51, v73
	v_lshlrev_b32_e32 v130, 1, v88
	v_cvt_pk_bf16_f32 v52, v52, s0
	v_lshl_add_u64 v[76:77], v[72:73], 0, v[130:131]
	v_lshlrev_b32_e32 v130, 1, v87
	global_store_short v[76:77], v52, off offset:2056
	v_cvt_pk_bf16_f32 v76, v53, s0
	v_lshl_add_u64 v[52:53], v[72:73], 0, v[130:131]
	v_add_co_u32_e32 v72, vcc, 0x1000, v52
	v_cvt_pk_bf16_f32 v54, v54, s0
	s_nop 0
	v_addc_co_u32_e32 v73, vcc, 0, v53, vcc
	v_add_co_u32_e32 v52, vcc, 0x2000, v52
	global_store_short v[72:73], v54, off offset:2304
	v_cvt_pk_bf16_f32 v54, v55, s0
	v_addc_co_u32_e32 v53, vcc, 0, v53, vcc
	global_store_short v[72:73], v76, off offset:128
	global_store_short v[52:53], v54, off offset:384
.LBB0_1255:
	s_andn2_saveexec_b64 s[28:29], s[28:29]
	s_cbranch_execz .LBB0_1257
	v_lshl_add_u64 v[76:77], s[70:71], 0, v[58:59]
	v_lshl_add_u64 v[76:77], v[130:131], 2, v[76:77]
	global_store_dwordx4 v[76:77], v[52:55], off
	v_add_u32_e32 v76, v73, v90
	v_ashrrev_i32_e32 v77, 31, v76
	v_lshlrev_b64 v[76:77], 20, v[76:77]
	v_lshlrev_b32_e32 v130, 13, v72
	v_lshl_add_u64 v[72:73], s[46:47], 0, v[76:77]
	v_lshl_add_u64 v[72:73], v[72:73], 0, v[130:131]
	v_lshlrev_b32_e32 v130, 1, v85
	v_cvt_pk_bf16_f32 v52, v52, s0
	v_lshl_add_u64 v[72:73], v[72:73], 0, v[130:131]
	s_movk_i32 s66, 0x2000
	global_store_short v[72:73], v52, off
	v_add_co_u32_e32 v52, vcc, s66, v72
	v_cvt_pk_bf16_f32 v76, v53, s0
	s_nop 0
	v_addc_co_u32_e32 v53, vcc, 0, v73, vcc
	global_store_short v[52:53], v76, off
	v_add_co_u32_e32 v52, vcc, 0x4000, v72
	v_cvt_pk_bf16_f32 v54, v54, s0
	s_nop 0
	v_addc_co_u32_e32 v53, vcc, 0, v73, vcc
	global_store_short v[52:53], v54, off
	v_add_co_u32_e32 v52, vcc, 0x6000, v72
	v_cvt_pk_bf16_f32 v54, v55, s0
	s_nop 0
	v_addc_co_u32_e32 v53, vcc, 0, v73, vcc
	global_store_short v[52:53], v54, off

.LBB0_1258:
	s_or_saveexec_b64 s[26:27], s[26:27]
	v_mul_lo_u32 v63, v63, s88
	v_and_b32_e32 v72, 0xfdf, v62
	v_or_b32_e32 v63, v63, v168
	v_cndmask_b32_e64 v72, v171, v72, s[20:21]
	v_add_u32_e32 v63, 0x400, v63
	v_lshlrev_b32_e32 v104, 3, v72
	v_mad_u64_u32 v[76:77], s[20:21], v63, s89, 0
	v_mad_i64_i32 v[62:63], s[20:21], v62, s62, 0
	s_xor_b64 exec, exec, s[26:27]
	s_cbranch_execz .LBB0_1270
	v_cmp_eq_u32_e32 vcc, 0, v160
	s_and_saveexec_b64 s[20:21], vcc
	s_cbranch_execz .LBB0_1261
	v_cmp_lt_i32_e32 vcc, v158, v156
	v_lshlrev_b32_e32 v130, 3, v104
	s_nop 0
	v_cndmask_b32_e32 v72, v155, v158, vcc
	v_lshlrev_b32_e32 v78, 2, v72
	ds_bpermute_b32 v72, v78, v52
	ds_bpermute_b32 v73, v78, v53
	ds_bpermute_b32 v82, v78, v54
	ds_bpermute_b32 v83, v78, v55
	v_lshl_add_u64 v[78:79], s[52:53], 0, v[130:131]
	v_lshlrev_b32_e32 v130, 3, v135
	v_lshl_add_u64 v[96:97], v[78:79], 0, v[130:131]
	global_load_dwordx4 v[78:81], v[96:97], off
	s_waitcnt vmcnt(0) lgkmcnt(0)
	v_mov_b32_e32 v103, v80
	v_mov_b32_e32 v80, v79
	v_mov_b32_e32 v102, v78
	v_pk_mul_f32 v[72:73], v[80:81], v[72:73]
	global_load_dwordx4 v[78:81], v[96:97], off offset:16
	v_cndmask_b32_e64 v73, v73, -v73, s[30:31]
	v_cndmask_b32_e64 v72, v72, -v72, s[30:31]
	v_pk_fma_f32 v[52:53], v[52:53], v[102:103], v[72:73]
	s_waitcnt vmcnt(0) lgkmcnt(0)
	v_mov_b32_e32 v73, v80
	v_mov_b32_e32 v80, v79
	v_mov_b32_e32 v72, v78
	v_pk_mul_f32 v[78:79], v[80:81], v[82:83]
	s_nop 0
	v_cndmask_b32_e64 v79, v79, -v79, s[30:31]
	v_cndmask_b32_e64 v78, v78, -v78, s[30:31]
	v_pk_fma_f32 v[54:55], v[54:55], v[72:73], v[78:79]
.LBB0_1261:
	s_or_b64 exec, exec, s[20:21]
	v_cvt_pk_bf16_f32 v72, v52, v53
	v_cvt_pk_bf16_f32 v73, v54, v55
	s_and_saveexec_b64 s[20:21], s[4:5]
	s_xor_b64 s[20:21], exec, s[20:21]
	s_cbranch_execz .LBB0_1267
	v_add_u32_e32 v130, 0xfffffd00, v132
	s_and_saveexec_b64 s[28:29], s[22:23]
	s_xor_b64 s[28:29], exec, s[28:29]
	s_cbranch_execz .LBB0_1264
	v_lshl_add_u64 v[78:79], s[56:57], 0, v[76:77]
	v_lshl_add_u64 v[78:79], v[130:131], 1, v[78:79]
	global_store_dwordx2 v[78:79], v[72:73], off
	v_lshl_add_u64 v[72:73], s[72:73], 0, v[56:57]
	v_lshl_add_u64 v[72:73], v[130:131], 2, v[72:73]
	global_store_dwordx4 v[72:73], v[52:55], off
.LBB0_1264:
	s_andn2_saveexec_b64 s[28:29], s[28:29]
	s_cbranch_execz .LBB0_1266
	v_lshl_add_u64 v[78:79], v[62:63], 1, s[44:45]
	v_lshl_add_u64 v[78:79], v[130:131], 1, v[78:79]
	global_store_dwordx2 v[78:79], v[72:73], off
	v_lshl_add_u64 v[72:73], v[62:63], 2, s[74:75]
	v_lshl_add_u64 v[72:73], v[130:131], 2, v[72:73]
	global_store_dwordx4 v[72:73], v[52:55], off

.LBB0_1267:
	s_andn2_saveexec_b64 s[20:21], s[20:21]
	s_cbranch_execz .LBB0_1269
	v_lshl_add_u64 v[52:53], s[54:55], 0, v[60:61]
	v_ashrrev_i32_e32 v133, 31, v132
	v_lshl_add_u64 v[52:53], v[132:133], 1, v[52:53]
	global_store_dwordx2 v[52:53], v[72:73], off

.LBB0_1270:
	s_or_b64 exec, exec, s[26:27]
	s_and_saveexec_b64 s[20:21], s[16:17]
	s_xor_b64 s[20:21], exec, s[20:21]
	s_cbranch_execz .LBB0_1279
	s_cmpk_lt_u32 s84, 0x900
	s_mov_b64 s[26:27], -1
	s_cbranch_scc1 .LBB0_1273
	v_lshl_add_u64 v[54:55], s[54:55], 0, v[60:61]
	v_mov_b32_e32 v133, v131
	v_lshl_add_u64 v[54:55], v[132:133], 1, v[54:55]
	v_add_co_u32_e32 v54, vcc, 0xfffff420, v54
	v_cvt_pk_bf16_f32 v52, v48, v49
	v_cvt_pk_bf16_f32 v53, v50, v51
	v_addc_co_u32_e32 v55, vcc, -1, v55, vcc
	s_mov_b64 s[26:27], 0
	global_store_dwordx2 v[54:55], v[52:53], off
.LBB0_1273:
	s_andn2_b64 vcc, exec, s[26:27]
	s_cbranch_vccnz .LBB0_1279
	v_add_u32_e32 v130, 0xfffffa10, v132
	v_lshrrev_b32_e32 v53, 7, v130
	v_and_b32_e32 v52, 0x7c, v161
	s_and_saveexec_b64 s[26:27], s[22:23]
	s_xor_b64 s[26:27], exec, s[26:27]
	s_cbranch_execz .LBB0_1276
	v_lshl_add_u64 v[54:55], s[68:69], 0, v[56:57]
	v_lshl_add_u64 v[54:55], v[130:131], 2, v[54:55]
	v_add_u32_e32 v130, v53, v98
	global_store_dwordx4 v[54:55], v[48:51], off
	v_lshlrev_b64 v[54:55], 7, v[130:131]
	v_or_b32_e32 v54, v54, v52
	v_mov_b64_e32 v[52:53], s[48:49]
	v_mad_u64_u32 v[52:53], s[28:29], v54, s51, v[52:53]
	v_mad_u32_u24 v53, v55, s51, v53
	v_lshlrev_b32_e32 v130, 1, v88
	v_cvt_pk_bf16_f32 v48, v48, s0
	v_lshl_add_u64 v[54:55], v[52:53], 0, v[130:131]
	v_lshlrev_b32_e32 v130, 1, v87
	global_store_short v[54:55], v48, off offset:2056
	v_cvt_pk_bf16_f32 v54, v49, s0
	v_lshl_add_u64 v[48:49], v[52:53], 0, v[130:131]
	v_add_co_u32_e32 v52, vcc, 0x1000, v48
	v_cvt_pk_bf16_f32 v50, v50, s0
	s_nop 0
	v_addc_co_u32_e32 v53, vcc, 0, v49, vcc
	v_add_co_u32_e32 v48, vcc, 0x2000, v48
	global_store_short v[52:53], v50, off offset:2304
	v_cvt_pk_bf16_f32 v50, v51, s0
	v_addc_co_u32_e32 v49, vcc, 0, v49, vcc
	global_store_short v[52:53], v54, off offset:128
	global_store_short v[48:49], v50, off offset:384
.LBB0_1276:
	s_andn2_saveexec_b64 s[26:27], s[26:27]
	s_cbranch_execz .LBB0_1278
	v_lshl_add_u64 v[54:55], s[70:71], 0, v[58:59]
	v_lshl_add_u64 v[54:55], v[130:131], 2, v[54:55]
	global_store_dwordx4 v[54:55], v[48:51], off
	v_add_u32_e32 v54, v53, v90
	v_ashrrev_i32_e32 v55, 31, v54
	v_lshlrev_b64 v[54:55], 20, v[54:55]
	v_lshlrev_b32_e32 v130, 13, v52
	v_lshl_add_u64 v[52:53], s[46:47], 0, v[54:55]
	v_lshl_add_u64 v[52:53], v[52:53], 0, v[130:131]
	v_lshlrev_b32_e32 v130, 1, v85
	v_cvt_pk_bf16_f32 v48, v48, s0
	v_lshl_add_u64 v[52:53], v[52:53], 0, v[130:131]
	s_movk_i32 s28, 0x2000
	global_store_short v[52:53], v48, off
	v_add_co_u32_e32 v48, vcc, s28, v52
	v_cvt_pk_bf16_f32 v54, v49, s0
	s_nop 0
	v_addc_co_u32_e32 v49, vcc, 0, v53, vcc
	global_store_short v[48:49], v54, off
	v_add_co_u32_e32 v48, vcc, 0x4000, v52
	v_cvt_pk_bf16_f32 v50, v50, s0
	s_nop 0
	v_addc_co_u32_e32 v49, vcc, 0, v53, vcc
	global_store_short v[48:49], v50, off
	v_add_co_u32_e32 v48, vcc, 0x6000, v52
	v_cvt_pk_bf16_f32 v50, v51, s0
	s_nop 0
	v_addc_co_u32_e32 v49, vcc, 0, v53, vcc
	global_store_short v[48:49], v50, off

.LBB0_1279:
	s_andn2_saveexec_b64 s[20:21], s[20:21]
	s_cbranch_execz .LBB0_1289
	v_cvt_pk_bf16_f32 v52, v48, v49
	v_cvt_pk_bf16_f32 v53, v50, v51
	s_and_saveexec_b64 s[26:27], s[10:11]
	s_xor_b64 s[26:27], exec, s[26:27]
	s_cbranch_execz .LBB0_1286
	v_add_u32_e32 v130, 0xfffffd10, v132
	s_and_saveexec_b64 s[28:29], s[22:23]
	s_xor_b64 s[28:29], exec, s[28:29]
	s_cbranch_execz .LBB0_1283
	v_lshl_add_u64 v[54:55], s[56:57], 0, v[76:77]
	v_lshl_add_u64 v[54:55], v[130:131], 1, v[54:55]
	global_store_dwordx2 v[54:55], v[52:53], off
	v_lshl_add_u64 v[52:53], s[72:73], 0, v[56:57]
	v_lshl_add_u64 v[52:53], v[130:131], 2, v[52:53]
	global_store_dwordx4 v[52:53], v[48:51], off
.LBB0_1283:
	s_andn2_saveexec_b64 s[28:29], s[28:29]
	s_cbranch_execz .LBB0_1285
	v_lshl_add_u64 v[54:55], v[62:63], 1, s[44:45]
	v_lshl_add_u64 v[54:55], v[130:131], 1, v[54:55]
	global_store_dwordx2 v[54:55], v[52:53], off
	v_lshl_add_u64 v[52:53], v[62:63], 2, s[74:75]
	v_lshl_add_u64 v[52:53], v[130:131], 2, v[52:53]
	global_store_dwordx4 v[52:53], v[48:51], off

.LBB0_1286:
	s_andn2_saveexec_b64 s[26:27], s[26:27]
	s_cbranch_execz .LBB0_1288
	v_lshl_add_u64 v[48:49], s[54:55], 0, v[60:61]
	v_ashrrev_i32_e32 v133, 31, v132
	v_lshl_add_u64 v[48:49], v[132:133], 1, v[48:49]
	global_store_dwordx2 v[48:49], v[52:53], off offset:32

.LBB0_1289:
	s_or_b64 exec, exec, s[20:21]
	v_add_u32_e32 v54, 0xa0, v134
	v_ashrrev_i32_e32 v55, 31, v54
	v_add_u32_e32 v48, 0xffff80a0, v134
	v_lshlrev_b32_e32 v50, 1, v54
	v_and_b32_e32 v51, 35, v54
	v_lshlrev_b64 v[52:53], 11, v[54:55]
	v_lshrrev_b32_e32 v55, 6, v48
	v_mad_u64_u32 v[48:49], s[28:29], v48, s63, 0
	v_and_or_b32 v96, v50, 24, v51
	v_mad_i64_i32 v[50:51], s[28:29], v54, s63, 0
	v_ashrrev_i32_e32 v72, 12, v54
	s_movk_i32 s28, 0xfe3
	v_cmp_lt_i32_e64 s[26:27], s2, v54
	v_cmp_gt_i32_e64 s[20:21], s61, v54
	v_mul_lo_u32 v100, v55, 6
	v_mul_i32_i24_e32 v97, 6, v72
	v_and_or_b32 v95, v54, s28, v162
	s_and_saveexec_b64 s[28:29], s[12:13]
	s_xor_b64 s[28:29], exec, s[28:29]
	s_cbranch_execz .LBB0_1298
	s_cmpk_lt_u32 s84, 0x900
	s_mov_b64 s[86:87], -1
	s_cbranch_scc1 .LBB0_1292
	v_lshl_add_u64 v[78:79], s[54:55], 0, v[52:53]
	v_mov_b32_e32 v133, v131
	v_lshl_add_u64 v[78:79], v[132:133], 1, v[78:79]
	v_add_co_u32_e32 v78, vcc, 0xfffff400, v78
	v_cvt_pk_bf16_f32 v72, v44, v45
	v_cvt_pk_bf16_f32 v73, v46, v47
	v_addc_co_u32_e32 v79, vcc, -1, v79, vcc
	s_mov_b64 s[86:87], 0
	global_store_dwordx2 v[78:79], v[72:73], off
.LBB0_1292:
	s_andn2_b64 vcc, exec, s[86:87]
	s_cbranch_vccnz .LBB0_1298
	v_add_u32_e32 v130, 0xfffffa00, v132
	v_lshrrev_b32_e32 v73, 7, v130
	v_and_b32_e32 v72, 0x6c, v132
	s_and_saveexec_b64 s[66:67], s[26:27]
	s_xor_b64 s[86:87], exec, s[66:67]
	s_cbranch_execz .LBB0_1295
	v_lshl_add_u64 v[78:79], s[68:69], 0, v[48:49]
	v_lshl_add_u64 v[78:79], v[130:131], 2, v[78:79]
	v_add_u32_e32 v130, v73, v100
	global_store_dwordx4 v[78:79], v[44:47], off
	v_lshlrev_b64 v[78:79], 7, v[130:131]
	v_or_b32_e32 v78, v78, v72
	v_mov_b64_e32 v[72:73], s[48:49]
	v_mad_u64_u32 v[72:73], s[66:67], v78, s51, v[72:73]
	v_mad_u32_u24 v73, v79, s51, v73
	v_lshlrev_b32_e32 v130, 1, v96
	v_cvt_pk_bf16_f32 v44, v44, s0
	v_lshl_add_u64 v[72:73], v[72:73], 0, v[130:131]
	global_store_short v[72:73], v44, off offset:2048
	v_add_co_u32_e32 v44, vcc, 0x1000, v72
	v_cvt_pk_bf16_f32 v78, v45, s0
	s_nop 0
	v_addc_co_u32_e32 v45, vcc, 0, v73, vcc
	v_cvt_pk_bf16_f32 v46, v46, s0
	global_store_short v[44:45], v78, off offset:128
	global_store_short v[44:45], v46, off offset:2304
	v_add_co_u32_e32 v44, vcc, 0x2000, v72
	v_cvt_pk_bf16_f32 v46, v47, s0
	s_nop 0
	v_addc_co_u32_e32 v45, vcc, 0, v73, vcc
	global_store_short v[44:45], v46, off offset:384
.LBB0_1295:
	s_andn2_saveexec_b64 s[86:87], s[86:87]
	s_cbranch_execz .LBB0_1297
	v_lshl_add_u64 v[78:79], s[70:71], 0, v[50:51]
	v_lshl_add_u64 v[78:79], v[130:131], 2, v[78:79]
	global_store_dwordx4 v[78:79], v[44:47], off
	v_add_u32_e32 v78, v73, v97
	v_ashrrev_i32_e32 v79, 31, v78
	v_lshlrev_b32_e32 v130, 1, v95
	v_lshl_add_u64 v[80:81], s[46:47], 0, v[130:131]
	v_lshlrev_b64 v[78:79], 20, v[78:79]
	v_lshlrev_b32_e32 v130, 13, v72
	v_lshl_add_u64 v[72:73], v[80:81], 0, v[78:79]
	v_cvt_pk_bf16_f32 v44, v44, s0
	v_lshl_add_u64 v[72:73], v[72:73], 0, v[130:131]
	s_movk_i32 s66, 0x2000
	global_store_short v[72:73], v44, off
	v_add_co_u32_e32 v44, vcc, s66, v72
	v_cvt_pk_bf16_f32 v78, v45, s0
	s_nop 0
	v_addc_co_u32_e32 v45, vcc, 0, v73, vcc
	global_store_short v[44:45], v78, off
	v_add_co_u32_e32 v44, vcc, 0x4000, v72
	v_cvt_pk_bf16_f32 v46, v46, s0
	s_nop 0
	v_addc_co_u32_e32 v45, vcc, 0, v73, vcc
	global_store_short v[44:45], v46, off
	v_add_co_u32_e32 v44, vcc, 0x6000, v72
	v_cvt_pk_bf16_f32 v46, v47, s0
	s_nop 0
	v_addc_co_u32_e32 v45, vcc, 0, v73, vcc
	global_store_short v[44:45], v46, off

.LBB0_1298:
	s_or_saveexec_b64 s[28:29], s[28:29]
	v_mul_lo_u32 v55, v55, s88
	v_and_b32_e32 v72, 0xfef, v54
	v_or_b32_e32 v55, v55, v166
	v_cndmask_b32_e64 v72, v169, v72, s[20:21]
	v_add_u32_e32 v55, 0x400, v55
	v_lshlrev_b32_e32 v102, 3, v72
	v_mad_u64_u32 v[78:79], s[20:21], v55, s89, 0
	v_mad_i64_i32 v[54:55], s[20:21], v54, s62, 0
	s_xor_b64 exec, exec, s[28:29]
	s_cbranch_execz .LBB0_1310
	v_cmp_eq_u32_e32 vcc, 0, v160
	s_and_saveexec_b64 s[20:21], vcc
	s_cbranch_execz .LBB0_1301
	v_cmp_lt_i32_e32 vcc, v158, v156
	v_lshlrev_b32_e32 v130, 3, v102
	s_nop 0
	v_cndmask_b32_e32 v72, v155, v158, vcc
	v_lshlrev_b32_e32 v80, 2, v72
	ds_bpermute_b32 v72, v80, v44
	ds_bpermute_b32 v73, v80, v45
	ds_bpermute_b32 v106, v80, v46
	ds_bpermute_b32 v107, v80, v47
	v_lshl_add_u64 v[80:81], s[52:53], 0, v[130:131]
	v_lshlrev_b32_e32 v130, 3, v135
	v_lshl_add_u64 v[108:109], v[80:81], 0, v[130:131]
	global_load_dwordx4 v[80:83], v[108:109], off
	s_waitcnt vmcnt(0) lgkmcnt(0)
	v_mov_b32_e32 v111, v82
	v_mov_b32_e32 v82, v81
	v_mov_b32_e32 v110, v80
	v_pk_mul_f32 v[72:73], v[82:83], v[72:73]
	global_load_dwordx4 v[80:83], v[108:109], off offset:16
	v_cndmask_b32_e64 v73, v73, -v73, s[30:31]
	v_cndmask_b32_e64 v72, v72, -v72, s[30:31]
	v_pk_fma_f32 v[44:45], v[44:45], v[110:111], v[72:73]
	s_waitcnt vmcnt(0) lgkmcnt(0)
	v_mov_b32_e32 v73, v82
	v_mov_b32_e32 v82, v81
	v_mov_b32_e32 v72, v80
	v_pk_mul_f32 v[80:81], v[82:83], v[106:107]
	s_nop 0
	v_cndmask_b32_e64 v81, v81, -v81, s[30:31]
	v_cndmask_b32_e64 v80, v80, -v80, s[30:31]
	v_pk_fma_f32 v[46:47], v[46:47], v[72:73], v[80:81]
.LBB0_1301:
	s_or_b64 exec, exec, s[20:21]
	v_cvt_pk_bf16_f32 v72, v44, v45
	v_cvt_pk_bf16_f32 v73, v46, v47
	s_and_saveexec_b64 s[20:21], s[4:5]
	s_xor_b64 s[20:21], exec, s[20:21]
	s_cbranch_execz .LBB0_1307
	v_add_u32_e32 v130, 0xfffffd00, v132
	s_and_saveexec_b64 s[66:67], s[26:27]
	s_xor_b64 s[86:87], exec, s[66:67]
	s_cbranch_execz .LBB0_1304
	v_lshl_add_u64 v[80:81], s[56:57], 0, v[78:79]
	v_lshl_add_u64 v[80:81], v[130:131], 1, v[80:81]
	global_store_dwordx2 v[80:81], v[72:73], off
	v_lshl_add_u64 v[72:73], s[72:73], 0, v[48:49]
	v_lshl_add_u64 v[72:73], v[130:131], 2, v[72:73]
	global_store_dwordx4 v[72:73], v[44:47], off
.LBB0_1304:
	s_andn2_saveexec_b64 s[86:87], s[86:87]
	s_cbranch_execz .LBB0_1306
	v_lshl_add_u64 v[80:81], v[54:55], 1, s[44:45]
	v_lshl_add_u64 v[80:81], v[130:131], 1, v[80:81]
	global_store_dwordx2 v[80:81], v[72:73], off
	v_lshl_add_u64 v[72:73], v[54:55], 2, s[74:75]
	v_lshl_add_u64 v[72:73], v[130:131], 2, v[72:73]
	global_store_dwordx4 v[72:73], v[44:47], off

.LBB0_1307:
	s_andn2_saveexec_b64 s[20:21], s[20:21]
	s_cbranch_execz .LBB0_1309
	v_lshl_add_u64 v[44:45], s[54:55], 0, v[52:53]
	v_ashrrev_i32_e32 v133, 31, v132
	v_lshl_add_u64 v[44:45], v[132:133], 1, v[44:45]
	global_store_dwordx2 v[44:45], v[72:73], off

.LBB0_1310:
	s_or_b64 exec, exec, s[28:29]
	s_and_saveexec_b64 s[20:21], s[16:17]
	s_xor_b64 s[20:21], exec, s[20:21]
	s_cbranch_execz .LBB0_1319
	s_cmpk_lt_u32 s84, 0x900
	s_mov_b64 s[28:29], -1
	s_cbranch_scc1 .LBB0_1313
	v_lshl_add_u64 v[46:47], s[54:55], 0, v[52:53]
	v_mov_b32_e32 v133, v131
	v_lshl_add_u64 v[46:47], v[132:133], 1, v[46:47]
	v_add_co_u32_e32 v46, vcc, 0xfffff420, v46
	v_cvt_pk_bf16_f32 v44, v40, v41
	v_cvt_pk_bf16_f32 v45, v42, v43
	v_addc_co_u32_e32 v47, vcc, -1, v47, vcc
	s_mov_b64 s[28:29], 0
	global_store_dwordx2 v[46:47], v[44:45], off
.LBB0_1313:
	s_andn2_b64 vcc, exec, s[28:29]
	s_cbranch_vccnz .LBB0_1319
	v_add_u32_e32 v130, 0xfffffa10, v132
	v_lshrrev_b32_e32 v45, 7, v130
	v_and_b32_e32 v44, 0x7c, v161
	s_and_saveexec_b64 s[28:29], s[26:27]
	s_xor_b64 s[28:29], exec, s[28:29]
	s_cbranch_execz .LBB0_1316
	v_lshl_add_u64 v[46:47], s[68:69], 0, v[48:49]
	v_lshl_add_u64 v[46:47], v[130:131], 2, v[46:47]
	v_add_u32_e32 v130, v45, v100
	global_store_dwordx4 v[46:47], v[40:43], off
	v_lshlrev_b64 v[46:47], 7, v[130:131]
	v_or_b32_e32 v46, v46, v44
	v_mov_b64_e32 v[44:45], s[48:49]
	v_mad_u64_u32 v[44:45], s[66:67], v46, s51, v[44:45]
	v_mad_u32_u24 v45, v47, s51, v45
	v_lshlrev_b32_e32 v130, 1, v96
	v_cvt_pk_bf16_f32 v40, v40, s0
	v_lshl_add_u64 v[44:45], v[44:45], 0, v[130:131]
	global_store_short v[44:45], v40, off offset:2048
	v_add_co_u32_e32 v40, vcc, 0x1000, v44
	v_cvt_pk_bf16_f32 v46, v41, s0
	s_nop 0
	v_addc_co_u32_e32 v41, vcc, 0, v45, vcc
	v_cvt_pk_bf16_f32 v42, v42, s0
	global_store_short v[40:41], v46, off offset:128
	global_store_short v[40:41], v42, off offset:2304
	v_add_co_u32_e32 v40, vcc, 0x2000, v44
	v_cvt_pk_bf16_f32 v42, v43, s0
	s_nop 0
	v_addc_co_u32_e32 v41, vcc, 0, v45, vcc
	global_store_short v[40:41], v42, off offset:384
.LBB0_1316:
	s_andn2_saveexec_b64 s[28:29], s[28:29]
	s_cbranch_execz .LBB0_1318
	v_lshl_add_u64 v[46:47], s[70:71], 0, v[50:51]
	v_lshl_add_u64 v[46:47], v[130:131], 2, v[46:47]
	global_store_dwordx4 v[46:47], v[40:43], off
	v_add_u32_e32 v46, v45, v97
	v_ashrrev_i32_e32 v47, 31, v46
	v_lshlrev_b32_e32 v130, 1, v95
	v_lshl_add_u64 v[72:73], s[46:47], 0, v[130:131]
	v_lshlrev_b64 v[46:47], 20, v[46:47]
	v_lshlrev_b32_e32 v130, 13, v44
	v_lshl_add_u64 v[44:45], v[72:73], 0, v[46:47]
	v_cvt_pk_bf16_f32 v40, v40, s0
	v_lshl_add_u64 v[44:45], v[44:45], 0, v[130:131]
	s_movk_i32 s66, 0x2000
	global_store_short v[44:45], v40, off
	v_add_co_u32_e32 v40, vcc, s66, v44
	v_cvt_pk_bf16_f32 v46, v41, s0
	s_nop 0
	v_addc_co_u32_e32 v41, vcc, 0, v45, vcc
	global_store_short v[40:41], v46, off
	v_add_co_u32_e32 v40, vcc, 0x4000, v44
	v_cvt_pk_bf16_f32 v42, v42, s0
	s_nop 0
	v_addc_co_u32_e32 v41, vcc, 0, v45, vcc
	global_store_short v[40:41], v42, off
	v_add_co_u32_e32 v40, vcc, 0x6000, v44
	v_cvt_pk_bf16_f32 v42, v43, s0
	s_nop 0
	v_addc_co_u32_e32 v41, vcc, 0, v45, vcc
	global_store_short v[40:41], v42, off

.LBB0_1319:
	s_andn2_saveexec_b64 s[20:21], s[20:21]
	s_cbranch_execz .LBB0_1329
	v_cvt_pk_bf16_f32 v44, v40, v41
	v_cvt_pk_bf16_f32 v45, v42, v43
	s_and_saveexec_b64 s[28:29], s[10:11]
	s_xor_b64 s[28:29], exec, s[28:29]
	s_cbranch_execz .LBB0_1326
	v_add_u32_e32 v130, 0xfffffd10, v132
	s_and_saveexec_b64 s[66:67], s[26:27]
	s_xor_b64 s[86:87], exec, s[66:67]
	s_cbranch_execz .LBB0_1323
	v_lshl_add_u64 v[46:47], s[56:57], 0, v[78:79]
	v_lshl_add_u64 v[46:47], v[130:131], 1, v[46:47]
	global_store_dwordx2 v[46:47], v[44:45], off
	v_lshl_add_u64 v[44:45], s[72:73], 0, v[48:49]
	v_lshl_add_u64 v[44:45], v[130:131], 2, v[44:45]
	global_store_dwordx4 v[44:45], v[40:43], off
.LBB0_1323:
	s_andn2_saveexec_b64 s[86:87], s[86:87]
	s_cbranch_execz .LBB0_1325
	v_lshl_add_u64 v[46:47], v[54:55], 1, s[44:45]
	v_lshl_add_u64 v[46:47], v[130:131], 1, v[46:47]
	global_store_dwordx2 v[46:47], v[44:45], off
	v_lshl_add_u64 v[44:45], v[54:55], 2, s[74:75]
	v_lshl_add_u64 v[44:45], v[130:131], 2, v[44:45]
	global_store_dwordx4 v[44:45], v[40:43], off

.LBB0_1326:
	s_andn2_saveexec_b64 s[28:29], s[28:29]
	s_cbranch_execz .LBB0_1328
	v_lshl_add_u64 v[40:41], s[54:55], 0, v[52:53]
	v_ashrrev_i32_e32 v133, 31, v132
	v_lshl_add_u64 v[40:41], v[132:133], 1, v[40:41]
	global_store_dwordx2 v[40:41], v[44:45], off offset:32

.LBB0_1329:
	s_or_b64 exec, exec, s[20:21]
	v_add_u32_e32 v46, 0xb0, v134
	v_lshlrev_b32_e32 v44, 1, v46
	v_ashrrev_i32_e32 v47, 31, v46
	v_add_u32_e32 v40, 0xffff80b0, v134
	v_and_b32_e32 v44, 24, v44
	v_ashrrev_i32_e32 v72, 12, v46
	v_lshlrev_b64 v[42:43], 11, v[46:47]
	v_lshrrev_b32_e32 v47, 6, v40
	v_and_or_b32 v84, v46, 35, v44
	v_mul_i32_i24_e32 v86, 6, v72
	v_and_b32_e32 v72, 0xfe3, v46
	v_cmp_lt_i32_e64 s[20:21], s2, v46
	v_cmp_gt_i32_e64 s[28:29], s61, v46
	v_mad_u64_u32 v[40:41], s[66:67], v40, s63, 0
	v_mul_lo_u32 v89, v47, 6
	v_or_b32_e32 v83, 4, v84
	v_mad_i64_i32 v[44:45], s[66:67], v46, s63, 0
	v_or3_b32 v82, v162, v72, 4
	s_and_saveexec_b64 s[66:67], s[12:13]
	s_xor_b64 s[12:13], exec, s[66:67]
	s_cbranch_execz .LBB0_1338
	s_cmpk_lt_u32 s84, 0x900
	s_mov_b64 s[86:87], -1
	s_cbranch_scc1 .LBB0_1332
	v_lshl_add_u64 v[80:81], s[54:55], 0, v[42:43]
	v_mov_b32_e32 v133, v131
	v_lshl_add_u64 v[80:81], v[132:133], 1, v[80:81]
	v_add_co_u32_e32 v80, vcc, 0xfffff400, v80
	v_cvt_pk_bf16_f32 v72, v36, v37
	v_cvt_pk_bf16_f32 v73, v38, v39
	v_addc_co_u32_e32 v81, vcc, -1, v81, vcc
	s_mov_b64 s[86:87], 0
	global_store_dwordx2 v[80:81], v[72:73], off
.LBB0_1332:
	s_andn2_b64 vcc, exec, s[86:87]
	s_cbranch_vccnz .LBB0_1338
	v_add_u32_e32 v130, 0xfffffa00, v132
	v_lshrrev_b32_e32 v73, 7, v130
	v_and_b32_e32 v72, 0x6c, v132
	s_and_saveexec_b64 s[66:67], s[20:21]
	s_xor_b64 s[86:87], exec, s[66:67]
	s_cbranch_execz .LBB0_1335
	v_lshl_add_u64 v[80:81], s[68:69], 0, v[40:41]
	v_lshl_add_u64 v[80:81], v[130:131], 2, v[80:81]
	v_add_u32_e32 v130, v73, v89
	global_store_dwordx4 v[80:81], v[36:39], off
	v_lshlrev_b64 v[80:81], 7, v[130:131]
	v_or_b32_e32 v80, v80, v72
	v_mov_b64_e32 v[72:73], s[48:49]
	v_mad_u64_u32 v[72:73], s[66:67], v80, s51, v[72:73]
	v_mad_u32_u24 v73, v81, s51, v73
	v_lshlrev_b32_e32 v130, 1, v84
	v_cvt_pk_bf16_f32 v36, v36, s0
	v_lshl_add_u64 v[80:81], v[72:73], 0, v[130:131]
	v_lshlrev_b32_e32 v130, 1, v83
	global_store_short v[80:81], v36, off offset:2056
	v_cvt_pk_bf16_f32 v80, v37, s0
	v_lshl_add_u64 v[36:37], v[72:73], 0, v[130:131]
	v_add_co_u32_e32 v72, vcc, 0x1000, v36
	v_cvt_pk_bf16_f32 v38, v38, s0
	s_nop 0
	v_addc_co_u32_e32 v73, vcc, 0, v37, vcc
	v_add_co_u32_e32 v36, vcc, 0x2000, v36
	global_store_short v[72:73], v38, off offset:2304
	v_cvt_pk_bf16_f32 v38, v39, s0
	v_addc_co_u32_e32 v37, vcc, 0, v37, vcc
	global_store_short v[72:73], v80, off offset:128
	global_store_short v[36:37], v38, off offset:384
.LBB0_1335:
	s_andn2_saveexec_b64 s[86:87], s[86:87]
	s_cbranch_execz .LBB0_1337
	v_lshl_add_u64 v[80:81], s[70:71], 0, v[44:45]
	v_lshl_add_u64 v[80:81], v[130:131], 2, v[80:81]
	global_store_dwordx4 v[80:81], v[36:39], off
	v_add_u32_e32 v80, v73, v86
	v_ashrrev_i32_e32 v81, 31, v80
	v_lshlrev_b64 v[80:81], 20, v[80:81]
	v_lshlrev_b32_e32 v130, 13, v72
	v_lshl_add_u64 v[72:73], s[46:47], 0, v[80:81]
	v_lshl_add_u64 v[72:73], v[72:73], 0, v[130:131]
	v_lshlrev_b32_e32 v130, 1, v82
	v_cvt_pk_bf16_f32 v36, v36, s0
	v_lshl_add_u64 v[72:73], v[72:73], 0, v[130:131]
	s_movk_i32 s66, 0x2000
	global_store_short v[72:73], v36, off
	v_add_co_u32_e32 v36, vcc, s66, v72
	v_cvt_pk_bf16_f32 v80, v37, s0
	s_nop 0
	v_addc_co_u32_e32 v37, vcc, 0, v73, vcc
	global_store_short v[36:37], v80, off
	v_add_co_u32_e32 v36, vcc, 0x4000, v72
	v_cvt_pk_bf16_f32 v38, v38, s0
	s_nop 0
	v_addc_co_u32_e32 v37, vcc, 0, v73, vcc
	global_store_short v[36:37], v38, off
	v_add_co_u32_e32 v36, vcc, 0x6000, v72
	v_cvt_pk_bf16_f32 v38, v39, s0
	s_nop 0
	v_addc_co_u32_e32 v37, vcc, 0, v73, vcc
	global_store_short v[36:37], v38, off

.LBB0_1338:
	s_or_saveexec_b64 s[12:13], s[12:13]
	v_mul_lo_u32 v47, v47, s88
	v_and_b32_e32 v72, 0xfff, v46
	v_or_b32_e32 v47, v47, v167
	v_cndmask_b32_e64 v72, v170, v72, s[28:29]
	v_add_u32_e32 v47, 0x400, v47
	v_lshlrev_b32_e32 v103, 3, v72
	v_mad_u64_u32 v[72:73], s[28:29], v47, s89, 0
	v_mad_i64_i32 v[46:47], s[28:29], v46, s62, 0
	s_xor_b64 exec, exec, s[12:13]
	s_cbranch_execz .LBB0_1350
	v_cmp_eq_u32_e32 vcc, 0, v160
	s_and_saveexec_b64 s[28:29], vcc
	s_cbranch_execz .LBB0_1341
	v_lshlrev_b32_e32 v130, 3, v103
	v_lshl_add_u64 v[106:107], s[52:53], 0, v[130:131]
	v_lshlrev_b32_e32 v130, 3, v135
	v_lshl_add_u64 v[112:113], v[106:107], 0, v[130:131]
	global_load_dwordx4 v[106:109], v[112:113], off
	v_cmp_lt_i32_e32 vcc, v158, v156
	s_waitcnt vmcnt(0) lgkmcnt(0)
	v_mov_b32_e32 v115, v108
	v_cndmask_b32_e32 v80, v155, v158, vcc
	v_lshlrev_b32_e32 v105, 2, v80
	ds_bpermute_b32 v80, v105, v36
	ds_bpermute_b32 v81, v105, v37
	v_mov_b32_e32 v108, v107
	v_mov_b32_e32 v114, v106
	ds_bpermute_b32 v110, v105, v38
	ds_bpermute_b32 v111, v105, v39
	s_waitcnt lgkmcnt(2)
	v_pk_mul_f32 v[80:81], v[108:109], v[80:81]
	global_load_dwordx4 v[106:109], v[112:113], off offset:16
	v_cndmask_b32_e64 v81, v81, -v81, s[30:31]
	v_cndmask_b32_e64 v80, v80, -v80, s[30:31]
	v_pk_fma_f32 v[36:37], v[36:37], v[114:115], v[80:81]
	s_waitcnt vmcnt(0) lgkmcnt(0)
	v_mov_b32_e32 v81, v108
	v_mov_b32_e32 v108, v107
	v_mov_b32_e32 v80, v106
	v_pk_mul_f32 v[106:107], v[108:109], v[110:111]
	s_nop 0
	v_cndmask_b32_e64 v107, v107, -v107, s[30:31]
	v_cndmask_b32_e64 v106, v106, -v106, s[30:31]
	v_pk_fma_f32 v[38:39], v[38:39], v[80:81], v[106:107]
.LBB0_1341:
	s_or_b64 exec, exec, s[28:29]
	v_cvt_pk_bf16_f32 v80, v36, v37
	v_cvt_pk_bf16_f32 v81, v38, v39
	s_and_saveexec_b64 s[28:29], s[4:5]
	s_xor_b64 s[4:5], exec, s[28:29]
	s_cbranch_execz .LBB0_1347
	v_add_u32_e32 v130, 0xfffffd00, v132
	s_and_saveexec_b64 s[28:29], s[20:21]
	s_xor_b64 s[28:29], exec, s[28:29]
	s_cbranch_execz .LBB0_1344
	v_lshl_add_u64 v[106:107], s[56:57], 0, v[72:73]
	v_lshl_add_u64 v[106:107], v[130:131], 1, v[106:107]
	global_store_dwordx2 v[106:107], v[80:81], off
	v_lshl_add_u64 v[80:81], s[72:73], 0, v[40:41]
	v_lshl_add_u64 v[80:81], v[130:131], 2, v[80:81]
	global_store_dwordx4 v[80:81], v[36:39], off
.LBB0_1344:
	s_andn2_saveexec_b64 s[28:29], s[28:29]
	s_cbranch_execz .LBB0_1346
	v_lshl_add_u64 v[106:107], v[46:47], 1, s[44:45]
	v_lshl_add_u64 v[106:107], v[130:131], 1, v[106:107]
	global_store_dwordx2 v[106:107], v[80:81], off
	v_lshl_add_u64 v[80:81], v[46:47], 2, s[74:75]
	v_lshl_add_u64 v[80:81], v[130:131], 2, v[80:81]
	global_store_dwordx4 v[80:81], v[36:39], off

.LBB0_1347:
	s_andn2_saveexec_b64 s[4:5], s[4:5]
	s_cbranch_execz .LBB0_1349
	v_lshl_add_u64 v[36:37], s[54:55], 0, v[42:43]
	v_ashrrev_i32_e32 v133, 31, v132
	v_lshl_add_u64 v[36:37], v[132:133], 1, v[36:37]
	global_store_dwordx2 v[36:37], v[80:81], off

.LBB0_1350:
	s_or_b64 exec, exec, s[12:13]
	s_and_saveexec_b64 s[4:5], s[16:17]
	s_xor_b64 s[4:5], exec, s[4:5]
	s_cbranch_execz .LBB0_1359
	s_cmpk_lt_u32 s84, 0x900
	s_mov_b64 s[12:13], -1
	s_cbranch_scc1 .LBB0_1353
	v_lshl_add_u64 v[38:39], s[54:55], 0, v[42:43]
	v_mov_b32_e32 v133, v131
	v_lshl_add_u64 v[38:39], v[132:133], 1, v[38:39]
	v_add_co_u32_e32 v38, vcc, 0xfffff420, v38
	v_cvt_pk_bf16_f32 v36, v32, v33
	v_cvt_pk_bf16_f32 v37, v34, v35
	v_addc_co_u32_e32 v39, vcc, -1, v39, vcc
	s_mov_b64 s[12:13], 0
	global_store_dwordx2 v[38:39], v[36:37], off
.LBB0_1353:
	s_andn2_b64 vcc, exec, s[12:13]
	s_cbranch_vccnz .LBB0_1359
	v_add_u32_e32 v130, 0xfffffa10, v132
	v_lshrrev_b32_e32 v37, 7, v130
	v_and_b32_e32 v36, 0x7c, v161
	s_and_saveexec_b64 s[12:13], s[20:21]
	s_xor_b64 s[12:13], exec, s[12:13]
	s_cbranch_execz .LBB0_1356
	v_lshl_add_u64 v[38:39], s[68:69], 0, v[40:41]
	v_lshl_add_u64 v[38:39], v[130:131], 2, v[38:39]
	v_add_u32_e32 v130, v37, v89
	global_store_dwordx4 v[38:39], v[32:35], off
	v_lshlrev_b64 v[38:39], 7, v[130:131]
	v_or_b32_e32 v38, v38, v36
	v_mov_b64_e32 v[36:37], s[48:49]
	v_mad_u64_u32 v[36:37], s[16:17], v38, s51, v[36:37]
	v_mad_u32_u24 v37, v39, s51, v37
	v_lshlrev_b32_e32 v130, 1, v84
	v_cvt_pk_bf16_f32 v32, v32, s0
	v_lshl_add_u64 v[38:39], v[36:37], 0, v[130:131]
	v_lshlrev_b32_e32 v130, 1, v83
	global_store_short v[38:39], v32, off offset:2056
	v_cvt_pk_bf16_f32 v38, v33, s0
	v_lshl_add_u64 v[32:33], v[36:37], 0, v[130:131]
	v_add_co_u32_e32 v36, vcc, 0x1000, v32
	v_cvt_pk_bf16_f32 v34, v34, s0
	s_nop 0
	v_addc_co_u32_e32 v37, vcc, 0, v33, vcc
	v_add_co_u32_e32 v32, vcc, 0x2000, v32
	global_store_short v[36:37], v34, off offset:2304
	v_cvt_pk_bf16_f32 v34, v35, s0
	v_addc_co_u32_e32 v33, vcc, 0, v33, vcc
	global_store_short v[36:37], v38, off offset:128
	global_store_short v[32:33], v34, off offset:384
.LBB0_1356:
	s_andn2_saveexec_b64 s[12:13], s[12:13]
	s_cbranch_execz .LBB0_1358
	v_lshl_add_u64 v[38:39], s[70:71], 0, v[44:45]
	v_lshl_add_u64 v[38:39], v[130:131], 2, v[38:39]
	global_store_dwordx4 v[38:39], v[32:35], off
	v_add_u32_e32 v38, v37, v86
	v_ashrrev_i32_e32 v39, 31, v38
	v_lshlrev_b64 v[38:39], 20, v[38:39]
	v_lshlrev_b32_e32 v130, 13, v36
	v_lshl_add_u64 v[36:37], s[46:47], 0, v[38:39]
	v_lshl_add_u64 v[36:37], v[36:37], 0, v[130:131]
	v_lshlrev_b32_e32 v130, 1, v82
	v_cvt_pk_bf16_f32 v32, v32, s0
	v_lshl_add_u64 v[36:37], v[36:37], 0, v[130:131]
	s_movk_i32 s16, 0x2000
	global_store_short v[36:37], v32, off
	v_add_co_u32_e32 v32, vcc, s16, v36
	v_cvt_pk_bf16_f32 v38, v33, s0
	s_nop 0
	v_addc_co_u32_e32 v33, vcc, 0, v37, vcc
	global_store_short v[32:33], v38, off
	v_add_co_u32_e32 v32, vcc, 0x4000, v36
	v_cvt_pk_bf16_f32 v34, v34, s0
	s_nop 0
	v_addc_co_u32_e32 v33, vcc, 0, v37, vcc
	global_store_short v[32:33], v34, off
	v_add_co_u32_e32 v32, vcc, 0x6000, v36
	v_cvt_pk_bf16_f32 v34, v35, s0
	s_nop 0
	v_addc_co_u32_e32 v33, vcc, 0, v37, vcc
	global_store_short v[32:33], v34, off

.LBB0_1359:
	s_andn2_saveexec_b64 s[4:5], s[4:5]
	s_cbranch_execz .LBB0_1369
	v_cvt_pk_bf16_f32 v36, v32, v33
	v_cvt_pk_bf16_f32 v37, v34, v35
	s_and_saveexec_b64 s[12:13], s[10:11]
	s_xor_b64 s[10:11], exec, s[12:13]
	s_cbranch_execz .LBB0_1366
	v_add_u32_e32 v130, 0xfffffd10, v132
	s_and_saveexec_b64 s[12:13], s[20:21]
	s_xor_b64 s[12:13], exec, s[12:13]
	s_cbranch_execz .LBB0_1363
	v_lshl_add_u64 v[38:39], s[56:57], 0, v[72:73]
	v_lshl_add_u64 v[38:39], v[130:131], 1, v[38:39]
	global_store_dwordx2 v[38:39], v[36:37], off
	v_lshl_add_u64 v[36:37], s[72:73], 0, v[40:41]
	v_lshl_add_u64 v[36:37], v[130:131], 2, v[36:37]
	global_store_dwordx4 v[36:37], v[32:35], off
.LBB0_1363:
	s_andn2_saveexec_b64 s[12:13], s[12:13]
	s_cbranch_execz .LBB0_1365
	v_lshl_add_u64 v[38:39], v[46:47], 1, s[44:45]
	v_lshl_add_u64 v[38:39], v[130:131], 1, v[38:39]
	global_store_dwordx2 v[38:39], v[36:37], off
	v_lshl_add_u64 v[36:37], v[46:47], 2, s[74:75]
	v_lshl_add_u64 v[36:37], v[130:131], 2, v[36:37]
	global_store_dwordx4 v[36:37], v[32:35], off

.LBB0_1366:
	s_andn2_saveexec_b64 s[10:11], s[10:11]
	s_cbranch_execz .LBB0_1368
	v_lshl_add_u64 v[32:33], s[54:55], 0, v[42:43]
	v_ashrrev_i32_e32 v133, 31, v132
	v_lshl_add_u64 v[32:33], v[132:133], 1, v[32:33]
	global_store_dwordx2 v[32:33], v[36:37], off offset:32

.LBB0_1369:
	s_or_b64 exec, exec, s[4:5]
	s_and_saveexec_b64 s[4:5], s[18:19]
	s_xor_b64 s[4:5], exec, s[4:5]
	s_cbranch_execz .LBB0_1378
	s_cmpk_lt_u32 s84, 0x900
	s_mov_b64 s[10:11], -1
	s_cbranch_scc1 .LBB0_1372
	v_lshl_add_u64 v[34:35], s[54:55], 0, v[68:69]
	v_mov_b32_e32 v133, v131
	v_lshl_add_u64 v[34:35], v[132:133], 1, v[34:35]
	v_add_co_u32_e32 v34, vcc, 0xfffff500, v34
	v_cvt_pk_bf16_f32 v32, v28, v29
	v_cvt_pk_bf16_f32 v33, v30, v31
	v_addc_co_u32_e32 v35, vcc, -1, v35, vcc
	s_mov_b64 s[10:11], 0
	global_store_dwordx2 v[34:35], v[32:33], off
.LBB0_1372:
	s_andn2_b64 vcc, exec, s[10:11]
	s_cbranch_vccnz .LBB0_1378
	v_add_u32_e32 v130, 0xfffffa80, v132
	v_lshrrev_b32_e32 v33, 7, v130
	v_and_b32_e32 v32, 0x6c, v132
	s_and_saveexec_b64 s[10:11], s[24:25]
	s_xor_b64 s[10:11], exec, s[10:11]
	s_cbranch_execz .LBB0_1375
	v_lshl_add_u64 v[34:35], s[68:69], 0, v[64:65]
	v_lshl_add_u64 v[34:35], v[130:131], 2, v[34:35]
	v_add_u32_e32 v130, v33, v99
	global_store_dwordx4 v[34:35], v[28:31], off
	v_lshlrev_b64 v[34:35], 7, v[130:131]
	v_or_b32_e32 v34, v34, v32
	v_mov_b64_e32 v[32:33], s[48:49]
	v_mad_u64_u32 v[32:33], s[12:13], v34, s51, v[32:33]
	v_mad_u32_u24 v33, v35, s51, v33
	v_lshlrev_b32_e32 v130, 1, v92
	v_cvt_pk_bf16_f32 v28, v28, s0
	v_lshl_add_u64 v[32:33], v[32:33], 0, v[130:131]
	global_store_short v[32:33], v28, off offset:2048
	v_add_co_u32_e32 v28, vcc, 0x1000, v32
	v_cvt_pk_bf16_f32 v34, v29, s0
	s_nop 0
	v_addc_co_u32_e32 v29, vcc, 0, v33, vcc
	v_cvt_pk_bf16_f32 v30, v30, s0
	global_store_short v[28:29], v34, off offset:128
	global_store_short v[28:29], v30, off offset:2304
	v_add_co_u32_e32 v28, vcc, 0x2000, v32
	v_cvt_pk_bf16_f32 v30, v31, s0
	s_nop 0
	v_addc_co_u32_e32 v29, vcc, 0, v33, vcc
	global_store_short v[28:29], v30, off offset:384
.LBB0_1375:
	s_andn2_saveexec_b64 s[10:11], s[10:11]
	s_cbranch_execz .LBB0_1377
	v_lshl_add_u64 v[34:35], s[70:71], 0, v[66:67]
	v_lshl_add_u64 v[34:35], v[130:131], 2, v[34:35]
	global_store_dwordx4 v[34:35], v[28:31], off
	v_add_u32_e32 v34, v33, v93
	v_ashrrev_i32_e32 v35, 31, v34
	v_lshlrev_b32_e32 v130, 1, v91
	v_lshl_add_u64 v[36:37], s[46:47], 0, v[130:131]
	v_lshlrev_b64 v[34:35], 20, v[34:35]
	v_lshlrev_b32_e32 v130, 13, v32
	v_lshl_add_u64 v[32:33], v[36:37], 0, v[34:35]
	v_cvt_pk_bf16_f32 v28, v28, s0
	v_lshl_add_u64 v[32:33], v[32:33], 0, v[130:131]
	s_movk_i32 s12, 0x2000
	global_store_short v[32:33], v28, off
	v_add_co_u32_e32 v28, vcc, s12, v32
	v_cvt_pk_bf16_f32 v34, v29, s0
	s_nop 0
	v_addc_co_u32_e32 v29, vcc, 0, v33, vcc
	global_store_short v[28:29], v34, off
	v_add_co_u32_e32 v28, vcc, 0x4000, v32
	v_cvt_pk_bf16_f32 v30, v30, s0
	s_nop 0
	v_addc_co_u32_e32 v29, vcc, 0, v33, vcc
	global_store_short v[28:29], v30, off
	v_add_co_u32_e32 v28, vcc, 0x6000, v32
	v_cvt_pk_bf16_f32 v30, v31, s0
	s_nop 0
	v_addc_co_u32_e32 v29, vcc, 0, v33, vcc
	global_store_short v[28:29], v30, off

.LBB0_1378:
	s_andn2_saveexec_b64 s[4:5], s[4:5]
	s_cbranch_execz .LBB0_1390
	v_cmp_eq_u32_e32 vcc, 0, v160
	s_and_saveexec_b64 s[10:11], vcc
	s_cbranch_execz .LBB0_1381
	v_cmp_lt_i32_e32 vcc, v158, v156
	v_lshlrev_b32_e32 v130, 3, v101
	s_nop 0
	v_cndmask_b32_e32 v32, v155, v158, vcc
	v_lshlrev_b32_e32 v32, 2, v32
	ds_bpermute_b32 v36, v32, v28
	ds_bpermute_b32 v37, v32, v29
	ds_bpermute_b32 v38, v32, v30
	ds_bpermute_b32 v39, v32, v31
	v_lshl_add_u64 v[32:33], s[52:53], 0, v[130:131]
	v_lshlrev_b32_e32 v130, 3, v135
	v_lshl_add_u64 v[80:81], v[32:33], 0, v[130:131]
	global_load_dwordx4 v[32:35], v[80:81], off
	s_waitcnt vmcnt(0) lgkmcnt(0)
	v_mov_b32_e32 v107, v34
	v_mov_b32_e32 v34, v33
	v_mov_b32_e32 v106, v32
	v_pk_mul_f32 v[32:33], v[34:35], v[36:37]
	s_nop 0
	v_cndmask_b32_e64 v33, v33, -v33, s[30:31]
	v_cndmask_b32_e64 v32, v32, -v32, s[30:31]
	v_pk_fma_f32 v[28:29], v[28:29], v[106:107], v[32:33]
	global_load_dwordx4 v[32:35], v[80:81], off offset:16
	s_waitcnt vmcnt(0) lgkmcnt(0)
	v_mov_b32_e32 v37, v34
	v_mov_b32_e32 v34, v33
	v_mov_b32_e32 v36, v32
	v_pk_mul_f32 v[32:33], v[34:35], v[38:39]
	s_nop 0
	v_cndmask_b32_e64 v33, v33, -v33, s[30:31]
	v_cndmask_b32_e64 v32, v32, -v32, s[30:31]
	v_pk_fma_f32 v[30:31], v[30:31], v[36:37], v[32:33]
.LBB0_1381:
	s_or_b64 exec, exec, s[10:11]
	v_cvt_pk_bf16_f32 v32, v28, v29
	v_cvt_pk_bf16_f32 v33, v30, v31
	s_and_saveexec_b64 s[10:11], s[6:7]
	s_xor_b64 s[10:11], exec, s[10:11]
	s_cbranch_execz .LBB0_1387
	v_add_u32_e32 v130, 0xfffffd80, v132
	s_and_saveexec_b64 s[12:13], s[24:25]
	s_xor_b64 s[12:13], exec, s[12:13]
	s_cbranch_execz .LBB0_1384
	v_lshl_add_u64 v[34:35], s[56:57], 0, v[74:75]
	v_lshl_add_u64 v[34:35], v[130:131], 1, v[34:35]
	global_store_dwordx2 v[34:35], v[32:33], off
	v_lshl_add_u64 v[32:33], s[72:73], 0, v[64:65]
	v_lshl_add_u64 v[32:33], v[130:131], 2, v[32:33]
	global_store_dwordx4 v[32:33], v[28:31], off
.LBB0_1384:
	s_andn2_saveexec_b64 s[12:13], s[12:13]
	s_cbranch_execz .LBB0_1386
	v_lshl_add_u64 v[34:35], v[70:71], 1, s[44:45]
	v_lshl_add_u64 v[34:35], v[130:131], 1, v[34:35]
	global_store_dwordx2 v[34:35], v[32:33], off
	v_lshl_add_u64 v[32:33], v[70:71], 2, s[74:75]
	v_lshl_add_u64 v[32:33], v[130:131], 2, v[32:33]
	global_store_dwordx4 v[32:33], v[28:31], off

.LBB0_1387:
	s_andn2_saveexec_b64 s[10:11], s[10:11]
	s_cbranch_execz .LBB0_1389
	v_lshl_add_u64 v[28:29], s[54:55], 0, v[68:69]
	v_ashrrev_i32_e32 v133, 31, v132
	v_lshl_add_u64 v[28:29], v[132:133], 1, v[28:29]
	global_store_dwordx2 v[28:29], v[32:33], off offset:256

.LBB0_1390:
	s_or_b64 exec, exec, s[4:5]
	s_and_saveexec_b64 s[4:5], s[14:15]
	s_xor_b64 s[4:5], exec, s[4:5]
	s_cbranch_execz .LBB0_1399
	s_cmpk_lt_u32 s84, 0x900
	s_mov_b64 s[10:11], -1
	s_cbranch_scc1 .LBB0_1393
	v_lshl_add_u64 v[30:31], s[54:55], 0, v[68:69]
	v_mov_b32_e32 v133, v131
	v_lshl_add_u64 v[30:31], v[132:133], 1, v[30:31]
	v_add_co_u32_e32 v30, vcc, 0xfffff520, v30
	v_cvt_pk_bf16_f32 v28, v24, v25
	v_cvt_pk_bf16_f32 v29, v26, v27
	v_addc_co_u32_e32 v31, vcc, -1, v31, vcc
	s_mov_b64 s[10:11], 0
	global_store_dwordx2 v[30:31], v[28:29], off
.LBB0_1393:
	s_andn2_b64 vcc, exec, s[10:11]
	s_cbranch_vccnz .LBB0_1399
	v_add_u32_e32 v130, 0xfffffa90, v132
	v_lshrrev_b32_e32 v29, 7, v130
	v_and_b32_e32 v28, 0x7c, v94
	s_and_saveexec_b64 s[10:11], s[24:25]
	s_xor_b64 s[10:11], exec, s[10:11]
	s_cbranch_execz .LBB0_1396
	v_lshl_add_u64 v[30:31], s[68:69], 0, v[64:65]
	v_lshl_add_u64 v[30:31], v[130:131], 2, v[30:31]
	v_add_u32_e32 v130, v29, v99
	global_store_dwordx4 v[30:31], v[24:27], off
	v_lshlrev_b64 v[30:31], 7, v[130:131]
	v_or_b32_e32 v30, v30, v28
	v_mov_b64_e32 v[28:29], s[48:49]
	v_mad_u64_u32 v[28:29], s[12:13], v30, s51, v[28:29]
	v_mad_u32_u24 v29, v31, s51, v29
	v_lshlrev_b32_e32 v130, 1, v92
	v_cvt_pk_bf16_f32 v24, v24, s0
	v_lshl_add_u64 v[28:29], v[28:29], 0, v[130:131]
	global_store_short v[28:29], v24, off offset:2048
	v_add_co_u32_e32 v24, vcc, 0x1000, v28
	v_cvt_pk_bf16_f32 v30, v25, s0
	s_nop 0
	v_addc_co_u32_e32 v25, vcc, 0, v29, vcc
	v_cvt_pk_bf16_f32 v26, v26, s0
	global_store_short v[24:25], v30, off offset:128
	global_store_short v[24:25], v26, off offset:2304
	v_add_co_u32_e32 v24, vcc, 0x2000, v28
	v_cvt_pk_bf16_f32 v26, v27, s0
	s_nop 0
	v_addc_co_u32_e32 v25, vcc, 0, v29, vcc
	global_store_short v[24:25], v26, off offset:384
.LBB0_1396:
	s_andn2_saveexec_b64 s[10:11], s[10:11]
	s_cbranch_execz .LBB0_1398
	v_lshl_add_u64 v[30:31], s[70:71], 0, v[66:67]
	v_lshl_add_u64 v[30:31], v[130:131], 2, v[30:31]
	global_store_dwordx4 v[30:31], v[24:27], off
	v_add_u32_e32 v30, v29, v93
	v_ashrrev_i32_e32 v31, 31, v30
	v_lshlrev_b32_e32 v130, 1, v91
	v_lshl_add_u64 v[32:33], s[46:47], 0, v[130:131]
	v_lshlrev_b64 v[30:31], 20, v[30:31]
	v_lshlrev_b32_e32 v130, 13, v28
	v_lshl_add_u64 v[28:29], v[32:33], 0, v[30:31]
	v_cvt_pk_bf16_f32 v24, v24, s0
	v_lshl_add_u64 v[28:29], v[28:29], 0, v[130:131]
	s_movk_i32 s12, 0x2000
	global_store_short v[28:29], v24, off
	v_add_co_u32_e32 v24, vcc, s12, v28
	v_cvt_pk_bf16_f32 v30, v25, s0
	s_nop 0
	v_addc_co_u32_e32 v25, vcc, 0, v29, vcc
	global_store_short v[24:25], v30, off
	v_add_co_u32_e32 v24, vcc, 0x4000, v28
	v_cvt_pk_bf16_f32 v26, v26, s0
	s_nop 0
	v_addc_co_u32_e32 v25, vcc, 0, v29, vcc
	global_store_short v[24:25], v26, off
	v_add_co_u32_e32 v24, vcc, 0x6000, v28
	v_cvt_pk_bf16_f32 v26, v27, s0
	s_nop 0
	v_addc_co_u32_e32 v25, vcc, 0, v29, vcc
	global_store_short v[24:25], v26, off

.LBB0_1399:
	s_andn2_saveexec_b64 s[4:5], s[4:5]
	s_cbranch_execz .LBB0_1409
	v_cvt_pk_bf16_f32 v28, v24, v25
	v_cvt_pk_bf16_f32 v29, v26, v27
	s_and_saveexec_b64 s[10:11], s[8:9]
	s_xor_b64 s[10:11], exec, s[10:11]
	s_cbranch_execz .LBB0_1406
	v_add_u32_e32 v130, 0xfffffd90, v132
	s_and_saveexec_b64 s[12:13], s[24:25]
	s_xor_b64 s[12:13], exec, s[12:13]
	s_cbranch_execz .LBB0_1403
	v_lshl_add_u64 v[30:31], s[56:57], 0, v[74:75]
	v_lshl_add_u64 v[30:31], v[130:131], 1, v[30:31]
	global_store_dwordx2 v[30:31], v[28:29], off
	v_lshl_add_u64 v[28:29], s[72:73], 0, v[64:65]
	v_lshl_add_u64 v[28:29], v[130:131], 2, v[28:29]
	global_store_dwordx4 v[28:29], v[24:27], off
.LBB0_1403:
	s_andn2_saveexec_b64 s[12:13], s[12:13]
	s_cbranch_execz .LBB0_1405
	v_lshl_add_u64 v[30:31], v[70:71], 1, s[44:45]
	v_lshl_add_u64 v[30:31], v[130:131], 1, v[30:31]
	global_store_dwordx2 v[30:31], v[28:29], off
	v_lshl_add_u64 v[28:29], v[70:71], 2, s[74:75]
	v_lshl_add_u64 v[28:29], v[130:131], 2, v[28:29]
	global_store_dwordx4 v[28:29], v[24:27], off

.LBB0_1406:
	s_andn2_saveexec_b64 s[10:11], s[10:11]
	s_cbranch_execz .LBB0_1408
	v_lshl_add_u64 v[24:25], s[54:55], 0, v[68:69]
	v_ashrrev_i32_e32 v133, 31, v132
	v_lshl_add_u64 v[24:25], v[132:133], 1, v[24:25]
	global_store_dwordx2 v[24:25], v[28:29], off offset:288

.LBB0_1409:
	s_or_b64 exec, exec, s[4:5]
	s_and_saveexec_b64 s[4:5], s[18:19]
	s_xor_b64 s[4:5], exec, s[4:5]
	s_cbranch_execz .LBB0_1418
	s_cmpk_lt_u32 s84, 0x900
	s_mov_b64 s[10:11], -1
	s_cbranch_scc1 .LBB0_1412
	v_lshl_add_u64 v[26:27], s[54:55], 0, v[60:61]
	v_mov_b32_e32 v133, v131
	v_lshl_add_u64 v[26:27], v[132:133], 1, v[26:27]
	v_add_co_u32_e32 v26, vcc, 0xfffff500, v26
	v_cvt_pk_bf16_f32 v24, v20, v21
	v_cvt_pk_bf16_f32 v25, v22, v23
	v_addc_co_u32_e32 v27, vcc, -1, v27, vcc
	s_mov_b64 s[10:11], 0
	global_store_dwordx2 v[26:27], v[24:25], off
.LBB0_1412:
	s_andn2_b64 vcc, exec, s[10:11]
	s_cbranch_vccnz .LBB0_1418
	v_add_u32_e32 v130, 0xfffffa80, v132
	v_lshrrev_b32_e32 v25, 7, v130
	v_and_b32_e32 v24, 0x6c, v132
	s_and_saveexec_b64 s[10:11], s[22:23]
	s_xor_b64 s[10:11], exec, s[10:11]
	s_cbranch_execz .LBB0_1415
	v_lshl_add_u64 v[26:27], s[68:69], 0, v[56:57]
	v_lshl_add_u64 v[26:27], v[130:131], 2, v[26:27]
	v_add_u32_e32 v130, v25, v98
	global_store_dwordx4 v[26:27], v[20:23], off
	v_lshlrev_b64 v[26:27], 7, v[130:131]
	v_or_b32_e32 v26, v26, v24
	v_mov_b64_e32 v[24:25], s[48:49]
	v_mad_u64_u32 v[24:25], s[12:13], v26, s51, v[24:25]
	v_mad_u32_u24 v25, v27, s51, v25
	v_lshlrev_b32_e32 v130, 1, v88
	v_cvt_pk_bf16_f32 v20, v20, s0
	v_lshl_add_u64 v[26:27], v[24:25], 0, v[130:131]
	v_lshlrev_b32_e32 v130, 1, v87
	global_store_short v[26:27], v20, off offset:2056
	v_cvt_pk_bf16_f32 v26, v21, s0
	v_lshl_add_u64 v[20:21], v[24:25], 0, v[130:131]
	v_add_co_u32_e32 v24, vcc, 0x1000, v20
	v_cvt_pk_bf16_f32 v22, v22, s0
	s_nop 0
	v_addc_co_u32_e32 v25, vcc, 0, v21, vcc
	v_add_co_u32_e32 v20, vcc, 0x2000, v20
	global_store_short v[24:25], v22, off offset:2304
	v_cvt_pk_bf16_f32 v22, v23, s0
	v_addc_co_u32_e32 v21, vcc, 0, v21, vcc
	global_store_short v[24:25], v26, off offset:128
	global_store_short v[20:21], v22, off offset:384
.LBB0_1415:
	s_andn2_saveexec_b64 s[10:11], s[10:11]
	s_cbranch_execz .LBB0_1417
	v_lshl_add_u64 v[26:27], s[70:71], 0, v[58:59]
	v_lshl_add_u64 v[26:27], v[130:131], 2, v[26:27]
	global_store_dwordx4 v[26:27], v[20:23], off
	v_add_u32_e32 v26, v25, v90
	v_ashrrev_i32_e32 v27, 31, v26
	v_lshlrev_b64 v[26:27], 20, v[26:27]
	v_lshlrev_b32_e32 v130, 13, v24
	v_lshl_add_u64 v[24:25], s[46:47], 0, v[26:27]
	v_lshl_add_u64 v[24:25], v[24:25], 0, v[130:131]
	v_lshlrev_b32_e32 v130, 1, v85
	v_cvt_pk_bf16_f32 v20, v20, s0
	v_lshl_add_u64 v[24:25], v[24:25], 0, v[130:131]
	s_movk_i32 s12, 0x2000
	global_store_short v[24:25], v20, off
	v_add_co_u32_e32 v20, vcc, s12, v24
	v_cvt_pk_bf16_f32 v26, v21, s0
	s_nop 0
	v_addc_co_u32_e32 v21, vcc, 0, v25, vcc
	global_store_short v[20:21], v26, off
	v_add_co_u32_e32 v20, vcc, 0x4000, v24
	v_cvt_pk_bf16_f32 v22, v22, s0
	s_nop 0
	v_addc_co_u32_e32 v21, vcc, 0, v25, vcc
	global_store_short v[20:21], v22, off
	v_add_co_u32_e32 v20, vcc, 0x6000, v24
	v_cvt_pk_bf16_f32 v22, v23, s0
	s_nop 0
	v_addc_co_u32_e32 v21, vcc, 0, v25, vcc
	global_store_short v[20:21], v22, off

.LBB0_1418:
	s_andn2_saveexec_b64 s[4:5], s[4:5]
	s_cbranch_execz .LBB0_1430
	v_cmp_eq_u32_e32 vcc, 0, v160
	s_and_saveexec_b64 s[10:11], vcc
	s_cbranch_execz .LBB0_1421
	v_cmp_lt_i32_e32 vcc, v158, v156
	v_lshlrev_b32_e32 v130, 3, v104
	s_nop 0
	v_cndmask_b32_e32 v24, v155, v158, vcc
	v_lshlrev_b32_e32 v24, 2, v24
	ds_bpermute_b32 v28, v24, v20
	ds_bpermute_b32 v29, v24, v21
	ds_bpermute_b32 v30, v24, v22
	ds_bpermute_b32 v31, v24, v23
	v_lshl_add_u64 v[24:25], s[52:53], 0, v[130:131]
	v_lshlrev_b32_e32 v130, 3, v135
	v_lshl_add_u64 v[32:33], v[24:25], 0, v[130:131]
	global_load_dwordx4 v[24:27], v[32:33], off
	s_waitcnt vmcnt(0) lgkmcnt(0)
	v_mov_b32_e32 v35, v26
	v_mov_b32_e32 v26, v25
	v_mov_b32_e32 v34, v24
	v_pk_mul_f32 v[24:25], v[26:27], v[28:29]
	s_nop 0
	v_cndmask_b32_e64 v25, v25, -v25, s[30:31]
	v_cndmask_b32_e64 v24, v24, -v24, s[30:31]
	v_pk_fma_f32 v[20:21], v[20:21], v[34:35], v[24:25]
	global_load_dwordx4 v[24:27], v[32:33], off offset:16
	s_waitcnt vmcnt(0) lgkmcnt(0)
	v_mov_b32_e32 v29, v26
	v_mov_b32_e32 v26, v25
	v_mov_b32_e32 v28, v24
	v_pk_mul_f32 v[24:25], v[26:27], v[30:31]
	s_nop 0
	v_cndmask_b32_e64 v25, v25, -v25, s[30:31]
	v_cndmask_b32_e64 v24, v24, -v24, s[30:31]
	v_pk_fma_f32 v[22:23], v[22:23], v[28:29], v[24:25]
.LBB0_1421:
	s_or_b64 exec, exec, s[10:11]
	v_cvt_pk_bf16_f32 v24, v20, v21
	v_cvt_pk_bf16_f32 v25, v22, v23
	s_and_saveexec_b64 s[10:11], s[6:7]
	s_xor_b64 s[10:11], exec, s[10:11]
	s_cbranch_execz .LBB0_1427
	v_add_u32_e32 v130, 0xfffffd80, v132
	s_and_saveexec_b64 s[12:13], s[22:23]
	s_xor_b64 s[12:13], exec, s[12:13]
	s_cbranch_execz .LBB0_1424
	v_lshl_add_u64 v[26:27], s[56:57], 0, v[76:77]
	v_lshl_add_u64 v[26:27], v[130:131], 1, v[26:27]
	global_store_dwordx2 v[26:27], v[24:25], off
	v_lshl_add_u64 v[24:25], s[72:73], 0, v[56:57]
	v_lshl_add_u64 v[24:25], v[130:131], 2, v[24:25]
	global_store_dwordx4 v[24:25], v[20:23], off
.LBB0_1424:
	s_andn2_saveexec_b64 s[12:13], s[12:13]
	s_cbranch_execz .LBB0_1426
	v_lshl_add_u64 v[26:27], v[62:63], 1, s[44:45]
	v_lshl_add_u64 v[26:27], v[130:131], 1, v[26:27]
	global_store_dwordx2 v[26:27], v[24:25], off
	v_lshl_add_u64 v[24:25], v[62:63], 2, s[74:75]
	v_lshl_add_u64 v[24:25], v[130:131], 2, v[24:25]
	global_store_dwordx4 v[24:25], v[20:23], off

.LBB0_1427:
	s_andn2_saveexec_b64 s[10:11], s[10:11]
	s_cbranch_execz .LBB0_1429
	v_lshl_add_u64 v[20:21], s[54:55], 0, v[60:61]
	v_ashrrev_i32_e32 v133, 31, v132
	v_lshl_add_u64 v[20:21], v[132:133], 1, v[20:21]
	global_store_dwordx2 v[20:21], v[24:25], off offset:256

.LBB0_1430:
	s_or_b64 exec, exec, s[4:5]
	s_and_saveexec_b64 s[4:5], s[14:15]
	s_xor_b64 s[4:5], exec, s[4:5]
	s_cbranch_execz .LBB0_1439
	s_cmpk_lt_u32 s84, 0x900
	s_mov_b64 s[10:11], -1
	s_cbranch_scc1 .LBB0_1433
	v_lshl_add_u64 v[22:23], s[54:55], 0, v[60:61]
	v_mov_b32_e32 v133, v131
	v_lshl_add_u64 v[22:23], v[132:133], 1, v[22:23]
	v_add_co_u32_e32 v22, vcc, 0xfffff520, v22
	v_cvt_pk_bf16_f32 v20, v16, v17
	v_cvt_pk_bf16_f32 v21, v18, v19
	v_addc_co_u32_e32 v23, vcc, -1, v23, vcc
	s_mov_b64 s[10:11], 0
	global_store_dwordx2 v[22:23], v[20:21], off
.LBB0_1433:
	s_andn2_b64 vcc, exec, s[10:11]
	s_cbranch_vccnz .LBB0_1439
	v_add_u32_e32 v130, 0xfffffa90, v132
	v_lshrrev_b32_e32 v21, 7, v130
	v_and_b32_e32 v20, 0x7c, v94
	s_and_saveexec_b64 s[10:11], s[22:23]
	s_xor_b64 s[10:11], exec, s[10:11]
	s_cbranch_execz .LBB0_1436
	v_lshl_add_u64 v[22:23], s[68:69], 0, v[56:57]
	v_lshl_add_u64 v[22:23], v[130:131], 2, v[22:23]
	v_add_u32_e32 v130, v21, v98
	global_store_dwordx4 v[22:23], v[16:19], off
	v_lshlrev_b64 v[22:23], 7, v[130:131]
	v_or_b32_e32 v22, v22, v20
	v_mov_b64_e32 v[20:21], s[48:49]
	v_mad_u64_u32 v[20:21], s[12:13], v22, s51, v[20:21]
	v_mad_u32_u24 v21, v23, s51, v21
	v_lshlrev_b32_e32 v130, 1, v88
	v_cvt_pk_bf16_f32 v16, v16, s0
	v_lshl_add_u64 v[22:23], v[20:21], 0, v[130:131]
	v_lshlrev_b32_e32 v130, 1, v87
	global_store_short v[22:23], v16, off offset:2056
	v_cvt_pk_bf16_f32 v22, v17, s0
	v_lshl_add_u64 v[16:17], v[20:21], 0, v[130:131]
	v_add_co_u32_e32 v20, vcc, 0x1000, v16
	v_cvt_pk_bf16_f32 v18, v18, s0
	s_nop 0
	v_addc_co_u32_e32 v21, vcc, 0, v17, vcc
	v_add_co_u32_e32 v16, vcc, 0x2000, v16
	global_store_short v[20:21], v18, off offset:2304
	v_cvt_pk_bf16_f32 v18, v19, s0
	v_addc_co_u32_e32 v17, vcc, 0, v17, vcc
	global_store_short v[20:21], v22, off offset:128
	global_store_short v[16:17], v18, off offset:384
.LBB0_1436:
	s_andn2_saveexec_b64 s[10:11], s[10:11]
	s_cbranch_execz .LBB0_1438
	v_lshl_add_u64 v[22:23], s[70:71], 0, v[58:59]
	v_lshl_add_u64 v[22:23], v[130:131], 2, v[22:23]
	global_store_dwordx4 v[22:23], v[16:19], off
	v_add_u32_e32 v22, v21, v90
	v_ashrrev_i32_e32 v23, 31, v22
	v_lshlrev_b64 v[22:23], 20, v[22:23]
	v_lshlrev_b32_e32 v130, 13, v20
	v_lshl_add_u64 v[20:21], s[46:47], 0, v[22:23]
	v_lshl_add_u64 v[20:21], v[20:21], 0, v[130:131]
	v_lshlrev_b32_e32 v130, 1, v85
	v_cvt_pk_bf16_f32 v16, v16, s0
	v_lshl_add_u64 v[20:21], v[20:21], 0, v[130:131]
	s_movk_i32 s12, 0x2000
	global_store_short v[20:21], v16, off
	v_add_co_u32_e32 v16, vcc, s12, v20
	v_cvt_pk_bf16_f32 v22, v17, s0
	s_nop 0
	v_addc_co_u32_e32 v17, vcc, 0, v21, vcc
	global_store_short v[16:17], v22, off
	v_add_co_u32_e32 v16, vcc, 0x4000, v20
	v_cvt_pk_bf16_f32 v18, v18, s0
	s_nop 0
	v_addc_co_u32_e32 v17, vcc, 0, v21, vcc
	global_store_short v[16:17], v18, off
	v_add_co_u32_e32 v16, vcc, 0x6000, v20
	v_cvt_pk_bf16_f32 v18, v19, s0
	s_nop 0
	v_addc_co_u32_e32 v17, vcc, 0, v21, vcc
	global_store_short v[16:17], v18, off

.LBB0_1439:
	s_andn2_saveexec_b64 s[4:5], s[4:5]
	s_cbranch_execz .LBB0_1449
	v_cvt_pk_bf16_f32 v20, v16, v17
	v_cvt_pk_bf16_f32 v21, v18, v19
	s_and_saveexec_b64 s[10:11], s[8:9]
	s_xor_b64 s[10:11], exec, s[10:11]
	s_cbranch_execz .LBB0_1446
	v_add_u32_e32 v130, 0xfffffd90, v132
	s_and_saveexec_b64 s[12:13], s[22:23]
	s_xor_b64 s[12:13], exec, s[12:13]
	s_cbranch_execz .LBB0_1443
	v_lshl_add_u64 v[22:23], s[56:57], 0, v[76:77]
	v_lshl_add_u64 v[22:23], v[130:131], 1, v[22:23]
	global_store_dwordx2 v[22:23], v[20:21], off
	v_lshl_add_u64 v[20:21], s[72:73], 0, v[56:57]
	v_lshl_add_u64 v[20:21], v[130:131], 2, v[20:21]
	global_store_dwordx4 v[20:21], v[16:19], off
.LBB0_1443:
	s_andn2_saveexec_b64 s[12:13], s[12:13]
	s_cbranch_execz .LBB0_1445
	v_lshl_add_u64 v[22:23], v[62:63], 1, s[44:45]
	v_lshl_add_u64 v[22:23], v[130:131], 1, v[22:23]
	global_store_dwordx2 v[22:23], v[20:21], off
	v_lshl_add_u64 v[20:21], v[62:63], 2, s[74:75]
	v_lshl_add_u64 v[20:21], v[130:131], 2, v[20:21]
	global_store_dwordx4 v[20:21], v[16:19], off

.LBB0_1446:
	s_andn2_saveexec_b64 s[10:11], s[10:11]
	s_cbranch_execz .LBB0_1448
	v_lshl_add_u64 v[16:17], s[54:55], 0, v[60:61]
	v_ashrrev_i32_e32 v133, 31, v132
	v_lshl_add_u64 v[16:17], v[132:133], 1, v[16:17]
	global_store_dwordx2 v[16:17], v[20:21], off offset:288

.LBB0_1449:
	s_or_b64 exec, exec, s[4:5]
	s_and_saveexec_b64 s[4:5], s[18:19]
	s_xor_b64 s[4:5], exec, s[4:5]
	s_cbranch_execz .LBB0_1458
	s_cmpk_lt_u32 s84, 0x900
	s_mov_b64 s[10:11], -1
	s_cbranch_scc1 .LBB0_1452
	v_lshl_add_u64 v[18:19], s[54:55], 0, v[52:53]
	v_mov_b32_e32 v133, v131
	v_lshl_add_u64 v[18:19], v[132:133], 1, v[18:19]
	v_add_co_u32_e32 v18, vcc, 0xfffff500, v18
	v_cvt_pk_bf16_f32 v16, v12, v13
	v_cvt_pk_bf16_f32 v17, v14, v15
	v_addc_co_u32_e32 v19, vcc, -1, v19, vcc
	s_mov_b64 s[10:11], 0
	global_store_dwordx2 v[18:19], v[16:17], off
.LBB0_1452:
	s_andn2_b64 vcc, exec, s[10:11]
	s_cbranch_vccnz .LBB0_1458
	v_add_u32_e32 v130, 0xfffffa80, v132
	v_lshrrev_b32_e32 v17, 7, v130
	v_and_b32_e32 v16, 0x6c, v132
	s_and_saveexec_b64 s[10:11], s[26:27]
	s_xor_b64 s[10:11], exec, s[10:11]
	s_cbranch_execz .LBB0_1455
	v_lshl_add_u64 v[18:19], s[68:69], 0, v[48:49]
	v_lshl_add_u64 v[18:19], v[130:131], 2, v[18:19]
	v_add_u32_e32 v130, v17, v100
	global_store_dwordx4 v[18:19], v[12:15], off
	v_lshlrev_b64 v[18:19], 7, v[130:131]
	v_or_b32_e32 v18, v18, v16
	v_mov_b64_e32 v[16:17], s[48:49]
	v_mad_u64_u32 v[16:17], s[12:13], v18, s51, v[16:17]
	v_mad_u32_u24 v17, v19, s51, v17
	v_lshlrev_b32_e32 v130, 1, v96
	v_cvt_pk_bf16_f32 v12, v12, s0
	v_lshl_add_u64 v[16:17], v[16:17], 0, v[130:131]
	global_store_short v[16:17], v12, off offset:2048
	v_add_co_u32_e32 v12, vcc, 0x1000, v16
	v_cvt_pk_bf16_f32 v18, v13, s0
	s_nop 0
	v_addc_co_u32_e32 v13, vcc, 0, v17, vcc
	v_cvt_pk_bf16_f32 v14, v14, s0
	global_store_short v[12:13], v18, off offset:128
	global_store_short v[12:13], v14, off offset:2304
	v_add_co_u32_e32 v12, vcc, 0x2000, v16
	v_cvt_pk_bf16_f32 v14, v15, s0
	s_nop 0
	v_addc_co_u32_e32 v13, vcc, 0, v17, vcc
	global_store_short v[12:13], v14, off offset:384
.LBB0_1455:
	s_andn2_saveexec_b64 s[10:11], s[10:11]
	s_cbranch_execz .LBB0_1457
	v_lshl_add_u64 v[18:19], s[70:71], 0, v[50:51]
	v_lshl_add_u64 v[18:19], v[130:131], 2, v[18:19]
	global_store_dwordx4 v[18:19], v[12:15], off
	v_add_u32_e32 v18, v17, v97
	v_ashrrev_i32_e32 v19, 31, v18
	v_lshlrev_b32_e32 v130, 1, v95
	v_lshl_add_u64 v[20:21], s[46:47], 0, v[130:131]
	v_lshlrev_b64 v[18:19], 20, v[18:19]
	v_lshlrev_b32_e32 v130, 13, v16
	v_lshl_add_u64 v[16:17], v[20:21], 0, v[18:19]
	v_cvt_pk_bf16_f32 v12, v12, s0
	v_lshl_add_u64 v[16:17], v[16:17], 0, v[130:131]
	s_movk_i32 s12, 0x2000
	global_store_short v[16:17], v12, off
	v_add_co_u32_e32 v12, vcc, s12, v16
	v_cvt_pk_bf16_f32 v18, v13, s0
	s_nop 0
	v_addc_co_u32_e32 v13, vcc, 0, v17, vcc
	global_store_short v[12:13], v18, off
	v_add_co_u32_e32 v12, vcc, 0x4000, v16
	v_cvt_pk_bf16_f32 v14, v14, s0
	s_nop 0
	v_addc_co_u32_e32 v13, vcc, 0, v17, vcc
	global_store_short v[12:13], v14, off
	v_add_co_u32_e32 v12, vcc, 0x6000, v16
	v_cvt_pk_bf16_f32 v14, v15, s0
	s_nop 0
	v_addc_co_u32_e32 v13, vcc, 0, v17, vcc
	global_store_short v[12:13], v14, off

.LBB0_1458:
	s_andn2_saveexec_b64 s[4:5], s[4:5]
	s_cbranch_execz .LBB0_1470
	v_cmp_eq_u32_e32 vcc, 0, v160
	s_and_saveexec_b64 s[10:11], vcc
	s_cbranch_execz .LBB0_1461
	v_cmp_lt_i32_e32 vcc, v158, v156
	v_lshlrev_b32_e32 v130, 3, v102
	s_nop 0
	v_cndmask_b32_e32 v16, v155, v158, vcc
	v_lshlrev_b32_e32 v16, 2, v16
	ds_bpermute_b32 v20, v16, v12
	ds_bpermute_b32 v21, v16, v13
	ds_bpermute_b32 v22, v16, v14
	ds_bpermute_b32 v23, v16, v15
	v_lshl_add_u64 v[16:17], s[52:53], 0, v[130:131]
	v_lshlrev_b32_e32 v130, 3, v135
	v_lshl_add_u64 v[24:25], v[16:17], 0, v[130:131]
	global_load_dwordx4 v[16:19], v[24:25], off
	s_waitcnt vmcnt(0) lgkmcnt(0)
	v_mov_b32_e32 v27, v18
	v_mov_b32_e32 v18, v17
	v_mov_b32_e32 v26, v16
	v_pk_mul_f32 v[16:17], v[18:19], v[20:21]
	s_nop 0
	v_cndmask_b32_e64 v17, v17, -v17, s[30:31]
	v_cndmask_b32_e64 v16, v16, -v16, s[30:31]
	v_pk_fma_f32 v[12:13], v[12:13], v[26:27], v[16:17]
	global_load_dwordx4 v[16:19], v[24:25], off offset:16
	s_waitcnt vmcnt(0) lgkmcnt(0)
	v_mov_b32_e32 v21, v18
	v_mov_b32_e32 v18, v17
	v_mov_b32_e32 v20, v16
	v_pk_mul_f32 v[16:17], v[18:19], v[22:23]
	s_nop 0
	v_cndmask_b32_e64 v17, v17, -v17, s[30:31]
	v_cndmask_b32_e64 v16, v16, -v16, s[30:31]
	v_pk_fma_f32 v[14:15], v[14:15], v[20:21], v[16:17]
.LBB0_1461:
	s_or_b64 exec, exec, s[10:11]
	v_cvt_pk_bf16_f32 v16, v12, v13
	v_cvt_pk_bf16_f32 v17, v14, v15
	s_and_saveexec_b64 s[10:11], s[6:7]
	s_xor_b64 s[10:11], exec, s[10:11]
	s_cbranch_execz .LBB0_1467
	v_add_u32_e32 v130, 0xfffffd80, v132
	s_and_saveexec_b64 s[12:13], s[26:27]
	s_xor_b64 s[12:13], exec, s[12:13]
	s_cbranch_execz .LBB0_1464
	v_lshl_add_u64 v[18:19], s[56:57], 0, v[78:79]
	v_lshl_add_u64 v[18:19], v[130:131], 1, v[18:19]
	global_store_dwordx2 v[18:19], v[16:17], off
	v_lshl_add_u64 v[16:17], s[72:73], 0, v[48:49]
	v_lshl_add_u64 v[16:17], v[130:131], 2, v[16:17]
	global_store_dwordx4 v[16:17], v[12:15], off
.LBB0_1464:
	s_andn2_saveexec_b64 s[12:13], s[12:13]
	s_cbranch_execz .LBB0_1466
	v_lshl_add_u64 v[18:19], v[54:55], 1, s[44:45]
	v_lshl_add_u64 v[18:19], v[130:131], 1, v[18:19]
	global_store_dwordx2 v[18:19], v[16:17], off
	v_lshl_add_u64 v[16:17], v[54:55], 2, s[74:75]
	v_lshl_add_u64 v[16:17], v[130:131], 2, v[16:17]
	global_store_dwordx4 v[16:17], v[12:15], off

.LBB0_1467:
	s_andn2_saveexec_b64 s[10:11], s[10:11]
	s_cbranch_execz .LBB0_1469
	v_lshl_add_u64 v[12:13], s[54:55], 0, v[52:53]
	v_ashrrev_i32_e32 v133, 31, v132
	v_lshl_add_u64 v[12:13], v[132:133], 1, v[12:13]
	global_store_dwordx2 v[12:13], v[16:17], off offset:256

.LBB0_1470:
	s_or_b64 exec, exec, s[4:5]
	s_and_saveexec_b64 s[4:5], s[14:15]
	s_xor_b64 s[4:5], exec, s[4:5]
	s_cbranch_execz .LBB0_1479
	s_cmpk_lt_u32 s84, 0x900
	s_mov_b64 s[10:11], -1
	s_cbranch_scc1 .LBB0_1473
	v_lshl_add_u64 v[14:15], s[54:55], 0, v[52:53]
	v_mov_b32_e32 v133, v131
	v_lshl_add_u64 v[14:15], v[132:133], 1, v[14:15]
	v_add_co_u32_e32 v14, vcc, 0xfffff520, v14
	v_cvt_pk_bf16_f32 v12, v8, v9
	v_cvt_pk_bf16_f32 v13, v10, v11
	v_addc_co_u32_e32 v15, vcc, -1, v15, vcc
	s_mov_b64 s[10:11], 0
	global_store_dwordx2 v[14:15], v[12:13], off
.LBB0_1473:
	s_andn2_b64 vcc, exec, s[10:11]
	s_cbranch_vccnz .LBB0_1479
	v_add_u32_e32 v130, 0xfffffa90, v132
	v_lshrrev_b32_e32 v13, 7, v130
	v_and_b32_e32 v12, 0x7c, v94
	s_and_saveexec_b64 s[10:11], s[26:27]
	s_xor_b64 s[10:11], exec, s[10:11]
	s_cbranch_execz .LBB0_1476
	v_lshl_add_u64 v[14:15], s[68:69], 0, v[48:49]
	v_lshl_add_u64 v[14:15], v[130:131], 2, v[14:15]
	v_add_u32_e32 v130, v13, v100
	global_store_dwordx4 v[14:15], v[8:11], off
	v_lshlrev_b64 v[14:15], 7, v[130:131]
	v_or_b32_e32 v14, v14, v12
	v_mov_b64_e32 v[12:13], s[48:49]
	v_mad_u64_u32 v[12:13], s[12:13], v14, s51, v[12:13]
	v_mad_u32_u24 v13, v15, s51, v13
	v_lshlrev_b32_e32 v130, 1, v96
	v_cvt_pk_bf16_f32 v8, v8, s0
	v_lshl_add_u64 v[12:13], v[12:13], 0, v[130:131]
	global_store_short v[12:13], v8, off offset:2048
	v_add_co_u32_e32 v8, vcc, 0x1000, v12
	v_cvt_pk_bf16_f32 v14, v9, s0
	s_nop 0
	v_addc_co_u32_e32 v9, vcc, 0, v13, vcc
	v_cvt_pk_bf16_f32 v10, v10, s0
	global_store_short v[8:9], v14, off offset:128
	global_store_short v[8:9], v10, off offset:2304
	v_add_co_u32_e32 v8, vcc, 0x2000, v12
	v_cvt_pk_bf16_f32 v10, v11, s0
	s_nop 0
	v_addc_co_u32_e32 v9, vcc, 0, v13, vcc
	global_store_short v[8:9], v10, off offset:384
.LBB0_1476:
	s_andn2_saveexec_b64 s[10:11], s[10:11]
	s_cbranch_execz .LBB0_1478
	v_lshl_add_u64 v[14:15], s[70:71], 0, v[50:51]
	v_lshl_add_u64 v[14:15], v[130:131], 2, v[14:15]
	global_store_dwordx4 v[14:15], v[8:11], off
	v_add_u32_e32 v14, v13, v97
	v_ashrrev_i32_e32 v15, 31, v14
	v_lshlrev_b32_e32 v130, 1, v95
	v_lshl_add_u64 v[16:17], s[46:47], 0, v[130:131]
	v_lshlrev_b64 v[14:15], 20, v[14:15]
	v_lshlrev_b32_e32 v130, 13, v12
	v_lshl_add_u64 v[12:13], v[16:17], 0, v[14:15]
	v_cvt_pk_bf16_f32 v8, v8, s0
	v_lshl_add_u64 v[12:13], v[12:13], 0, v[130:131]
	s_movk_i32 s12, 0x2000
	global_store_short v[12:13], v8, off
	v_add_co_u32_e32 v8, vcc, s12, v12
	v_cvt_pk_bf16_f32 v14, v9, s0
	s_nop 0
	v_addc_co_u32_e32 v9, vcc, 0, v13, vcc
	global_store_short v[8:9], v14, off
	v_add_co_u32_e32 v8, vcc, 0x4000, v12
	v_cvt_pk_bf16_f32 v10, v10, s0
	s_nop 0
	v_addc_co_u32_e32 v9, vcc, 0, v13, vcc
	global_store_short v[8:9], v10, off
	v_add_co_u32_e32 v8, vcc, 0x6000, v12
	v_cvt_pk_bf16_f32 v10, v11, s0
	s_nop 0
	v_addc_co_u32_e32 v9, vcc, 0, v13, vcc
	global_store_short v[8:9], v10, off

.LBB0_1479:
	s_andn2_saveexec_b64 s[4:5], s[4:5]
	s_cbranch_execz .LBB0_1489
	v_cvt_pk_bf16_f32 v12, v8, v9
	v_cvt_pk_bf16_f32 v13, v10, v11
	s_and_saveexec_b64 s[10:11], s[8:9]
	s_xor_b64 s[10:11], exec, s[10:11]
	s_cbranch_execz .LBB0_1486
	v_add_u32_e32 v130, 0xfffffd90, v132
	s_and_saveexec_b64 s[12:13], s[26:27]
	s_xor_b64 s[12:13], exec, s[12:13]
	s_cbranch_execz .LBB0_1483
	v_lshl_add_u64 v[14:15], s[56:57], 0, v[78:79]
	v_lshl_add_u64 v[14:15], v[130:131], 1, v[14:15]
	global_store_dwordx2 v[14:15], v[12:13], off
	v_lshl_add_u64 v[12:13], s[72:73], 0, v[48:49]
	v_lshl_add_u64 v[12:13], v[130:131], 2, v[12:13]
	global_store_dwordx4 v[12:13], v[8:11], off
.LBB0_1483:
	s_andn2_saveexec_b64 s[12:13], s[12:13]
	s_cbranch_execz .LBB0_1485
	v_lshl_add_u64 v[14:15], v[54:55], 1, s[44:45]
	v_lshl_add_u64 v[14:15], v[130:131], 1, v[14:15]
	global_store_dwordx2 v[14:15], v[12:13], off
	v_lshl_add_u64 v[12:13], v[54:55], 2, s[74:75]
	v_lshl_add_u64 v[12:13], v[130:131], 2, v[12:13]
	global_store_dwordx4 v[12:13], v[8:11], off

.LBB0_1486:
	s_andn2_saveexec_b64 s[10:11], s[10:11]
	s_cbranch_execz .LBB0_1488
	v_lshl_add_u64 v[8:9], s[54:55], 0, v[52:53]
	v_ashrrev_i32_e32 v133, 31, v132
	v_lshl_add_u64 v[8:9], v[132:133], 1, v[8:9]
	global_store_dwordx2 v[8:9], v[12:13], off offset:288

.LBB0_1489:
	s_or_b64 exec, exec, s[4:5]
	s_and_saveexec_b64 s[4:5], s[18:19]
	s_xor_b64 s[4:5], exec, s[4:5]
	s_cbranch_execz .LBB0_1498
	s_cmpk_lt_u32 s84, 0x900
	s_mov_b64 s[10:11], -1
	s_cbranch_scc1 .LBB0_1492
	v_lshl_add_u64 v[10:11], s[54:55], 0, v[42:43]
	v_mov_b32_e32 v133, v131
	v_lshl_add_u64 v[10:11], v[132:133], 1, v[10:11]
	v_add_co_u32_e32 v10, vcc, 0xfffff500, v10
	v_cvt_pk_bf16_f32 v8, v4, v5
	v_cvt_pk_bf16_f32 v9, v6, v7
	v_addc_co_u32_e32 v11, vcc, -1, v11, vcc
	s_mov_b64 s[10:11], 0
	global_store_dwordx2 v[10:11], v[8:9], off
.LBB0_1492:
	s_andn2_b64 vcc, exec, s[10:11]
	s_cbranch_vccnz .LBB0_1498
	v_add_u32_e32 v130, 0xfffffa80, v132
	v_lshrrev_b32_e32 v9, 7, v130
	v_and_b32_e32 v8, 0x6c, v132
	s_and_saveexec_b64 s[10:11], s[20:21]
	s_xor_b64 s[10:11], exec, s[10:11]
	s_cbranch_execz .LBB0_1495
	v_lshl_add_u64 v[10:11], s[68:69], 0, v[40:41]
	v_lshl_add_u64 v[10:11], v[130:131], 2, v[10:11]
	v_add_u32_e32 v130, v9, v89
	global_store_dwordx4 v[10:11], v[4:7], off
	v_lshlrev_b64 v[10:11], 7, v[130:131]
	v_or_b32_e32 v10, v10, v8
	v_mov_b64_e32 v[8:9], s[48:49]
	v_mad_u64_u32 v[8:9], s[12:13], v10, s51, v[8:9]
	v_mad_u32_u24 v9, v11, s51, v9
	v_lshlrev_b32_e32 v130, 1, v84
	v_cvt_pk_bf16_f32 v4, v4, s0
	v_lshl_add_u64 v[10:11], v[8:9], 0, v[130:131]
	v_lshlrev_b32_e32 v130, 1, v83
	global_store_short v[10:11], v4, off offset:2056
	v_cvt_pk_bf16_f32 v10, v5, s0
	v_lshl_add_u64 v[4:5], v[8:9], 0, v[130:131]
	v_add_co_u32_e32 v8, vcc, 0x1000, v4
	v_cvt_pk_bf16_f32 v6, v6, s0
	s_nop 0
	v_addc_co_u32_e32 v9, vcc, 0, v5, vcc
	v_add_co_u32_e32 v4, vcc, 0x2000, v4
	global_store_short v[8:9], v6, off offset:2304
	v_cvt_pk_bf16_f32 v6, v7, s0
	v_addc_co_u32_e32 v5, vcc, 0, v5, vcc
	global_store_short v[8:9], v10, off offset:128
	global_store_short v[4:5], v6, off offset:384
.LBB0_1495:
	s_andn2_saveexec_b64 s[10:11], s[10:11]
	s_cbranch_execz .LBB0_1497
	v_lshl_add_u64 v[10:11], s[70:71], 0, v[44:45]
	v_lshl_add_u64 v[10:11], v[130:131], 2, v[10:11]
	global_store_dwordx4 v[10:11], v[4:7], off
	v_add_u32_e32 v10, v9, v86
	v_ashrrev_i32_e32 v11, 31, v10
	v_lshlrev_b64 v[10:11], 20, v[10:11]
	v_lshlrev_b32_e32 v130, 13, v8
	v_lshl_add_u64 v[8:9], s[46:47], 0, v[10:11]
	v_lshl_add_u64 v[8:9], v[8:9], 0, v[130:131]
	v_lshlrev_b32_e32 v130, 1, v82
	v_cvt_pk_bf16_f32 v4, v4, s0
	v_lshl_add_u64 v[8:9], v[8:9], 0, v[130:131]
	s_movk_i32 s12, 0x2000
	global_store_short v[8:9], v4, off
	v_add_co_u32_e32 v4, vcc, s12, v8
	v_cvt_pk_bf16_f32 v10, v5, s0
	s_nop 0
	v_addc_co_u32_e32 v5, vcc, 0, v9, vcc
	global_store_short v[4:5], v10, off
	v_add_co_u32_e32 v4, vcc, 0x4000, v8
	v_cvt_pk_bf16_f32 v6, v6, s0
	s_nop 0
	v_addc_co_u32_e32 v5, vcc, 0, v9, vcc
	global_store_short v[4:5], v6, off
	v_add_co_u32_e32 v4, vcc, 0x6000, v8
	v_cvt_pk_bf16_f32 v6, v7, s0
	s_nop 0
	v_addc_co_u32_e32 v5, vcc, 0, v9, vcc
	global_store_short v[4:5], v6, off

.LBB0_1498:
	s_andn2_saveexec_b64 s[4:5], s[4:5]
	s_cbranch_execz .LBB0_1510
	v_cmp_eq_u32_e32 vcc, 0, v160
	s_and_saveexec_b64 s[10:11], vcc
	s_cbranch_execz .LBB0_1501
	v_cmp_lt_i32_e32 vcc, v158, v156
	v_lshlrev_b32_e32 v130, 3, v103
	s_nop 0
	v_cndmask_b32_e32 v8, v155, v158, vcc
	v_lshlrev_b32_e32 v8, 2, v8
	ds_bpermute_b32 v12, v8, v4
	ds_bpermute_b32 v13, v8, v5
	ds_bpermute_b32 v14, v8, v6
	ds_bpermute_b32 v15, v8, v7
	v_lshl_add_u64 v[8:9], s[52:53], 0, v[130:131]
	v_lshlrev_b32_e32 v130, 3, v135
	v_lshl_add_u64 v[16:17], v[8:9], 0, v[130:131]
	global_load_dwordx4 v[8:11], v[16:17], off
	s_waitcnt vmcnt(0) lgkmcnt(0)
	v_mov_b32_e32 v19, v10
	v_mov_b32_e32 v10, v9
	v_mov_b32_e32 v18, v8
	v_pk_mul_f32 v[8:9], v[10:11], v[12:13]
	s_nop 0
	v_cndmask_b32_e64 v9, v9, -v9, s[30:31]
	v_cndmask_b32_e64 v8, v8, -v8, s[30:31]
	v_pk_fma_f32 v[4:5], v[4:5], v[18:19], v[8:9]
	global_load_dwordx4 v[8:11], v[16:17], off offset:16
	s_waitcnt vmcnt(0) lgkmcnt(0)
	v_mov_b32_e32 v13, v10
	v_mov_b32_e32 v10, v9
	v_mov_b32_e32 v12, v8
	v_pk_mul_f32 v[8:9], v[10:11], v[14:15]
	s_nop 0
	v_cndmask_b32_e64 v9, v9, -v9, s[30:31]
	v_cndmask_b32_e64 v8, v8, -v8, s[30:31]
	v_pk_fma_f32 v[6:7], v[6:7], v[12:13], v[8:9]
.LBB0_1501:
	s_or_b64 exec, exec, s[10:11]
	v_cvt_pk_bf16_f32 v8, v4, v5
	v_cvt_pk_bf16_f32 v9, v6, v7
	s_and_saveexec_b64 s[10:11], s[6:7]
	s_xor_b64 s[6:7], exec, s[10:11]
	s_cbranch_execz .LBB0_1507
	v_add_u32_e32 v130, 0xfffffd80, v132
	s_and_saveexec_b64 s[10:11], s[20:21]
	s_xor_b64 s[10:11], exec, s[10:11]
	s_cbranch_execz .LBB0_1504
	v_lshl_add_u64 v[10:11], s[56:57], 0, v[72:73]
	v_lshl_add_u64 v[10:11], v[130:131], 1, v[10:11]
	global_store_dwordx2 v[10:11], v[8:9], off
	v_lshl_add_u64 v[8:9], s[72:73], 0, v[40:41]
	v_lshl_add_u64 v[8:9], v[130:131], 2, v[8:9]
	global_store_dwordx4 v[8:9], v[4:7], off
.LBB0_1504:
	s_andn2_saveexec_b64 s[10:11], s[10:11]
	s_cbranch_execz .LBB0_1506
	v_lshl_add_u64 v[10:11], v[46:47], 1, s[44:45]
	v_lshl_add_u64 v[10:11], v[130:131], 1, v[10:11]
	global_store_dwordx2 v[10:11], v[8:9], off
	v_lshl_add_u64 v[8:9], v[46:47], 2, s[74:75]
	v_lshl_add_u64 v[8:9], v[130:131], 2, v[8:9]
	global_store_dwordx4 v[8:9], v[4:7], off

.LBB0_1507:
	s_andn2_saveexec_b64 s[6:7], s[6:7]
	s_cbranch_execz .LBB0_1509
	v_lshl_add_u64 v[4:5], s[54:55], 0, v[42:43]
	v_ashrrev_i32_e32 v133, 31, v132
	v_lshl_add_u64 v[4:5], v[132:133], 1, v[4:5]
	global_store_dwordx2 v[4:5], v[8:9], off offset:256

.LBB0_1510:
	s_or_b64 exec, exec, s[4:5]
	s_and_saveexec_b64 s[4:5], s[14:15]
	s_xor_b64 s[4:5], exec, s[4:5]
	s_cbranch_execz .LBB0_1519
	s_cmpk_lt_u32 s84, 0x900
	s_mov_b64 s[6:7], -1
	s_cbranch_scc1 .LBB0_1513
	v_lshl_add_u64 v[6:7], s[54:55], 0, v[42:43]
	v_mov_b32_e32 v133, v131
	v_lshl_add_u64 v[6:7], v[132:133], 1, v[6:7]
	v_add_co_u32_e32 v6, vcc, 0xfffff520, v6
	v_cvt_pk_bf16_f32 v4, v0, v1
	v_cvt_pk_bf16_f32 v5, v2, v3
	v_addc_co_u32_e32 v7, vcc, -1, v7, vcc
	s_mov_b64 s[6:7], 0
	global_store_dwordx2 v[6:7], v[4:5], off
.LBB0_1513:
	s_andn2_b64 vcc, exec, s[6:7]
	s_cbranch_vccnz .LBB0_1519
	v_add_u32_e32 v130, 0xfffffa90, v132
	v_lshrrev_b32_e32 v5, 7, v130
	v_and_b32_e32 v4, 0x7c, v94
	s_and_saveexec_b64 s[6:7], s[20:21]
	s_xor_b64 s[6:7], exec, s[6:7]
	s_cbranch_execz .LBB0_1516
	v_lshl_add_u64 v[6:7], s[68:69], 0, v[40:41]
	v_lshl_add_u64 v[6:7], v[130:131], 2, v[6:7]
	v_add_u32_e32 v130, v5, v89
	global_store_dwordx4 v[6:7], v[0:3], off
	v_lshlrev_b64 v[6:7], 7, v[130:131]
	v_or_b32_e32 v6, v6, v4
	v_mov_b64_e32 v[4:5], s[48:49]
	v_mad_u64_u32 v[4:5], s[10:11], v6, s51, v[4:5]
	v_mad_u32_u24 v5, v7, s51, v5
	v_lshlrev_b32_e32 v130, 1, v84
	v_cvt_pk_bf16_f32 v0, v0, s0
	v_lshl_add_u64 v[6:7], v[4:5], 0, v[130:131]
	v_lshlrev_b32_e32 v130, 1, v83
	global_store_short v[6:7], v0, off offset:2056
	v_cvt_pk_bf16_f32 v6, v1, s0
	v_lshl_add_u64 v[0:1], v[4:5], 0, v[130:131]
	v_add_co_u32_e32 v4, vcc, 0x1000, v0
	v_cvt_pk_bf16_f32 v2, v2, s0
	s_nop 0
	v_addc_co_u32_e32 v5, vcc, 0, v1, vcc
	v_add_co_u32_e32 v0, vcc, 0x2000, v0
	global_store_short v[4:5], v2, off offset:2304
	v_cvt_pk_bf16_f32 v2, v3, s0
	v_addc_co_u32_e32 v1, vcc, 0, v1, vcc
	global_store_short v[4:5], v6, off offset:128
	global_store_short v[0:1], v2, off offset:384
.LBB0_1516:
	s_andn2_saveexec_b64 s[6:7], s[6:7]
	s_cbranch_execz .LBB0_1518
	v_lshl_add_u64 v[6:7], s[70:71], 0, v[44:45]
	v_lshl_add_u64 v[6:7], v[130:131], 2, v[6:7]
	global_store_dwordx4 v[6:7], v[0:3], off
	v_add_u32_e32 v6, v5, v86
	v_ashrrev_i32_e32 v7, 31, v6
	v_lshlrev_b64 v[6:7], 20, v[6:7]
	v_lshlrev_b32_e32 v130, 13, v4
	v_lshl_add_u64 v[4:5], s[46:47], 0, v[6:7]
	v_lshl_add_u64 v[4:5], v[4:5], 0, v[130:131]
	v_lshlrev_b32_e32 v130, 1, v82
	v_cvt_pk_bf16_f32 v0, v0, s0
	v_lshl_add_u64 v[4:5], v[4:5], 0, v[130:131]
	s_movk_i32 s10, 0x2000
	global_store_short v[4:5], v0, off
	v_add_co_u32_e32 v0, vcc, s10, v4
	v_cvt_pk_bf16_f32 v6, v1, s0
	s_nop 0
	v_addc_co_u32_e32 v1, vcc, 0, v5, vcc
	global_store_short v[0:1], v6, off
	v_add_co_u32_e32 v0, vcc, 0x4000, v4
	v_cvt_pk_bf16_f32 v2, v2, s0
	s_nop 0
	v_addc_co_u32_e32 v1, vcc, 0, v5, vcc
	global_store_short v[0:1], v2, off
	v_add_co_u32_e32 v0, vcc, 0x6000, v4
	v_cvt_pk_bf16_f32 v2, v3, s0
	s_nop 0
	v_addc_co_u32_e32 v1, vcc, 0, v5, vcc
	global_store_short v[0:1], v2, off

.LBB0_1519:
	s_or_saveexec_b64 s[4:5], s[4:5]
	v_readlane_b32 s84, v255, 37
	v_readlane_b32 s85, v255, 38
	s_xor_b64 exec, exec, s[4:5]
	s_cbranch_execz .LBB0_880
	v_cvt_pk_bf16_f32 v4, v0, v1
	v_cvt_pk_bf16_f32 v5, v2, v3
	s_and_saveexec_b64 s[6:7], s[8:9]
	s_xor_b64 s[6:7], exec, s[6:7]
	s_cbranch_execz .LBB0_1526
	v_add_u32_e32 v130, 0xfffffd90, v132
	s_and_saveexec_b64 s[8:9], s[20:21]
	s_xor_b64 s[8:9], exec, s[8:9]
	s_cbranch_execz .LBB0_1523
	v_lshl_add_u64 v[6:7], s[56:57], 0, v[72:73]
	v_lshl_add_u64 v[6:7], v[130:131], 1, v[6:7]
	global_store_dwordx2 v[6:7], v[4:5], off
	v_lshl_add_u64 v[4:5], s[72:73], 0, v[40:41]
	v_lshl_add_u64 v[4:5], v[130:131], 2, v[4:5]
	global_store_dwordx4 v[4:5], v[0:3], off
.LBB0_1523:
	s_andn2_saveexec_b64 s[8:9], s[8:9]
	s_cbranch_execz .LBB0_1525
	v_lshl_add_u64 v[6:7], v[46:47], 1, s[44:45]
	v_lshl_add_u64 v[6:7], v[130:131], 1, v[6:7]
	global_store_dwordx2 v[6:7], v[4:5], off
	v_lshl_add_u64 v[4:5], v[46:47], 2, s[74:75]
	v_lshl_add_u64 v[4:5], v[130:131], 2, v[4:5]
	global_store_dwordx4 v[4:5], v[0:3], off

.LBB0_1526:
	s_andn2_saveexec_b64 s[6:7], s[6:7]
	s_cbranch_execz .LBB0_879
	v_lshl_add_u64 v[0:1], s[54:55], 0, v[42:43]
	v_ashrrev_i32_e32 v133, 31, v132
	v_lshl_add_u64 v[0:1], v[132:133], 1, v[0:1]
	global_store_dwordx2 v[0:1], v[4:5], off offset:288
	s_branch .LBB0_879

.LBB0_1585:
	v_mov_b32_e32 v0, v154
	s_nop 0
	v_cmp_eq_u32_e32 vcc, 0, v0
	s_and_saveexec_b64 s[0:1], vcc
	s_cbranch_execz .LBB0_1587
	v_mov_b64_e32 v[2:3], s[8:9]
	global_atomic_add v0, v[2:3], v140, off offset:4 sc0
	v_mov_b32_e32 v2, s69
	s_waitcnt vmcnt(0) lgkmcnt(0)
	ds_write_b32 v2, v0

.LBB0_1594:
	s_and_b32 s50, s10, 3
	s_add_i32 s10, s45, 24
	s_lshl_b64 s[6:7], s[10:11], 17
	s_add_u32 s45, s54, s6
	s_addc_u32 s49, s55, s7
	s_lshl_b32 s6, s50, 7
	v_lshrrev_b32_e32 v18, 4, v2
	s_add_u32 s48, s45, s6
	s_addc_u32 s49, s49, 0
	s_lshl_b32 s10, s10, 2
	v_xor_b32_e32 v0, v18, v2
	s_or_b32 s10, s10, s50
	v_lshlrev_b32_e32 v0, 4, v0
	s_lshl_b64 s[50:51], s[10:11], 15
	v_and_b32_e32 v0, 0x70, v0
	s_add_u32 s50, s56, s50
	v_readfirstlane_b32 s10, v2
	v_ashrrev_i32_e32 v4, 3, v2
	v_lshl_add_u64 v[6:7], s[48:49], 0, v[0:1]
	v_ashrrev_i32_e32 v8, 5, v2
	v_and_b32_e32 v0, 31, v2
	s_addc_u32 s51, s57, s51
	s_lshl_b32 s10, s10, 4
	v_bitop3_b32 v0, v8, v0, 15 bitop3:0x6c
	v_ashrrev_i32_e32 v5, 31, v4
	s_and_b32 s10, s10, 0xfffffc00
	v_lshlrev_b32_e32 v0, 4, v0
	v_lshlrev_b64 v[4:5], 9, v[4:5]
	v_ashrrev_i32_e32 v9, 31, v8
	s_waitcnt vmcnt(0) lgkmcnt(0)
	s_barrier
	s_add_i32 s10, s10, 0
	v_lshl_add_u64 v[10:11], s[50:51], 0, v[0:1]
	v_lshl_add_u64 v[4:5], v[6:7], 0, v[4:5]
	s_mov_b32 s48, m0
	s_mov_b32 m0, s10
	s_nop 0
	global_load_lds_dwordx4 v[4:5], off
	s_mov_b32 m0, s48
	v_lshlrev_b64 v[6:7], 9, v[8:9]
	s_add_i32 s45, s10, 0x8000
	v_lshl_add_u64 v[6:7], v[10:11], 0, v[6:7]
	s_mov_b32 s48, m0
	s_mov_b32 m0, s45
	s_nop 0
	global_load_lds_dwordx4 v[6:7], off
	s_mov_b32 m0, s48
	v_lshl_add_u64 v[8:9], v[4:5], 0, s[12:13]
	s_add_i32 s45, s10, 0x2000
	s_mov_b32 s48, m0
	s_mov_b32 m0, s45
	s_nop 0
	global_load_lds_dwordx4 v[8:9], off
	s_mov_b32 m0, s48
	v_lshl_add_u64 v[8:9], v[6:7], 0, s[14:15]
	s_add_i32 s45, s10, 0xa000
	s_mov_b32 s48, m0
	s_mov_b32 m0, s45
	s_nop 0
	global_load_lds_dwordx4 v[8:9], off
	s_mov_b32 m0, s48
	v_lshl_add_u64 v[8:9], v[4:5], 0, s[16:17]
	s_add_i32 s45, s10, 0x4000
	s_mov_b32 s48, m0
	s_mov_b32 m0, s45
	s_nop 0
	global_load_lds_dwordx4 v[8:9], off
	s_mov_b32 m0, s48
	v_ashrrev_i32_e32 v3, 6, v2
	v_lshl_add_u64 v[8:9], v[6:7], 0, s[18:19]
	s_add_i32 s45, s10, 0xc000
	s_mov_b32 s48, m0
	s_mov_b32 m0, s45
	s_nop 0
	global_load_lds_dwordx4 v[8:9], off
	s_mov_b32 m0, s48
	v_lshl_add_u64 v[4:5], v[4:5], 0, s[20:21]
	s_add_i32 s45, s10, 0x6000
	s_mov_b32 s48, m0
	s_mov_b32 m0, s45
	s_nop 0
	global_load_lds_dwordx4 v[4:5], off
	s_mov_b32 m0, s48
	v_lshl_add_u64 v[4:5], v[6:7], 0, s[22:23]
	v_lshlrev_b32_e32 v0, 4, v3
	s_add_i32 s10, s10, 0xe000
	s_mov_b32 s45, m0
	s_mov_b32 m0, s10
	s_nop 0
	global_load_lds_dwordx4 v[4:5], off
	s_mov_b32 m0, s45
	v_and_b32_e32 v4, 48, v0
	v_and_b32_e32 v19, 15, v2
	v_cndmask_b32_e64 v0, v4, v0, s[0:1]
	s_mov_b32 s45, s11
	v_ashrrev_i32_e32 v5, 31, v0
	v_or_b32_e32 v4, v0, v19
	v_lshl_add_u64 v[4:5], v[4:5], 0, s[44:45]
	v_lshlrev_b64 v[4:5], 11, v[4:5]
	v_bfe_u32 v20, v2, 4, 2
	s_mov_b32 s7, s11
	v_lshl_add_u64 v[6:7], s[30:31], 0, v[4:5]
	v_lshl_add_u64 v[6:7], v[6:7], 0, s[6:7]
	v_lshlrev_b32_e32 v0, 4, v20
	v_lshl_add_u64 v[6:7], v[6:7], 0, v[0:1]
	global_load_dwordx4 v[14:17], v[6:7], off
	global_load_dwordx4 v[10:13], v[6:7], off offset:64
	v_lshrrev_b32_e32 v6, 1, v2
	v_bfe_u32 v7, v2, 1, 3
	v_cmp_gt_i32_e32 vcc, 4, v3
	v_lshl_add_u32 v3, v19, 7, 0
	v_mul_u32_u24_e32 v8, 0x180, v19
	v_and_b32_e32 v6, 8, v6
	v_bfe_u32 v9, v18, 1, 1
	v_bitop3_b32 v18, v18, v7, 3 bitop3:0x6c
	v_add3_u32 v6, v3, v8, v6
	v_lshlrev_b32_e32 v8, 4, v18
	v_bitop3_b32 v18, v9, v19, 2 bitop3:0x36
	v_lshlrev_b32_e32 v22, 4, v18
	v_bitop3_b32 v18, v9, v19, 6 bitop3:0x36
	v_lshlrev_b32_e32 v24, 4, v18
	v_bitop3_b32 v18, v9, v19, 8 bitop3:0x36
	v_lshlrev_b32_e32 v25, 4, v18
	v_bitop3_b32 v18, v9, v19, 10 bitop3:0x36
	v_lshlrev_b32_e32 v26, 4, v18
	v_bitop3_b32 v18, v9, v19, 12 bitop3:0x36
	v_lshlrev_b32_e32 v27, 4, v18
	v_bitop3_b32 v18, v9, v19, 14 bitop3:0x36
	v_lshlrev_b32_e32 v28, 4, v18
	v_bitop3_b32 v18, v9, v19, 16 bitop3:0x36
	v_lshlrev_b32_e32 v29, 4, v18
	v_bitop3_b32 v18, v9, v19, 18 bitop3:0x36
	v_lshlrev_b32_e32 v30, 4, v18
	v_bitop3_b32 v18, v9, v19, 20 bitop3:0x36
	v_lshlrev_b32_e32 v31, 4, v18
	v_bitop3_b32 v18, v9, v19, 22 bitop3:0x36
	v_bitop3_b32 v21, v9, v19, 4 bitop3:0x36
	v_lshlrev_b32_e32 v32, 4, v18
	v_bitop3_b32 v18, v9, v19, 24 bitop3:0x36
	v_lshlrev_b32_e32 v23, 4, v21
	v_lshlrev_b32_e32 v33, 4, v18
	v_bitop3_b32 v18, v9, v19, 26 bitop3:0x36
	v_or_b32_e32 v21, s6, v4
	v_bitop3_b32 v7, v20, v7, 4 bitop3:0x36
	v_bitop3_b32 v2, v9, v2, 15 bitop3:0x78
	v_lshlrev_b32_e32 v34, 4, v18
	v_bitop3_b32 v18, v9, v19, 28 bitop3:0x36
	v_bitop3_b32 v9, v9, v19, 30 bitop3:0x36
	v_or_b32_e32 v4, v21, v0
	v_lshlrev_b32_e32 v7, 4, v7
	v_lshlrev_b32_e32 v2, 4, v2
	s_waitcnt vmcnt(0) lgkmcnt(0)
	s_waitcnt vmcnt(0)
	v_lshlrev_b32_e32 v35, 4, v18
	v_lshlrev_b32_e32 v9, 4, v9
	v_lshl_add_u64 v[18:19], s[8:9], 0, v[4:5]
	v_lshl_or_b32 v4, v20, 3, v21
	v_lshl_add_u64 v[20:21], s[8:9], 0, v[4:5]
	v_add_u32_e32 v76, v3, v8
	v_add_u32_e32 v77, v3, v7
	v_add_u32_e32 v78, v6, v2
	v_add_u32_e32 v79, v6, v22
	v_add_u32_e32 v80, v6, v23
	v_add_u32_e32 v81, v6, v24
	v_add_u32_e32 v82, v6, v25
	v_add_u32_e32 v83, v6, v26
	v_add_u32_e32 v84, v6, v27
	v_add_u32_e32 v85, v6, v28
	v_add_u32_e32 v86, v6, v29
	v_add_u32_e32 v87, v6, v30
	v_add_u32_e32 v88, v6, v31
	v_add_u32_e32 v89, v6, v32
	v_add_u32_e32 v90, v6, v33
	v_add_u32_e32 v91, v6, v34
	v_add_u32_e32 v92, v6, v35
	v_add_u32_e32 v93, v6, v9
	v_mov_b64_e32 v[2:3], v[14:15]
	v_mov_b64_e32 v[6:7], v[10:11]
	s_or_b64 s[0:1], s[0:1], vcc
	s_lshl_b32 s10, s47, 18
	s_mov_b64 s[6:7], 0
	v_mov_b64_e32 v[4:5], v[16:17]
	v_mov_b64_e32 v[8:9], v[12:13]
	s_barrier
	s_branch .LBB0_1596

.LBB0_1596:
	s_cmp_ge_u32 s46, s47
	s_cbranch_scc1 .LBB0_1598
	v_lshl_add_u64 v[2:3], v[18:19], 0, s[6:7]
	v_add_co_u32_e32 v6, vcc, 0xc904000, v2
	s_nop 1
	v_addc_co_u32_e32 v7, vcc, 0, v3, vcc
	global_load_dwordx4 v[2:5], v[6:7], off offset:1536
	s_nop 0
	global_load_dwordx4 v[6:9], v[6:7], off offset:1600
.LBB0_1598:
	s_and_saveexec_b64 s[44:45], s[0:1]
	s_cbranch_execz .LBB0_1595
	ds_read_b128 v[22:25], v76
	ds_read_b128 v[26:29], v76 offset:2048
	ds_read_b128 v[30:33], v77
	ds_read_b128 v[34:37], v77 offset:2048
	s_waitcnt lgkmcnt(0)
	v_mfma_f32_16x16x32_bf16 v[22:25], v[22:25], v[14:17], 0
	v_mfma_f32_16x16x32_bf16 v[26:29], v[26:29], v[14:17], 0
	v_mfma_f32_16x16x32_bf16 v[22:25], v[30:33], v[10:13], v[22:25]
	ds_read_b128 v[30:33], v77 offset:4096
	ds_read_b128 v[38:41], v76 offset:4096
	ds_read_b128 v[42:45], v76 offset:6144
	v_mfma_f32_16x16x32_bf16 v[26:29], v[34:37], v[10:13], v[26:29]
	s_nop 3
	v_max_f32_e32 v0, v25, v25
	v_max_f32_e32 v34, v24, v24
	v_max_f32_e32 v0, v34, v0
	v_max3_f32 v0, v22, v23, v0
	v_max_f32_e32 v35, v29, v29
	v_max_f32_e32 v36, v28, v28
	v_max_f32_e32 v46, v36, v35
	s_waitcnt lgkmcnt(0)
	v_mfma_f32_16x16x32_bf16 v[34:37], v[38:41], v[14:17], 0
	v_max3_f32 v38, v26, v27, v46
	v_max3_f32 v0, v0, s25, v38
	ds_read_b128 v[38:41], v77 offset:6144
	v_mfma_f32_16x16x32_bf16 v[30:33], v[30:33], v[10:13], v[34:37]
	s_nop 7
	v_max_f32_e32 v34, v33, v33
	v_max_f32_e32 v35, v32, v32
	v_max_f32_e32 v46, v35, v34
	v_mfma_f32_16x16x32_bf16 v[34:37], v[42:45], v[14:17], 0
	v_max3_f32 v54, v30, v31, v46
	ds_read_b128 v[42:45], v76 offset:8192
	ds_read_b128 v[46:49], v77 offset:8192
	s_waitcnt lgkmcnt(0)
	v_mfma_f32_16x16x32_bf16 v[34:37], v[38:41], v[10:13], v[34:37]
	ds_read_b128 v[38:41], v76 offset:10240
	v_mfma_f32_16x16x32_bf16 v[42:45], v[42:45], v[14:17], 0
	v_mfma_f32_16x16x32_bf16 v[42:45], v[46:49], v[10:13], v[42:45]
	s_nop 4
	v_max_f32_e32 v50, v37, v37
	v_max_f32_e32 v51, v36, v36
	v_max_f32_e32 v50, v51, v50
	v_max3_f32 v55, v34, v35, v50
	ds_read_b128 v[50:53], v77 offset:10240
	v_max_f32_e32 v46, v45, v45
	v_max_f32_e32 v47, v44, v44
	v_max_f32_e32 v46, v47, v46
	v_max3_f32 v58, v42, v43, v46
	ds_read_b128 v[46:49], v76 offset:12288
	s_waitcnt lgkmcnt(0)
	v_mfma_f32_16x16x32_bf16 v[38:41], v[38:41], v[14:17], 0
	v_max3_f32 v0, v0, v54, v55
	v_mfma_f32_16x16x32_bf16 v[38:41], v[50:53], v[10:13], v[38:41]
	ds_read_b128 v[50:53], v77 offset:12288
	v_mfma_f32_16x16x32_bf16 v[46:49], v[46:49], v[14:17], 0
	s_nop 5
	v_max_f32_e32 v54, v41, v41
	v_max_f32_e32 v55, v40, v40
	v_max_f32_e32 v59, v55, v54
	ds_read_b128 v[54:57], v76 offset:14336
	v_max3_f32 v59, v38, v39, v59
	v_max3_f32 v0, v0, v58, v59
	ds_read_b128 v[58:61], v77 offset:14336
	s_waitcnt lgkmcnt(0)
	v_mfma_f32_16x16x32_bf16 v[46:49], v[50:53], v[10:13], v[46:49]
	s_nop 7
	v_max_f32_e32 v50, v49, v49
	v_max_f32_e32 v51, v48, v48
	v_max_f32_e32 v62, v51, v50
	v_mfma_f32_16x16x32_bf16 v[50:53], v[54:57], v[14:17], 0
	v_max3_f32 v66, v46, v47, v62
	ds_read_b128 v[54:57], v76 offset:16384
	ds_read_b128 v[62:65], v77 offset:16384
	v_mfma_f32_16x16x32_bf16 v[94:97], v[58:61], v[10:13], v[50:53]
	s_waitcnt lgkmcnt(0)
	v_mfma_f32_16x16x32_bf16 v[54:57], v[54:57], v[14:17], 0
	s_nop 1
	ds_read_b128 v[50:53], v76 offset:18432
	s_nop 2
	v_max_f32_e32 v58, v97, v97
	v_max_f32_e32 v59, v96, v96
	v_max_f32_e32 v58, v59, v58
	v_mfma_f32_16x16x32_bf16 v[98:101], v[62:65], v[10:13], v[54:57]
	v_max3_f32 v67, v94, v95, v58
	ds_read_b128 v[58:61], v77 offset:18432
	v_max3_f32 v0, v0, v66, v67
	s_nop 4
	v_max_f32_e32 v54, v101, v101
	v_max_f32_e32 v55, v100, v100
	v_max_f32_e32 v54, v55, v54
	v_max3_f32 v62, v98, v99, v54
	ds_read_b128 v[54:57], v76 offset:20480
	s_waitcnt lgkmcnt(0)
	v_mfma_f32_16x16x32_bf16 v[50:53], v[50:53], v[14:17], 0
	v_mfma_f32_16x16x32_bf16 v[102:105], v[58:61], v[10:13], v[50:53]
	v_mfma_f32_16x16x32_bf16 v[54:57], v[54:57], v[14:17], 0
	s_nop 5
	ds_read_b128 v[50:53], v77 offset:20480
	v_max_f32_e32 v58, v105, v105
	v_max_f32_e32 v59, v104, v104
	v_max_f32_e32 v63, v59, v58
	ds_read_b128 v[58:61], v76 offset:22528
	v_max3_f32 v63, v102, v103, v63
	v_max3_f32 v0, v0, v62, v63
	ds_read_b128 v[62:65], v77 offset:22528
	s_waitcnt lgkmcnt(0)
	v_mfma_f32_16x16x32_bf16 v[106:109], v[50:53], v[10:13], v[54:57]
	s_nop 7
	v_max_f32_e32 v50, v109, v109
	v_max_f32_e32 v51, v108, v108
	v_max_f32_e32 v54, v51, v50
	v_mfma_f32_16x16x32_bf16 v[50:53], v[58:61], v[14:17], 0
	v_max3_f32 v66, v106, v107, v54
	ds_read_b128 v[54:57], v76 offset:24576
	ds_read_b128 v[58:61], v77 offset:24576
	v_mfma_f32_16x16x32_bf16 v[110:113], v[62:65], v[10:13], v[50:53]
	s_nop 3
	ds_read_b128 v[50:53], v76 offset:26624
	s_waitcnt lgkmcnt(0)
	v_mfma_f32_16x16x32_bf16 v[54:57], v[54:57], v[14:17], 0
	s_nop 0
	v_max_f32_e32 v62, v113, v113
	v_max_f32_e32 v63, v112, v112
	v_max_f32_e32 v62, v63, v62
	v_max3_f32 v67, v110, v111, v62
	ds_read_b128 v[62:65], v77 offset:26624
	v_mfma_f32_16x16x32_bf16 v[114:117], v[58:61], v[10:13], v[54:57]
	v_max3_f32 v0, v0, v66, v67
	s_nop 1
	ds_read_b128 v[54:57], v76 offset:28672
	v_mfma_f32_16x16x32_bf16 v[50:53], v[50:53], v[14:17], 0
	s_nop 2
	v_max_f32_e32 v58, v117, v117
	v_max_f32_e32 v59, v116, v116
	v_max_f32_e32 v66, v59, v58
	s_waitcnt lgkmcnt(0)
	v_mfma_f32_16x16x32_bf16 v[118:121], v[62:65], v[10:13], v[50:53]
	ds_read_b128 v[58:61], v77 offset:28672
	v_max3_f32 v66, v114, v115, v66
	s_nop 0
	ds_read_b128 v[50:53], v76 offset:30720
	v_mfma_f32_16x16x32_bf16 v[54:57], v[54:57], v[14:17], 0
	s_nop 2
	v_max_f32_e32 v62, v121, v121
	v_max_f32_e32 v63, v120, v120
	v_max_f32_e32 v67, v63, v62
	ds_read_b128 v[62:65], v77 offset:30720
	s_waitcnt lgkmcnt(0)
	v_mfma_f32_16x16x32_bf16 v[14:17], v[50:53], v[14:17], 0
	v_mfma_f32_16x16x32_bf16 v[122:125], v[58:61], v[10:13], v[54:57]
	v_mfma_f32_16x16x32_bf16 v[12:15], v[62:65], v[10:13], v[14:17]
	s_nop 1
	v_max3_f32 v54, v118, v119, v67
	v_max3_f32 v0, v0, v66, v54
	s_nop 2
	v_max_f32_e32 v54, v125, v125
	v_max_f32_e32 v50, v124, v124
	v_max_f32_e32 v50, v50, v54
	v_max_f32_e32 v10, v15, v15
	v_max_f32_e32 v11, v14, v14
	v_max_f32_e32 v10, v11, v10
	v_max3_f32 v50, v122, v123, v50
	v_max3_f32 v10, v12, v13, v10
	v_max3_f32 v0, v0, v50, v10
	ds_bpermute_b32 v10, v146, v0
	s_waitcnt lgkmcnt(0)
	v_max_f32_e32 v10, v10, v10
	v_max_f32_e32 v0, v0, v10
	ds_bpermute_b32 v10, v147, v0
	s_waitcnt lgkmcnt(0)
	v_max_f32_e32 v10, v10, v10
	v_max_f32_e32 v11, v0, v10
	v_mov_b32_e32 v10, v15
	v_pk_mul_f32 v[126:127], v[10:11], s[24:25] op_sel_hi:[1,0]
	s_nop 0
	v_fma_f32 v0, v22, s24, -v127
	v_exp_f32_e32 v70, v0
	v_fma_f32 v0, v23, s24, -v127
	v_exp_f32_e32 v71, v0
	v_fma_f32 v0, v24, s24, -v127
	v_exp_f32_e32 v128, v0
	v_fma_f32 v0, v25, s24, -v127
	v_exp_f32_e32 v129, v0
	v_fma_f32 v10, v26, s24, -v127
	v_add_f32_e32 v0, 0, v70
	v_exp_f32_e32 v72, v10
	v_fma_f32 v10, v27, s24, -v127
	v_add_f32_e32 v0, v71, v0
	v_exp_f32_e32 v73, v10
	v_fma_f32 v10, v28, s24, -v127
	v_add_f32_e32 v0, v128, v0
	v_exp_f32_e32 v74, v10
	v_fma_f32 v10, v29, s24, -v127
	v_add_f32_e32 v0, v129, v0
	v_exp_f32_e32 v75, v10
	v_fma_f32 v10, v30, s24, -v127
	v_add_f32_e32 v0, v72, v0
	v_exp_f32_e32 v62, v10
	v_fma_f32 v10, v31, s24, -v127
	v_add_f32_e32 v0, v73, v0
	v_exp_f32_e32 v63, v10
	v_fma_f32 v10, v32, s24, -v127
	v_add_f32_e32 v0, v74, v0
	v_exp_f32_e32 v68, v10
	v_fma_f32 v10, v33, s24, -v127
	v_add_f32_e32 v0, v75, v0
	v_exp_f32_e32 v69, v10
	v_fma_f32 v10, v34, s24, -v127
	v_add_f32_e32 v0, v62, v0
	v_exp_f32_e32 v64, v10
	v_fma_f32 v10, v35, s24, -v127
	v_add_f32_e32 v0, v63, v0
	v_exp_f32_e32 v65, v10
	v_fma_f32 v10, v36, s24, -v127
	v_add_f32_e32 v0, v68, v0
	v_exp_f32_e32 v66, v10
	v_fma_f32 v10, v37, s24, -v127
	v_add_f32_e32 v0, v69, v0
	v_exp_f32_e32 v67, v10
	v_fma_f32 v10, v42, s24, -v127
	v_add_f32_e32 v0, v64, v0
	v_exp_f32_e32 v54, v10
	v_fma_f32 v10, v43, s24, -v127
	v_add_f32_e32 v0, v65, v0
	v_exp_f32_e32 v55, v10
	v_fma_f32 v10, v44, s24, -v127
	v_add_f32_e32 v0, v66, v0
	v_exp_f32_e32 v60, v10
	v_fma_f32 v10, v45, s24, -v127
	v_add_f32_e32 v0, v67, v0
	v_exp_f32_e32 v61, v10
	v_fma_f32 v10, v38, s24, -v127
	v_add_f32_e32 v0, v54, v0
	v_exp_f32_e32 v56, v10
	v_fma_f32 v10, v39, s24, -v127
	v_add_f32_e32 v0, v55, v0
	v_exp_f32_e32 v57, v10
	v_fma_f32 v10, v40, s24, -v127
	v_add_f32_e32 v0, v60, v0
	v_exp_f32_e32 v58, v10
	v_fma_f32 v10, v41, s24, -v127
	v_add_f32_e32 v0, v61, v0
	v_exp_f32_e32 v59, v10
	v_fma_f32 v10, v46, s24, -v127
	v_add_f32_e32 v0, v56, v0
	v_exp_f32_e32 v46, v10
	v_fma_f32 v10, v47, s24, -v127
	v_add_f32_e32 v0, v57, v0
	v_exp_f32_e32 v47, v10
	v_fma_f32 v10, v48, s24, -v127
	v_add_f32_e32 v0, v58, v0
	v_exp_f32_e32 v52, v10
	v_fma_f32 v10, v49, s24, -v127
	v_add_f32_e32 v0, v59, v0
	v_exp_f32_e32 v53, v10
	v_fma_f32 v10, v94, s24, -v127
	v_add_f32_e32 v0, v46, v0
	v_exp_f32_e32 v48, v10
	v_fma_f32 v10, v95, s24, -v127
	v_add_f32_e32 v0, v47, v0
	v_exp_f32_e32 v49, v10
	v_fma_f32 v10, v96, s24, -v127
	v_add_f32_e32 v0, v52, v0
	v_exp_f32_e32 v50, v10
	v_fma_f32 v10, v97, s24, -v127
	v_add_f32_e32 v0, v53, v0
	v_exp_f32_e32 v51, v10
	v_fma_f32 v10, v98, s24, -v127
	v_add_f32_e32 v0, v48, v0
	v_exp_f32_e32 v38, v10
	v_fma_f32 v10, v99, s24, -v127
	v_add_f32_e32 v0, v49, v0
	v_exp_f32_e32 v39, v10
	v_fma_f32 v10, v100, s24, -v127
	v_add_f32_e32 v0, v50, v0
	v_exp_f32_e32 v44, v10
	v_fma_f32 v10, v101, s24, -v127
	v_add_f32_e32 v0, v51, v0
	v_exp_f32_e32 v45, v10
	v_fma_f32 v10, v102, s24, -v127
	v_add_f32_e32 v0, v38, v0
	v_exp_f32_e32 v40, v10
	v_fma_f32 v10, v103, s24, -v127
	v_add_f32_e32 v0, v39, v0
	v_exp_f32_e32 v41, v10
	v_fma_f32 v10, v104, s24, -v127
	v_add_f32_e32 v0, v44, v0
	v_exp_f32_e32 v42, v10
	v_fma_f32 v10, v105, s24, -v127
	v_add_f32_e32 v0, v45, v0
	v_exp_f32_e32 v43, v10
	v_fma_f32 v10, v106, s24, -v127
	v_add_f32_e32 v0, v40, v0
	v_exp_f32_e32 v30, v10
	v_fma_f32 v10, v107, s24, -v127
	v_add_f32_e32 v0, v41, v0
	v_exp_f32_e32 v31, v10
	v_fma_f32 v10, v108, s24, -v127
	v_add_f32_e32 v0, v42, v0
	v_exp_f32_e32 v36, v10
	v_fma_f32 v10, v109, s24, -v127
	v_add_f32_e32 v0, v43, v0
	v_exp_f32_e32 v37, v10
	v_fma_f32 v10, v110, s24, -v127
	v_add_f32_e32 v0, v30, v0
	v_exp_f32_e32 v32, v10
	v_fma_f32 v10, v111, s24, -v127
	v_add_f32_e32 v0, v31, v0
	v_exp_f32_e32 v33, v10
	v_fma_f32 v10, v112, s24, -v127
	v_add_f32_e32 v0, v36, v0
	v_exp_f32_e32 v34, v10
	v_fma_f32 v10, v113, s24, -v127
	v_add_f32_e32 v0, v37, v0
	v_exp_f32_e32 v35, v10
	v_fma_f32 v10, v114, s24, -v127
	v_add_f32_e32 v0, v32, v0
	v_exp_f32_e32 v22, v10
	v_fma_f32 v10, v115, s24, -v127
	v_add_f32_e32 v0, v33, v0
	v_exp_f32_e32 v23, v10
	v_fma_f32 v10, v116, s24, -v127
	v_add_f32_e32 v0, v34, v0
	v_exp_f32_e32 v28, v10
	v_fma_f32 v10, v117, s24, -v127
	v_add_f32_e32 v0, v35, v0
	v_exp_f32_e32 v29, v10
	v_fma_f32 v10, v118, s24, -v127
	v_add_f32_e32 v0, v22, v0
	v_exp_f32_e32 v24, v10
	v_fma_f32 v10, v119, s24, -v127
	v_add_f32_e32 v0, v23, v0
	v_exp_f32_e32 v25, v10
	v_fma_f32 v10, v120, s24, -v127
	v_add_f32_e32 v0, v28, v0
	v_exp_f32_e32 v26, v10
	v_fma_f32 v10, v121, s24, -v127
	v_add_f32_e32 v0, v29, v0
	v_exp_f32_e32 v27, v10
	v_fma_f32 v10, v122, s24, -v127
	v_add_f32_e32 v0, v24, v0
	v_exp_f32_e32 v10, v10
	v_fma_f32 v11, v123, s24, -v127
	v_add_f32_e32 v0, v25, v0
	v_exp_f32_e32 v11, v11
	v_fma_f32 v15, v124, s24, -v127
	v_add_f32_e32 v0, v26, v0
	v_exp_f32_e32 v16, v15
	v_fma_f32 v15, v125, s24, -v127
	v_add_f32_e32 v0, v27, v0
	v_exp_f32_e32 v17, v15
	v_fma_f32 v12, v12, s24, -v127
	v_add_f32_e32 v0, v10, v0
	v_exp_f32_e32 v12, v12
	v_fma_f32 v13, v13, s24, -v127
	v_add_f32_e32 v0, v11, v0
	v_exp_f32_e32 v13, v13
	v_fma_f32 v14, v14, s24, -v127
	v_add_f32_e32 v0, v16, v0
	v_exp_f32_e32 v14, v14
	v_sub_f32_e32 v15, v126, v127
	v_add_f32_e32 v0, v17, v0
	v_exp_f32_e32 v15, v15
	v_add_f32_e32 v0, v12, v0
	v_add_f32_e32 v0, v13, v0
	v_add_f32_e32 v0, v14, v0
	v_add_f32_e32 v0, v15, v0
	ds_bpermute_b32 v94, v146, v0
	s_waitcnt lgkmcnt(0)
	v_add_f32_e32 v0, v0, v94
	ds_bpermute_b32 v94, v147, v0
	s_waitcnt lgkmcnt(0)
	v_add_f32_e32 v0, v0, v94
	v_div_scale_f32 v94, s[48:49], v0, v0, 1.0
	v_rcp_f32_e32 v95, v94
	s_nop 0
	v_fma_f32 v96, -v94, v95, 1.0
	v_fmac_f32_e32 v95, v96, v95
	v_div_scale_f32 v96, vcc, 1.0, v0, 1.0
	v_mul_f32_e32 v97, v96, v95
	v_fma_f32 v98, -v94, v97, v96
	v_fmac_f32_e32 v97, v98, v95
	v_fma_f32 v94, -v94, v97, v96
	v_div_fmas_f32 v94, v94, v95, v97
	v_div_fixup_f32 v0, v94, v0, 1.0
	ds_read2st64_b64 v[94:97], v78 offset0:64 offset1:80
	ds_read2st64_b64 v[98:101], v79 offset0:64 offset1:80
	v_pk_mul_f32 v[104:105], v[128:129], v[0:1] op_sel_hi:[1,0]
	v_pk_mul_f32 v[102:103], v[70:71], v[0:1] op_sel_hi:[1,0]
	v_pk_mul_f32 v[106:107], v[72:73], v[0:1] op_sel_hi:[1,0]
	s_waitcnt lgkmcnt(0)
	v_mov_b32_e32 v70, v94
	v_mov_b32_e32 v71, v95
	v_mov_b32_e32 v72, v98
	v_mov_b32_e32 v73, v99
	v_cvt_pk_bf16_f32 v102, v102, v103
	v_cvt_pk_bf16_f32 v103, v104, v105
	v_cvt_pk_bf16_f32 v104, v106, v107
	v_mov_b32_e32 v98, v96
	v_mov_b32_e32 v99, v97
	ds_read2st64_b64 v[94:97], v78 offset0:96 offset1:112
	ds_read2st64_b64 v[106:109], v79 offset0:96 offset1:112
	v_pk_mul_f32 v[74:75], v[74:75], v[0:1] op_sel_hi:[1,0]
	v_pk_mul_f32 v[116:117], v[64:65], v[0:1] op_sel_hi:[1,0]
	v_cvt_pk_bf16_f32 v105, v74, v75
	s_waitcnt lgkmcnt(0)
	v_mov_b32_e32 v110, v94
	v_mov_b32_e32 v111, v95
	v_mov_b32_e32 v112, v106
	v_mov_b32_e32 v113, v107
	v_mov_b32_e32 v106, v96
	v_mov_b32_e32 v107, v97
	v_mfma_f32_16x16x32_bf16 v[70:73], v[70:73], v[102:105], 0
	v_mul_f32_e64 v74, v62, v0
	v_mul_f32_e64 v75, v63, v0
	v_pk_mul_f32 v[68:69], v[68:69], v[0:1] op_sel_hi:[1,0]
	v_pk_mul_f32 v[114:115], v[66:67], v[0:1] op_sel_hi:[1,0]
	v_mfma_f32_16x16x32_bf16 v[98:101], v[98:101], v[102:105], 0
	v_cvt_pk_bf16_f32 v66, v74, v75
	v_cvt_pk_bf16_f32 v67, v68, v69
	v_cvt_pk_bf16_f32 v68, v116, v117
	v_mfma_f32_16x16x32_bf16 v[110:113], v[110:113], v[102:105], 0
	v_cvt_pk_bf16_f32 v69, v114, v115
	v_pk_mul_f32 v[74:75], v[54:55], v[0:1] op_sel_hi:[1,0]
	v_pk_mul_f32 v[60:61], v[60:61], v[0:1] op_sel_hi:[1,0]
	v_mfma_f32_16x16x32_bf16 v[94:97], v[106:109], v[102:105], 0
	ds_read2st64_b64 v[102:105], v80 offset0:64 offset1:80
	ds_read2st64_b64 v[106:109], v81 offset0:64 offset1:80
	v_pk_mul_f32 v[52:53], v[52:53], v[0:1] op_sel_hi:[1,0]
	v_pk_mul_f32 v[44:45], v[44:45], v[0:1] op_sel_hi:[1,0]
	v_pk_mul_f32 v[36:37], v[36:37], v[0:1] op_sel_hi:[1,0]
	s_waitcnt lgkmcnt(0)
	v_mov_b32_e32 v62, v102
	v_mov_b32_e32 v63, v103
	v_mov_b32_e32 v64, v106
	v_mov_b32_e32 v65, v107
	v_mov_b32_e32 v106, v104
	v_mov_b32_e32 v107, v105
	v_mfma_f32_16x16x32_bf16 v[62:65], v[62:65], v[66:69], v[70:73]
	s_nop 2
	ds_read2st64_b64 v[70:73], v80 offset0:96 offset1:112
	ds_read2st64_b64 v[102:105], v81 offset0:96 offset1:112
	v_pk_mul_f32 v[28:29], v[28:29], v[0:1] op_sel_hi:[1,0]
	v_pk_mul_f32 v[16:17], v[16:17], v[0:1] op_sel_hi:[1,0]
	v_mfma_f32_16x16x32_bf16 v[98:101], v[106:109], v[66:69], v[98:101]
	s_waitcnt lgkmcnt(0)
	v_mov_b32_e32 v106, v70
	v_mov_b32_e32 v107, v71
	v_mov_b32_e32 v108, v102
	v_mov_b32_e32 v109, v103
	v_mov_b32_e32 v102, v72
	v_mov_b32_e32 v103, v73
	v_mfma_f32_16x16x32_bf16 v[106:109], v[106:109], v[66:69], v[110:113]
	ds_read2st64_b64 v[70:73], v82 offset0:64 offset1:80
	s_waitcnt lgkmcnt(0)
	v_mov_b32_e32 v54, v70
	v_mfma_f32_16x16x32_bf16 v[66:69], v[102:105], v[66:69], v[94:97]
	v_mul_f32_e64 v104, v56, v0
	v_mul_f32_e64 v105, v57, v0
	v_mov_b32_e32 v55, v71
	v_pk_mul_f32 v[102:103], v[58:59], v[0:1] op_sel_hi:[1,0]
	ds_read2st64_b64 v[94:97], v83 offset0:64 offset1:80
	v_cvt_pk_bf16_f32 v58, v74, v75
	v_cvt_pk_bf16_f32 v59, v60, v61
	v_cvt_pk_bf16_f32 v60, v104, v105
	v_cvt_pk_bf16_f32 v61, v102, v103
	s_waitcnt lgkmcnt(0)
	v_mov_b32_e32 v56, v94
	v_mov_b32_e32 v57, v95
	v_mov_b32_e32 v94, v72
	v_mov_b32_e32 v95, v73
	v_mfma_f32_16x16x32_bf16 v[54:57], v[54:57], v[58:61], v[62:65]
	s_nop 2
	ds_read2st64_b64 v[62:65], v82 offset0:96 offset1:112
	ds_read2st64_b64 v[70:73], v83 offset0:96 offset1:112
	v_pk_mul_f32 v[74:75], v[48:49], v[0:1] op_sel_hi:[1,0]
	v_mfma_f32_16x16x32_bf16 v[94:97], v[94:97], v[58:61], v[98:101]
	s_waitcnt lgkmcnt(0)
	s_nop 1
	v_mov_b32_e32 v98, v62
	v_mov_b32_e32 v99, v63
	v_mov_b32_e32 v100, v70
	v_mov_b32_e32 v101, v71
	v_mov_b32_e32 v70, v64
	v_mov_b32_e32 v71, v65
	v_mfma_f32_16x16x32_bf16 v[98:101], v[98:101], v[58:61], v[106:109]
	ds_read2st64_b64 v[62:65], v84 offset0:64 offset1:80
	v_mfma_f32_16x16x32_bf16 v[58:61], v[70:73], v[58:61], v[66:69]
	v_mul_f32_e64 v70, v46, v0
	v_mul_f32_e64 v71, v47, v0
	s_waitcnt lgkmcnt(0)
	v_mov_b32_e32 v46, v62
	v_mov_b32_e32 v47, v63
	ds_read2st64_b64 v[66:69], v85 offset0:64 offset1:80
	v_pk_mul_f32 v[72:73], v[50:51], v[0:1] op_sel_hi:[1,0]
	v_cvt_pk_bf16_f32 v50, v70, v71
	v_cvt_pk_bf16_f32 v51, v52, v53
	v_cvt_pk_bf16_f32 v52, v74, v75
	s_waitcnt lgkmcnt(0)
	v_mov_b32_e32 v48, v66
	v_mov_b32_e32 v49, v67
	v_cvt_pk_bf16_f32 v53, v72, v73
	v_mov_b32_e32 v66, v64
	v_mov_b32_e32 v67, v65
	v_mfma_f32_16x16x32_bf16 v[46:49], v[46:49], v[50:53], v[54:57]
	s_nop 2
	ds_read2st64_b64 v[54:57], v84 offset0:96 offset1:112
	ds_read2st64_b64 v[62:65], v85 offset0:96 offset1:112
	v_pk_mul_f32 v[74:75], v[40:41], v[0:1] op_sel_hi:[1,0]
	s_waitcnt lgkmcnt(0)
	v_mov_b32_e32 v70, v54
	v_mov_b32_e32 v71, v55
	v_mov_b32_e32 v72, v62
	v_mov_b32_e32 v73, v63
	v_mov_b32_e32 v62, v56
	v_mov_b32_e32 v63, v57
	v_mfma_f32_16x16x32_bf16 v[66:69], v[66:69], v[50:53], v[94:97]
	ds_read2st64_b64 v[54:57], v86 offset0:64 offset1:80
	v_mfma_f32_16x16x32_bf16 v[70:73], v[70:73], v[50:53], v[98:101]
	v_mfma_f32_16x16x32_bf16 v[50:53], v[62:65], v[50:53], v[58:61]
	v_mul_f32_e64 v62, v38, v0
	v_mul_f32_e64 v63, v39, v0
	s_waitcnt lgkmcnt(0)
	v_mov_b32_e32 v38, v54
	v_mov_b32_e32 v39, v55
	ds_read2st64_b64 v[58:61], v87 offset0:64 offset1:80
	v_pk_mul_f32 v[64:65], v[42:43], v[0:1] op_sel_hi:[1,0]
	v_cvt_pk_bf16_f32 v42, v62, v63
	v_cvt_pk_bf16_f32 v43, v44, v45
	v_cvt_pk_bf16_f32 v44, v74, v75
	s_waitcnt lgkmcnt(0)
	v_mov_b32_e32 v40, v58
	v_mov_b32_e32 v41, v59
	v_cvt_pk_bf16_f32 v45, v64, v65
	v_mov_b32_e32 v58, v56
	v_mov_b32_e32 v59, v57
	v_mfma_f32_16x16x32_bf16 v[38:41], v[38:41], v[42:45], v[46:49]
	s_nop 2
	ds_read2st64_b64 v[46:49], v86 offset0:96 offset1:112
	ds_read2st64_b64 v[54:57], v87 offset0:96 offset1:112
	s_waitcnt lgkmcnt(0)
	v_mov_b32_e32 v62, v46
	v_mov_b32_e32 v63, v47
	v_mov_b32_e32 v64, v54
	v_mov_b32_e32 v65, v55
	v_mov_b32_e32 v54, v48
	v_mov_b32_e32 v55, v49
	v_mfma_f32_16x16x32_bf16 v[58:61], v[58:61], v[42:45], v[66:69]
	ds_read2st64_b64 v[46:49], v88 offset0:64 offset1:80
	v_mfma_f32_16x16x32_bf16 v[62:65], v[62:65], v[42:45], v[70:73]
	s_nop 0
	v_mul_f32_e64 v66, v32, v0
	v_mul_f32_e64 v67, v33, v0
	v_mfma_f32_16x16x32_bf16 v[42:45], v[54:57], v[42:45], v[50:53]
	v_mul_f32_e64 v54, v30, v0
	v_mul_f32_e64 v55, v31, v0
	s_waitcnt lgkmcnt(0)
	v_mov_b32_e32 v30, v46
	v_mov_b32_e32 v31, v47
	ds_read2st64_b64 v[50:53], v89 offset0:64 offset1:80
	v_pk_mul_f32 v[56:57], v[34:35], v[0:1] op_sel_hi:[1,0]
	v_cvt_pk_bf16_f32 v34, v54, v55
	v_cvt_pk_bf16_f32 v35, v36, v37
	v_cvt_pk_bf16_f32 v36, v66, v67
	s_waitcnt lgkmcnt(0)
	v_mov_b32_e32 v32, v50
	v_mov_b32_e32 v33, v51
	v_cvt_pk_bf16_f32 v37, v56, v57
	v_mov_b32_e32 v50, v48
	v_mov_b32_e32 v51, v49
	v_mfma_f32_16x16x32_bf16 v[30:33], v[30:33], v[34:37], v[38:41]
	s_nop 2
	ds_read2st64_b64 v[38:41], v88 offset0:96 offset1:112
	ds_read2st64_b64 v[46:49], v89 offset0:96 offset1:112
	s_waitcnt lgkmcnt(0)
	v_mov_b32_e32 v54, v38
	v_mov_b32_e32 v55, v39
	v_mov_b32_e32 v56, v46
	v_mov_b32_e32 v57, v47
	v_mov_b32_e32 v46, v40
	v_mov_b32_e32 v47, v41
	v_mfma_f32_16x16x32_bf16 v[50:53], v[50:53], v[34:37], v[58:61]
	ds_read2st64_b64 v[38:41], v90 offset0:64 offset1:80
	v_mfma_f32_16x16x32_bf16 v[54:57], v[54:57], v[34:37], v[62:65]
	s_nop 0
	v_mul_f32_e64 v58, v24, v0
	v_mul_f32_e64 v59, v25, v0
	v_mfma_f32_16x16x32_bf16 v[34:37], v[46:49], v[34:37], v[42:45]
	v_mul_f32_e64 v46, v22, v0
	v_mul_f32_e64 v47, v23, v0
	s_waitcnt lgkmcnt(0)
	v_mov_b32_e32 v22, v38
	v_mov_b32_e32 v23, v39
	ds_read2st64_b64 v[42:45], v91 offset0:64 offset1:80
	v_pk_mul_f32 v[48:49], v[26:27], v[0:1] op_sel_hi:[1,0]
	v_cvt_pk_bf16_f32 v26, v46, v47
	v_cvt_pk_bf16_f32 v27, v28, v29
	v_cvt_pk_bf16_f32 v28, v58, v59
	s_waitcnt lgkmcnt(0)
	v_mov_b32_e32 v24, v42
	v_mov_b32_e32 v25, v43
	v_cvt_pk_bf16_f32 v29, v48, v49
	v_mov_b32_e32 v42, v40
	v_mov_b32_e32 v43, v41
	v_mfma_f32_16x16x32_bf16 v[22:25], v[22:25], v[26:29], v[30:33]
	s_nop 2
	ds_read2st64_b64 v[30:33], v90 offset0:96 offset1:112
	ds_read2st64_b64 v[38:41], v91 offset0:96 offset1:112
	s_waitcnt lgkmcnt(0)
	v_mov_b32_e32 v46, v30
	v_mov_b32_e32 v47, v31
	v_mov_b32_e32 v48, v38
	v_mov_b32_e32 v49, v39
	v_mov_b32_e32 v38, v32
	v_mov_b32_e32 v39, v33
	v_mfma_f32_16x16x32_bf16 v[42:45], v[42:45], v[26:29], v[50:53]
	ds_read2st64_b64 v[30:33], v92 offset0:64 offset1:80
	v_mfma_f32_16x16x32_bf16 v[46:49], v[46:49], v[26:29], v[54:57]
	s_nop 0
	v_mul_f32_e64 v50, v12, v0
	v_mul_f32_e64 v51, v13, v0
	v_mfma_f32_16x16x32_bf16 v[26:29], v[38:41], v[26:29], v[34:37]
	v_mul_f32_e64 v38, v10, v0
	v_mul_f32_e64 v39, v11, v0
	s_waitcnt lgkmcnt(0)
	v_mov_b32_e32 v10, v30
	v_mov_b32_e32 v11, v31
	ds_read2st64_b64 v[34:37], v93 offset0:64 offset1:80
	v_pk_mul_f32 v[40:41], v[14:15], v[0:1] op_sel_hi:[1,0]
	v_cvt_pk_bf16_f32 v14, v38, v39
	v_cvt_pk_bf16_f32 v15, v16, v17
	v_cvt_pk_bf16_f32 v16, v50, v51
	s_waitcnt lgkmcnt(0)
	v_mov_b32_e32 v12, v34
	v_mov_b32_e32 v13, v35
	v_cvt_pk_bf16_f32 v17, v40, v41
	v_mov_b32_e32 v34, v32
	v_mov_b32_e32 v35, v33
	v_mfma_f32_16x16x32_bf16 v[10:13], v[10:13], v[14:17], v[22:25]
	s_nop 2
	ds_read2st64_b64 v[22:25], v92 offset0:96 offset1:112
	ds_read2st64_b64 v[30:33], v93 offset0:96 offset1:112
	s_nop 2
	v_cvt_pk_bf16_f32 v10, v10, v11
	s_waitcnt lgkmcnt(0)
	v_mov_b32_e32 v38, v22
	v_mov_b32_e32 v39, v23
	v_mov_b32_e32 v40, v30
	v_mov_b32_e32 v41, v31
	v_mov_b32_e32 v30, v24
	v_mov_b32_e32 v31, v25
	v_mfma_f32_16x16x32_bf16 v[34:37], v[34:37], v[14:17], v[42:45]
	v_lshl_add_u64 v[22:23], v[20:21], 0, s[6:7]
	v_cvt_pk_bf16_f32 v11, v12, v13
	v_add_co_u32_e32 v12, vcc, s52, v22
	v_mfma_f32_16x16x32_bf16 v[38:41], v[38:41], v[14:17], v[46:49]
	s_nop 0
	v_addc_co_u32_e32 v13, vcc, 0, v23, vcc
	global_store_dwordx2 v[12:13], v[10:11], off offset:1536
	v_mfma_f32_16x16x32_bf16 v[14:17], v[30:33], v[14:17], v[26:29]
	v_cvt_pk_bf16_f32 v10, v34, v35
	v_cvt_pk_bf16_f32 v11, v36, v37
	global_store_dwordx2 v[12:13], v[10:11], off offset:1568
	s_nop 0
	v_cvt_pk_bf16_f32 v10, v38, v39
	v_cvt_pk_bf16_f32 v11, v40, v41
	global_store_dwordx2 v[12:13], v[10:11], off offset:1600
	s_nop 0
	v_cvt_pk_bf16_f32 v10, v14, v15
	v_cvt_pk_bf16_f32 v11, v16, v17
	global_store_dwordx2 v[12:13], v[10:11], off offset:1632
	s_branch .LBB0_1595

.LBB0_1614:
	s_lshl_b32 s5, s49, 1
	s_add_i32 s10, s5, 2
	v_mov_b32_e32 v36, v154
	s_and_b64 s[72:73], s[0:1], exec
	s_cselect_b32 s47, s10, 17
	v_ashrrev_i32_e32 v28, 6, v36
	s_or_b32 s5, s5, 1
	v_lshlrev_b32_e32 v2, 4, v28
	s_and_b64 s[72:73], s[0:1], exec
	v_and_b32_e32 v3, 48, v2
	s_cselect_b32 s5, s5, 17
	v_and_b32_e32 v0, 15, v36
	s_ashr_i32 s49, s48, 31
	v_cndmask_b32_e64 v2, v3, v2, s[0:1]
	v_ashrrev_i32_e32 v3, 31, v2
	v_lshl_add_u64 v[4:5], v[0:1], 0, s[48:49]
	v_lshl_add_u64 v[2:3], v[4:5], 0, v[2:3]
	s_and_b64 s[0:1], s[0:1], exec
	v_lshlrev_b64 v[110:111], 11, v[2:3]
	v_bfe_u32 v145, v36, 4, 2
	s_cselect_b32 s0, s10, 0
	v_lshl_add_u64 v[2:3], s[28:29], 0, v[110:111]
	s_ashr_i32 s77, s76, 31
	v_lshl_add_u64 v[2:3], s[76:77], 1, v[2:3]
	v_lshlrev_b32_e32 v108, 4, v145
	v_mov_b32_e32 v109, v1
	v_lshl_add_u64 v[2:3], v[2:3], 0, v[108:109]
	global_load_dwordx4 v[4:7], v[2:3], off
	global_load_dwordx4 v[8:11], v[2:3], off offset:64
	global_load_dwordx4 v[12:15], v[2:3], off offset:128
	global_load_dwordx4 v[16:19], v[2:3], off offset:192
	v_mov_b64_e32 v[2:3], s[50:51]
	v_ashrrev_i32_e32 v20, 4, v36
	v_ashrrev_i32_e32 v22, 3, v36
	v_readfirstlane_b32 s10, v36
	v_mad_i64_i32 v[24:25], s[50:51], s46, v22, 0
	v_xor_b32_e32 v22, v22, v36
	v_mad_i64_i32 v[2:3], s[50:51], v20, s53, v[2:3]
	v_xor_b32_e32 v26, v20, v36
	v_lshlrev_b32_e32 v22, 4, v22
	v_mov_b32_e32 v29, s5
	s_lshl_b32 s5, s10, 4
	s_add_i32 s50, s47, -1
	v_mov_b32_e32 v23, v1
	v_lshlrev_b32_e32 v20, 4, v26
	v_lshl_add_u64 v[24:25], v[24:25], 1, s[6:7]
	v_and_b32_e32 v22, 0x70, v22
	s_and_b32 s51, s5, 0xfffffc00
	s_min_u32 s5, s50, 2
	v_mov_b32_e32 v21, v1
	s_mov_b32 s49, s11
	v_and_b32_e32 v20, 0xf0, v20
	v_lshl_add_u64 v[114:115], v[24:25], 0, v[22:23]
	s_lshl_b32 s48, s5, 7
	v_lshl_add_u64 v[112:113], v[2:3], 0, v[20:21]
	s_add_i32 s51, s51, 0
	v_lshl_add_u64 v[32:33], v[114:115], 0, s[48:49]
	v_lshl_add_u64 v[2:3], v[112:113], 0, s[78:79]
	v_mov_b32_e32 v30, s0
	s_mul_i32 s0, s5, 0x18000
	s_add_i32 s5, s51, 0x2000
	s_lshl_b32 s10, s46, 7
	s_add_i32 s6, s51, 0x4000
	v_lshl_add_u64 v[26:27], v[114:115], 0, s[10:11]
	s_add_i32 s7, s51, 0x6000
	v_lshl_add_u64 v[20:21], v[112:113], 0, s[20:21]
	s_add_i32 s47, s51, 0x8000
	v_lshl_add_u64 v[24:25], v[112:113], 0, s[82:83]
	s_add_i32 s72, s51, 0xa000
	v_lshl_add_u64 v[22:23], v[114:115], 0, s[80:81]
	v_cmp_gt_i32_e32 vcc, 4, v28
	s_add_i32 s73, s51, 0xc000
	s_mov_b32 s1, s11
	v_cndmask_b32_e32 v109, v30, v29, vcc
	v_lshl_add_u64 v[28:29], v[26:27], 0, s[80:81]
	s_add_i32 s74, s51, 0xe000
	v_lshl_add_u64 v[30:31], v[112:113], 0, s[0:1]
	s_add_i32 s0, s51, 0x10000
	s_add_i32 s1, s51, 0x12000
	v_lshl_add_u64 v[34:35], v[30:31], 0, s[78:79]
	s_add_i32 s48, s51, 0x14000
	v_xor_b32_e32 v95, v145, v0
	v_bitop3_b32 v94, v145, v0, 4 bitop3:0x36
	v_lshlrev_b32_e32 v152, 8, v0
	v_lshlrev_b32_e32 v153, 7, v0
	v_lshlrev_b32_e32 v155, 4, v95
	v_lshlrev_b32_e32 v156, 4, v94
	s_waitcnt vmcnt(0) lgkmcnt(0)
	s_waitcnt vmcnt(0) lgkmcnt(0)
	s_barrier
	s_mov_b32 s49, m0
	s_mov_b32 m0, s51
	s_nop 0
	global_load_lds_dwordx4 v[112:113], off
	s_mov_b32 m0, s49
	s_nop 0
	s_mov_b32 s49, m0
	s_mov_b32 m0, s5
	s_nop 0
	global_load_lds_dwordx4 v[2:3], off
	s_mov_b32 m0, s49
	s_mov_b32 s5, m0
	s_mov_b32 m0, s6
	s_nop 0
	global_load_lds_dwordx4 v[114:115], off
	s_mov_b32 m0, s5
	v_lshl_add_u64 v[2:3], v[32:33], 0, s[10:11]
	s_mov_b32 s5, m0
	s_mov_b32 m0, s7
	s_nop 0
	global_load_lds_dwordx4 v[26:27], off
	s_mov_b32 m0, s5
	s_nop 0
	s_mov_b32 s5, m0
	s_mov_b32 m0, s47
	s_nop 0
	global_load_lds_dwordx4 v[20:21], off
	s_mov_b32 m0, s5
	s_nop 0
	s_mov_b32 s5, m0
	s_mov_b32 m0, s72
	s_nop 0
	global_load_lds_dwordx4 v[24:25], off
	s_mov_b32 m0, s5
	s_nop 0
	s_mov_b32 s5, m0
	s_mov_b32 m0, s73
	s_nop 0
	global_load_lds_dwordx4 v[22:23], off
	s_mov_b32 m0, s5
	v_and_b32_e32 v22, 7, v36
	s_mov_b32 s5, m0
	s_mov_b32 m0, s74
	s_nop 0
	global_load_lds_dwordx4 v[28:29], off
	s_mov_b32 m0, s5
	v_xor_b32_e32 v93, v145, v22
	s_mov_b32 s5, m0
	s_mov_b32 m0, s0
	s_nop 0
	global_load_lds_dwordx4 v[30:31], off
	s_mov_b32 m0, s5
	s_mov_b32 s0, m0
	s_mov_b32 m0, s1
	s_nop 0
	global_load_lds_dwordx4 v[34:35], off
	s_mov_b32 m0, s0
	s_min_u32 s5, s50, 3
	s_mov_b32 s0, m0
	s_mov_b32 m0, s48
	s_nop 0
	global_load_lds_dwordx4 v[32:33], off
	s_mov_b32 m0, s0
	s_add_i32 s0, s51, 0x16000
	s_mov_b32 s1, m0
	s_mov_b32 m0, s0
	s_nop 0
	global_load_lds_dwordx4 v[2:3], off
	s_mov_b32 m0, s1
	s_mul_i32 s0, s5, 0x18000
	s_mov_b32 s1, s11
	v_lshl_add_u64 v[2:3], v[112:113], 0, s[0:1]
	s_lshl_b32 s0, s5, 7
	s_waitcnt vmcnt(8)
	s_barrier
	v_lshl_add_u64 v[20:21], v[114:115], 0, s[0:1]
	s_add_i32 s0, s51, 0x18000
	s_mov_b32 s1, m0
	s_mov_b32 m0, s0
	s_nop 0
	global_load_lds_dwordx4 v[2:3], off
	s_mov_b32 m0, s1
	v_lshl_add_u64 v[2:3], v[2:3], 0, s[78:79]
	s_add_i32 s0, s51, 0x1a000
	s_mov_b32 s1, m0
	s_mov_b32 m0, s0
	s_nop 0
	global_load_lds_dwordx4 v[2:3], off
	s_mov_b32 m0, s1
	s_add_i32 s0, s51, 0x1c000
	s_mov_b32 s1, m0
	s_mov_b32 m0, s0
	s_nop 0
	global_load_lds_dwordx4 v[20:21], off
	s_mov_b32 m0, s1
	v_lshl_add_u64 v[2:3], v[20:21], 0, s[10:11]
	s_add_i32 s0, s51, 0x1e000
	s_mov_b32 s1, m0
	s_mov_b32 m0, s0
	s_nop 0
	global_load_lds_dwordx4 v[2:3], off
	s_mov_b32 m0, s1
	v_bitop3_b32 v3, v145, v0, 8 bitop3:0x36
	v_bitop3_b32 v2, v145, v0, 12 bitop3:0x36
	v_bitop3_b32 v92, v145, v22, 4 bitop3:0x36
	v_cmp_ne_u32_e64 s[0:1], 0, v109
	v_lshlrev_b32_e32 v157, 4, v3
	v_lshlrev_b32_e32 v158, 4, v2
	v_lshlrev_b32_e32 v159, 4, v93
	v_lshlrev_b32_e32 v160, 4, v92
	s_and_saveexec_b64 s[6:7], s[0:1]
	s_xor_b64 s[48:49], exec, s[6:7]
	s_cbranch_execz .LBB0_1616
	v_add_u32_e32 v0, 0, v152
	v_lshlrev_b32_e32 v155, 4, v95
	v_lshlrev_b32_e32 v156, 4, v94
	v_add_u32_e32 v36, v0, v155
	v_add_u32_e32 v40, v0, v156
	ds_read_b128 v[20:23], v36
	ds_read_b128 v[24:27], v36 offset:4096
	ds_read_b128 v[28:31], v40
	s_waitcnt lgkmcnt(2)
	v_mfma_f32_16x16x32_bf16 v[20:23], v[20:23], v[4:7], 0
	ds_read_b128 v[32:35], v40 offset:4096
	v_lshlrev_b32_e32 v157, 4, v3
	v_add_u32_e32 v3, v0, v157
	s_waitcnt lgkmcnt(1)
	v_mfma_f32_16x16x32_bf16 v[20:23], v[28:31], v[8:11], v[20:23]
	ds_read_b128 v[28:31], v36 offset:8192
	v_lshlrev_b32_e32 v158, 4, v2
	v_add_u32_e32 v2, v0, v158
	v_mfma_f32_16x16x32_bf16 v[24:27], v[24:27], v[4:7], 0
	s_nop 3
	v_mul_f32_e32 v68, 0x3e38aa3b, v22
	v_mul_f32_e32 v69, 0x3e38aa3b, v23
	v_sub_u32_e32 v0, v0, v153
	s_waitcnt lgkmcnt(0)
	v_mfma_f32_16x16x32_bf16 v[28:31], v[28:31], v[4:7], 0
	v_lshlrev_b32_e32 v159, 4, v93
	s_mov_b32 s6, s4
	s_mov_b32 s7, s4
	v_mfma_f32_16x16x32_bf16 v[24:27], v[32:35], v[8:11], v[24:27]
	ds_read_b128 v[32:35], v40 offset:8192
	ds_read_b128 v[36:39], v36 offset:12288
	ds_read_b128 v[40:43], v40 offset:12288
	s_mov_b32 s5, s4
	v_mov_b64_e32 v[126:127], s[6:7]
	s_waitcnt lgkmcnt(2)
	v_mfma_f32_16x16x32_bf16 v[28:31], v[32:35], v[8:11], v[28:31]
	ds_read_b128 v[32:35], v3
	ds_read_b128 v[44:47], v3 offset:4096
	ds_read_b128 v[48:51], v2
	ds_read_b128 v[52:55], v2 offset:4096
	ds_read_b128 v[56:59], v3 offset:8192
	ds_read_b128 v[60:63], v3 offset:12288
	v_mul_f32_e32 v3, 0x3e38aa3b, v21
	s_waitcnt lgkmcnt(7)
	v_mfma_f32_16x16x32_bf16 v[36:39], v[36:39], v[4:7], 0
	v_mul_f32_e32 v72, 0x3e38aa3b, v26
	v_mul_f32_e32 v73, 0x3e38aa3b, v27
	v_mul_f32_e32 v70, 0x3e38aa3b, v24
	s_waitcnt lgkmcnt(5)
	v_mfma_f32_16x16x32_bf16 v[32:35], v[32:35], v[12:15], 0
	v_mul_f32_e32 v71, 0x3e38aa3b, v25
	v_mul_f32_e32 v74, 0x3e38aa3b, v28
	v_mul_f32_e32 v75, 0x3e38aa3b, v29
	v_mfma_f32_16x16x32_bf16 v[36:39], v[40:43], v[8:11], v[36:39]
	ds_read_b128 v[40:43], v2 offset:8192
	ds_read_b128 v[64:67], v2 offset:12288
	v_mul_f32_e32 v2, 0x3e38aa3b, v20
	v_mov_b64_e32 v[124:125], s[4:5]
	s_waitcnt lgkmcnt(5)
	v_mfma_f32_16x16x32_bf16 v[32:35], v[48:51], v[16:19], v[32:35]
	v_lshlrev_b32_e32 v160, 4, v92
	s_waitcnt lgkmcnt(3)
	v_mfma_f32_16x16x32_bf16 v[48:51], v[56:59], v[12:15], 0
	v_mul_f32_e32 v56, 0x3e38aa3b, v38
	v_mul_f32_e32 v57, 0x3e38aa3b, v39
	v_mfma_f32_16x16x32_bf16 v[44:47], v[44:47], v[12:15], 0
	s_waitcnt lgkmcnt(1)
	v_mfma_f32_16x16x32_bf16 v[40:43], v[40:43], v[16:19], v[48:51]
	s_nop 2
	v_max_f32_e32 v48, v68, v69
	v_max3_f32 v2, v2, v3, v48
	v_max_f32_e32 v3, v72, v73
	v_mfma_f32_16x16x32_bf16 v[44:47], v[52:55], v[16:19], v[44:47]
	v_mul_f32_e32 v52, 0x3e38aa3b, v30
	v_mul_f32_e32 v53, 0x3e38aa3b, v31
	v_max3_f32 v3, v70, v71, v3
	v_mul_f32_e32 v54, 0x3e38aa3b, v36
	v_mul_f32_e32 v55, 0x3e38aa3b, v37
	v_max3_f32 v2, v2, s25, v3
	v_max_f32_e32 v3, v52, v53
	v_max_f32_e32 v48, v56, v57
	v_max3_f32 v3, v74, v75, v3
	v_max3_f32 v48, v54, v55, v48
	v_max3_f32 v2, v2, v3, v48
	ds_bpermute_b32 v3, v146, v2
	v_mfma_f32_16x16x32_bf16 v[48:51], v[60:63], v[12:15], 0
	v_mul_f32_e32 v53, 0x3e38aa3b, v34
	v_mul_f32_e32 v54, 0x3e38aa3b, v35
	v_mul_f32_e32 v52, 0x3e38aa3b, v33
	s_waitcnt lgkmcnt(0)
	v_max_f32_e32 v3, v3, v3
	v_max_f32_e32 v2, v2, v3
	ds_bpermute_b32 v3, v147, v2
	v_mfma_f32_16x16x32_bf16 v[48:51], v[64:67], v[16:19], v[48:51]
	v_mul_f32_e32 v57, 0x3e38aa3b, v46
	v_mul_f32_e32 v58, 0x3e38aa3b, v47
	v_max_f32_e32 v53, v53, v54
	s_waitcnt lgkmcnt(0)
	v_max_f32_e32 v3, v3, v3
	v_max_f32_e32 v3, v2, v3
	v_fma_f32 v2, v27, s24, -v3
	v_mul_f32_e32 v27, 0x3e38aa3b, v32
	v_mul_f32_e32 v55, 0x3e38aa3b, v44
	v_mul_f32_e32 v56, 0x3e38aa3b, v45
	v_max3_f32 v27, v27, v52, v53
	v_max_f32_e32 v52, v57, v58
	v_mul_f32_e32 v61, 0x3e38aa3b, v42
	v_mul_f32_e32 v62, 0x3e38aa3b, v43
	v_mul_f32_e32 v65, 0x3e38aa3b, v50
	v_mul_f32_e32 v66, 0x3e38aa3b, v51
	v_max3_f32 v52, v55, v56, v52
	v_mul_f32_e32 v59, 0x3e38aa3b, v40
	v_mul_f32_e32 v60, 0x3e38aa3b, v41
	v_mul_f32_e32 v63, 0x3e38aa3b, v48
	v_mul_f32_e32 v64, 0x3e38aa3b, v49
	v_max3_f32 v27, v27, s25, v52
	v_max_f32_e32 v52, v61, v62
	v_max_f32_e32 v53, v65, v66
	v_max3_f32 v52, v59, v60, v52
	v_max3_f32 v53, v63, v64, v53
	v_max3_f32 v27, v27, v52, v53
	ds_bpermute_b32 v52, v146, v27
	v_fma_f32 v20, v20, s24, -v3
	v_exp_f32_e32 v53, v20
	v_fma_f32 v21, v21, s24, -v3
	v_exp_f32_e32 v54, v21
	s_waitcnt lgkmcnt(0)
	v_max_f32_e32 v20, v52, v52
	v_max_f32_e32 v20, v27, v20
	ds_bpermute_b32 v21, v147, v20
	v_exp_f32_e32 v58, v2
	v_fma_f32 v24, v24, s24, -v3
	v_fma_f32 v25, v25, s24, -v3
	v_fma_f32 v26, v26, s24, -v3
	s_waitcnt lgkmcnt(0)
	v_max_f32_e32 v2, v21, v21
	v_fma_f32 v23, v23, s24, -v3
	v_fma_f32 v22, v22, s24, -v3
	v_max_f32_e32 v2, v20, v2
	v_exp_f32_e32 v55, v22
	v_exp_f32_e32 v56, v23
	v_exp_f32_e32 v27, v24
	v_exp_f32_e32 v52, v25
	v_exp_f32_e32 v57, v26
	v_fma_f32 v24, v47, s24, -v2
	v_fma_f32 v20, v44, s24, -v2
	v_fma_f32 v21, v45, s24, -v2
	v_fma_f32 v25, v46, s24, -v2
	v_fma_f32 v22, v35, s24, -v2
	v_fma_f32 v23, v32, s24, -v2
	v_fma_f32 v26, v33, s24, -v2
	v_fma_f32 v32, v34, s24, -v2
	v_exp_f32_e32 v33, v23
	v_exp_f32_e32 v34, v26
	v_exp_f32_e32 v35, v32
	v_exp_f32_e32 v59, v22
	v_exp_f32_e32 v60, v20
	v_exp_f32_e32 v61, v21
	v_exp_f32_e32 v62, v25
	v_exp_f32_e32 v63, v24
	v_add_u32_e32 v68, v0, v159
	v_cvt_pk_bf16_f32 v32, v33, v34
	v_cvt_pk_bf16_f32 v33, v35, v59
	v_cvt_pk_bf16_f32 v34, v60, v61
	v_cvt_pk_bf16_f32 v35, v62, v63
	ds_read_b128 v[60:63], v68 offset:20480
	ds_read_b128 v[64:67], v68 offset:22528
	v_cvt_pk_bf16_f32 v24, v53, v54
	v_cvt_pk_bf16_f32 v25, v55, v56
	v_cvt_pk_bf16_f32 v26, v27, v52
	v_cvt_pk_bf16_f32 v27, v57, v58
	v_fma_f32 v69, v39, s24, -v3
	v_fma_f32 v70, v36, s24, -v3
	s_waitcnt lgkmcnt(1)
	v_mfma_f32_16x16x32_bf16 v[76:79], v[60:63], v[24:27], 0
	v_fma_f32 v71, v37, s24, -v3
	v_fma_f32 v72, v38, s24, -v3
	v_fma_f32 v28, v28, s24, -v3
	v_mfma_f32_16x16x32_bf16 v[36:39], v[60:63], v[32:35], 0
	ds_read_b128 v[60:63], v68 offset:24576
	v_fma_f32 v29, v29, s24, -v3
	ds_read_b128 v[20:23], v68 offset:16384
	ds_read_b128 v[44:47], v68 offset:18432
	v_fma_f32 v73, v31, s24, -v3
	s_waitcnt lgkmcnt(3)
	v_mfma_f32_16x16x32_bf16 v[80:83], v[64:67], v[24:27], 0
	v_fma_f32 v74, v30, s24, -v3
	v_exp_f32_e32 v75, v28
	v_exp_f32_e32 v93, v29
	v_mfma_f32_16x16x32_bf16 v[28:31], v[64:67], v[32:35], 0
	ds_read_b128 v[64:67], v68 offset:26624
	v_fma_f32 v106, v51, s24, -v2
	v_fma_f32 v107, v48, s24, -v2
	s_waitcnt lgkmcnt(3)
	v_mfma_f32_16x16x32_bf16 v[84:87], v[60:63], v[24:27], 0
	v_fma_f32 v132, v49, s24, -v2
	v_fma_f32 v133, v50, s24, -v2
	ds_read_b128 v[48:51], v68 offset:30720
	v_mfma_f32_16x16x32_bf16 v[88:91], v[60:63], v[32:35], 0
	ds_read_b128 v[60:63], v68 offset:28672
	v_add_u32_e32 v0, v0, v160
	v_fma_f32 v43, v43, s24, -v2
	s_waitcnt lgkmcnt(4)
	v_mfma_f32_16x16x32_bf16 v[52:55], v[20:23], v[24:27], 0
	v_fma_f32 v40, v40, s24, -v2
	v_fma_f32 v41, v41, s24, -v2
	v_fma_f32 v42, v42, s24, -v2
	s_waitcnt lgkmcnt(3)
	v_mfma_f32_16x16x32_bf16 v[56:59], v[44:47], v[24:27], 0
	v_exp_f32_e32 v74, v74
	v_exp_f32_e32 v73, v73
	v_exp_f32_e32 v70, v70
	s_waitcnt lgkmcnt(2)
	v_mfma_f32_16x16x32_bf16 v[94:97], v[64:67], v[24:27], 0
	v_exp_f32_e32 v71, v71
	v_exp_f32_e32 v72, v72
	v_exp_f32_e32 v69, v69
	s_waitcnt lgkmcnt(0)
	v_mfma_f32_16x16x32_bf16 v[102:105], v[60:63], v[24:27], 0
	v_exp_f32_e32 v40, v40
	v_exp_f32_e32 v41, v41
	v_exp_f32_e32 v42, v42
	v_mfma_f32_16x16x32_bf16 v[120:123], v[48:51], v[24:27], 0
	v_exp_f32_e32 v43, v43
	v_cvt_pk_bf16_f32 v162, v75, v93
	v_cvt_pk_bf16_f32 v163, v74, v73
	v_mfma_f32_16x16x32_bf16 v[128:131], v[48:51], v[32:35], 0
	v_exp_f32_e32 v49, v132
	v_exp_f32_e32 v50, v133
	v_exp_f32_e32 v48, v107
	v_mfma_f32_16x16x32_bf16 v[132:135], v[124:127], v[24:27], 0
	ds_read_b128 v[24:27], v0 offset:16384
	v_exp_f32_e32 v51, v106
	v_cvt_pk_bf16_f32 v164, v70, v71
	v_mfma_f32_16x16x32_bf16 v[20:23], v[20:23], v[32:35], 0
	v_cvt_pk_bf16_f32 v165, v72, v69
	v_cvt_pk_bf16_f32 v166, v40, v41
	v_cvt_pk_bf16_f32 v167, v42, v43
	v_mfma_f32_16x16x32_bf16 v[44:47], v[44:47], v[32:35], 0
	v_cvt_pk_bf16_f32 v168, v48, v49
	v_cvt_pk_bf16_f32 v169, v50, v51
	v_mfma_f32_16x16x32_bf16 v[98:101], v[64:67], v[32:35], 0
	v_mfma_f32_16x16x32_bf16 v[116:119], v[60:63], v[32:35], 0
	v_mfma_f32_16x16x32_bf16 v[136:139], v[124:127], v[32:35], 0
	ds_read_b128 v[32:35], v0 offset:18432
	s_waitcnt lgkmcnt(1)
	v_mfma_f32_16x16x32_bf16 v[68:71], v[24:27], v[162:165], v[52:55]
	v_mfma_f32_16x16x32_bf16 v[72:75], v[24:27], v[166:169], v[20:23]
	s_nop 2
	ds_read_b128 v[20:23], v0 offset:20480
	ds_read_b128 v[24:27], v0 offset:22528
	s_waitcnt lgkmcnt(2)
	v_mfma_f32_16x16x32_bf16 v[60:63], v[32:35], v[162:165], v[56:59]
	v_mfma_f32_16x16x32_bf16 v[64:67], v[32:35], v[166:169], v[44:47]
	s_waitcnt lgkmcnt(1)
	v_mfma_f32_16x16x32_bf16 v[52:55], v[20:23], v[162:165], v[76:79]
	v_mfma_f32_16x16x32_bf16 v[56:59], v[20:23], v[166:169], v[36:39]
	s_waitcnt lgkmcnt(0)
	v_mfma_f32_16x16x32_bf16 v[44:47], v[24:27], v[162:165], v[80:83]
	v_mfma_f32_16x16x32_bf16 v[48:51], v[24:27], v[166:169], v[28:31]
	ds_read_b128 v[20:23], v0 offset:24576
	ds_read_b128 v[24:27], v0 offset:26624
	s_waitcnt lgkmcnt(1)
	v_mfma_f32_16x16x32_bf16 v[36:39], v[20:23], v[162:165], v[84:87]
	v_mfma_f32_16x16x32_bf16 v[40:43], v[20:23], v[166:169], v[88:91]
	ds_read_b128 v[20:23], v0 offset:28672
	ds_read_b128 v[76:79], v0 offset:30720
	s_waitcnt lgkmcnt(2)
	v_mfma_f32_16x16x32_bf16 v[32:35], v[24:27], v[162:165], v[94:97]
	v_mfma_f32_16x16x32_bf16 v[28:31], v[24:27], v[166:169], v[98:101]
	s_waitcnt lgkmcnt(1)
	v_mfma_f32_16x16x32_bf16 v[24:27], v[20:23], v[162:165], v[102:105]
	v_mfma_f32_16x16x32_bf16 v[20:23], v[20:23], v[166:169], v[116:119]
	s_nop 2
	v_add_f32_e64 v116, v2, 0
	v_add_f32_e64 v117, v3, 0
	s_waitcnt lgkmcnt(0)
	v_mfma_f32_16x16x32_bf16 v[84:87], v[76:79], v[162:165], v[120:123]
	v_mov_b32_e32 v0, v117
	v_mfma_f32_16x16x32_bf16 v[80:83], v[76:79], v[166:169], v[128:131]
	v_mfma_f32_16x16x32_bf16 v[88:91], v[124:127], v[162:165], v[132:135]
	v_mfma_f32_16x16x32_bf16 v[76:79], v[124:127], v[166:169], v[136:139]

.Ldf_nodrain:
	s_waitcnt vmcnt(0)
	s_and_saveexec_b64 s[6:7], s[0:1]
	s_xor_b64 s[0:1], exec, s[6:7]
	s_cbranch_execz .LBB0_1582
	v_div_scale_f32 v0, s[6:7], v88, v88, 1.0
	v_rcp_f32_e32 v2, v0
	v_div_scale_f32 v3, vcc, 1.0, v88, 1.0
	v_readlane_b32 s36, v255, 2
	v_fma_f32 v4, -v0, v2, 1.0
	v_fmac_f32_e32 v2, v4, v2
	v_mul_f32_e32 v4, v3, v2
	v_fma_f32 v5, -v0, v4, v3
	v_fmac_f32_e32 v4, v5, v2
	v_fma_f32 v0, -v0, v4, v3
	v_div_scale_f32 v3, s[6:7], v76, v76, v141
	v_rcp_f32_e32 v5, v3
	v_div_fmas_f32 v0, v0, v2, v4
	v_div_fixup_f32 v0, v0, v88, 1.0
	v_readlane_b32 s50, v255, 16
	v_fma_f32 v2, -v3, v5, 1.0
	v_fmac_f32_e32 v5, v2, v5
	v_div_scale_f32 v2, vcc, v141, v76, v141
	v_mul_f32_e32 v4, v2, v5
	v_fma_f32 v6, -v3, v4, v2
	v_fmac_f32_e32 v4, v6, v5
	v_fma_f32 v2, -v3, v4, v2
	v_div_fmas_f32 v2, v2, v5, v4
	v_div_fixup_f32 v6, v2, v76, v141
	v_pk_mul_f32 v[2:3], v[80:81], v[6:7] op_sel_hi:[1,0]
	v_readlane_b32 s51, v255, 17
	v_pk_fma_f32 v[8:9], v[84:85], v[0:1], v[2:3] op_sel_hi:[1,0,1] neg_lo:[0,0,1] neg_hi:[0,0,1]
	v_pk_mul_f32 v[2:3], v[82:83], v[6:7] op_sel_hi:[1,0]
	v_pk_mul_f32 v[66:67], v[66:67], v[6:7] op_sel_hi:[1,0]
	v_pk_fma_f32 v[12:13], v[86:87], v[0:1], v[2:3] op_sel_hi:[1,0,1] neg_lo:[0,0,1] neg_hi:[0,0,1]
	v_pk_mul_f32 v[2:3], v[74:75], v[6:7] op_sel_hi:[1,0]
	v_pk_mul_f32 v[64:65], v[64:65], v[6:7] op_sel_hi:[1,0]
	v_pk_fma_f32 v[16:17], v[70:71], v[0:1], v[2:3] op_sel_hi:[1,0,1] neg_lo:[0,0,1] neg_hi:[0,0,1]
	global_load_dwordx4 v[182:185], v108, s[50:51]
	global_load_dwordx4 v[186:189], v108, s[50:51] offset:64
	global_load_dwordx4 v[190:193], v108, s[50:51] offset:128
	global_load_dwordx4 v[194:197], v108, s[50:51] offset:192
	global_load_dwordx4 v[198:201], v108, s[50:51] offset:256
	global_load_dwordx4 v[202:205], v108, s[50:51] offset:320
	global_load_dwordx4 v[206:209], v108, s[50:51] offset:384
	global_load_dwordx4 v[210:213], v108, s[50:51] offset:448
	v_pk_mul_f32 v[70:71], v[72:73], v[6:7] op_sel_hi:[1,0]
	v_pk_mul_f32 v[58:59], v[58:59], v[6:7] op_sel_hi:[1,0]
	v_pk_fma_f32 v[68:69], v[68:69], v[0:1], v[70:71] op_sel_hi:[1,0,1] neg_lo:[0,0,1] neg_hi:[0,0,1]
	v_pk_mul_f32 v[56:57], v[56:57], v[6:7] op_sel_hi:[1,0]
	v_pk_mul_f32 v[70:71], v[68:69], v[68:69]
	v_pk_mul_f32 v[50:51], v[50:51], v[6:7] op_sel_hi:[1,0]
	v_pk_mul_f32 v[48:49], v[48:49], v[6:7] op_sel_hi:[1,0]
	v_pk_mul_f32 v[42:43], v[42:43], v[6:7] op_sel_hi:[1,0]
	v_pk_mul_f32 v[40:41], v[40:41], v[6:7] op_sel_hi:[1,0]
	v_pk_mul_f32 v[30:31], v[30:31], v[6:7] op_sel_hi:[1,0]
	v_pk_mul_f32 v[28:29], v[28:29], v[6:7] op_sel_hi:[1,0]
	v_pk_mul_f32 v[22:23], v[22:23], v[6:7] op_sel_hi:[1,0]
	v_pk_mul_f32 v[6:7], v[20:21], v[6:7] op_sel_hi:[1,0]
	v_pk_mul_f32 v[18:19], v[16:17], v[16:17]
	v_pk_fma_f32 v[62:63], v[62:63], v[0:1], v[66:67] op_sel_hi:[1,0,1] neg_lo:[0,0,1] neg_hi:[0,0,1]
	v_pk_fma_f32 v[60:61], v[60:61], v[0:1], v[64:65] op_sel_hi:[1,0,1] neg_lo:[0,0,1] neg_hi:[0,0,1]
	v_pk_fma_f32 v[54:55], v[54:55], v[0:1], v[58:59] op_sel_hi:[1,0,1] neg_lo:[0,0,1] neg_hi:[0,0,1]
	v_pk_fma_f32 v[52:53], v[52:53], v[0:1], v[56:57] op_sel_hi:[1,0,1] neg_lo:[0,0,1] neg_hi:[0,0,1]
	v_pk_fma_f32 v[46:47], v[46:47], v[0:1], v[50:51] op_sel_hi:[1,0,1] neg_lo:[0,0,1] neg_hi:[0,0,1]
	v_pk_fma_f32 v[44:45], v[44:45], v[0:1], v[48:49] op_sel_hi:[1,0,1] neg_lo:[0,0,1] neg_hi:[0,0,1]
	v_pk_fma_f32 v[38:39], v[38:39], v[0:1], v[42:43] op_sel_hi:[1,0,1] neg_lo:[0,0,1] neg_hi:[0,0,1]
	v_pk_fma_f32 v[36:37], v[36:37], v[0:1], v[40:41] op_sel_hi:[1,0,1] neg_lo:[0,0,1] neg_hi:[0,0,1]
	v_pk_fma_f32 v[30:31], v[34:35], v[0:1], v[30:31] op_sel_hi:[1,0,1] neg_lo:[0,0,1] neg_hi:[0,0,1]
	v_pk_fma_f32 v[28:29], v[32:33], v[0:1], v[28:29] op_sel_hi:[1,0,1] neg_lo:[0,0,1] neg_hi:[0,0,1]
	v_pk_fma_f32 v[22:23], v[26:27], v[0:1], v[22:23] op_sel_hi:[1,0,1] neg_lo:[0,0,1] neg_hi:[0,0,1]
	v_pk_fma_f32 v[6:7], v[24:25], v[0:1], v[6:7] op_sel_hi:[1,0,1] neg_lo:[0,0,1] neg_hi:[0,0,1]
	v_add_f32_e32 v0, v70, v71
	v_add_f32_e32 v0, v18, v0
	v_pk_mul_f32 v[64:65], v[60:61], v[60:61]
	v_add_f32_e32 v0, v19, v0
	v_add_f32_e32 v0, v64, v0
	v_pk_mul_f32 v[66:67], v[62:63], v[62:63]
	v_add_f32_e32 v0, v65, v0
	v_add_f32_e32 v0, v66, v0
	v_pk_mul_f32 v[56:57], v[52:53], v[52:53]
	v_add_f32_e32 v0, v67, v0
	v_add_f32_e32 v0, v56, v0
	v_pk_mul_f32 v[58:59], v[54:55], v[54:55]
	v_add_f32_e32 v0, v57, v0
	v_add_f32_e32 v0, v58, v0
	v_pk_mul_f32 v[48:49], v[44:45], v[44:45]
	v_add_f32_e32 v0, v59, v0
	v_add_f32_e32 v0, v48, v0
	v_pk_mul_f32 v[50:51], v[46:47], v[46:47]
	v_add_f32_e32 v0, v49, v0
	v_add_f32_e32 v0, v50, v0
	v_pk_mul_f32 v[40:41], v[36:37], v[36:37]
	v_add_f32_e32 v0, v51, v0
	v_add_f32_e32 v0, v40, v0
	v_pk_mul_f32 v[42:43], v[38:39], v[38:39]
	v_add_f32_e32 v0, v41, v0
	v_add_f32_e32 v0, v42, v0
	v_pk_mul_f32 v[32:33], v[28:29], v[28:29]
	v_add_f32_e32 v0, v43, v0
	v_add_f32_e32 v0, v32, v0
	v_pk_mul_f32 v[34:35], v[30:31], v[30:31]
	v_add_f32_e32 v0, v33, v0
	v_add_f32_e32 v0, v34, v0
	v_pk_mul_f32 v[20:21], v[6:7], v[6:7]
	v_add_f32_e32 v0, v35, v0
	v_add_f32_e32 v0, v20, v0
	v_pk_mul_f32 v[26:27], v[22:23], v[22:23]
	v_add_f32_e32 v0, v21, v0
	v_add_f32_e32 v0, v26, v0
	v_pk_mul_f32 v[10:11], v[8:9], v[8:9]
	v_add_f32_e32 v0, v27, v0
	v_add_f32_e32 v0, v10, v0
	v_pk_mul_f32 v[14:15], v[12:13], v[12:13]
	v_add_f32_e32 v0, v11, v0
	v_add_f32_e32 v0, v14, v0
	v_add_f32_e32 v0, v15, v0
	ds_bpermute_b32 v10, v146, v0
	v_readlane_b32 s37, v255, 3
	v_readlane_b32 s36, v255, 18
	v_readlane_b32 s37, v255, 19
	v_readlane_b32 s38, v255, 4
	s_waitcnt lgkmcnt(0)
	v_add_f32_e32 v0, v0, v10
	ds_bpermute_b32 v14, v147, v0
	v_lshl_add_u64 v[10:11], s[26:27], 0, v[110:111]
	v_lshl_add_u64 v[10:11], s[76:77], 1, v[10:11]
	v_readlane_b32 s39, v255, 5
	v_readlane_b32 s40, v255, 6
	s_waitcnt lgkmcnt(0)
	v_add_f32_e32 v0, v0, v14
	v_fmamk_f32 v0, v0, 0x3c000000, v142
	v_mul_f32_e32 v14, 0x4b800000, v0
	v_cmp_gt_f32_e32 vcc, s71, v0
	v_readlane_b32 s41, v255, 7
	v_readlane_b32 s42, v255, 8
	v_cndmask_b32_e32 v0, v0, v14, vcc
	v_rsq_f32_e32 v14, v0
	v_lshlrev_b32_e32 v0, 3, v145
	v_lshl_add_u64 v[10:11], v[10:11], 0, v[0:1]
	v_readlane_b32 s43, v255, 9
	v_mul_f32_e32 v0, 0x45800000, v14
	v_cndmask_b32_e32 v0, v14, v0, vcc
	v_mul_f32_e32 v0, 0x3f24fd5c, v0
	v_readlane_b32 s44, v255, 10
	v_readlane_b32 s45, v255, 11
	v_readlane_b32 s46, v255, 12
	v_readlane_b32 s47, v255, 13
	v_readlane_b32 s48, v255, 14
	v_readlane_b32 s49, v255, 15
	s_waitcnt vmcnt(0)
	v_pk_mul_f32 v[14:15], v[68:69], v[0:1] op_sel_hi:[1,0]
	v_pk_mul_f32 v[16:17], v[16:17], v[0:1] op_sel_hi:[1,0]
	v_pk_mul_f32 v[14:15], v[14:15], v[182:183]
	v_pk_mul_f32 v[16:17], v[16:17], v[184:185]
	v_cvt_pk_bf16_f32 v92, v14, v15
	v_cvt_pk_bf16_f32 v93, v16, v17
	global_store_dwordx2 v[10:11], v[92:93], off
	v_pk_mul_f32 v[14:15], v[60:61], v[0:1] op_sel_hi:[1,0]
	v_pk_mul_f32 v[16:17], v[62:63], v[0:1] op_sel_hi:[1,0]
	v_pk_mul_f32 v[14:15], v[14:15], v[186:187]
	v_pk_mul_f32 v[16:17], v[16:17], v[188:189]
	v_cvt_pk_bf16_f32 v94, v14, v15
	v_cvt_pk_bf16_f32 v95, v16, v17
	global_store_dwordx2 v[10:11], v[94:95], off offset:32
	v_pk_mul_f32 v[14:15], v[52:53], v[0:1] op_sel_hi:[1,0]
	v_pk_mul_f32 v[16:17], v[54:55], v[0:1] op_sel_hi:[1,0]
	v_pk_mul_f32 v[14:15], v[14:15], v[190:191]
	v_pk_mul_f32 v[16:17], v[16:17], v[192:193]
	v_cvt_pk_bf16_f32 v96, v14, v15
	v_cvt_pk_bf16_f32 v97, v16, v17
	global_store_dwordx2 v[10:11], v[96:97], off offset:64
	v_pk_mul_f32 v[14:15], v[44:45], v[0:1] op_sel_hi:[1,0]
	v_pk_mul_f32 v[16:17], v[46:47], v[0:1] op_sel_hi:[1,0]
	v_pk_mul_f32 v[14:15], v[14:15], v[194:195]
	v_pk_mul_f32 v[16:17], v[16:17], v[196:197]
	v_cvt_pk_bf16_f32 v98, v14, v15
	v_cvt_pk_bf16_f32 v99, v16, v17
	global_store_dwordx2 v[10:11], v[98:99], off offset:96
	v_pk_mul_f32 v[14:15], v[36:37], v[0:1] op_sel_hi:[1,0]
	v_pk_mul_f32 v[16:17], v[38:39], v[0:1] op_sel_hi:[1,0]
	v_pk_mul_f32 v[14:15], v[14:15], v[198:199]
	v_pk_mul_f32 v[16:17], v[16:17], v[200:201]
	v_cvt_pk_bf16_f32 v100, v14, v15
	v_cvt_pk_bf16_f32 v101, v16, v17
	global_store_dwordx2 v[10:11], v[100:101], off offset:128
	v_pk_mul_f32 v[14:15], v[28:29], v[0:1] op_sel_hi:[1,0]
	v_pk_mul_f32 v[16:17], v[30:31], v[0:1] op_sel_hi:[1,0]
	v_pk_mul_f32 v[14:15], v[14:15], v[202:203]
	v_pk_mul_f32 v[16:17], v[16:17], v[204:205]
	v_cvt_pk_bf16_f32 v102, v14, v15
	v_cvt_pk_bf16_f32 v103, v16, v17
	global_store_dwordx2 v[10:11], v[102:103], off offset:160
	v_pk_mul_f32 v[14:15], v[6:7], v[0:1] op_sel_hi:[1,0]
	v_pk_mul_f32 v[16:17], v[22:23], v[0:1] op_sel_hi:[1,0]
	v_pk_mul_f32 v[14:15], v[14:15], v[206:207]
	v_pk_mul_f32 v[16:17], v[16:17], v[208:209]
	v_cvt_pk_bf16_f32 v104, v14, v15
	v_cvt_pk_bf16_f32 v105, v16, v17
	global_store_dwordx2 v[10:11], v[104:105], off offset:192
	v_pk_mul_f32 v[14:15], v[8:9], v[0:1] op_sel_hi:[1,0]
	v_pk_mul_f32 v[16:17], v[12:13], v[0:1] op_sel_hi:[1,0]
	v_pk_mul_f32 v[14:15], v[14:15], v[210:211]
	v_pk_mul_f32 v[16:17], v[16:17], v[212:213]
	v_cvt_pk_bf16_f32 v106, v14, v15
	v_cvt_pk_bf16_f32 v107, v16, v17
	global_store_dwordx2 v[10:11], v[106:107], off offset:224
	s_branch .LBB0_1582

.LBB0_1800:
	s_or_b64 exec, exec, s[38:39]
	v_mul_f32_e32 v131, 0xbfb8aa3b, v124
	v_exp_f32_e32 v132, v131
	v_mul_f32_e32 v131, 0xbfb8aa3b, v125
	v_exp_f32_e32 v133, v131
	v_or_b32_e32 v130, s30, v152
	s_lshl_b32 s38, s56, 7
	v_lshlrev_b32_e32 v131, 4, v145
	v_pk_add_f32 v[132:133], v[132:133], 1.0 op_sel_hi:[1,0]
	v_lshlrev_b32_e32 v134, 2, v144
	v_or3_b32 v134, v131, s38, v134
	v_add_u32_e32 v130, v130, v153
	v_ashrrev_i32_e32 v135, 31, v134
	v_div_scale_f32 v139, s[30:31], v132, v132, v124
	v_rcp_f32_e32 v140, v139
	v_rcp_f32_e32 v131, v133
	s_nop 0
	v_mul_f32_e32 v125, v125, v131
	v_fma_f32 v131, -v139, v140, 1.0
	v_fmac_f32_e32 v140, v131, v140
	v_mul_f32_e32 v136, 0xbfb8aa3b, v126
	v_mul_f32_e32 v137, 0xbfb8aa3b, v127
	v_exp_f32_e32 v136, v136
	v_exp_f32_e32 v137, v137
	v_rcp_f32_e32 v131, v132
	s_nop 0
	v_mul_f32_e32 v124, v124, v131
	v_pk_add_f32 v[136:137], v[136:137], 1.0 op_sel_hi:[1,0]
	v_pk_mul_f32 v[120:121], v[120:121], v[124:125]
	v_div_scale_f32 v133, s[30:31], v137, v137, v127
	v_rcp_f32_e32 v138, v133
	v_cvt_pk_bf16_f32 v132, v120, v121
	v_fma_f32 v120, -v133, v138, 1.0
	v_fmac_f32_e32 v138, v120, v138
	v_rcp_f32_e32 v120, v137
	s_nop 0
	v_mul_f32_e32 v121, v127, v120
	v_rcp_f32_e32 v120, v136
	s_nop 0
	v_mul_f32_e32 v120, v126, v120
	v_pk_mul_f32 v[120:121], v[122:123], v[120:121]
	v_lshlrev_b64 v[122:123], 1, v[134:135]
	v_cvt_pk_bf16_f32 v133, v120, v121
	v_mov_b64_e32 v[120:121], s[6:7]
	v_mad_i64_i32 v[124:125], s[30:31], v130, s53, v[120:121]
	v_lshl_add_u64 v[124:125], v[124:125], 0, v[122:123]
	global_store_dwordx2 v[124:125], v[132:133], off
	v_mul_f32_e32 v126, 0xbfb8aa3b, v116
	v_mul_f32_e32 v127, 0xbfb8aa3b, v117
	v_exp_f32_e32 v126, v126
	v_exp_f32_e32 v127, v127
	v_or_b32_e32 v134, 16, v130
	v_pk_add_f32 v[126:127], v[126:127], 1.0 op_sel_hi:[1,0]
	s_nop 0
	v_div_scale_f32 v136, s[30:31], v126, v126, v116
	v_rcp_f32_e32 v137, v136
	v_rcp_f32_e32 v131, v127
	s_nop 0
	v_mul_f32_e32 v117, v117, v131
	v_fma_f32 v127, -v136, v137, 1.0
	v_fmac_f32_e32 v137, v127, v137
	v_mul_f32_e32 v132, 0xbfb8aa3b, v118
	v_mul_f32_e32 v133, 0xbfb8aa3b, v119
	v_exp_f32_e32 v132, v132
	v_exp_f32_e32 v133, v133
	v_rcp_f32_e32 v127, v126
	s_nop 0
	v_mul_f32_e32 v116, v116, v127
	v_pk_add_f32 v[132:133], v[132:133], 1.0 op_sel_hi:[1,0]
	v_pk_mul_f32 v[112:113], v[112:113], v[116:117]
	v_div_scale_f32 v131, s[30:31], v133, v133, v119
	v_rcp_f32_e32 v135, v131
	v_cvt_pk_bf16_f32 v116, v112, v113
	v_fma_f32 v112, -v131, v135, 1.0
	v_fmac_f32_e32 v135, v112, v135
	v_rcp_f32_e32 v112, v133
	s_nop 0
	v_mul_f32_e32 v113, v119, v112
	v_rcp_f32_e32 v112, v132
	s_nop 0
	v_mul_f32_e32 v112, v118, v112
	v_pk_mul_f32 v[112:113], v[114:115], v[112:113]
	s_nop 0
	v_cvt_pk_bf16_f32 v117, v112, v113
	v_mad_i64_i32 v[112:113], s[30:31], v134, s53, v[120:121]
	v_lshl_add_u64 v[112:113], v[112:113], 0, v[122:123]
	global_store_dwordx2 v[112:113], v[116:117], off
	v_mul_f32_e32 v114, 0xbfb8aa3b, v108
	v_mul_f32_e32 v115, 0xbfb8aa3b, v109
	v_exp_f32_e32 v114, v114
	v_exp_f32_e32 v115, v115
	v_or_b32_e32 v118, 32, v130
	v_pk_add_f32 v[114:115], v[114:115], 1.0 op_sel_hi:[1,0]
	s_nop 0
	v_rcp_f32_e32 v116, v115
	s_nop 0
	v_mul_f32_e32 v109, v109, v116
	v_mul_f32_e32 v117, 0xbfb8aa3b, v111
	v_mul_f32_e32 v116, 0xbfb8aa3b, v110
	v_exp_f32_e32 v116, v116
	v_exp_f32_e32 v117, v117
	v_rcp_f32_e32 v115, v114
	s_nop 0
	v_mul_f32_e32 v108, v108, v115
	v_pk_add_f32 v[116:117], v[116:117], 1.0 op_sel_hi:[1,0]
	v_pk_mul_f32 v[104:105], v[104:105], v[108:109]
	s_nop 0
	v_cvt_pk_bf16_f32 v108, v104, v105
	v_rcp_f32_e32 v104, v117
	s_nop 0
	v_mul_f32_e32 v105, v111, v104
	v_rcp_f32_e32 v104, v116
	s_nop 0
	v_mul_f32_e32 v104, v110, v104
	v_pk_mul_f32 v[104:105], v[106:107], v[104:105]
	s_nop 0
	v_cvt_pk_bf16_f32 v109, v104, v105
	v_mad_i64_i32 v[104:105], s[30:31], v118, s53, v[120:121]
	v_lshl_add_u64 v[104:105], v[104:105], 0, v[122:123]
	global_store_dwordx2 v[104:105], v[108:109], off
	v_mul_f32_e32 v106, 0xbfb8aa3b, v100
	v_mul_f32_e32 v107, 0xbfb8aa3b, v101
	v_exp_f32_e32 v106, v106
	v_exp_f32_e32 v107, v107
	v_or_b32_e32 v110, 48, v130
	v_pk_add_f32 v[106:107], v[106:107], 1.0 op_sel_hi:[1,0]
	s_nop 0
	v_rcp_f32_e32 v108, v107
	s_nop 0
	v_mul_f32_e32 v101, v101, v108
	v_mul_f32_e32 v109, 0xbfb8aa3b, v103
	v_mul_f32_e32 v108, 0xbfb8aa3b, v102
	v_exp_f32_e32 v108, v108
	v_exp_f32_e32 v109, v109
	v_rcp_f32_e32 v107, v106
	s_nop 0
	v_mul_f32_e32 v100, v100, v107
	v_pk_add_f32 v[108:109], v[108:109], 1.0 op_sel_hi:[1,0]
	v_pk_mul_f32 v[96:97], v[96:97], v[100:101]
	s_nop 0
	v_cvt_pk_bf16_f32 v100, v96, v97
	v_rcp_f32_e32 v96, v109
	s_nop 0
	v_mul_f32_e32 v97, v103, v96
	v_rcp_f32_e32 v96, v108
	s_nop 0
	v_mul_f32_e32 v96, v102, v96
	v_pk_mul_f32 v[96:97], v[98:99], v[96:97]
	s_nop 0
	v_cvt_pk_bf16_f32 v101, v96, v97
	v_mad_i64_i32 v[96:97], s[30:31], v110, s53, v[120:121]
	v_lshl_add_u64 v[96:97], v[96:97], 0, v[122:123]
	global_store_dwordx2 v[96:97], v[100:101], off
	v_mul_f32_e32 v98, 0xbfb8aa3b, v92
	v_mul_f32_e32 v99, 0xbfb8aa3b, v93
	v_exp_f32_e32 v98, v98
	v_exp_f32_e32 v99, v99
	s_nop 0
	v_pk_add_f32 v[98:99], v[98:99], 1.0 op_sel_hi:[1,0]
	s_nop 0
	v_rcp_f32_e32 v100, v99
	s_nop 0
	v_mul_f32_e32 v93, v93, v100
	v_mul_f32_e32 v101, 0xbfb8aa3b, v95
	v_mul_f32_e32 v100, 0xbfb8aa3b, v94
	v_exp_f32_e32 v100, v100
	v_exp_f32_e32 v101, v101
	v_rcp_f32_e32 v99, v98
	s_nop 0
	v_mul_f32_e32 v92, v92, v99
	v_pk_add_f32 v[100:101], v[100:101], 1.0 op_sel_hi:[1,0]
	v_pk_mul_f32 v[88:89], v[88:89], v[92:93]
	s_nop 0
	v_cvt_pk_bf16_f32 v88, v88, v89
	v_rcp_f32_e32 v89, v101
	s_nop 0
	v_mul_f32_e32 v93, v95, v89
	v_rcp_f32_e32 v89, v100
	s_nop 0
	v_mul_f32_e32 v92, v94, v89
	v_pk_mul_f32 v[90:91], v[90:91], v[92:93]
	s_nop 0
	v_cvt_pk_bf16_f32 v89, v90, v91
	global_store_dwordx2 v[124:125], v[88:89], off offset:128
	v_mul_f32_e32 v88, 0xbfb8aa3b, v84
	v_mul_f32_e32 v89, 0xbfb8aa3b, v85
	v_exp_f32_e32 v88, v88
	v_exp_f32_e32 v89, v89
	s_nop 0
	v_pk_add_f32 v[88:89], v[88:89], 1.0 op_sel_hi:[1,0]
	s_nop 0
	v_rcp_f32_e32 v90, v89
	s_nop 0
	v_mul_f32_e32 v85, v85, v90
	v_mul_f32_e32 v91, 0xbfb8aa3b, v87
	v_mul_f32_e32 v90, 0xbfb8aa3b, v86
	v_exp_f32_e32 v90, v90
	v_exp_f32_e32 v91, v91
	v_rcp_f32_e32 v89, v88
	s_nop 0
	v_mul_f32_e32 v84, v84, v89
	v_pk_add_f32 v[90:91], v[90:91], 1.0 op_sel_hi:[1,0]
	v_pk_mul_f32 v[80:81], v[80:81], v[84:85]
	s_nop 0
	v_cvt_pk_bf16_f32 v80, v80, v81
	v_rcp_f32_e32 v81, v91
	s_nop 0
	v_mul_f32_e32 v85, v87, v81
	v_rcp_f32_e32 v81, v90
	s_nop 0
	v_mul_f32_e32 v84, v86, v81
	v_pk_mul_f32 v[82:83], v[82:83], v[84:85]
	s_nop 0
	v_cvt_pk_bf16_f32 v81, v82, v83
	global_store_dwordx2 v[112:113], v[80:81], off offset:128
	v_mul_f32_e32 v80, 0xbfb8aa3b, v76
	v_mul_f32_e32 v81, 0xbfb8aa3b, v77
	v_exp_f32_e32 v80, v80
	v_exp_f32_e32 v81, v81
	s_nop 0
	v_pk_add_f32 v[80:81], v[80:81], 1.0 op_sel_hi:[1,0]
	s_nop 0
	v_rcp_f32_e32 v82, v81
	s_nop 0
	v_mul_f32_e32 v77, v77, v82
	v_mul_f32_e32 v83, 0xbfb8aa3b, v79
	v_mul_f32_e32 v82, 0xbfb8aa3b, v78
	v_exp_f32_e32 v82, v82
	v_exp_f32_e32 v83, v83
	v_rcp_f32_e32 v81, v80
	s_nop 0
	v_mul_f32_e32 v76, v76, v81
	v_pk_add_f32 v[82:83], v[82:83], 1.0 op_sel_hi:[1,0]
	v_pk_mul_f32 v[72:73], v[72:73], v[76:77]
	s_nop 0
	v_cvt_pk_bf16_f32 v72, v72, v73
	v_rcp_f32_e32 v73, v83
	s_nop 0
	v_mul_f32_e32 v77, v79, v73
	v_rcp_f32_e32 v73, v82
	s_nop 0
	v_mul_f32_e32 v76, v78, v73
	v_pk_mul_f32 v[74:75], v[74:75], v[76:77]
	s_nop 0
	v_cvt_pk_bf16_f32 v73, v74, v75
	global_store_dwordx2 v[104:105], v[72:73], off offset:128
	v_mul_f32_e32 v72, 0xbfb8aa3b, v68
	v_mul_f32_e32 v73, 0xbfb8aa3b, v69
	v_exp_f32_e32 v72, v72
	v_exp_f32_e32 v73, v73
	s_nop 0
	v_pk_add_f32 v[72:73], v[72:73], 1.0 op_sel_hi:[1,0]
	s_nop 0
	v_rcp_f32_e32 v74, v73
	s_nop 0
	v_mul_f32_e32 v69, v69, v74
	v_mul_f32_e32 v75, 0xbfb8aa3b, v71
	v_mul_f32_e32 v74, 0xbfb8aa3b, v70
	v_exp_f32_e32 v74, v74
	v_exp_f32_e32 v75, v75
	v_rcp_f32_e32 v73, v72
	s_nop 0
	v_mul_f32_e32 v68, v68, v73
	v_pk_add_f32 v[74:75], v[74:75], 1.0 op_sel_hi:[1,0]
	v_pk_mul_f32 v[64:65], v[64:65], v[68:69]
	s_nop 0
	v_cvt_pk_bf16_f32 v64, v64, v65
	v_rcp_f32_e32 v65, v75
	s_nop 0
	v_mul_f32_e32 v69, v71, v65
	v_rcp_f32_e32 v65, v74
	s_nop 0
	v_mul_f32_e32 v68, v70, v65
	v_pk_mul_f32 v[66:67], v[66:67], v[68:69]
	s_nop 0
	v_cvt_pk_bf16_f32 v65, v66, v67
	global_store_dwordx2 v[96:97], v[64:65], off offset:128
	v_mul_f32_e32 v64, 0xbfb8aa3b, v60
	v_mul_f32_e32 v65, 0xbfb8aa3b, v61
	v_exp_f32_e32 v64, v64
	v_exp_f32_e32 v65, v65
	v_add_u32_e32 v68, 0x80, v130
	v_pk_add_f32 v[64:65], v[64:65], 1.0 op_sel_hi:[1,0]
	s_nop 0
	v_rcp_f32_e32 v66, v65
	s_nop 0
	v_mul_f32_e32 v61, v61, v66
	v_mul_f32_e32 v67, 0xbfb8aa3b, v63
	v_mul_f32_e32 v66, 0xbfb8aa3b, v62
	v_exp_f32_e32 v66, v66
	v_exp_f32_e32 v67, v67
	v_rcp_f32_e32 v65, v64
	s_nop 0
	v_mul_f32_e32 v60, v60, v65
	v_pk_add_f32 v[66:67], v[66:67], 1.0 op_sel_hi:[1,0]
	v_pk_mul_f32 v[56:57], v[56:57], v[60:61]
	s_nop 0
	v_cvt_pk_bf16_f32 v60, v56, v57
	v_rcp_f32_e32 v56, v67
	s_nop 0
	v_mul_f32_e32 v57, v63, v56
	v_rcp_f32_e32 v56, v66
	s_nop 0
	v_mul_f32_e32 v56, v62, v56
	v_pk_mul_f32 v[56:57], v[58:59], v[56:57]
	s_nop 0
	v_cvt_pk_bf16_f32 v61, v56, v57
	v_mad_i64_i32 v[56:57], s[30:31], v68, s53, v[120:121]
	v_lshl_add_u64 v[56:57], v[56:57], 0, v[122:123]
	global_store_dwordx2 v[56:57], v[60:61], off
	v_mul_f32_e32 v58, 0xbfb8aa3b, v52
	v_mul_f32_e32 v59, 0xbfb8aa3b, v53
	v_exp_f32_e32 v58, v58
	v_exp_f32_e32 v59, v59
	v_add_u32_e32 v62, 0x90, v130
	v_pk_add_f32 v[58:59], v[58:59], 1.0 op_sel_hi:[1,0]
	s_nop 0
	v_rcp_f32_e32 v60, v59
	s_nop 0
	v_mul_f32_e32 v53, v53, v60
	v_mul_f32_e32 v61, 0xbfb8aa3b, v55
	v_mul_f32_e32 v60, 0xbfb8aa3b, v54
	v_exp_f32_e32 v60, v60
	v_exp_f32_e32 v61, v61
	v_rcp_f32_e32 v59, v58
	s_nop 0
	v_mul_f32_e32 v52, v52, v59
	v_pk_add_f32 v[60:61], v[60:61], 1.0 op_sel_hi:[1,0]
	v_pk_mul_f32 v[48:49], v[48:49], v[52:53]
	s_nop 0
	v_cvt_pk_bf16_f32 v52, v48, v49
	v_rcp_f32_e32 v48, v61
	s_nop 0
	v_mul_f32_e32 v49, v55, v48
	v_rcp_f32_e32 v48, v60
	s_nop 0
	v_mul_f32_e32 v48, v54, v48
	v_pk_mul_f32 v[48:49], v[50:51], v[48:49]
	s_nop 0
	v_cvt_pk_bf16_f32 v53, v48, v49
	v_mad_i64_i32 v[48:49], s[30:31], v62, s53, v[120:121]
	v_lshl_add_u64 v[48:49], v[48:49], 0, v[122:123]
	global_store_dwordx2 v[48:49], v[52:53], off
	v_mul_f32_e32 v50, 0xbfb8aa3b, v44
	v_mul_f32_e32 v51, 0xbfb8aa3b, v45
	v_exp_f32_e32 v50, v50
	v_exp_f32_e32 v51, v51
	v_add_u32_e32 v54, 0xa0, v130
	v_pk_add_f32 v[50:51], v[50:51], 1.0 op_sel_hi:[1,0]
	s_nop 0
	v_rcp_f32_e32 v52, v51
	s_nop 0
	v_mul_f32_e32 v45, v45, v52
	v_mul_f32_e32 v53, 0xbfb8aa3b, v47
	v_mul_f32_e32 v52, 0xbfb8aa3b, v46
	v_exp_f32_e32 v52, v52
	v_exp_f32_e32 v53, v53
	v_rcp_f32_e32 v51, v50
	s_nop 0
	v_mul_f32_e32 v44, v44, v51
	v_pk_add_f32 v[52:53], v[52:53], 1.0 op_sel_hi:[1,0]
	v_pk_mul_f32 v[40:41], v[40:41], v[44:45]
	s_nop 0
	v_cvt_pk_bf16_f32 v44, v40, v41
	v_rcp_f32_e32 v40, v53
	s_nop 0
	v_mul_f32_e32 v41, v47, v40
	v_rcp_f32_e32 v40, v52
	s_nop 0
	v_mul_f32_e32 v40, v46, v40
	v_pk_mul_f32 v[40:41], v[42:43], v[40:41]
	s_nop 0
	v_cvt_pk_bf16_f32 v45, v40, v41
	v_mad_i64_i32 v[40:41], s[30:31], v54, s53, v[120:121]
	v_lshl_add_u64 v[40:41], v[40:41], 0, v[122:123]
	global_store_dwordx2 v[40:41], v[44:45], off
	v_mul_f32_e32 v42, 0xbfb8aa3b, v36
	v_mul_f32_e32 v43, 0xbfb8aa3b, v37
	v_exp_f32_e32 v42, v42
	v_exp_f32_e32 v43, v43
	v_add_u32_e32 v46, 0xb0, v130
	v_pk_add_f32 v[42:43], v[42:43], 1.0 op_sel_hi:[1,0]
	s_nop 0
	v_rcp_f32_e32 v44, v43
	s_nop 0
	v_mul_f32_e32 v37, v37, v44
	v_mul_f32_e32 v45, 0xbfb8aa3b, v39
	v_mul_f32_e32 v44, 0xbfb8aa3b, v38
	v_exp_f32_e32 v44, v44
	v_exp_f32_e32 v45, v45
	v_rcp_f32_e32 v43, v42
	s_nop 0
	v_mul_f32_e32 v36, v36, v43
	v_pk_add_f32 v[44:45], v[44:45], 1.0 op_sel_hi:[1,0]
	v_pk_mul_f32 v[32:33], v[32:33], v[36:37]
	s_nop 0
	v_cvt_pk_bf16_f32 v36, v32, v33
	v_rcp_f32_e32 v32, v45
	s_nop 0
	v_mul_f32_e32 v33, v39, v32
	v_rcp_f32_e32 v32, v44
	s_nop 0
	v_mul_f32_e32 v32, v38, v32
	v_pk_mul_f32 v[32:33], v[34:35], v[32:33]
	s_nop 0
	v_cvt_pk_bf16_f32 v37, v32, v33
	v_mad_i64_i32 v[32:33], s[30:31], v46, s53, v[120:121]
	v_lshl_add_u64 v[32:33], v[32:33], 0, v[122:123]
	global_store_dwordx2 v[32:33], v[36:37], off
	v_mul_f32_e32 v34, 0xbfb8aa3b, v28
	v_mul_f32_e32 v35, 0xbfb8aa3b, v29
	v_exp_f32_e32 v34, v34
	v_exp_f32_e32 v35, v35
	s_nop 0
	v_pk_add_f32 v[34:35], v[34:35], 1.0 op_sel_hi:[1,0]
	s_nop 0
	v_rcp_f32_e32 v36, v35
	s_nop 0
	v_mul_f32_e32 v29, v29, v36
	v_mul_f32_e32 v37, 0xbfb8aa3b, v31
	v_mul_f32_e32 v36, 0xbfb8aa3b, v30
	v_exp_f32_e32 v36, v36
	v_exp_f32_e32 v37, v37
	v_rcp_f32_e32 v35, v34
	s_nop 0
	v_mul_f32_e32 v28, v28, v35
	v_pk_add_f32 v[36:37], v[36:37], 1.0 op_sel_hi:[1,0]
	v_pk_mul_f32 v[24:25], v[24:25], v[28:29]
	s_nop 0
	v_cvt_pk_bf16_f32 v24, v24, v25
	v_rcp_f32_e32 v25, v37
	s_nop 0
	v_mul_f32_e32 v29, v31, v25
	v_rcp_f32_e32 v25, v36
	s_nop 0
	v_mul_f32_e32 v28, v30, v25
	v_pk_mul_f32 v[26:27], v[26:27], v[28:29]
	s_nop 0
	v_cvt_pk_bf16_f32 v25, v26, v27
	global_store_dwordx2 v[56:57], v[24:25], off offset:128
	v_mul_f32_e32 v24, 0xbfb8aa3b, v20
	v_mul_f32_e32 v25, 0xbfb8aa3b, v21
	v_exp_f32_e32 v24, v24
	v_exp_f32_e32 v25, v25
	s_nop 0
	v_pk_add_f32 v[24:25], v[24:25], 1.0 op_sel_hi:[1,0]
	s_nop 0
	v_rcp_f32_e32 v26, v25
	s_nop 0
	v_mul_f32_e32 v21, v21, v26
	v_mul_f32_e32 v27, 0xbfb8aa3b, v23
	v_mul_f32_e32 v26, 0xbfb8aa3b, v22
	v_exp_f32_e32 v26, v26
	v_exp_f32_e32 v27, v27
	v_rcp_f32_e32 v25, v24
	s_nop 0
	v_mul_f32_e32 v20, v20, v25
	v_pk_add_f32 v[26:27], v[26:27], 1.0 op_sel_hi:[1,0]
	v_pk_mul_f32 v[16:17], v[16:17], v[20:21]
	s_nop 0
	v_cvt_pk_bf16_f32 v16, v16, v17
	v_rcp_f32_e32 v17, v27
	s_nop 0
	v_mul_f32_e32 v21, v23, v17
	v_rcp_f32_e32 v17, v26
	s_nop 0
	v_mul_f32_e32 v20, v22, v17
	v_pk_mul_f32 v[18:19], v[18:19], v[20:21]
	s_nop 0
	v_cvt_pk_bf16_f32 v17, v18, v19
	global_store_dwordx2 v[48:49], v[16:17], off offset:128
	v_mul_f32_e32 v16, 0xbfb8aa3b, v12
	v_mul_f32_e32 v17, 0xbfb8aa3b, v13
	v_exp_f32_e32 v16, v16
	v_exp_f32_e32 v17, v17
	s_nop 0
	v_pk_add_f32 v[16:17], v[16:17], 1.0 op_sel_hi:[1,0]
	s_nop 0
	v_rcp_f32_e32 v18, v17
	s_nop 0
	v_mul_f32_e32 v13, v13, v18
	v_mul_f32_e32 v19, 0xbfb8aa3b, v15
	v_mul_f32_e32 v18, 0xbfb8aa3b, v14
	v_exp_f32_e32 v18, v18
	v_exp_f32_e32 v19, v19
	v_rcp_f32_e32 v17, v16
	s_nop 0
	v_mul_f32_e32 v12, v12, v17
	v_pk_add_f32 v[18:19], v[18:19], 1.0 op_sel_hi:[1,0]
	v_pk_mul_f32 v[8:9], v[8:9], v[12:13]
	s_nop 0
	v_cvt_pk_bf16_f32 v8, v8, v9
	v_rcp_f32_e32 v9, v19
	s_nop 0
	v_mul_f32_e32 v13, v15, v9
	v_rcp_f32_e32 v9, v18
	s_nop 0
	v_mul_f32_e32 v12, v14, v9
	v_pk_mul_f32 v[10:11], v[10:11], v[12:13]
	s_nop 0
	v_cvt_pk_bf16_f32 v9, v10, v11
	global_store_dwordx2 v[40:41], v[8:9], off offset:128
	v_mul_f32_e32 v8, 0xbfb8aa3b, v4
	v_mul_f32_e32 v9, 0xbfb8aa3b, v5
	v_exp_f32_e32 v8, v8
	v_exp_f32_e32 v9, v9
	s_nop 0
	v_pk_add_f32 v[8:9], v[8:9], 1.0 op_sel_hi:[1,0]
	s_nop 0
	v_rcp_f32_e32 v10, v9
	s_nop 0
	v_mul_f32_e32 v5, v5, v10
	v_mul_f32_e32 v11, 0xbfb8aa3b, v7
	v_mul_f32_e32 v10, 0xbfb8aa3b, v6
	v_exp_f32_e32 v10, v10
	v_exp_f32_e32 v11, v11
	v_rcp_f32_e32 v9, v8
	s_nop 0
	v_mul_f32_e32 v4, v4, v9
	v_pk_add_f32 v[10:11], v[10:11], 1.0 op_sel_hi:[1,0]
	v_pk_mul_f32 v[0:1], v[0:1], v[4:5]
	s_nop 0
	v_cvt_pk_bf16_f32 v0, v0, v1
	v_div_scale_f32 v8, s[30:31], v10, v10, v6
	v_rcp_f32_e32 v1, v11
	s_nop 0
	v_mul_f32_e32 v5, v7, v1
	v_rcp_f32_e32 v1, v10
	s_nop 0
	v_mul_f32_e32 v4, v6, v1
	v_pk_mul_f32 v[2:3], v[2:3], v[4:5]
	s_nop 0
	v_cvt_pk_bf16_f32 v1, v2, v3
	global_store_dwordx2 v[32:33], v[0:1], off offset:128
	s_andn2_b64 vcc, exec, s[0:1]
	s_mov_b32 s56, s54
	s_mov_b32 s38, s55
	s_cbranch_vccz .LBB0_1809
